# v42 + removed the s_setprio 0 / s_setprio 1 toggle between the two 16-MFMA blocks of every MMA segment (52 sites)
# baseline (speedup 1.0000x reference)
; #define GPROBE_BEGIN(id) do { if (((PROBE_GEMM_SEL >> (id)) & 1) && blockIdx.x == 0 && tid_in < 64 && g.N == 20480) { volatile PG8_LAS unsigned long long* PW_ = (volatile PG8_LAS unsigned long long*)(lds + 163840 - 512 + 64); PW_[0] = __builtin_amdgcn_s_memrealtime(); } } while (0)
; #define GPROBE_END(id) do { if (((PROBE_GEMM_SEL >> (id)) & 1) && blockIdx.x == 0 && tid_in < 64 && g.N == 20480) { volatile PG8_LAS unsigned long long* PW_ = (volatile PG8_LAS unsigned long long*)(lds + 163840 - 512 + 64); PW_[1] += __builtin_amdgcn_s_memrealtime() - PW_[0]; } } while (0)
; #define PG8_STAGE(bufoff, gbase, voff) do { _Pragma("unroll") for (int _i = 0; _i < 2; ++_i) \
;         __builtin_amdgcn_global_load_lds((const unsigned*)((const char*)(gbase) + (voff)[_i]), (PG8_LAS unsigned*)(lds + (bufoff) + ldsw + _i * 8192), 16, 0, 0); } while (0)
; #define PG8_LDA(dst, b, h) do { _Pragma("unroll") for (int m = 0; m < 4; ++m) _Pragma("unroll") for (int k = 0; k < 2; ++k) dst[m][k] = *(const PG8_LAS bf16x8*)(lds + PG8_SA(b, h) + aoff + m * 2048 + k * 1024); } while (0)
; #define PG8_BAR __builtin_amdgcn_s_barrier()
; template <class Epi, class Sched, bool ALIGN_EPI = false, bool SP2 = false, bool KHOOK = false>
; __device__ __forceinline__ void gemm_phase(PG8_LAS unsigned char* lds, const Gemm g, const Sched& S, const Epi& E, const int tid_in) {
;     ...
;         const bool has_next = S.next(ui + 1, nxt);
;         const char* nA = has_next ? (const char*)g.A + (size_t)nxt.pm * tstep + (size_t)nxt.pn * ksl : cA; const char* nB = has_next ? (const char*)g.Bt + (size_t)nxt.pn * bts + (size_t)nxt.pn * ksl + (gdv ? (size_t)(nxt.pm / gdv) * gst : 0) : cB;
;         GPROBE_END(2); GPROBE_BEGIN(1);
;         for (int t = 0; t < nt; t += 2) {
;             const bool last = (t == nt - 2);
;             const char* a1 = cA + (size_t)(t + 1) * kstep;
;             const char* a2 = last ? nA : cA + (size_t)(t + 2) * kstep; const char* b2 = last ? nB : cB + (size_t)(t + 2) * kstep;
;             const char* a3 = a2 + kstep; const char* b3 = b2 + kstep;
;             if (last && has_next) S.a_ready(nxt);
;             if constexpr (SP2) {
;             PG8_LDB(B0, 0, 0); PG8_LDB(B1, 0, 1); PG8_SCHED; PG8_LDA(At, 0, 0); PG8_STAGE(PG8_SA(1, 1), a1 + hstep, voffA);
;             PG8_WAIT_V(8); PG8_WAIT_L(0); PG8_BAR; PG8_MMA(0, 0, At, B0); PG8_MMA(0, 1, At, B1); PG8_BAR; PG8_SCHED;
.LBB0_262:
	s_ashr_i32 s17, s16, 31
	s_lshl_b64 s[18:19], s[16:17], 20
	s_add_u32 s26, s78, s18
	s_addc_u32 s27, s79, s19
	s_and_b64 s[18:19], s[22:23], exec
	s_cselect_b32 s11, s27, s49
	s_cselect_b32 s17, s26, s48
	s_ashr_i32 s15, s14, 31
	s_lshl_b64 s[18:19], s[14:15], 20
	v_readlane_b32 s5, v255, 25
	s_add_u32 s30, s5, s18
	v_readlane_b32 s5, v255, 26
	s_addc_u32 s31, s5, s19
	s_and_b64 s[18:19], s[22:23], exec
	s_cselect_b32 s15, s31, s53
	s_cselect_b32 s18, s30, s52
	s_add_u32 s48, s48, 0x80080
	s_addc_u32 s49, s49, 0
	s_add_u32 s19, s52, 0x100
	s_addc_u32 s42, s53, 0
	s_mov_b32 s44, -2
	s_add_u32 s45, s48, 0xfff80080
	s_addc_u32 s46, s49, -1
	s_add_i32 s47, 0, 0x10000
	s_cmp_eq_u32 s44, 28
	s_cselect_b32 s57, s11, s46
	s_cselect_b32 s56, s17, s45
	s_cselect_b32 s53, s15, s42
	s_cselect_b32 s52, s18, s19
	s_add_i32 s45, 0, 0x14000
	v_add_u32_e32 v156, s47, v141
	v_add_u32_e32 v172, s45, v141
	ds_read_b128 v[144:147], v156
	ds_read_b128 v[148:151], v156 offset:1024
	ds_read_b128 v[152:155], v156 offset:2048
	ds_read_b128 v[156:159], v156 offset:3072
	ds_read_b128 v[160:163], v172
	ds_read_b128 v[164:167], v172 offset:1024
	ds_read_b128 v[168:171], v172 offset:2048
	ds_read_b128 v[172:175], v172 offset:3072
	v_lshl_add_u64 v[192:193], s[48:49], 0, v[136:137]
	s_add_i32 m0, s13, 0xc000
	ds_read_b128 v[176:179], v143
	ds_read_b128 v[180:183], v143 offset:1024
	ds_read_b128 v[184:187], v143 offset:2048
	ds_read_b128 v[188:191], v143 offset:3072
	ds_read_b128 v[198:201], v143 offset:4096
	ds_read_b128 v[202:205], v143 offset:5120
	ds_read_b128 v[206:209], v143 offset:6144
	ds_read_b128 v[210:213], v143 offset:7168
	global_load_lds_dwordx4 v[192:193], off
	v_lshl_add_u64 v[192:193], s[48:49], 0, v[138:139]
	s_add_i32 m0, s13, 0xe000
	s_nop 0
	global_load_lds_dwordx4 v[192:193], off
	s_waitcnt vmcnt(18)
	s_waitcnt lgkmcnt(0)
	s_barrier
	s_setprio 1
	s_waitcnt lgkmcnt(0)
	v_mfma_f32_16x16x32_bf16 v[126:129], v[144:147], v[176:179], 0
	v_mfma_f32_16x16x32_bf16 v[122:125], v[152:155], v[176:179], 0
	v_mfma_f32_16x16x32_bf16 v[118:121], v[144:147], v[184:187], 0
	v_mfma_f32_16x16x32_bf16 v[114:117], v[152:155], v[184:187], 0
	v_mfma_f32_16x16x32_bf16 v[102:105], v[144:147], v[198:201], 0
	v_mfma_f32_16x16x32_bf16 v[98:101], v[152:155], v[198:201], 0
	v_mfma_f32_16x16x32_bf16 v[86:89], v[144:147], v[206:209], 0
	v_mfma_f32_16x16x32_bf16 v[82:85], v[152:155], v[206:209], 0
	v_mfma_f32_16x16x32_bf16 v[126:129], v[148:151], v[180:183], v[126:129]
	v_mfma_f32_16x16x32_bf16 v[122:125], v[156:159], v[180:183], v[122:125]
	v_mfma_f32_16x16x32_bf16 v[118:121], v[148:151], v[188:191], v[118:121]
	v_mfma_f32_16x16x32_bf16 v[114:117], v[156:159], v[188:191], v[114:117]
	v_mfma_f32_16x16x32_bf16 v[102:105], v[148:151], v[202:205], v[102:105]
	v_mfma_f32_16x16x32_bf16 v[98:101], v[156:159], v[202:205], v[98:101]
	v_mfma_f32_16x16x32_bf16 v[86:89], v[148:151], v[210:213], v[86:89]
	v_mfma_f32_16x16x32_bf16 v[82:85], v[156:159], v[210:213], v[82:85]
	v_mfma_f32_16x16x32_bf16 v[110:113], v[160:163], v[176:179], 0
	v_mfma_f32_16x16x32_bf16 v[106:109], v[168:171], v[176:179], 0
	v_mfma_f32_16x16x32_bf16 v[94:97], v[160:163], v[184:187], 0
	v_mfma_f32_16x16x32_bf16 v[90:93], v[168:171], v[184:187], 0
	v_mfma_f32_16x16x32_bf16 v[78:81], v[160:163], v[198:201], 0
	v_mfma_f32_16x16x32_bf16 v[74:77], v[168:171], v[198:201], 0
	v_mfma_f32_16x16x32_bf16 v[70:73], v[160:163], v[206:209], 0
	v_mfma_f32_16x16x32_bf16 v[66:69], v[168:171], v[206:209], 0
	v_mfma_f32_16x16x32_bf16 v[110:113], v[164:167], v[180:183], v[110:113]
	v_mfma_f32_16x16x32_bf16 v[106:109], v[172:175], v[180:183], v[106:109]
	v_mfma_f32_16x16x32_bf16 v[94:97], v[164:167], v[188:191], v[94:97]
	v_mfma_f32_16x16x32_bf16 v[90:93], v[172:175], v[188:191], v[90:93]
	v_mfma_f32_16x16x32_bf16 v[78:81], v[164:167], v[202:205], v[78:81]
	v_mfma_f32_16x16x32_bf16 v[74:77], v[172:175], v[202:205], v[74:77]
	v_mfma_f32_16x16x32_bf16 v[70:73], v[164:167], v[210:213], v[70:73]
	v_mfma_f32_16x16x32_bf16 v[66:69], v[172:175], v[210:213], v[66:69]
	s_setprio 0
	s_barrier
	s_add_i32 s46, s47, s37
	v_lshl_add_u64 v[192:193], s[52:53], 0, v[32:33]
	s_mov_b32 m0, s46
	ds_read_b128 v[176:179], v143 offset:16384
	ds_read_b128 v[180:183], v143 offset:17408
	ds_read_b128 v[184:187], v143 offset:18432
	ds_read_b128 v[188:191], v143 offset:19456
	ds_read_b128 v[198:201], v143 offset:20480
	ds_read_b128 v[202:205], v143 offset:21504
	ds_read_b128 v[206:209], v143 offset:22528
	ds_read_b128 v[210:213], v143 offset:23552
	global_load_lds_dwordx4 v[192:193], off
	s_add_i32 m0, s46, 0x2000
	s_add_u32 s46, s52, 0x80000
	v_lshl_add_u64 v[214:215], s[52:53], 0, v[134:135]
	s_addc_u32 s47, s53, 0
	s_add_i32 s45, s45, s37
	global_load_lds_dwordx4 v[214:215], off
	v_lshl_add_u64 v[216:217], s[46:47], 0, v[32:33]
	s_mov_b32 m0, s45
	v_lshl_add_u64 v[218:219], s[56:57], 0, v[132:133]
	global_load_lds_dwordx4 v[216:217], off
	v_lshl_add_u64 v[216:217], s[46:47], 0, v[134:135]
	s_add_i32 m0, s45, 0x2000
	s_nop 0
	global_load_lds_dwordx4 v[216:217], off
	v_lshl_add_u64 v[216:217], s[56:57], 0, v[130:131]
	s_mov_b32 m0, s13
	s_nop 0
	global_load_lds_dwordx4 v[216:217], off
	s_mov_b32 m0, s24
	s_nop 0
	global_load_lds_dwordx4 v[218:219], off
	s_waitcnt vmcnt(24)
	s_waitcnt lgkmcnt(0)
	s_barrier
; #define PG8_STAGE(bufoff, gbase, voff) do { _Pragma("unroll") for (int _i = 0; _i < 2; ++_i) \
;         __builtin_amdgcn_global_load_lds((const unsigned*)((const char*)(gbase) + (voff)[_i]), (PG8_LAS unsigned*)(lds + (bufoff) + ldsw + _i * 8192), 16, 0, 0); } while (0)
; #define PG8_LDA(dst, b, h) do { _Pragma("unroll") for (int m = 0; m < 4; ++m) _Pragma("unroll") for (int k = 0; k < 2; ++k) dst[m][k] = *(const PG8_LAS bf16x8*)(lds + PG8_SA(b, h) + aoff + m * 2048 + k * 1024); } while (0)
; #define PG8_LDB(dst, b, h) do { _Pragma("unroll") for (int n = 0; n < 2; ++n) _Pragma("unroll") for (int k = 0; k < 2; ++k) dst[n][k] = *(const PG8_LAS bf16x8*)(lds + PG8_SB(b, h) + boff + n * 2048 + k * 1024); } while (0)
; #define PG8_MMA(ai, bj, At, Bt) do { __builtin_amdgcn_s_setprio(1); _Pragma("unroll") for (int m = 0; m < 4; ++m) _Pragma("unroll") for (int n = 0; n < 2; ++n) _Pragma("unroll") for (int k = 0; k < 2; ++k) \
;         acc[ai][bj][m][n] = __builtin_amdgcn_mfma_f32_16x16x32_bf16(Bt[n][k], At[m][k], acc[ai][bj][m][n], 0, 0, 0); __builtin_amdgcn_s_setprio(0); } while (0)
; #define PG8_WAIT_V(n) asm volatile("s_waitcnt vmcnt(" #n ")" ::: "memory")
; #define PG8_WAIT_L(n) asm volatile("s_waitcnt lgkmcnt(" #n ")" ::: "memory")
; #define PG8_BAR __builtin_amdgcn_s_barrier()
; #define PG8_SCHED __builtin_amdgcn_sched_barrier(0)
; template <class Epi, class Sched, bool ALIGN_EPI = false, bool SP2 = false, bool KHOOK = false>
; __device__ __forceinline__ void gemm_phase(PG8_LAS unsigned char* lds, const Gemm g, const Sched& S, const Epi& E, const int tid_in) {
;     ...
;             PG8_LDA(At, 0, 1); PG8_STAGE(PG8_SB(0, 0), b2, voffB); PG8_STAGE(PG8_SB(0, 1), b2 + hstep, voffB); PG8_STAGE(PG8_SA(0, 0), a2, voffA);
;             PG8_WAIT_V(8); PG8_WAIT_L(0); PG8_BAR; PG8_MMA(1, 0, At, B0); PG8_MMA(1, 1, At, B1); PG8_BAR; PG8_SCHED;
;             PG8_LDB(B0, 1, 0); PG8_LDB(B1, 1, 1); PG8_SCHED; PG8_LDA(At, 1, 0); PG8_STAGE(PG8_SA(0, 1), a2 + hstep, voffA);
;             PG8_WAIT_V(8); PG8_WAIT_L(0); PG8_BAR; PG8_MMA(0, 0, At, B0); PG8_MMA(0, 1, At, B1); PG8_BAR; PG8_SCHED;
	s_setprio 1
	s_waitcnt lgkmcnt(0)
	v_mfma_f32_16x16x32_bf16 v[62:65], v[144:147], v[176:179], 0
	v_mfma_f32_16x16x32_bf16 v[58:61], v[152:155], v[176:179], 0
	v_mfma_f32_16x16x32_bf16 v[54:57], v[144:147], v[184:187], 0
	v_mfma_f32_16x16x32_bf16 v[50:53], v[152:155], v[184:187], 0
	v_mfma_f32_16x16x32_bf16 v[38:41], v[144:147], v[198:201], 0
	v_mfma_f32_16x16x32_bf16 v[34:37], v[152:155], v[198:201], 0
	v_mfma_f32_16x16x32_bf16 v[20:23], v[144:147], v[206:209], 0
	v_mfma_f32_16x16x32_bf16 v[16:19], v[152:155], v[206:209], 0
	v_mfma_f32_16x16x32_bf16 v[62:65], v[148:151], v[180:183], v[62:65]
	v_mfma_f32_16x16x32_bf16 v[58:61], v[156:159], v[180:183], v[58:61]
	v_mfma_f32_16x16x32_bf16 v[54:57], v[148:151], v[188:191], v[54:57]
	v_mfma_f32_16x16x32_bf16 v[50:53], v[156:159], v[188:191], v[50:53]
	v_mfma_f32_16x16x32_bf16 v[38:41], v[148:151], v[202:205], v[38:41]
	v_mfma_f32_16x16x32_bf16 v[34:37], v[156:159], v[202:205], v[34:37]
	v_mfma_f32_16x16x32_bf16 v[20:23], v[148:151], v[210:213], v[20:23]
	v_mfma_f32_16x16x32_bf16 v[16:19], v[156:159], v[210:213], v[16:19]
	v_mfma_f32_16x16x32_bf16 v[46:49], v[160:163], v[176:179], 0
	v_mfma_f32_16x16x32_bf16 v[42:45], v[168:171], v[176:179], 0
	v_mfma_f32_16x16x32_bf16 v[28:31], v[160:163], v[184:187], 0
	v_mfma_f32_16x16x32_bf16 v[24:27], v[168:171], v[184:187], 0
	v_mfma_f32_16x16x32_bf16 v[12:15], v[160:163], v[198:201], 0
	v_mfma_f32_16x16x32_bf16 v[8:11], v[168:171], v[198:201], 0
	v_mfma_f32_16x16x32_bf16 v[4:7], v[160:163], v[206:209], 0
	v_mfma_f32_16x16x32_bf16 v[0:3], v[168:171], v[206:209], 0
	v_mfma_f32_16x16x32_bf16 v[46:49], v[164:167], v[180:183], v[46:49]
	v_mfma_f32_16x16x32_bf16 v[42:45], v[172:175], v[180:183], v[42:45]
	v_mfma_f32_16x16x32_bf16 v[28:31], v[164:167], v[188:191], v[28:31]
	v_mfma_f32_16x16x32_bf16 v[24:27], v[172:175], v[188:191], v[24:27]
	v_mfma_f32_16x16x32_bf16 v[12:15], v[164:167], v[202:205], v[12:15]
	v_mfma_f32_16x16x32_bf16 v[8:11], v[172:175], v[202:205], v[8:11]
	v_mfma_f32_16x16x32_bf16 v[4:7], v[164:167], v[210:213], v[4:7]
	v_mfma_f32_16x16x32_bf16 v[0:3], v[172:175], v[210:213], v[0:3]
	s_setprio 0
	s_barrier
	s_add_i32 s45, 0, 0x18000
	s_add_i32 s50, 0, 0x1c000
	v_add_u32_e32 v156, s45, v141
	v_add_u32_e32 v172, s50, v141
	ds_read_b128 v[144:147], v156
	ds_read_b128 v[148:151], v156 offset:1024
	ds_read_b128 v[152:155], v156 offset:2048
	ds_read_b128 v[156:159], v156 offset:3072
	ds_read_b128 v[160:163], v172
	ds_read_b128 v[164:167], v172 offset:1024
	ds_read_b128 v[168:171], v172 offset:2048
	ds_read_b128 v[172:175], v172 offset:3072
	s_add_u32 s46, s56, 0x80000
	s_addc_u32 s47, s57, 0
	s_mov_b32 m0, s25
	v_lshl_add_u64 v[220:221], s[46:47], 0, v[130:131]
	ds_read_b128 v[176:179], v143 offset:32768
	ds_read_b128 v[180:183], v143 offset:33792
	ds_read_b128 v[184:187], v143 offset:34816
	ds_read_b128 v[188:191], v143 offset:35840
	ds_read_b128 v[198:201], v143 offset:36864
	ds_read_b128 v[202:205], v143 offset:37888
	ds_read_b128 v[206:209], v143 offset:38912
	ds_read_b128 v[210:213], v143 offset:39936
	global_load_lds_dwordx4 v[220:221], off
	v_lshl_add_u64 v[220:221], s[46:47], 0, v[132:133]
	s_mov_b32 m0, s38
	s_nop 0
	global_load_lds_dwordx4 v[220:221], off
	s_waitcnt vmcnt(8)
	s_waitcnt lgkmcnt(0)
	s_barrier
	s_setprio 1
	s_waitcnt lgkmcnt(0)
	v_mfma_f32_16x16x32_bf16 v[126:129], v[144:147], v[176:179], v[126:129]
	v_mfma_f32_16x16x32_bf16 v[122:125], v[152:155], v[176:179], v[122:125]
	v_mfma_f32_16x16x32_bf16 v[118:121], v[144:147], v[184:187], v[118:121]
	v_mfma_f32_16x16x32_bf16 v[114:117], v[152:155], v[184:187], v[114:117]
	v_mfma_f32_16x16x32_bf16 v[102:105], v[144:147], v[198:201], v[102:105]
	v_mfma_f32_16x16x32_bf16 v[98:101], v[152:155], v[198:201], v[98:101]
	v_mfma_f32_16x16x32_bf16 v[86:89], v[144:147], v[206:209], v[86:89]
	v_mfma_f32_16x16x32_bf16 v[82:85], v[152:155], v[206:209], v[82:85]
	v_mfma_f32_16x16x32_bf16 v[126:129], v[148:151], v[180:183], v[126:129]
	v_mfma_f32_16x16x32_bf16 v[122:125], v[156:159], v[180:183], v[122:125]
	v_mfma_f32_16x16x32_bf16 v[118:121], v[148:151], v[188:191], v[118:121]
	v_mfma_f32_16x16x32_bf16 v[114:117], v[156:159], v[188:191], v[114:117]
	v_mfma_f32_16x16x32_bf16 v[102:105], v[148:151], v[202:205], v[102:105]
	v_mfma_f32_16x16x32_bf16 v[98:101], v[156:159], v[202:205], v[98:101]
	v_mfma_f32_16x16x32_bf16 v[86:89], v[148:151], v[210:213], v[86:89]
	v_mfma_f32_16x16x32_bf16 v[82:85], v[156:159], v[210:213], v[82:85]
	v_mfma_f32_16x16x32_bf16 v[110:113], v[160:163], v[176:179], v[110:113]
	v_mfma_f32_16x16x32_bf16 v[106:109], v[168:171], v[176:179], v[106:109]
	v_mfma_f32_16x16x32_bf16 v[94:97], v[160:163], v[184:187], v[94:97]
	v_mfma_f32_16x16x32_bf16 v[90:93], v[168:171], v[184:187], v[90:93]
	v_mfma_f32_16x16x32_bf16 v[78:81], v[160:163], v[198:201], v[78:81]
	v_mfma_f32_16x16x32_bf16 v[74:77], v[168:171], v[198:201], v[74:77]
	v_mfma_f32_16x16x32_bf16 v[70:73], v[160:163], v[206:209], v[70:73]
	v_mfma_f32_16x16x32_bf16 v[66:69], v[168:171], v[206:209], v[66:69]
	v_mfma_f32_16x16x32_bf16 v[110:113], v[164:167], v[180:183], v[110:113]
	v_mfma_f32_16x16x32_bf16 v[106:109], v[172:175], v[180:183], v[106:109]
	v_mfma_f32_16x16x32_bf16 v[94:97], v[164:167], v[188:191], v[94:97]
	v_mfma_f32_16x16x32_bf16 v[90:93], v[172:175], v[188:191], v[90:93]
	v_mfma_f32_16x16x32_bf16 v[78:81], v[164:167], v[202:205], v[78:81]
	v_mfma_f32_16x16x32_bf16 v[74:77], v[172:175], v[202:205], v[74:77]
	v_mfma_f32_16x16x32_bf16 v[70:73], v[164:167], v[210:213], v[70:73]
	v_mfma_f32_16x16x32_bf16 v[66:69], v[172:175], v[210:213], v[66:69]
	s_setprio 0
	s_barrier
; #define PG8_STAGE(bufoff, gbase, voff) do { _Pragma("unroll") for (int _i = 0; _i < 2; ++_i) \
;         __builtin_amdgcn_global_load_lds((const unsigned*)((const char*)(gbase) + (voff)[_i]), (PG8_LAS unsigned*)(lds + (bufoff) + ldsw + _i * 8192), 16, 0, 0); } while (0)
; #define PG8_LDA(dst, b, h) do { _Pragma("unroll") for (int m = 0; m < 4; ++m) _Pragma("unroll") for (int k = 0; k < 2; ++k) dst[m][k] = *(const PG8_LAS bf16x8*)(lds + PG8_SA(b, h) + aoff + m * 2048 + k * 1024); } while (0)
; #define PG8_LDB(dst, b, h) do { _Pragma("unroll") for (int n = 0; n < 2; ++n) _Pragma("unroll") for (int k = 0; k < 2; ++k) dst[n][k] = *(const PG8_LAS bf16x8*)(lds + PG8_SB(b, h) + boff + n * 2048 + k * 1024); } while (0)
; #define PG8_MMA(ai, bj, At, Bt) do { __builtin_amdgcn_s_setprio(1); _Pragma("unroll") for (int m = 0; m < 4; ++m) _Pragma("unroll") for (int n = 0; n < 2; ++n) _Pragma("unroll") for (int k = 0; k < 2; ++k) \
;         acc[ai][bj][m][n] = __builtin_amdgcn_mfma_f32_16x16x32_bf16(Bt[n][k], At[m][k], acc[ai][bj][m][n], 0, 0, 0); __builtin_amdgcn_s_setprio(0); } while (0)
; #define PG8_WAIT_V(n) asm volatile("s_waitcnt vmcnt(" #n ")" ::: "memory")
; #define PG8_WAIT_L(n) asm volatile("s_waitcnt lgkmcnt(" #n ")" ::: "memory")
; #define PG8_BAR __builtin_amdgcn_s_barrier()
; #define PG8_SCHED __builtin_amdgcn_sched_barrier(0)
; template <class Epi, class Sched, bool ALIGN_EPI = false, bool SP2 = false, bool KHOOK = false>
; __device__ __forceinline__ void gemm_phase(PG8_LAS unsigned char* lds, const Gemm g, const Sched& S, const Epi& E, const int tid_in) {
;     ...
;             PG8_LDB(B0, 0, 0); PG8_LDB(B1, 0, 1); PG8_SCHED; PG8_LDA(At, 0, 0); PG8_STAGE(PG8_SA(1, 1), a1 + hstep, voffA);
;             PG8_WAIT_V(8); PG8_WAIT_L(0); PG8_BAR; PG8_MMA(0, 0, At, B0); PG8_MMA(0, 1, At, B1); PG8_BAR; PG8_SCHED;
;     ...
;             PG8_LDA(At, 1, 1); PG8_STAGE(PG8_SB(1, 0), b3, voffB); PG8_STAGE(PG8_SB(1, 1), b3 + hstep, voffB); PG8_STAGE(PG8_SA(1, 0), a3, voffA);
;             PG8_WAIT_V(8); PG8_WAIT_L(0); PG8_BAR; PG8_MMA(1, 0, At, B0); PG8_MMA(1, 1, At, B1); PG8_BAR; PG8_SCHED;
	s_add_i32 s45, s45, s37
	v_lshl_add_u64 v[192:193], v[192:193], 0, s[90:91]
	s_mov_b32 m0, s45
	ds_read_b128 v[176:179], v143 offset:49152
	ds_read_b128 v[180:183], v143 offset:50176
	ds_read_b128 v[184:187], v143 offset:51200
	ds_read_b128 v[188:191], v143 offset:52224
	ds_read_b128 v[198:201], v143 offset:53248
	ds_read_b128 v[202:205], v143 offset:54272
	ds_read_b128 v[206:209], v143 offset:55296
	ds_read_b128 v[210:213], v143 offset:56320
	global_load_lds_dwordx4 v[192:193], off
	s_add_i32 m0, s45, 0x2000
	s_add_u32 s46, s52, 0x80080
	v_lshl_add_u64 v[192:193], v[214:215], 0, s[90:91]
	s_addc_u32 s47, s53, 0
	s_add_i32 s45, s50, s37
	global_load_lds_dwordx4 v[192:193], off
	v_lshl_add_u64 v[192:193], s[46:47], 0, v[32:33]
	s_mov_b32 m0, s45
	s_nop 0
	global_load_lds_dwordx4 v[192:193], off
	v_lshl_add_u64 v[192:193], s[46:47], 0, v[134:135]
	s_add_i32 m0, s45, 0x2000
	s_nop 0
	global_load_lds_dwordx4 v[192:193], off
	v_lshl_add_u64 v[192:193], v[216:217], 0, s[90:91]
	s_mov_b32 m0, s39
	s_nop 0
	global_load_lds_dwordx4 v[192:193], off
	v_lshl_add_u64 v[192:193], v[218:219], 0, s[90:91]
	s_mov_b32 m0, s40
	s_nop 0
	global_load_lds_dwordx4 v[192:193], off
	s_waitcnt vmcnt(8)
	s_waitcnt lgkmcnt(0)
	s_barrier
	s_setprio 1
	s_waitcnt lgkmcnt(0)
	v_mfma_f32_16x16x32_bf16 v[62:65], v[144:147], v[176:179], v[62:65]
	v_mfma_f32_16x16x32_bf16 v[58:61], v[152:155], v[176:179], v[58:61]
	v_mfma_f32_16x16x32_bf16 v[54:57], v[144:147], v[184:187], v[54:57]
	v_mfma_f32_16x16x32_bf16 v[50:53], v[152:155], v[184:187], v[50:53]
	v_mfma_f32_16x16x32_bf16 v[38:41], v[144:147], v[198:201], v[38:41]
	v_mfma_f32_16x16x32_bf16 v[34:37], v[152:155], v[198:201], v[34:37]
	v_mfma_f32_16x16x32_bf16 v[20:23], v[144:147], v[206:209], v[20:23]
	v_mfma_f32_16x16x32_bf16 v[16:19], v[152:155], v[206:209], v[16:19]
	v_mfma_f32_16x16x32_bf16 v[62:65], v[148:151], v[180:183], v[62:65]
	v_mfma_f32_16x16x32_bf16 v[58:61], v[156:159], v[180:183], v[58:61]
	v_mfma_f32_16x16x32_bf16 v[54:57], v[148:151], v[188:191], v[54:57]
	v_mfma_f32_16x16x32_bf16 v[50:53], v[156:159], v[188:191], v[50:53]
	v_mfma_f32_16x16x32_bf16 v[38:41], v[148:151], v[202:205], v[38:41]
	v_mfma_f32_16x16x32_bf16 v[34:37], v[156:159], v[202:205], v[34:37]
	v_mfma_f32_16x16x32_bf16 v[20:23], v[148:151], v[210:213], v[20:23]
	v_mfma_f32_16x16x32_bf16 v[16:19], v[156:159], v[210:213], v[16:19]
	v_mfma_f32_16x16x32_bf16 v[46:49], v[160:163], v[176:179], v[46:49]
	v_mfma_f32_16x16x32_bf16 v[42:45], v[168:171], v[176:179], v[42:45]
	v_mfma_f32_16x16x32_bf16 v[28:31], v[160:163], v[184:187], v[28:31]
	v_mfma_f32_16x16x32_bf16 v[24:27], v[168:171], v[184:187], v[24:27]
	v_mfma_f32_16x16x32_bf16 v[12:15], v[160:163], v[198:201], v[12:15]
	v_mfma_f32_16x16x32_bf16 v[8:11], v[168:171], v[198:201], v[8:11]
	v_mfma_f32_16x16x32_bf16 v[4:7], v[160:163], v[206:209], v[4:7]
	v_mfma_f32_16x16x32_bf16 v[0:3], v[168:171], v[206:209], v[0:3]
	v_mfma_f32_16x16x32_bf16 v[46:49], v[164:167], v[180:183], v[46:49]
	v_mfma_f32_16x16x32_bf16 v[42:45], v[172:175], v[180:183], v[42:45]
	v_mfma_f32_16x16x32_bf16 v[28:31], v[164:167], v[188:191], v[28:31]
	v_mfma_f32_16x16x32_bf16 v[24:27], v[172:175], v[188:191], v[24:27]
	v_mfma_f32_16x16x32_bf16 v[12:15], v[164:167], v[202:205], v[12:15]
	v_mfma_f32_16x16x32_bf16 v[8:11], v[172:175], v[202:205], v[8:11]
	v_mfma_f32_16x16x32_bf16 v[4:7], v[164:167], v[210:213], v[4:7]
	v_mfma_f32_16x16x32_bf16 v[0:3], v[172:175], v[210:213], v[0:3]
	s_setprio 0
	s_barrier
	s_add_i32 s44, s44, 2
	s_add_u32 s48, s48, 0x100
	s_addc_u32 s49, s49, 0
	s_add_u32 s19, s19, 0x100
	s_addc_u32 s42, s42, 0
	s_cmp_gt_u32 s44, 29
.LBB0_263:
	s_add_u32 s45, s48, 0xfff80080
	s_addc_u32 s46, s49, -1
	s_add_i32 s47, 0, 0x10000
	s_cmp_eq_u32 s44, 28
	s_cselect_b32 s57, s11, s46
	s_cselect_b32 s56, s17, s45
	s_cselect_b32 s53, s15, s42
	s_cselect_b32 s52, s18, s19
	s_add_i32 s45, 0, 0x14000
	v_add_u32_e32 v156, s47, v141
	v_add_u32_e32 v172, s45, v141
	ds_read_b128 v[144:147], v156
	ds_read_b128 v[148:151], v156 offset:1024
	ds_read_b128 v[152:155], v156 offset:2048
	ds_read_b128 v[156:159], v156 offset:3072
	ds_read_b128 v[160:163], v172
	ds_read_b128 v[164:167], v172 offset:1024
	ds_read_b128 v[168:171], v172 offset:2048
	ds_read_b128 v[172:175], v172 offset:3072
	v_lshl_add_u64 v[192:193], s[48:49], 0, v[136:137]
	s_add_i32 m0, s13, 0xc000
	ds_read_b128 v[176:179], v143
	ds_read_b128 v[180:183], v143 offset:1024
	ds_read_b128 v[184:187], v143 offset:2048
	ds_read_b128 v[188:191], v143 offset:3072
	ds_read_b128 v[198:201], v143 offset:4096
	ds_read_b128 v[202:205], v143 offset:5120
	ds_read_b128 v[206:209], v143 offset:6144
	ds_read_b128 v[210:213], v143 offset:7168
	global_load_lds_dwordx4 v[192:193], off
	v_lshl_add_u64 v[192:193], s[48:49], 0, v[138:139]
	s_add_i32 m0, s13, 0xe000
	s_nop 0
	global_load_lds_dwordx4 v[192:193], off
	s_waitcnt vmcnt(8)
	s_waitcnt lgkmcnt(0)
	s_barrier
; #define PG8_STAGE(bufoff, gbase, voff) do { _Pragma("unroll") for (int _i = 0; _i < 2; ++_i) \
;         __builtin_amdgcn_global_load_lds((const unsigned*)((const char*)(gbase) + (voff)[_i]), (PG8_LAS unsigned*)(lds + (bufoff) + ldsw + _i * 8192), 16, 0, 0); } while (0)
; #define PG8_LDA(dst, b, h) do { _Pragma("unroll") for (int m = 0; m < 4; ++m) _Pragma("unroll") for (int k = 0; k < 2; ++k) dst[m][k] = *(const PG8_LAS bf16x8*)(lds + PG8_SA(b, h) + aoff + m * 2048 + k * 1024); } while (0)
; #define PG8_MMA(ai, bj, At, Bt) do { __builtin_amdgcn_s_setprio(1); _Pragma("unroll") for (int m = 0; m < 4; ++m) _Pragma("unroll") for (int n = 0; n < 2; ++n) _Pragma("unroll") for (int k = 0; k < 2; ++k) \
;         acc[ai][bj][m][n] = __builtin_amdgcn_mfma_f32_16x16x32_bf16(Bt[n][k], At[m][k], acc[ai][bj][m][n], 0, 0, 0); __builtin_amdgcn_s_setprio(0); } while (0)
; #define PG8_WAIT_V(n) asm volatile("s_waitcnt vmcnt(" #n ")" ::: "memory")
; #define PG8_WAIT_L(n) asm volatile("s_waitcnt lgkmcnt(" #n ")" ::: "memory")
; #define PG8_BAR __builtin_amdgcn_s_barrier()
; #define PG8_SCHED __builtin_amdgcn_sched_barrier(0)
; template <class Epi, class Sched, bool ALIGN_EPI = false, bool SP2 = false, bool KHOOK = false>
; __device__ __forceinline__ void gemm_phase(PG8_LAS unsigned char* lds, const Gemm g, const Sched& S, const Epi& E, const int tid_in) {
;     ...
;             PG8_WAIT_V(8); PG8_WAIT_L(0); PG8_BAR; PG8_MMA(0, 0, At, B0); PG8_MMA(0, 1, At, B1); PG8_BAR; PG8_SCHED;
;             PG8_LDA(At, 0, 1); PG8_STAGE(PG8_SB(0, 0), b2, voffB); PG8_STAGE(PG8_SB(0, 1), b2 + hstep, voffB); PG8_STAGE(PG8_SA(0, 0), a2, voffA);
;             PG8_WAIT_V(8); PG8_WAIT_L(0); PG8_BAR; PG8_MMA(1, 0, At, B0); PG8_MMA(1, 1, At, B1); PG8_BAR; PG8_SCHED;
	s_setprio 1
	s_waitcnt lgkmcnt(0)
	v_mfma_f32_16x16x32_bf16 v[126:129], v[144:147], v[176:179], v[126:129]
	v_mfma_f32_16x16x32_bf16 v[122:125], v[152:155], v[176:179], v[122:125]
	v_mfma_f32_16x16x32_bf16 v[118:121], v[144:147], v[184:187], v[118:121]
	v_mfma_f32_16x16x32_bf16 v[114:117], v[152:155], v[184:187], v[114:117]
	v_mfma_f32_16x16x32_bf16 v[102:105], v[144:147], v[198:201], v[102:105]
	v_mfma_f32_16x16x32_bf16 v[98:101], v[152:155], v[198:201], v[98:101]
	v_mfma_f32_16x16x32_bf16 v[86:89], v[144:147], v[206:209], v[86:89]
	v_mfma_f32_16x16x32_bf16 v[82:85], v[152:155], v[206:209], v[82:85]
	v_mfma_f32_16x16x32_bf16 v[126:129], v[148:151], v[180:183], v[126:129]
	v_mfma_f32_16x16x32_bf16 v[122:125], v[156:159], v[180:183], v[122:125]
	v_mfma_f32_16x16x32_bf16 v[118:121], v[148:151], v[188:191], v[118:121]
	v_mfma_f32_16x16x32_bf16 v[114:117], v[156:159], v[188:191], v[114:117]
	v_mfma_f32_16x16x32_bf16 v[102:105], v[148:151], v[202:205], v[102:105]
	v_mfma_f32_16x16x32_bf16 v[98:101], v[156:159], v[202:205], v[98:101]
	v_mfma_f32_16x16x32_bf16 v[86:89], v[148:151], v[210:213], v[86:89]
	v_mfma_f32_16x16x32_bf16 v[82:85], v[156:159], v[210:213], v[82:85]
	v_mfma_f32_16x16x32_bf16 v[110:113], v[160:163], v[176:179], v[110:113]
	v_mfma_f32_16x16x32_bf16 v[106:109], v[168:171], v[176:179], v[106:109]
	v_mfma_f32_16x16x32_bf16 v[94:97], v[160:163], v[184:187], v[94:97]
	v_mfma_f32_16x16x32_bf16 v[90:93], v[168:171], v[184:187], v[90:93]
	v_mfma_f32_16x16x32_bf16 v[78:81], v[160:163], v[198:201], v[78:81]
	v_mfma_f32_16x16x32_bf16 v[74:77], v[168:171], v[198:201], v[74:77]
	v_mfma_f32_16x16x32_bf16 v[70:73], v[160:163], v[206:209], v[70:73]
	v_mfma_f32_16x16x32_bf16 v[66:69], v[168:171], v[206:209], v[66:69]
	v_mfma_f32_16x16x32_bf16 v[110:113], v[164:167], v[180:183], v[110:113]
	v_mfma_f32_16x16x32_bf16 v[106:109], v[172:175], v[180:183], v[106:109]
	v_mfma_f32_16x16x32_bf16 v[94:97], v[164:167], v[188:191], v[94:97]
	v_mfma_f32_16x16x32_bf16 v[90:93], v[172:175], v[188:191], v[90:93]
	v_mfma_f32_16x16x32_bf16 v[78:81], v[164:167], v[202:205], v[78:81]
	v_mfma_f32_16x16x32_bf16 v[74:77], v[172:175], v[202:205], v[74:77]
	v_mfma_f32_16x16x32_bf16 v[70:73], v[164:167], v[210:213], v[70:73]
	v_mfma_f32_16x16x32_bf16 v[66:69], v[172:175], v[210:213], v[66:69]
	s_setprio 0
	s_barrier
	s_add_i32 s46, s47, s37
	v_lshl_add_u64 v[192:193], s[52:53], 0, v[32:33]
	s_mov_b32 m0, s46
	ds_read_b128 v[176:179], v143 offset:16384
	ds_read_b128 v[180:183], v143 offset:17408
	ds_read_b128 v[184:187], v143 offset:18432
	ds_read_b128 v[188:191], v143 offset:19456
	ds_read_b128 v[198:201], v143 offset:20480
	ds_read_b128 v[202:205], v143 offset:21504
	ds_read_b128 v[206:209], v143 offset:22528
	ds_read_b128 v[210:213], v143 offset:23552
	global_load_lds_dwordx4 v[192:193], off
	s_add_i32 m0, s46, 0x2000
	s_add_u32 s46, s52, 0x80000
	v_lshl_add_u64 v[214:215], s[52:53], 0, v[134:135]
	s_addc_u32 s47, s53, 0
	s_add_i32 s45, s45, s37
	global_load_lds_dwordx4 v[214:215], off
	v_lshl_add_u64 v[216:217], s[46:47], 0, v[32:33]
	s_mov_b32 m0, s45
	v_lshl_add_u64 v[218:219], s[56:57], 0, v[132:133]
	global_load_lds_dwordx4 v[216:217], off
	v_lshl_add_u64 v[216:217], s[46:47], 0, v[134:135]
	s_add_i32 m0, s45, 0x2000
	s_nop 0
	global_load_lds_dwordx4 v[216:217], off
	v_lshl_add_u64 v[216:217], s[56:57], 0, v[130:131]
	s_mov_b32 m0, s13
	s_nop 0
	global_load_lds_dwordx4 v[216:217], off
	s_mov_b32 m0, s24
	s_nop 0
	global_load_lds_dwordx4 v[218:219], off
	s_waitcnt vmcnt(8)
	s_waitcnt lgkmcnt(0)
	s_barrier
	s_setprio 1
	s_waitcnt lgkmcnt(0)
	v_mfma_f32_16x16x32_bf16 v[62:65], v[144:147], v[176:179], v[62:65]
	v_mfma_f32_16x16x32_bf16 v[58:61], v[152:155], v[176:179], v[58:61]
	v_mfma_f32_16x16x32_bf16 v[54:57], v[144:147], v[184:187], v[54:57]
	v_mfma_f32_16x16x32_bf16 v[50:53], v[152:155], v[184:187], v[50:53]
	v_mfma_f32_16x16x32_bf16 v[38:41], v[144:147], v[198:201], v[38:41]
	v_mfma_f32_16x16x32_bf16 v[34:37], v[152:155], v[198:201], v[34:37]
	v_mfma_f32_16x16x32_bf16 v[20:23], v[144:147], v[206:209], v[20:23]
	v_mfma_f32_16x16x32_bf16 v[16:19], v[152:155], v[206:209], v[16:19]
	v_mfma_f32_16x16x32_bf16 v[62:65], v[148:151], v[180:183], v[62:65]
	v_mfma_f32_16x16x32_bf16 v[58:61], v[156:159], v[180:183], v[58:61]
	v_mfma_f32_16x16x32_bf16 v[54:57], v[148:151], v[188:191], v[54:57]
	v_mfma_f32_16x16x32_bf16 v[50:53], v[156:159], v[188:191], v[50:53]
	v_mfma_f32_16x16x32_bf16 v[38:41], v[148:151], v[202:205], v[38:41]
	v_mfma_f32_16x16x32_bf16 v[34:37], v[156:159], v[202:205], v[34:37]
	v_mfma_f32_16x16x32_bf16 v[20:23], v[148:151], v[210:213], v[20:23]
	v_mfma_f32_16x16x32_bf16 v[16:19], v[156:159], v[210:213], v[16:19]
	v_mfma_f32_16x16x32_bf16 v[46:49], v[160:163], v[176:179], v[46:49]
	v_mfma_f32_16x16x32_bf16 v[42:45], v[168:171], v[176:179], v[42:45]
	v_mfma_f32_16x16x32_bf16 v[28:31], v[160:163], v[184:187], v[28:31]
	v_mfma_f32_16x16x32_bf16 v[24:27], v[168:171], v[184:187], v[24:27]
	v_mfma_f32_16x16x32_bf16 v[12:15], v[160:163], v[198:201], v[12:15]
	v_mfma_f32_16x16x32_bf16 v[8:11], v[168:171], v[198:201], v[8:11]
	v_mfma_f32_16x16x32_bf16 v[4:7], v[160:163], v[206:209], v[4:7]
	v_mfma_f32_16x16x32_bf16 v[0:3], v[168:171], v[206:209], v[0:3]
	v_mfma_f32_16x16x32_bf16 v[46:49], v[164:167], v[180:183], v[46:49]
	v_mfma_f32_16x16x32_bf16 v[42:45], v[172:175], v[180:183], v[42:45]
	v_mfma_f32_16x16x32_bf16 v[28:31], v[164:167], v[188:191], v[28:31]
	v_mfma_f32_16x16x32_bf16 v[24:27], v[172:175], v[188:191], v[24:27]
	v_mfma_f32_16x16x32_bf16 v[12:15], v[164:167], v[202:205], v[12:15]
	v_mfma_f32_16x16x32_bf16 v[8:11], v[172:175], v[202:205], v[8:11]
	v_mfma_f32_16x16x32_bf16 v[4:7], v[164:167], v[210:213], v[4:7]
	v_mfma_f32_16x16x32_bf16 v[0:3], v[172:175], v[210:213], v[0:3]
	s_setprio 0
	s_barrier
; #define PG8_STAGE(bufoff, gbase, voff) do { _Pragma("unroll") for (int _i = 0; _i < 2; ++_i) \
;         __builtin_amdgcn_global_load_lds((const unsigned*)((const char*)(gbase) + (voff)[_i]), (PG8_LAS unsigned*)(lds + (bufoff) + ldsw + _i * 8192), 16, 0, 0); } while (0)
; #define PG8_LDA(dst, b, h) do { _Pragma("unroll") for (int m = 0; m < 4; ++m) _Pragma("unroll") for (int k = 0; k < 2; ++k) dst[m][k] = *(const PG8_LAS bf16x8*)(lds + PG8_SA(b, h) + aoff + m * 2048 + k * 1024); } while (0)
; #define PG8_LDB(dst, b, h) do { _Pragma("unroll") for (int n = 0; n < 2; ++n) _Pragma("unroll") for (int k = 0; k < 2; ++k) dst[n][k] = *(const PG8_LAS bf16x8*)(lds + PG8_SB(b, h) + boff + n * 2048 + k * 1024); } while (0)
; #define PG8_MMA(ai, bj, At, Bt) do { __builtin_amdgcn_s_setprio(1); _Pragma("unroll") for (int m = 0; m < 4; ++m) _Pragma("unroll") for (int n = 0; n < 2; ++n) _Pragma("unroll") for (int k = 0; k < 2; ++k) \
;         acc[ai][bj][m][n] = __builtin_amdgcn_mfma_f32_16x16x32_bf16(Bt[n][k], At[m][k], acc[ai][bj][m][n], 0, 0, 0); __builtin_amdgcn_s_setprio(0); } while (0)
; #define PG8_WAIT_V(n) asm volatile("s_waitcnt vmcnt(" #n ")" ::: "memory")
; #define PG8_WAIT_L(n) asm volatile("s_waitcnt lgkmcnt(" #n ")" ::: "memory")
; #define PG8_BAR __builtin_amdgcn_s_barrier()
; #define PG8_SCHED __builtin_amdgcn_sched_barrier(0)
; template <class Epi, class Sched, bool ALIGN_EPI = false, bool SP2 = false, bool KHOOK = false>
; __device__ __forceinline__ void gemm_phase(PG8_LAS unsigned char* lds, const Gemm g, const Sched& S, const Epi& E, const int tid_in) {
;     ...
;             PG8_LDB(B0, 1, 0); PG8_LDB(B1, 1, 1); PG8_SCHED; PG8_LDA(At, 1, 0); PG8_STAGE(PG8_SA(0, 1), a2 + hstep, voffA);
;             PG8_WAIT_V(8); PG8_WAIT_L(0); PG8_BAR; PG8_MMA(0, 0, At, B0); PG8_MMA(0, 1, At, B1); PG8_BAR; PG8_SCHED;
	s_add_i32 s45, 0, 0x18000
	s_add_i32 s50, 0, 0x1c000
	v_add_u32_e32 v156, s45, v141
	v_add_u32_e32 v172, s50, v141
	ds_read_b128 v[144:147], v156
	ds_read_b128 v[148:151], v156 offset:1024
	ds_read_b128 v[152:155], v156 offset:2048
	ds_read_b128 v[156:159], v156 offset:3072
	ds_read_b128 v[160:163], v172
	ds_read_b128 v[164:167], v172 offset:1024
	ds_read_b128 v[168:171], v172 offset:2048
	ds_read_b128 v[172:175], v172 offset:3072
	s_add_u32 s46, s56, 0x80000
	s_addc_u32 s47, s57, 0
	s_mov_b32 m0, s25
	v_lshl_add_u64 v[220:221], s[46:47], 0, v[130:131]
	ds_read_b128 v[176:179], v143 offset:32768
	ds_read_b128 v[180:183], v143 offset:33792
	ds_read_b128 v[184:187], v143 offset:34816
	ds_read_b128 v[188:191], v143 offset:35840
	ds_read_b128 v[198:201], v143 offset:36864
	ds_read_b128 v[202:205], v143 offset:37888
	ds_read_b128 v[206:209], v143 offset:38912
	ds_read_b128 v[210:213], v143 offset:39936
	global_load_lds_dwordx4 v[220:221], off
	v_lshl_add_u64 v[220:221], s[46:47], 0, v[132:133]
	s_mov_b32 m0, s38
	s_nop 0
	global_load_lds_dwordx4 v[220:221], off
	s_waitcnt vmcnt(8)
	s_waitcnt lgkmcnt(0)
	s_barrier
	s_setprio 1
	s_waitcnt lgkmcnt(0)
	v_mfma_f32_16x16x32_bf16 v[126:129], v[144:147], v[176:179], v[126:129]
	v_mfma_f32_16x16x32_bf16 v[122:125], v[152:155], v[176:179], v[122:125]
	v_mfma_f32_16x16x32_bf16 v[118:121], v[144:147], v[184:187], v[118:121]
	v_mfma_f32_16x16x32_bf16 v[114:117], v[152:155], v[184:187], v[114:117]
	v_mfma_f32_16x16x32_bf16 v[102:105], v[144:147], v[198:201], v[102:105]
	v_mfma_f32_16x16x32_bf16 v[98:101], v[152:155], v[198:201], v[98:101]
	v_mfma_f32_16x16x32_bf16 v[86:89], v[144:147], v[206:209], v[86:89]
	v_mfma_f32_16x16x32_bf16 v[82:85], v[152:155], v[206:209], v[82:85]
	v_mfma_f32_16x16x32_bf16 v[126:129], v[148:151], v[180:183], v[126:129]
	v_mfma_f32_16x16x32_bf16 v[122:125], v[156:159], v[180:183], v[122:125]
	v_mfma_f32_16x16x32_bf16 v[118:121], v[148:151], v[188:191], v[118:121]
	v_mfma_f32_16x16x32_bf16 v[114:117], v[156:159], v[188:191], v[114:117]
	v_mfma_f32_16x16x32_bf16 v[102:105], v[148:151], v[202:205], v[102:105]
	v_mfma_f32_16x16x32_bf16 v[98:101], v[156:159], v[202:205], v[98:101]
	v_mfma_f32_16x16x32_bf16 v[86:89], v[148:151], v[210:213], v[86:89]
	v_mfma_f32_16x16x32_bf16 v[82:85], v[156:159], v[210:213], v[82:85]
	v_mfma_f32_16x16x32_bf16 v[110:113], v[160:163], v[176:179], v[110:113]
	v_mfma_f32_16x16x32_bf16 v[106:109], v[168:171], v[176:179], v[106:109]
	v_mfma_f32_16x16x32_bf16 v[94:97], v[160:163], v[184:187], v[94:97]
	v_mfma_f32_16x16x32_bf16 v[90:93], v[168:171], v[184:187], v[90:93]
	v_mfma_f32_16x16x32_bf16 v[78:81], v[160:163], v[198:201], v[78:81]
	v_mfma_f32_16x16x32_bf16 v[74:77], v[168:171], v[198:201], v[74:77]
	v_mfma_f32_16x16x32_bf16 v[70:73], v[160:163], v[206:209], v[70:73]
	v_mfma_f32_16x16x32_bf16 v[66:69], v[168:171], v[206:209], v[66:69]
	v_mfma_f32_16x16x32_bf16 v[110:113], v[164:167], v[180:183], v[110:113]
	v_mfma_f32_16x16x32_bf16 v[106:109], v[172:175], v[180:183], v[106:109]
	v_mfma_f32_16x16x32_bf16 v[94:97], v[164:167], v[188:191], v[94:97]
	v_mfma_f32_16x16x32_bf16 v[90:93], v[172:175], v[188:191], v[90:93]
	v_mfma_f32_16x16x32_bf16 v[78:81], v[164:167], v[202:205], v[78:81]
	v_mfma_f32_16x16x32_bf16 v[74:77], v[172:175], v[202:205], v[74:77]
	v_mfma_f32_16x16x32_bf16 v[70:73], v[164:167], v[210:213], v[70:73]
	v_mfma_f32_16x16x32_bf16 v[66:69], v[172:175], v[210:213], v[66:69]
	s_setprio 0
	s_barrier
; #define PG8_STAGE(bufoff, gbase, voff) do { _Pragma("unroll") for (int _i = 0; _i < 2; ++_i) \
;         __builtin_amdgcn_global_load_lds((const unsigned*)((const char*)(gbase) + (voff)[_i]), (PG8_LAS unsigned*)(lds + (bufoff) + ldsw + _i * 8192), 16, 0, 0); } while (0)
; #define PG8_LDA(dst, b, h) do { _Pragma("unroll") for (int m = 0; m < 4; ++m) _Pragma("unroll") for (int k = 0; k < 2; ++k) dst[m][k] = *(const PG8_LAS bf16x8*)(lds + PG8_SA(b, h) + aoff + m * 2048 + k * 1024); } while (0)
; #define PG8_MMA(ai, bj, At, Bt) do { __builtin_amdgcn_s_setprio(1); _Pragma("unroll") for (int m = 0; m < 4; ++m) _Pragma("unroll") for (int n = 0; n < 2; ++n) _Pragma("unroll") for (int k = 0; k < 2; ++k) \
;         acc[ai][bj][m][n] = __builtin_amdgcn_mfma_f32_16x16x32_bf16(Bt[n][k], At[m][k], acc[ai][bj][m][n], 0, 0, 0); __builtin_amdgcn_s_setprio(0); } while (0)
; #define PG8_WAIT_V(n) asm volatile("s_waitcnt vmcnt(" #n ")" ::: "memory")
; #define PG8_WAIT_L(n) asm volatile("s_waitcnt lgkmcnt(" #n ")" ::: "memory")
; #define PG8_BAR __builtin_amdgcn_s_barrier()
; #define PG8_SCHED __builtin_amdgcn_sched_barrier(0)
; template <class Epi, class Sched, bool ALIGN_EPI = false, bool SP2 = false, bool KHOOK = false>
; __device__ __forceinline__ void gemm_phase(PG8_LAS unsigned char* lds, const Gemm g, const Sched& S, const Epi& E, const int tid_in) {
;     ...
;             PG8_LDA(At, 1, 1); PG8_STAGE(PG8_SB(1, 0), b3, voffB); PG8_STAGE(PG8_SB(1, 1), b3 + hstep, voffB); PG8_STAGE(PG8_SA(1, 0), a3, voffA);
;             PG8_WAIT_V(8); PG8_WAIT_L(0); PG8_BAR; PG8_MMA(1, 0, At, B0); PG8_MMA(1, 1, At, B1); PG8_BAR; PG8_SCHED;
;     ...
;         if constexpr (ALIGN_EPI) { if (wr == 0) PG8_BAR; }
	s_add_i32 s45, s45, s37
	v_lshl_add_u64 v[192:193], v[192:193], 0, s[90:91]
	s_mov_b32 m0, s45
	ds_read_b128 v[176:179], v143 offset:49152
	ds_read_b128 v[180:183], v143 offset:50176
	ds_read_b128 v[184:187], v143 offset:51200
	ds_read_b128 v[188:191], v143 offset:52224
	ds_read_b128 v[198:201], v143 offset:53248
	ds_read_b128 v[202:205], v143 offset:54272
	ds_read_b128 v[206:209], v143 offset:55296
	ds_read_b128 v[210:213], v143 offset:56320
	global_load_lds_dwordx4 v[192:193], off
	s_add_i32 m0, s45, 0x2000
	s_add_u32 s46, s52, 0x80080
	v_lshl_add_u64 v[192:193], v[214:215], 0, s[90:91]
	s_addc_u32 s47, s53, 0
	s_add_i32 s45, s50, s37
	global_load_lds_dwordx4 v[192:193], off
	v_lshl_add_u64 v[192:193], s[46:47], 0, v[32:33]
	s_mov_b32 m0, s45
	s_nop 0
	global_load_lds_dwordx4 v[192:193], off
	v_lshl_add_u64 v[192:193], s[46:47], 0, v[134:135]
	s_add_i32 m0, s45, 0x2000
	s_nop 0
	global_load_lds_dwordx4 v[192:193], off
	v_lshl_add_u64 v[192:193], v[216:217], 0, s[90:91]
	s_mov_b32 m0, s39
	s_nop 0
	global_load_lds_dwordx4 v[192:193], off
	v_lshl_add_u64 v[192:193], v[218:219], 0, s[90:91]
	s_mov_b32 m0, s40
	s_nop 0
	global_load_lds_dwordx4 v[192:193], off
	s_waitcnt vmcnt(8)
	s_waitcnt lgkmcnt(0)
	s_barrier
	s_setprio 1
	s_waitcnt lgkmcnt(0)
	v_mfma_f32_16x16x32_bf16 v[62:65], v[144:147], v[176:179], v[62:65]
	v_mfma_f32_16x16x32_bf16 v[58:61], v[152:155], v[176:179], v[58:61]
	v_mfma_f32_16x16x32_bf16 v[54:57], v[144:147], v[184:187], v[54:57]
	v_mfma_f32_16x16x32_bf16 v[50:53], v[152:155], v[184:187], v[50:53]
	v_mfma_f32_16x16x32_bf16 v[38:41], v[144:147], v[198:201], v[38:41]
	v_mfma_f32_16x16x32_bf16 v[34:37], v[152:155], v[198:201], v[34:37]
	v_mfma_f32_16x16x32_bf16 v[20:23], v[144:147], v[206:209], v[20:23]
	v_mfma_f32_16x16x32_bf16 v[16:19], v[152:155], v[206:209], v[16:19]
	v_mfma_f32_16x16x32_bf16 v[62:65], v[148:151], v[180:183], v[62:65]
	v_mfma_f32_16x16x32_bf16 v[58:61], v[156:159], v[180:183], v[58:61]
	v_mfma_f32_16x16x32_bf16 v[54:57], v[148:151], v[188:191], v[54:57]
	v_mfma_f32_16x16x32_bf16 v[50:53], v[156:159], v[188:191], v[50:53]
	v_mfma_f32_16x16x32_bf16 v[38:41], v[148:151], v[202:205], v[38:41]
	v_mfma_f32_16x16x32_bf16 v[34:37], v[156:159], v[202:205], v[34:37]
	v_mfma_f32_16x16x32_bf16 v[20:23], v[148:151], v[210:213], v[20:23]
	v_mfma_f32_16x16x32_bf16 v[16:19], v[156:159], v[210:213], v[16:19]
	v_mfma_f32_16x16x32_bf16 v[46:49], v[160:163], v[176:179], v[46:49]
	v_mfma_f32_16x16x32_bf16 v[42:45], v[168:171], v[176:179], v[42:45]
	v_mfma_f32_16x16x32_bf16 v[28:31], v[160:163], v[184:187], v[28:31]
	v_mfma_f32_16x16x32_bf16 v[24:27], v[168:171], v[184:187], v[24:27]
	v_mfma_f32_16x16x32_bf16 v[12:15], v[160:163], v[198:201], v[12:15]
	v_mfma_f32_16x16x32_bf16 v[8:11], v[168:171], v[198:201], v[8:11]
	v_mfma_f32_16x16x32_bf16 v[4:7], v[160:163], v[206:209], v[4:7]
	v_mfma_f32_16x16x32_bf16 v[0:3], v[168:171], v[206:209], v[0:3]
	v_mfma_f32_16x16x32_bf16 v[46:49], v[164:167], v[180:183], v[46:49]
	v_mfma_f32_16x16x32_bf16 v[42:45], v[172:175], v[180:183], v[42:45]
	v_mfma_f32_16x16x32_bf16 v[28:31], v[164:167], v[188:191], v[28:31]
	v_mfma_f32_16x16x32_bf16 v[24:27], v[172:175], v[188:191], v[24:27]
	v_mfma_f32_16x16x32_bf16 v[12:15], v[164:167], v[202:205], v[12:15]
	v_mfma_f32_16x16x32_bf16 v[8:11], v[172:175], v[202:205], v[8:11]
	v_mfma_f32_16x16x32_bf16 v[4:7], v[164:167], v[210:213], v[4:7]
	v_mfma_f32_16x16x32_bf16 v[0:3], v[172:175], v[210:213], v[0:3]
	s_setprio 0
	s_barrier
	s_add_i32 s44, s44, 2
	s_add_u32 s48, s48, 0x100
	s_addc_u32 s49, s49, 0
	s_add_u32 s19, s19, 0x100
	s_addc_u32 s42, s42, 0
	s_cmp_gt_u32 s44, 29
	s_cbranch_scc0 .LBB0_263
	s_and_b64 vcc, exec, s[8:9]
	s_cbranch_vccz .LBB0_266
	s_barrier

; #define PG8_STAGE(bufoff, gbase, voff) do { _Pragma("unroll") for (int _i = 0; _i < 2; ++_i) \
;         __builtin_amdgcn_global_load_lds((const unsigned*)((const char*)(gbase) + (voff)[_i]), (PG8_LAS unsigned*)(lds + (bufoff) + ldsw + _i * 8192), 16, 0, 0); } while (0)
; #define PG8_LDA(dst, b, h) do { _Pragma("unroll") for (int m = 0; m < 4; ++m) _Pragma("unroll") for (int k = 0; k < 2; ++k) dst[m][k] = *(const PG8_LAS bf16x8*)(lds + PG8_SA(b, h) + aoff + m * 2048 + k * 1024); } while (0)
; #define PG8_LDB(dst, b, h) do { _Pragma("unroll") for (int n = 0; n < 2; ++n) _Pragma("unroll") for (int k = 0; k < 2; ++k) dst[n][k] = *(const PG8_LAS bf16x8*)(lds + PG8_SB(b, h) + boff + n * 2048 + k * 1024); } while (0)
; #define PG8_WAIT_V(n) asm volatile("s_waitcnt vmcnt(" #n ")" ::: "memory")
; #define PG8_WAIT_L(n) asm volatile("s_waitcnt lgkmcnt(" #n ")" ::: "memory")
; #define PG8_BAR __builtin_amdgcn_s_barrier()
; template <class Epi, class Sched, bool ALIGN_EPI = false, bool SP2 = false, bool KHOOK = false>
; __device__ __forceinline__ void gemm_phase(PG8_LAS unsigned char* lds, const Gemm g, const Sched& S, const Epi& E, const int tid_in) {
;     ...
;         for (int t = 0; t < nt; t += 2) {
;             const bool last = (t == nt - 2);
;             const char* a1 = cA + (size_t)(t + 1) * kstep;
;             const char* a2 = last ? nA : cA + (size_t)(t + 2) * kstep; const char* b2 = last ? nB : cB + (size_t)(t + 2) * kstep;
;             const char* a3 = a2 + kstep; const char* b3 = b2 + kstep;
;             if (last && has_next) S.a_ready(nxt);
;             if constexpr (SP2) {
;             PG8_LDB(B0, 0, 0); PG8_LDB(B1, 0, 1); PG8_SCHED; PG8_LDA(At, 0, 0); PG8_STAGE(PG8_SA(1, 1), a1 + hstep, voffA);
;             PG8_WAIT_V(8); PG8_WAIT_L(0); PG8_BAR; PG8_MMA(0, 0, At, B0); PG8_MMA(0, 1, At, B1); PG8_BAR; PG8_SCHED;
;             PG8_LDA(At, 0, 1); PG8_STAGE(PG8_SB(0, 0), b2, voffB); PG8_STAGE(PG8_SB(0, 1), b2 + hstep, voffB); PG8_STAGE(PG8_SA(0, 0), a2, voffA);
;             PG8_WAIT_V(8); PG8_WAIT_L(0); PG8_BAR; PG8_MMA(1, 0, At, B0); PG8_MMA(1, 1, At, B1); PG8_BAR; PG8_SCHED;
;             PG8_LDB(B0, 1, 0); PG8_LDB(B1, 1, 1); PG8_SCHED; PG8_LDA(At, 1, 0); PG8_STAGE(PG8_SA(0, 1), a2 + hstep, voffA);
;             PG8_WAIT_V(8); PG8_WAIT_L(0); PG8_BAR; PG8_MMA(0, 0, At, B0); PG8_MMA(0, 1, At, B1); PG8_BAR; PG8_SCHED;
.LBB0_416:
	s_ashr_i32 s13, s12, 31
	s_lshl_b64 s[22:23], s[12:13], 20
	s_add_u32 s13, s78, s22
	s_addc_u32 s23, s79, s23
	s_ashr_i32 s11, s10, 31
	s_lshl_b64 s[26:27], s[10:11], 9
	s_add_u32 s22, s13, s26
	s_addc_u32 s23, s23, s27
	s_and_b64 s[44:45], s[16:17], exec
	s_cselect_b32 s57, s23, s53
	s_cselect_b32 s56, s22, s52
	s_add_u32 s26, s2, s26
	s_addc_u32 s27, s18, s27
	s_and_b64 s[44:45], s[16:17], exec
	s_cselect_b32 s49, s27, s31
	s_cselect_b32 s48, s26, s30
	s_add_i32 s44, 0, 0x10000
	v_add_u32_e32 v132, s44, v71
	ds_read_b128 v[0:3], v132
	ds_read_b128 v[4:7], v132 offset:1024
	ds_read_b128 v[8:11], v132 offset:2048
	ds_read_b128 v[12:15], v132 offset:3072
	s_add_u32 s46, s52, 0x80080
	s_addc_u32 s47, s53, 0
	s_add_i32 s45, s20, 0xc000
	v_lshl_add_u64 v[50:51], s[46:47], 0, v[32:33]
	s_mov_b32 m0, s45
	s_add_i32 s11, s20, 0xe000
	ds_read_b128 v[16:19], v72
	ds_read_b128 v[20:23], v72 offset:1024
	ds_read_b128 v[24:27], v72 offset:2048
	ds_read_b128 v[28:31], v72 offset:3072
	ds_read_b128 v[34:37], v72 offset:4096
	ds_read_b128 v[38:41], v72 offset:5120
	ds_read_b128 v[42:45], v72 offset:6144
	ds_read_b128 v[46:49], v72 offset:7168
	global_load_lds_dwordx4 v[50:51], off
	v_lshl_add_u64 v[50:51], s[46:47], 0, v[66:67]
	s_mov_b32 m0, s11
	s_nop 0
	global_load_lds_dwordx4 v[50:51], off
	s_waitcnt vmcnt(8)
	s_waitcnt lgkmcnt(0)
	s_barrier
	s_setprio 1
	s_waitcnt lgkmcnt(0)
	v_mfma_f32_16x16x32_bf16 v[50:53], v[0:3], v[16:19], 0
	v_mfma_f32_16x16x32_bf16 v[16:19], v[8:11], v[16:19], 0
	v_mfma_f32_16x16x32_bf16 v[50:53], v[4:7], v[20:23], v[50:53]
	v_mfma_f32_16x16x32_bf16 v[16:19], v[12:15], v[20:23], v[16:19]
	v_mfma_f32_16x16x32_bf16 v[20:23], v[0:3], v[24:27], 0
	v_mfma_f32_16x16x32_bf16 v[24:27], v[8:11], v[24:27], 0
	v_mfma_f32_16x16x32_bf16 v[20:23], v[4:7], v[28:31], v[20:23]
	v_mfma_f32_16x16x32_bf16 v[24:27], v[12:15], v[28:31], v[24:27]
	v_mfma_f32_16x16x32_bf16 v[28:31], v[0:3], v[34:37], 0
	v_mfma_f32_16x16x32_bf16 v[34:37], v[8:11], v[34:37], 0
	v_mfma_f32_16x16x32_bf16 v[28:31], v[4:7], v[38:41], v[28:31]
	v_mfma_f32_16x16x32_bf16 v[34:37], v[12:15], v[38:41], v[34:37]
	v_mfma_f32_16x16x32_bf16 v[38:41], v[0:3], v[42:45], 0
	v_mfma_f32_16x16x32_bf16 v[42:45], v[8:11], v[42:45], 0
	v_mfma_f32_16x16x32_bf16 v[38:41], v[4:7], v[46:49], v[38:41]
	v_mfma_f32_16x16x32_bf16 v[42:45], v[12:15], v[46:49], v[42:45]
	s_setprio 0
	s_barrier
	s_add_i32 s44, s44, s19
	v_lshl_add_u64 v[122:123], s[30:31], 0, v[32:33]
	s_mov_b64 s[50:51], 0x100
	s_add_i32 s13, s44, 0x2000
	v_lshl_add_u64 v[90:91], v[122:123], 0, s[50:51]
	s_mov_b32 m0, s44
	v_lshl_add_u64 v[124:125], s[30:31], 0, v[66:67]
	s_add_u32 s46, s30, 0x80100
	ds_read_b128 v[46:49], v72 offset:16384
	ds_read_b128 v[54:57], v72 offset:17408
	ds_read_b128 v[58:61], v72 offset:18432
	ds_read_b128 v[62:65], v72 offset:19456
	ds_read_b128 v[74:77], v72 offset:20480
	ds_read_b128 v[78:81], v72 offset:21504
	ds_read_b128 v[82:85], v72 offset:22528
	ds_read_b128 v[86:89], v72 offset:23552
	global_load_lds_dwordx4 v[90:91], off
	v_lshl_add_u64 v[90:91], v[124:125], 0, s[50:51]
	s_mov_b32 m0, s13
	s_addc_u32 s47, s31, 0
	global_load_lds_dwordx4 v[90:91], off
	v_lshl_add_u64 v[90:91], s[46:47], 0, v[32:33]
	s_mov_b32 m0, s24
	v_lshl_add_u64 v[126:127], s[52:53], 0, v[32:33]
	global_load_lds_dwordx4 v[90:91], off
	v_lshl_add_u64 v[90:91], s[46:47], 0, v[66:67]
	s_mov_b32 m0, s25
	v_lshl_add_u64 v[128:129], s[52:53], 0, v[66:67]
	global_load_lds_dwordx4 v[90:91], off
	v_lshl_add_u64 v[90:91], v[126:127], 0, s[50:51]
	s_mov_b32 m0, s20
	s_nop 0
	global_load_lds_dwordx4 v[90:91], off
	v_lshl_add_u64 v[90:91], v[128:129], 0, s[50:51]
	s_mov_b32 m0, s33
	s_nop 0
	global_load_lds_dwordx4 v[90:91], off
	s_waitcnt vmcnt(8)
	s_waitcnt lgkmcnt(0)
	s_barrier
	s_setprio 1
	s_waitcnt lgkmcnt(0)
	v_mfma_f32_16x16x32_bf16 v[90:93], v[0:3], v[46:49], 0
	v_mfma_f32_16x16x32_bf16 v[46:49], v[8:11], v[46:49], 0
	v_mfma_f32_16x16x32_bf16 v[90:93], v[4:7], v[54:57], v[90:93]
	v_mfma_f32_16x16x32_bf16 v[46:49], v[12:15], v[54:57], v[46:49]
	v_mfma_f32_16x16x32_bf16 v[54:57], v[0:3], v[58:61], 0
	v_mfma_f32_16x16x32_bf16 v[58:61], v[8:11], v[58:61], 0
	v_mfma_f32_16x16x32_bf16 v[54:57], v[4:7], v[62:65], v[54:57]
	v_mfma_f32_16x16x32_bf16 v[58:61], v[12:15], v[62:65], v[58:61]
	v_mfma_f32_16x16x32_bf16 v[62:65], v[0:3], v[74:77], 0
	v_mfma_f32_16x16x32_bf16 v[0:3], v[0:3], v[82:85], 0
	v_mfma_f32_16x16x32_bf16 v[62:65], v[4:7], v[78:81], v[62:65]
	v_mfma_f32_16x16x32_bf16 v[0:3], v[4:7], v[86:89], v[0:3]
	v_mfma_f32_16x16x32_bf16 v[4:7], v[8:11], v[82:85], 0
	v_mfma_f32_16x16x32_bf16 v[74:77], v[8:11], v[74:77], 0
	v_mfma_f32_16x16x32_bf16 v[4:7], v[12:15], v[86:89], v[4:7]
	v_mfma_f32_16x16x32_bf16 v[74:77], v[12:15], v[78:81], v[74:77]
	s_setprio 0
	s_barrier
	s_add_i32 s42, 0, 0x18000
	v_add_u32_e32 v133, s42, v71
	ds_read_b128 v[8:11], v133
	ds_read_b128 v[12:15], v133 offset:1024
	ds_read_b128 v[78:81], v133 offset:2048
	ds_read_b128 v[82:85], v133 offset:3072
	s_add_u32 s46, s52, 0x80100
	s_addc_u32 s47, s53, 0
	s_mov_b32 m0, s36
	v_lshl_add_u64 v[130:131], s[46:47], 0, v[32:33]
	ds_read_b128 v[86:89], v72 offset:32768
	ds_read_b128 v[94:97], v72 offset:33792
	ds_read_b128 v[98:101], v72 offset:34816
	ds_read_b128 v[102:105], v72 offset:35840
	ds_read_b128 v[106:109], v72 offset:36864
	ds_read_b128 v[110:113], v72 offset:37888
	ds_read_b128 v[114:117], v72 offset:38912
	ds_read_b128 v[118:121], v72 offset:39936
	global_load_lds_dwordx4 v[130:131], off
	v_lshl_add_u64 v[130:131], s[46:47], 0, v[66:67]
	s_mov_b32 m0, s37
	s_nop 0
	global_load_lds_dwordx4 v[130:131], off
	s_waitcnt vmcnt(8)
	s_waitcnt lgkmcnt(0)
	s_barrier
; #define PG8_STAGE(bufoff, gbase, voff) do { _Pragma("unroll") for (int _i = 0; _i < 2; ++_i) \
;         __builtin_amdgcn_global_load_lds((const unsigned*)((const char*)(gbase) + (voff)[_i]), (PG8_LAS unsigned*)(lds + (bufoff) + ldsw + _i * 8192), 16, 0, 0); } while (0)
; #define PG8_LDA(dst, b, h) do { _Pragma("unroll") for (int m = 0; m < 4; ++m) _Pragma("unroll") for (int k = 0; k < 2; ++k) dst[m][k] = *(const PG8_LAS bf16x8*)(lds + PG8_SA(b, h) + aoff + m * 2048 + k * 1024); } while (0)
; #define PG8_LDB(dst, b, h) do { _Pragma("unroll") for (int n = 0; n < 2; ++n) _Pragma("unroll") for (int k = 0; k < 2; ++k) dst[n][k] = *(const PG8_LAS bf16x8*)(lds + PG8_SB(b, h) + boff + n * 2048 + k * 1024); } while (0)
; #define PG8_MMA(ai, bj, At, Bt) do { __builtin_amdgcn_s_setprio(1); _Pragma("unroll") for (int m = 0; m < 4; ++m) _Pragma("unroll") for (int n = 0; n < 2; ++n) _Pragma("unroll") for (int k = 0; k < 2; ++k) \
;         acc[ai][bj][m][n] = __builtin_amdgcn_mfma_f32_16x16x32_bf16(Bt[n][k], At[m][k], acc[ai][bj][m][n], 0, 0, 0); __builtin_amdgcn_s_setprio(0); } while (0)
; #define PG8_WAIT_V(n) asm volatile("s_waitcnt vmcnt(" #n ")" ::: "memory")
; #define PG8_WAIT_L(n) asm volatile("s_waitcnt lgkmcnt(" #n ")" ::: "memory")
; #define PG8_BAR __builtin_amdgcn_s_barrier()
; #define PG8_SCHED __builtin_amdgcn_sched_barrier(0)
; template <class Epi, class Sched, bool ALIGN_EPI = false, bool SP2 = false, bool KHOOK = false>
; __device__ __forceinline__ void gemm_phase(PG8_LAS unsigned char* lds, const Gemm g, const Sched& S, const Epi& E, const int tid_in) {
;     ...
;             PG8_LDB(B0, 0, 0); PG8_LDB(B1, 0, 1); PG8_SCHED; PG8_LDA(At, 0, 0); PG8_STAGE(PG8_SA(1, 1), a1 + hstep, voffA);
;             PG8_WAIT_V(8); PG8_WAIT_L(0); PG8_BAR; PG8_MMA(0, 0, At, B0); PG8_MMA(0, 1, At, B1); PG8_BAR; PG8_SCHED;
;     ...
;             PG8_WAIT_V(8); PG8_WAIT_L(0); PG8_BAR; PG8_MMA(0, 0, At, B0); PG8_MMA(0, 1, At, B1); PG8_BAR; PG8_SCHED;
;             PG8_LDA(At, 1, 1); PG8_STAGE(PG8_SB(1, 0), b3, voffB); PG8_STAGE(PG8_SB(1, 1), b3 + hstep, voffB); PG8_STAGE(PG8_SA(1, 0), a3, voffA);
;             PG8_WAIT_V(8); PG8_WAIT_L(0); PG8_BAR; PG8_MMA(1, 0, At, B0); PG8_MMA(1, 1, At, B1); PG8_BAR; PG8_SCHED;
	s_setprio 1
	s_waitcnt lgkmcnt(0)
	v_mfma_f32_16x16x32_bf16 v[50:53], v[8:11], v[86:89], v[50:53]
	v_mfma_f32_16x16x32_bf16 v[16:19], v[78:81], v[86:89], v[16:19]
	v_mfma_f32_16x16x32_bf16 v[20:23], v[8:11], v[98:101], v[20:23]
	v_mfma_f32_16x16x32_bf16 v[24:27], v[78:81], v[98:101], v[24:27]
	v_mfma_f32_16x16x32_bf16 v[28:31], v[8:11], v[106:109], v[28:31]
	v_mfma_f32_16x16x32_bf16 v[34:37], v[78:81], v[106:109], v[34:37]
	v_mfma_f32_16x16x32_bf16 v[38:41], v[8:11], v[114:117], v[38:41]
	v_mfma_f32_16x16x32_bf16 v[42:45], v[78:81], v[114:117], v[42:45]
	v_mfma_f32_16x16x32_bf16 v[50:53], v[12:15], v[94:97], v[50:53]
	v_mfma_f32_16x16x32_bf16 v[16:19], v[82:85], v[94:97], v[16:19]
	v_mfma_f32_16x16x32_bf16 v[20:23], v[12:15], v[102:105], v[20:23]
	v_mfma_f32_16x16x32_bf16 v[24:27], v[82:85], v[102:105], v[24:27]
	v_mfma_f32_16x16x32_bf16 v[28:31], v[12:15], v[110:113], v[28:31]
	v_mfma_f32_16x16x32_bf16 v[34:37], v[82:85], v[110:113], v[34:37]
	v_mfma_f32_16x16x32_bf16 v[38:41], v[12:15], v[118:121], v[38:41]
	v_mfma_f32_16x16x32_bf16 v[42:45], v[82:85], v[118:121], v[42:45]
	s_setprio 0
	s_barrier
	s_add_i32 s46, s42, s19
	s_mov_b64 s[50:51], 0x180
	s_add_i32 s42, s46, 0x2000
	v_lshl_add_u64 v[122:123], v[122:123], 0, s[50:51]
	s_mov_b32 m0, s46
	s_add_u32 s30, s30, 0x80180
	ds_read_b128 v[86:89], v72 offset:49152
	ds_read_b128 v[94:97], v72 offset:50176
	ds_read_b128 v[98:101], v72 offset:51200
	ds_read_b128 v[102:105], v72 offset:52224
	ds_read_b128 v[106:109], v72 offset:53248
	ds_read_b128 v[110:113], v72 offset:54272
	ds_read_b128 v[114:117], v72 offset:55296
	ds_read_b128 v[118:121], v72 offset:56320
	global_load_lds_dwordx4 v[122:123], off
	v_lshl_add_u64 v[122:123], v[124:125], 0, s[50:51]
	s_mov_b32 m0, s42
	s_addc_u32 s31, s31, 0
	global_load_lds_dwordx4 v[122:123], off
	v_lshl_add_u64 v[122:123], s[30:31], 0, v[32:33]
	s_mov_b32 m0, s40
	s_nop 0
	global_load_lds_dwordx4 v[122:123], off
	v_lshl_add_u64 v[122:123], s[30:31], 0, v[66:67]
	s_mov_b32 m0, s41
	s_nop 0
	global_load_lds_dwordx4 v[122:123], off
	v_lshl_add_u64 v[122:123], v[126:127], 0, s[50:51]
	s_mov_b32 m0, s38
	s_nop 0
	global_load_lds_dwordx4 v[122:123], off
	v_lshl_add_u64 v[122:123], v[128:129], 0, s[50:51]
	s_mov_b32 m0, s39
	s_nop 0
	global_load_lds_dwordx4 v[122:123], off
	s_waitcnt vmcnt(8)
	s_waitcnt lgkmcnt(0)
	s_barrier
	s_setprio 1
	s_waitcnt lgkmcnt(0)
	v_mfma_f32_16x16x32_bf16 v[46:49], v[78:81], v[86:89], v[46:49]
	v_mfma_f32_16x16x32_bf16 v[54:57], v[8:11], v[98:101], v[54:57]
	v_mfma_f32_16x16x32_bf16 v[58:61], v[78:81], v[98:101], v[58:61]
	v_mfma_f32_16x16x32_bf16 v[62:65], v[8:11], v[106:109], v[62:65]
	v_mfma_f32_16x16x32_bf16 v[0:3], v[8:11], v[114:117], v[0:3]
	v_mfma_f32_16x16x32_bf16 v[4:7], v[78:81], v[114:117], v[4:7]
	v_mfma_f32_16x16x32_bf16 v[90:93], v[8:11], v[86:89], v[90:93]
	v_mfma_f32_16x16x32_bf16 v[46:49], v[82:85], v[94:97], v[46:49]
	v_mfma_f32_16x16x32_bf16 v[54:57], v[12:15], v[102:105], v[54:57]
	v_mfma_f32_16x16x32_bf16 v[58:61], v[82:85], v[102:105], v[58:61]
	v_mfma_f32_16x16x32_bf16 v[62:65], v[12:15], v[110:113], v[62:65]
	v_mfma_f32_16x16x32_bf16 v[74:77], v[78:81], v[106:109], v[74:77]
	v_mfma_f32_16x16x32_bf16 v[0:3], v[12:15], v[118:121], v[0:3]
	v_mfma_f32_16x16x32_bf16 v[4:7], v[82:85], v[118:121], v[4:7]
	v_mfma_f32_16x16x32_bf16 v[90:93], v[12:15], v[94:97], v[90:93]
	v_mfma_f32_16x16x32_bf16 v[74:77], v[82:85], v[110:113], v[74:77]
	s_setprio 0
	s_barrier
	ds_read_b128 v[8:11], v132
	ds_read_b128 v[12:15], v132 offset:1024
	ds_read_b128 v[78:81], v132 offset:2048
	ds_read_b128 v[82:85], v132 offset:3072
	s_add_u32 s30, s52, 0x80180
	s_addc_u32 s31, s53, 0
	s_mov_b32 m0, s45
	v_lshl_add_u64 v[122:123], s[30:31], 0, v[32:33]
	ds_read_b128 v[86:89], v72
	ds_read_b128 v[94:97], v72 offset:1024
	ds_read_b128 v[98:101], v72 offset:2048
	ds_read_b128 v[102:105], v72 offset:3072
	ds_read_b128 v[106:109], v72 offset:4096
	ds_read_b128 v[110:113], v72 offset:5120
	ds_read_b128 v[114:117], v72 offset:6144
	ds_read_b128 v[118:121], v72 offset:7168
	global_load_lds_dwordx4 v[122:123], off
	v_lshl_add_u64 v[122:123], s[30:31], 0, v[66:67]
	s_mov_b32 m0, s11
	s_nop 0
	global_load_lds_dwordx4 v[122:123], off
	s_waitcnt vmcnt(8)
	s_waitcnt lgkmcnt(0)
	s_barrier
	s_setprio 1
	s_waitcnt lgkmcnt(0)
	v_mfma_f32_16x16x32_bf16 v[24:27], v[78:81], v[98:101], v[24:27]
	v_mfma_f32_16x16x32_bf16 v[50:53], v[8:11], v[86:89], v[50:53]
	v_mfma_f32_16x16x32_bf16 v[16:19], v[78:81], v[86:89], v[16:19]
	v_mfma_f32_16x16x32_bf16 v[86:89], v[82:85], v[102:105], v[24:27]
	v_mfma_f32_16x16x32_bf16 v[24:27], v[8:11], v[106:109], v[28:31]
	v_mfma_f32_16x16x32_bf16 v[50:53], v[12:15], v[94:97], v[50:53]
	v_mfma_f32_16x16x32_bf16 v[16:19], v[82:85], v[94:97], v[16:19]
	v_mfma_f32_16x16x32_bf16 v[94:97], v[12:15], v[110:113], v[24:27]
	v_mfma_f32_16x16x32_bf16 v[24:27], v[78:81], v[106:109], v[34:37]
	v_mfma_f32_16x16x32_bf16 v[34:37], v[82:85], v[110:113], v[24:27]
	v_mfma_f32_16x16x32_bf16 v[24:27], v[8:11], v[114:117], v[38:41]
	v_mfma_f32_16x16x32_bf16 v[20:23], v[8:11], v[98:101], v[20:23]
	v_mfma_f32_16x16x32_bf16 v[38:41], v[12:15], v[118:121], v[24:27]
	v_mfma_f32_16x16x32_bf16 v[24:27], v[78:81], v[114:117], v[42:45]
	v_mfma_f32_16x16x32_bf16 v[20:23], v[12:15], v[102:105], v[20:23]
	v_mfma_f32_16x16x32_bf16 v[42:45], v[82:85], v[118:121], v[24:27]
	s_setprio 0
	s_barrier
; #define PG8_STAGE(bufoff, gbase, voff) do { _Pragma("unroll") for (int _i = 0; _i < 2; ++_i) \
;         __builtin_amdgcn_global_load_lds((const unsigned*)((const char*)(gbase) + (voff)[_i]), (PG8_LAS unsigned*)(lds + (bufoff) + ldsw + _i * 8192), 16, 0, 0); } while (0)
; #define PG8_LDA(dst, b, h) do { _Pragma("unroll") for (int m = 0; m < 4; ++m) _Pragma("unroll") for (int k = 0; k < 2; ++k) dst[m][k] = *(const PG8_LAS bf16x8*)(lds + PG8_SA(b, h) + aoff + m * 2048 + k * 1024); } while (0)
; #define PG8_LDB(dst, b, h) do { _Pragma("unroll") for (int n = 0; n < 2; ++n) _Pragma("unroll") for (int k = 0; k < 2; ++k) dst[n][k] = *(const PG8_LAS bf16x8*)(lds + PG8_SB(b, h) + boff + n * 2048 + k * 1024); } while (0)
; #define PG8_MMA(ai, bj, At, Bt) do { __builtin_amdgcn_s_setprio(1); _Pragma("unroll") for (int m = 0; m < 4; ++m) _Pragma("unroll") for (int n = 0; n < 2; ++n) _Pragma("unroll") for (int k = 0; k < 2; ++k) \
;         acc[ai][bj][m][n] = __builtin_amdgcn_mfma_f32_16x16x32_bf16(Bt[n][k], At[m][k], acc[ai][bj][m][n], 0, 0, 0); __builtin_amdgcn_s_setprio(0); } while (0)
; #define PG8_WAIT_V(n) asm volatile("s_waitcnt vmcnt(" #n ")" ::: "memory")
; #define PG8_WAIT_L(n) asm volatile("s_waitcnt lgkmcnt(" #n ")" ::: "memory")
; #define PG8_BAR __builtin_amdgcn_s_barrier()
; #define PG8_SCHED __builtin_amdgcn_sched_barrier(0)
; template <class Epi, class Sched, bool ALIGN_EPI = false, bool SP2 = false, bool KHOOK = false>
; __device__ __forceinline__ void gemm_phase(PG8_LAS unsigned char* lds, const Gemm g, const Sched& S, const Epi& E, const int tid_in) {
;     ...
;             PG8_LDA(At, 0, 1); PG8_STAGE(PG8_SB(0, 0), b2, voffB); PG8_STAGE(PG8_SB(0, 1), b2 + hstep, voffB); PG8_STAGE(PG8_SA(0, 0), a2, voffA);
;             PG8_WAIT_V(8); PG8_WAIT_L(0); PG8_BAR; PG8_MMA(1, 0, At, B0); PG8_MMA(1, 1, At, B1); PG8_BAR; PG8_SCHED;
;             PG8_LDB(B0, 1, 0); PG8_LDB(B1, 1, 1); PG8_SCHED; PG8_LDA(At, 1, 0); PG8_STAGE(PG8_SA(0, 1), a2 + hstep, voffA);
;             PG8_WAIT_V(8); PG8_WAIT_L(0); PG8_BAR; PG8_MMA(0, 0, At, B0); PG8_MMA(0, 1, At, B1); PG8_BAR; PG8_SCHED;
;             PG8_LDA(At, 1, 1); PG8_STAGE(PG8_SB(1, 0), b3, voffB); PG8_STAGE(PG8_SB(1, 1), b3 + hstep, voffB); PG8_STAGE(PG8_SA(1, 0), a3, voffA);
;             PG8_WAIT_V(8); PG8_WAIT_L(0); PG8_BAR; PG8_MMA(1, 0, At, B0); PG8_MMA(1, 1, At, B1); PG8_BAR; PG8_SCHED;
	s_mov_b32 m0, s44
	v_lshl_add_u64 v[134:135], s[48:49], 0, v[32:33]
	s_add_u32 s30, s48, 0x80000
	ds_read_b128 v[24:27], v72 offset:16384
	ds_read_b128 v[28:31], v72 offset:17408
	ds_read_b128 v[98:101], v72 offset:18432
	ds_read_b128 v[102:105], v72 offset:19456
	ds_read_b128 v[106:109], v72 offset:20480
	ds_read_b128 v[110:113], v72 offset:21504
	ds_read_b128 v[114:117], v72 offset:22528
	ds_read_b128 v[118:121], v72 offset:23552
	global_load_lds_dwordx4 v[134:135], off
	v_lshl_add_u64 v[136:137], s[48:49], 0, v[66:67]
	s_mov_b32 m0, s13
	s_addc_u32 s31, s49, 0
	global_load_lds_dwordx4 v[136:137], off
	v_lshl_add_u64 v[122:123], s[30:31], 0, v[32:33]
	s_mov_b32 m0, s24
	v_lshl_add_u64 v[138:139], s[56:57], 0, v[32:33]
	global_load_lds_dwordx4 v[122:123], off
	v_lshl_add_u64 v[122:123], s[30:31], 0, v[66:67]
	s_mov_b32 m0, s25
	v_lshl_add_u64 v[140:141], s[56:57], 0, v[66:67]
	global_load_lds_dwordx4 v[122:123], off
	s_mov_b32 m0, s20
	s_nop 0
	global_load_lds_dwordx4 v[138:139], off
	s_mov_b32 m0, s33
	s_nop 0
	global_load_lds_dwordx4 v[140:141], off
	s_waitcnt vmcnt(8)
	s_waitcnt lgkmcnt(0)
	s_barrier
	s_setprio 1
	s_waitcnt lgkmcnt(0)
	v_mfma_f32_16x16x32_bf16 v[90:93], v[8:11], v[24:27], v[90:93]
	v_mfma_f32_16x16x32_bf16 v[24:27], v[78:81], v[24:27], v[46:49]
	v_mfma_f32_16x16x32_bf16 v[46:49], v[82:85], v[28:31], v[24:27]
	v_mfma_f32_16x16x32_bf16 v[24:27], v[8:11], v[98:101], v[54:57]
	v_mfma_f32_16x16x32_bf16 v[54:57], v[12:15], v[102:105], v[24:27]
	v_mfma_f32_16x16x32_bf16 v[24:27], v[78:81], v[98:101], v[58:61]
	v_mfma_f32_16x16x32_bf16 v[98:101], v[82:85], v[102:105], v[24:27]
	v_mfma_f32_16x16x32_bf16 v[24:27], v[8:11], v[106:109], v[62:65]
	v_mfma_f32_16x16x32_bf16 v[0:3], v[8:11], v[114:117], v[0:3]
	v_mfma_f32_16x16x32_bf16 v[102:105], v[12:15], v[110:113], v[24:27]
	v_mfma_f32_16x16x32_bf16 v[24:27], v[78:81], v[106:109], v[74:77]
	v_mfma_f32_16x16x32_bf16 v[106:109], v[12:15], v[118:121], v[0:3]
	v_mfma_f32_16x16x32_bf16 v[0:3], v[78:81], v[114:117], v[4:7]
	v_mfma_f32_16x16x32_bf16 v[90:93], v[12:15], v[28:31], v[90:93]
	v_mfma_f32_16x16x32_bf16 v[74:77], v[82:85], v[110:113], v[24:27]
	v_mfma_f32_16x16x32_bf16 v[78:81], v[82:85], v[118:121], v[0:3]
	s_setprio 0
	s_barrier
	ds_read_b128 v[82:85], v133
	ds_read_b128 v[110:113], v133 offset:1024
	ds_read_b128 v[114:117], v133 offset:2048
	ds_read_b128 v[118:121], v133 offset:3072
	s_add_u32 s30, s56, 0x80000
	s_addc_u32 s31, s57, 0
	s_mov_b32 m0, s36
	v_lshl_add_u64 v[24:25], s[30:31], 0, v[32:33]
	ds_read_b128 v[0:3], v72 offset:32768
	ds_read_b128 v[4:7], v72 offset:33792
	ds_read_b128 v[8:11], v72 offset:34816
	ds_read_b128 v[12:15], v72 offset:35840
	ds_read_b128 v[58:61], v72 offset:36864
	ds_read_b128 v[62:65], v72 offset:37888
	ds_read_b128 v[122:125], v72 offset:38912
	ds_read_b128 v[126:129], v72 offset:39936
	global_load_lds_dwordx4 v[24:25], off
	v_lshl_add_u64 v[24:25], s[30:31], 0, v[66:67]
	s_mov_b32 m0, s37
	s_nop 0
	global_load_lds_dwordx4 v[24:25], off
	s_waitcnt vmcnt(8)
	s_waitcnt lgkmcnt(0)
	s_barrier
	s_setprio 1
	s_waitcnt lgkmcnt(0)
	v_mfma_f32_16x16x32_bf16 v[24:27], v[82:85], v[0:3], v[50:53]
	v_mfma_f32_16x16x32_bf16 v[0:3], v[114:117], v[0:3], v[16:19]
	v_mfma_f32_16x16x32_bf16 v[28:31], v[118:121], v[4:7], v[0:3]
	v_mfma_f32_16x16x32_bf16 v[0:3], v[82:85], v[8:11], v[20:23]
	v_mfma_f32_16x16x32_bf16 v[16:19], v[110:113], v[12:15], v[0:3]
	v_mfma_f32_16x16x32_bf16 v[0:3], v[114:117], v[8:11], v[86:89]
	v_mfma_f32_16x16x32_bf16 v[20:23], v[118:121], v[12:15], v[0:3]
	v_mfma_f32_16x16x32_bf16 v[0:3], v[82:85], v[58:61], v[94:97]
	v_mfma_f32_16x16x32_bf16 v[8:11], v[110:113], v[62:65], v[0:3]
	v_mfma_f32_16x16x32_bf16 v[0:3], v[114:117], v[58:61], v[34:37]
	v_mfma_f32_16x16x32_bf16 v[24:27], v[110:113], v[4:7], v[24:27]
	v_mfma_f32_16x16x32_bf16 v[12:15], v[118:121], v[62:65], v[0:3]
	v_mfma_f32_16x16x32_bf16 v[0:3], v[82:85], v[122:125], v[38:41]
	v_mfma_f32_16x16x32_bf16 v[4:7], v[114:117], v[122:125], v[42:45]
	v_mfma_f32_16x16x32_bf16 v[0:3], v[110:113], v[126:129], v[0:3]
	v_mfma_f32_16x16x32_bf16 v[4:7], v[118:121], v[126:129], v[4:7]
	s_setprio 0
	s_barrier
	s_mov_b32 m0, s46
	v_lshl_add_u64 v[50:51], v[134:135], 0, s[90:91]
	s_add_u32 s30, s48, 0x80080
	ds_read_b128 v[34:37], v72 offset:49152
	ds_read_b128 v[38:41], v72 offset:50176
	ds_read_b128 v[42:45], v72 offset:51200
	ds_read_b128 v[86:89], v72 offset:52224
	ds_read_b128 v[94:97], v72 offset:53248
	ds_read_b128 v[122:125], v72 offset:54272
	ds_read_b128 v[126:129], v72 offset:55296
	ds_read_b128 v[130:133], v72 offset:56320
	global_load_lds_dwordx4 v[50:51], off
	v_lshl_add_u64 v[50:51], v[136:137], 0, s[90:91]
	s_mov_b32 m0, s42
	s_addc_u32 s31, s49, 0
	global_load_lds_dwordx4 v[50:51], off
	v_lshl_add_u64 v[50:51], s[30:31], 0, v[32:33]
	s_mov_b32 m0, s40
	s_nop 0
	global_load_lds_dwordx4 v[50:51], off
	v_lshl_add_u64 v[50:51], s[30:31], 0, v[66:67]
	s_mov_b32 m0, s41
	s_nop 0
	global_load_lds_dwordx4 v[50:51], off
	v_lshl_add_u64 v[50:51], v[138:139], 0, s[90:91]
	s_mov_b32 m0, s38
	s_nop 0
	global_load_lds_dwordx4 v[50:51], off
	v_lshl_add_u64 v[50:51], v[140:141], 0, s[90:91]
	s_mov_b32 m0, s39
	s_nop 0
	global_load_lds_dwordx4 v[50:51], off
	s_waitcnt vmcnt(8)
	s_waitcnt lgkmcnt(0)
	s_barrier
	s_setprio 1
	s_waitcnt lgkmcnt(0)
	v_mfma_f32_16x16x32_bf16 v[50:53], v[82:85], v[34:37], v[90:93]
	v_mfma_f32_16x16x32_bf16 v[34:37], v[114:117], v[34:37], v[46:49]
	v_mfma_f32_16x16x32_bf16 v[62:65], v[118:121], v[38:41], v[34:37]
	v_mfma_f32_16x16x32_bf16 v[34:37], v[82:85], v[42:45], v[54:57]
	v_mfma_f32_16x16x32_bf16 v[58:61], v[110:113], v[38:41], v[50:53]
	v_mfma_f32_16x16x32_bf16 v[50:53], v[110:113], v[86:89], v[34:37]
	v_mfma_f32_16x16x32_bf16 v[34:37], v[114:117], v[42:45], v[98:101]
	v_mfma_f32_16x16x32_bf16 v[54:57], v[118:121], v[86:89], v[34:37]
	v_mfma_f32_16x16x32_bf16 v[34:37], v[82:85], v[94:97], v[102:105]
	v_mfma_f32_16x16x32_bf16 v[42:45], v[110:113], v[122:125], v[34:37]
	v_mfma_f32_16x16x32_bf16 v[34:37], v[114:117], v[94:97], v[74:77]
	v_mfma_f32_16x16x32_bf16 v[46:49], v[118:121], v[122:125], v[34:37]
	v_mfma_f32_16x16x32_bf16 v[34:37], v[82:85], v[126:129], v[106:109]
	v_mfma_f32_16x16x32_bf16 v[38:41], v[114:117], v[126:129], v[78:81]
	v_mfma_f32_16x16x32_bf16 v[34:37], v[110:113], v[130:133], v[34:37]
	v_mfma_f32_16x16x32_bf16 v[38:41], v[118:121], v[130:133], v[38:41]
	s_setprio 0
	s_barrier
	s_andn2_b64 vcc, exec, s[4:5]
	s_cbranch_vccnz .LBB0_421
	s_barrier
	s_andn2_b64 vcc, exec, s[6:7]
	s_cbranch_vccz .LBB0_422

; #define PG8_STAGE(bufoff, gbase, voff) do { _Pragma("unroll") for (int _i = 0; _i < 2; ++_i) \
;         __builtin_amdgcn_global_load_lds((const unsigned*)((const char*)(gbase) + (voff)[_i]), (PG8_LAS unsigned*)(lds + (bufoff) + ldsw + _i * 8192), 16, 0, 0); } while (0)
; #define PG8_LDA(dst, b, h) do { _Pragma("unroll") for (int m = 0; m < 4; ++m) _Pragma("unroll") for (int k = 0; k < 2; ++k) dst[m][k] = *(const PG8_LAS bf16x8*)(lds + PG8_SA(b, h) + aoff + m * 2048 + k * 1024); } while (0)
; #define PG8_LDB(dst, b, h) do { _Pragma("unroll") for (int n = 0; n < 2; ++n) _Pragma("unroll") for (int k = 0; k < 2; ++k) dst[n][k] = *(const PG8_LAS bf16x8*)(lds + PG8_SB(b, h) + boff + n * 2048 + k * 1024); } while (0)
; #define PG8_MMA(ai, bj, At, Bt) do { __builtin_amdgcn_s_setprio(1); _Pragma("unroll") for (int m = 0; m < 4; ++m) _Pragma("unroll") for (int n = 0; n < 2; ++n) _Pragma("unroll") for (int k = 0; k < 2; ++k) \
;         acc[ai][bj][m][n] = __builtin_amdgcn_mfma_f32_16x16x32_bf16(Bt[n][k], At[m][k], acc[ai][bj][m][n], 0, 0, 0); __builtin_amdgcn_s_setprio(0); } while (0)
; #define PG8_WAIT_V(n) asm volatile("s_waitcnt vmcnt(" #n ")" ::: "memory")
; #define PG8_WAIT_L(n) asm volatile("s_waitcnt lgkmcnt(" #n ")" ::: "memory")
; template <class Epi, class Sched, bool ALIGN_EPI = false, bool SP2 = false, bool KHOOK = false>
; __device__ __forceinline__ void gemm_phase(PG8_LAS unsigned char* lds, const Gemm g, const Sched& S, const Epi& E, const int tid_in) {
;     ...
;             const bool last = (t == nt - 2);
;             const char* a1 = cA + (size_t)(t + 1) * kstep;
;             const char* a2 = last ? nA : cA + (size_t)(t + 2) * kstep; const char* b2 = last ? nB : cB + (size_t)(t + 2) * kstep;
;             const char* a3 = a2 + kstep; const char* b3 = b2 + kstep;
;             if (last && has_next) S.a_ready(nxt);
;             if constexpr (SP2) {
;             PG8_LDB(B0, 0, 0); PG8_LDB(B1, 0, 1); PG8_SCHED; PG8_LDA(At, 0, 0); PG8_STAGE(PG8_SA(1, 1), a1 + hstep, voffA);
;             PG8_WAIT_V(8); PG8_WAIT_L(0); PG8_BAR; PG8_MMA(0, 0, At, B0); PG8_MMA(0, 1, At, B1); PG8_BAR; PG8_SCHED;
;             PG8_LDA(At, 0, 1); PG8_STAGE(PG8_SB(0, 0), b2, voffB); PG8_STAGE(PG8_SB(0, 1), b2 + hstep, voffB); PG8_STAGE(PG8_SA(0, 0), a2, voffA);
;             PG8_WAIT_V(8); PG8_WAIT_L(0); PG8_BAR; PG8_MMA(1, 0, At, B0); PG8_MMA(1, 1, At, B1); PG8_BAR; PG8_SCHED;
.LBB0_845:
	s_add_i32 s47, s47, 2
	s_add_u32 s26, s16, s22
	s_addc_u32 s27, s17, s23
	s_add_u32 s26, s26, 0x100
	s_addc_u32 s27, s27, 0
	s_add_u32 s48, s44, s22
	s_addc_u32 s49, s45, s23
	s_add_i32 s50, 0, 0x10000
	s_cmpk_eq_i32 s22, 0x1f00
	s_cselect_b32 s31, s9, s27
	s_cselect_b32 s30, s41, s26
	v_add_u32_e32 v32, s50, v187
	s_cselect_b32 s27, s7, s49
	s_cselect_b32 s26, s42, s48
	s_add_i32 s51, 0, 0x14000
	ds_read_b128 v[112:115], v32
	ds_read_b128 v[124:127], v32 offset:1024
	ds_read_b128 v[136:139], v32 offset:2048
	ds_read_b128 v[140:143], v32 offset:3072
	v_add_u32_e32 v32, s51, v187
	ds_read_b128 v[144:147], v32
	ds_read_b128 v[152:155], v32 offset:1024
	ds_read_b128 v[174:177], v32 offset:2048
	ds_read_b128 v[178:181], v32 offset:3072
	v_lshl_add_u64 v[34:35], v[100:101], 0, s[22:23]
	s_add_i32 m0, s20, 0xc000
	ds_read_b128 v[202:205], v190
	ds_read_b128 v[206:209], v190 offset:1024
	ds_read_b128 v[210:213], v190 offset:2048
	ds_read_b128 v[214:217], v190 offset:3072
	ds_read_b128 v[218:221], v190 offset:4096
	ds_read_b128 v[222:225], v190 offset:5120
	ds_read_b128 v[246:249], v190 offset:6144
	ds_read_b128 v[198:201], v190 offset:7168
	global_load_lds_dwordx4 v[34:35], off
	v_lshl_add_u64 v[34:35], v[102:103], 0, s[22:23]
	s_add_i32 m0, s20, 0xe000
	s_nop 0
	global_load_lds_dwordx4 v[34:35], off
	s_waitcnt vmcnt(8)
	s_waitcnt lgkmcnt(0)
	s_barrier
	s_setprio 1
	s_waitcnt lgkmcnt(0)
	v_mfma_f32_16x16x32_bf16 v[156:159], v[112:115], v[202:205], v[156:159]
	v_mfma_f32_16x16x32_bf16 v[148:151], v[136:139], v[202:205], v[148:151]
	v_mfma_f32_16x16x32_bf16 v[120:123], v[112:115], v[210:213], v[120:123]
	v_mfma_f32_16x16x32_bf16 v[116:119], v[136:139], v[210:213], v[116:119]
	v_mfma_f32_16x16x32_bf16 v[96:99], v[112:115], v[218:221], v[96:99]
	v_mfma_f32_16x16x32_bf16 v[92:95], v[136:139], v[218:221], v[92:95]
	v_mfma_f32_16x16x32_bf16 v[80:83], v[112:115], v[246:249], v[80:83]
	v_mfma_f32_16x16x32_bf16 v[76:79], v[136:139], v[246:249], v[76:79]
	v_mfma_f32_16x16x32_bf16 v[156:159], v[124:127], v[206:209], v[156:159]
	v_mfma_f32_16x16x32_bf16 v[148:151], v[140:143], v[206:209], v[148:151]
	v_mfma_f32_16x16x32_bf16 v[120:123], v[124:127], v[214:217], v[120:123]
	v_mfma_f32_16x16x32_bf16 v[116:119], v[140:143], v[214:217], v[116:119]
	v_mfma_f32_16x16x32_bf16 v[96:99], v[124:127], v[222:225], v[96:99]
	v_mfma_f32_16x16x32_bf16 v[92:95], v[140:143], v[222:225], v[92:95]
	v_mfma_f32_16x16x32_bf16 v[80:83], v[124:127], v[198:201], v[80:83]
	v_mfma_f32_16x16x32_bf16 v[76:79], v[140:143], v[198:201], v[76:79]
	v_mfma_f32_16x16x32_bf16 v[132:135], v[144:147], v[202:205], v[132:135]
	v_mfma_f32_16x16x32_bf16 v[128:131], v[174:177], v[202:205], v[128:131]
	v_mfma_f32_16x16x32_bf16 v[108:111], v[144:147], v[210:213], v[108:111]
	v_mfma_f32_16x16x32_bf16 v[104:107], v[174:177], v[210:213], v[104:107]
	v_mfma_f32_16x16x32_bf16 v[88:91], v[144:147], v[218:221], v[88:91]
	v_mfma_f32_16x16x32_bf16 v[84:87], v[174:177], v[218:221], v[84:87]
	v_mfma_f32_16x16x32_bf16 v[72:75], v[144:147], v[246:249], v[72:75]
	v_mfma_f32_16x16x32_bf16 v[68:71], v[174:177], v[246:249], v[68:71]
	v_mfma_f32_16x16x32_bf16 v[132:135], v[152:155], v[206:209], v[132:135]
	v_mfma_f32_16x16x32_bf16 v[128:131], v[178:181], v[206:209], v[128:131]
	v_mfma_f32_16x16x32_bf16 v[108:111], v[152:155], v[214:217], v[108:111]
	v_mfma_f32_16x16x32_bf16 v[104:107], v[178:181], v[214:217], v[104:107]
	v_mfma_f32_16x16x32_bf16 v[88:91], v[152:155], v[222:225], v[88:91]
	v_mfma_f32_16x16x32_bf16 v[84:87], v[178:181], v[222:225], v[84:87]
	v_mfma_f32_16x16x32_bf16 v[72:75], v[152:155], v[198:201], v[72:75]
	v_mfma_f32_16x16x32_bf16 v[68:71], v[178:181], v[198:201], v[68:71]
	s_setprio 0
	s_barrier
	s_add_i32 s48, s50, s19
	v_lshl_add_u64 v[182:183], s[26:27], 0, v[164:165]
	s_mov_b32 m0, s48
	ds_read_b128 v[198:201], v190 offset:16384
	ds_read_b128 v[202:205], v190 offset:17408
	ds_read_b128 v[206:209], v190 offset:18432
	ds_read_b128 v[210:213], v190 offset:19456
	ds_read_b128 v[214:217], v190 offset:20480
	ds_read_b128 v[218:221], v190 offset:21504
	ds_read_b128 v[222:225], v190 offset:22528
	ds_read_b128 v[246:249], v190 offset:23552
	global_load_lds_dwordx4 v[182:183], off
	s_add_i32 m0, s48, 0x2000
	s_add_u32 s48, s26, 0x100000
	v_lshl_add_u64 v[192:193], s[26:27], 0, v[160:161]
	s_addc_u32 s49, s27, 0
	s_add_i32 s50, s51, s19
	global_load_lds_dwordx4 v[192:193], off
	v_lshl_add_u64 v[34:35], s[48:49], 0, v[164:165]
	s_mov_b32 m0, s50
	v_lshl_add_u64 v[226:227], s[30:31], 0, v[166:167]
	global_load_lds_dwordx4 v[34:35], off
	v_lshl_add_u64 v[34:35], s[48:49], 0, v[160:161]
	s_add_i32 m0, s50, 0x2000
	v_lshl_add_u64 v[230:231], s[30:31], 0, v[162:163]
	global_load_lds_dwordx4 v[34:35], off
	s_mov_b32 m0, s20
	s_nop 0
	global_load_lds_dwordx4 v[226:227], off
	s_mov_b32 m0, s33
	s_nop 0
	global_load_lds_dwordx4 v[230:231], off
	s_waitcnt vmcnt(8)
	s_waitcnt lgkmcnt(0)
	s_barrier
; #define PG8_STAGE(bufoff, gbase, voff) do { _Pragma("unroll") for (int _i = 0; _i < 2; ++_i) \
;         __builtin_amdgcn_global_load_lds((const unsigned*)((const char*)(gbase) + (voff)[_i]), (PG8_LAS unsigned*)(lds + (bufoff) + ldsw + _i * 8192), 16, 0, 0); } while (0)
; #define PG8_LDA(dst, b, h) do { _Pragma("unroll") for (int m = 0; m < 4; ++m) _Pragma("unroll") for (int k = 0; k < 2; ++k) dst[m][k] = *(const PG8_LAS bf16x8*)(lds + PG8_SA(b, h) + aoff + m * 2048 + k * 1024); } while (0)
; #define PG8_LDB(dst, b, h) do { _Pragma("unroll") for (int n = 0; n < 2; ++n) _Pragma("unroll") for (int k = 0; k < 2; ++k) dst[n][k] = *(const PG8_LAS bf16x8*)(lds + PG8_SB(b, h) + boff + n * 2048 + k * 1024); } while (0)
; #define PG8_MMA(ai, bj, At, Bt) do { __builtin_amdgcn_s_setprio(1); _Pragma("unroll") for (int m = 0; m < 4; ++m) _Pragma("unroll") for (int n = 0; n < 2; ++n) _Pragma("unroll") for (int k = 0; k < 2; ++k) \
;         acc[ai][bj][m][n] = __builtin_amdgcn_mfma_f32_16x16x32_bf16(Bt[n][k], At[m][k], acc[ai][bj][m][n], 0, 0, 0); __builtin_amdgcn_s_setprio(0); } while (0)
; #define PG8_WAIT_V(n) asm volatile("s_waitcnt vmcnt(" #n ")" ::: "memory")
; #define PG8_WAIT_L(n) asm volatile("s_waitcnt lgkmcnt(" #n ")" ::: "memory")
; #define PG8_BAR __builtin_amdgcn_s_barrier()
; #define PG8_SCHED __builtin_amdgcn_sched_barrier(0)
; template <class Epi, class Sched, bool ALIGN_EPI = false, bool SP2 = false, bool KHOOK = false>
; __device__ __forceinline__ void gemm_phase(PG8_LAS unsigned char* lds, const Gemm g, const Sched& S, const Epi& E, const int tid_in) {
;     ...
;             PG8_WAIT_V(8); PG8_WAIT_L(0); PG8_BAR; PG8_MMA(1, 0, At, B0); PG8_MMA(1, 1, At, B1); PG8_BAR; PG8_SCHED;
;             PG8_LDB(B0, 1, 0); PG8_LDB(B1, 1, 1); PG8_SCHED; PG8_LDA(At, 1, 0); PG8_STAGE(PG8_SA(0, 1), a2 + hstep, voffA);
;             PG8_WAIT_V(8); PG8_WAIT_L(0); PG8_BAR; PG8_MMA(0, 0, At, B0); PG8_MMA(0, 1, At, B1); PG8_BAR; PG8_SCHED;
	s_setprio 1
	s_waitcnt lgkmcnt(0)
	v_mfma_f32_16x16x32_bf16 v[64:67], v[112:115], v[198:201], v[64:67]
	v_mfma_f32_16x16x32_bf16 v[60:63], v[136:139], v[198:201], v[60:63]
	v_mfma_f32_16x16x32_bf16 v[48:51], v[112:115], v[206:209], v[48:51]
	v_mfma_f32_16x16x32_bf16 v[44:47], v[136:139], v[206:209], v[44:47]
	v_mfma_f32_16x16x32_bf16 v[28:31], v[112:115], v[214:217], v[28:31]
	v_mfma_f32_16x16x32_bf16 v[24:27], v[136:139], v[214:217], v[24:27]
	v_mfma_f32_16x16x32_bf16 v[12:15], v[112:115], v[222:225], v[12:15]
	v_mfma_f32_16x16x32_bf16 v[8:11], v[136:139], v[222:225], v[8:11]
	v_mfma_f32_16x16x32_bf16 v[64:67], v[124:127], v[202:205], v[64:67]
	v_mfma_f32_16x16x32_bf16 v[60:63], v[140:143], v[202:205], v[60:63]
	v_mfma_f32_16x16x32_bf16 v[48:51], v[124:127], v[210:213], v[48:51]
	v_mfma_f32_16x16x32_bf16 v[44:47], v[140:143], v[210:213], v[44:47]
	v_mfma_f32_16x16x32_bf16 v[28:31], v[124:127], v[218:221], v[28:31]
	v_mfma_f32_16x16x32_bf16 v[24:27], v[140:143], v[218:221], v[24:27]
	v_mfma_f32_16x16x32_bf16 v[12:15], v[124:127], v[246:249], v[12:15]
	v_mfma_f32_16x16x32_bf16 v[8:11], v[140:143], v[246:249], v[8:11]
	v_mfma_f32_16x16x32_bf16 v[56:59], v[144:147], v[198:201], v[56:59]
	v_mfma_f32_16x16x32_bf16 v[52:55], v[174:177], v[198:201], v[52:55]
	v_mfma_f32_16x16x32_bf16 v[40:43], v[144:147], v[206:209], v[40:43]
	v_mfma_f32_16x16x32_bf16 v[34:37], v[174:177], v[206:209], v[36:39]
	v_mfma_f32_16x16x32_bf16 v[20:23], v[144:147], v[214:217], v[20:23]
	v_mfma_f32_16x16x32_bf16 v[16:19], v[174:177], v[214:217], v[16:19]
	v_mfma_f32_16x16x32_bf16 v[4:7], v[144:147], v[222:225], v[4:7]
	v_mfma_f32_16x16x32_bf16 v[0:3], v[174:177], v[222:225], v[0:3]
	v_mfma_f32_16x16x32_bf16 v[56:59], v[152:155], v[202:205], v[56:59]
	v_mfma_f32_16x16x32_bf16 v[52:55], v[178:181], v[202:205], v[52:55]
	v_mfma_f32_16x16x32_bf16 v[40:43], v[152:155], v[210:213], v[40:43]
	v_mfma_f32_16x16x32_bf16 v[34:37], v[178:181], v[210:213], v[34:37]
	v_mfma_f32_16x16x32_bf16 v[20:23], v[152:155], v[218:221], v[20:23]
	v_mfma_f32_16x16x32_bf16 v[16:19], v[178:181], v[218:221], v[16:19]
	v_mfma_f32_16x16x32_bf16 v[4:7], v[152:155], v[246:249], v[4:7]
	v_mfma_f32_16x16x32_bf16 v[0:3], v[178:181], v[246:249], v[0:3]
	s_setprio 0
	s_barrier
	s_add_i32 s48, 0, 0x18000
	v_add_u32_e32 v32, s48, v187
	s_add_i32 s49, 0, 0x1c000
	ds_read_b128 v[112:115], v32
	ds_read_b128 v[124:127], v32 offset:1024
	ds_read_b128 v[136:139], v32 offset:2048
	ds_read_b128 v[140:143], v32 offset:3072
	v_add_u32_e32 v32, s49, v187
	ds_read_b128 v[144:147], v32
	ds_read_b128 v[152:155], v32 offset:1024
	ds_read_b128 v[174:177], v32 offset:2048
	ds_read_b128 v[178:181], v32 offset:3072
	s_add_u32 s30, s30, 0x100000
	s_addc_u32 s31, s31, 0
	s_mov_b32 m0, s36
	v_lshl_add_u64 v[38:39], s[30:31], 0, v[166:167]
	ds_read_b128 v[198:201], v190 offset:32768
	ds_read_b128 v[202:205], v190 offset:33792
	ds_read_b128 v[206:209], v190 offset:34816
	ds_read_b128 v[210:213], v190 offset:35840
	ds_read_b128 v[214:217], v190 offset:36864
	ds_read_b128 v[218:221], v190 offset:37888
	ds_read_b128 v[222:225], v190 offset:38912
	ds_read_b128 v[246:249], v190 offset:39936
	global_load_lds_dwordx4 v[38:39], off
	v_lshl_add_u64 v[38:39], s[30:31], 0, v[162:163]
	s_mov_b32 m0, s37
	s_nop 0
	global_load_lds_dwordx4 v[38:39], off
	s_waitcnt vmcnt(8)
	s_waitcnt lgkmcnt(0)
	s_barrier
	s_setprio 1
	s_waitcnt lgkmcnt(0)
	v_mfma_f32_16x16x32_bf16 v[156:159], v[112:115], v[198:201], v[156:159]
	v_mfma_f32_16x16x32_bf16 v[148:151], v[136:139], v[198:201], v[148:151]
	v_mfma_f32_16x16x32_bf16 v[120:123], v[112:115], v[206:209], v[120:123]
	v_mfma_f32_16x16x32_bf16 v[116:119], v[136:139], v[206:209], v[116:119]
	v_mfma_f32_16x16x32_bf16 v[96:99], v[112:115], v[214:217], v[96:99]
	v_mfma_f32_16x16x32_bf16 v[92:95], v[136:139], v[214:217], v[92:95]
	v_mfma_f32_16x16x32_bf16 v[80:83], v[112:115], v[222:225], v[80:83]
	v_mfma_f32_16x16x32_bf16 v[76:79], v[136:139], v[222:225], v[76:79]
	v_mfma_f32_16x16x32_bf16 v[156:159], v[124:127], v[202:205], v[156:159]
	v_mfma_f32_16x16x32_bf16 v[148:151], v[140:143], v[202:205], v[148:151]
	v_mfma_f32_16x16x32_bf16 v[120:123], v[124:127], v[210:213], v[120:123]
	v_mfma_f32_16x16x32_bf16 v[116:119], v[140:143], v[210:213], v[116:119]
	v_mfma_f32_16x16x32_bf16 v[96:99], v[124:127], v[218:221], v[96:99]
	v_mfma_f32_16x16x32_bf16 v[92:95], v[140:143], v[218:221], v[92:95]
	v_mfma_f32_16x16x32_bf16 v[80:83], v[124:127], v[246:249], v[80:83]
	v_mfma_f32_16x16x32_bf16 v[76:79], v[140:143], v[246:249], v[76:79]
	v_mfma_f32_16x16x32_bf16 v[132:135], v[144:147], v[198:201], v[132:135]
	v_mfma_f32_16x16x32_bf16 v[128:131], v[174:177], v[198:201], v[128:131]
	v_mfma_f32_16x16x32_bf16 v[108:111], v[144:147], v[206:209], v[108:111]
	v_mfma_f32_16x16x32_bf16 v[104:107], v[174:177], v[206:209], v[104:107]
	v_mfma_f32_16x16x32_bf16 v[88:91], v[144:147], v[214:217], v[88:91]
	v_mfma_f32_16x16x32_bf16 v[84:87], v[174:177], v[214:217], v[84:87]
	v_mfma_f32_16x16x32_bf16 v[72:75], v[144:147], v[222:225], v[72:75]
	v_mfma_f32_16x16x32_bf16 v[68:71], v[174:177], v[222:225], v[68:71]
	v_mfma_f32_16x16x32_bf16 v[132:135], v[152:155], v[202:205], v[132:135]
	v_mfma_f32_16x16x32_bf16 v[128:131], v[178:181], v[202:205], v[128:131]
	v_mfma_f32_16x16x32_bf16 v[108:111], v[152:155], v[210:213], v[108:111]
	v_mfma_f32_16x16x32_bf16 v[104:107], v[178:181], v[210:213], v[104:107]
	v_mfma_f32_16x16x32_bf16 v[88:91], v[152:155], v[218:221], v[88:91]
	v_mfma_f32_16x16x32_bf16 v[84:87], v[178:181], v[218:221], v[84:87]
	v_mfma_f32_16x16x32_bf16 v[72:75], v[152:155], v[246:249], v[72:75]
	v_mfma_f32_16x16x32_bf16 v[68:71], v[178:181], v[246:249], v[68:71]
	s_setprio 0
	s_barrier
; #define PG8_STAGE(bufoff, gbase, voff) do { _Pragma("unroll") for (int _i = 0; _i < 2; ++_i) \
;         __builtin_amdgcn_global_load_lds((const unsigned*)((const char*)(gbase) + (voff)[_i]), (PG8_LAS unsigned*)(lds + (bufoff) + ldsw + _i * 8192), 16, 0, 0); } while (0)
; #define PG8_LDA(dst, b, h) do { _Pragma("unroll") for (int m = 0; m < 4; ++m) _Pragma("unroll") for (int k = 0; k < 2; ++k) dst[m][k] = *(const PG8_LAS bf16x8*)(lds + PG8_SA(b, h) + aoff + m * 2048 + k * 1024); } while (0)
; #define PG8_MMA(ai, bj, At, Bt) do { __builtin_amdgcn_s_setprio(1); _Pragma("unroll") for (int m = 0; m < 4; ++m) _Pragma("unroll") for (int n = 0; n < 2; ++n) _Pragma("unroll") for (int k = 0; k < 2; ++k) \
;         acc[ai][bj][m][n] = __builtin_amdgcn_mfma_f32_16x16x32_bf16(Bt[n][k], At[m][k], acc[ai][bj][m][n], 0, 0, 0); __builtin_amdgcn_s_setprio(0); } while (0)
; #define PG8_WAIT_V(n) asm volatile("s_waitcnt vmcnt(" #n ")" ::: "memory")
; #define PG8_WAIT_L(n) asm volatile("s_waitcnt lgkmcnt(" #n ")" ::: "memory")
; #define PG8_BAR __builtin_amdgcn_s_barrier()
; #define PG8_SCHED __builtin_amdgcn_sched_barrier(0)
; template <class Epi, class Sched, bool ALIGN_EPI = false, bool SP2 = false, bool KHOOK = false>
; __device__ __forceinline__ void gemm_phase(PG8_LAS unsigned char* lds, const Gemm g, const Sched& S, const Epi& E, const int tid_in) {
;     ...
;             PG8_LDA(At, 1, 1); PG8_STAGE(PG8_SB(1, 0), b3, voffB); PG8_STAGE(PG8_SB(1, 1), b3 + hstep, voffB); PG8_STAGE(PG8_SA(1, 0), a3, voffA);
;             PG8_WAIT_V(8); PG8_WAIT_L(0); PG8_BAR; PG8_MMA(1, 0, At, B0); PG8_MMA(1, 1, At, B1); PG8_BAR; PG8_SCHED;
;             if constexpr (KHOOK) { if ((t & 7) == 6) {
	s_add_i32 s30, s48, s19
	v_lshl_add_u64 v[38:39], v[182:183], 0, s[90:91]
	s_mov_b32 m0, s30
	ds_read_b128 v[198:201], v190 offset:49152
	ds_read_b128 v[202:205], v190 offset:50176
	ds_read_b128 v[206:209], v190 offset:51200
	ds_read_b128 v[210:213], v190 offset:52224
	ds_read_b128 v[214:217], v190 offset:53248
	ds_read_b128 v[218:221], v190 offset:54272
	ds_read_b128 v[222:225], v190 offset:55296
	ds_read_b128 v[246:249], v190 offset:56320
	global_load_lds_dwordx4 v[38:39], off
	s_add_i32 m0, s30, 0x2000
	s_add_u32 s26, s26, 0x100080
	v_lshl_add_u64 v[38:39], v[192:193], 0, s[90:91]
	s_addc_u32 s27, s27, 0
	s_add_i32 s30, s49, s19
	global_load_lds_dwordx4 v[38:39], off
	v_lshl_add_u64 v[38:39], s[26:27], 0, v[164:165]
	s_mov_b32 m0, s30
	s_nop 0
	global_load_lds_dwordx4 v[38:39], off
	v_lshl_add_u64 v[38:39], s[26:27], 0, v[160:161]
	s_add_i32 m0, s30, 0x2000
	s_nop 0
	global_load_lds_dwordx4 v[38:39], off
	v_lshl_add_u64 v[38:39], v[226:227], 0, s[90:91]
	s_mov_b32 m0, s38
	s_nop 0
	global_load_lds_dwordx4 v[38:39], off
	v_lshl_add_u64 v[38:39], v[230:231], 0, s[90:91]
	s_mov_b32 m0, s39
	s_nop 0
	global_load_lds_dwordx4 v[38:39], off
	s_waitcnt vmcnt(8)
	s_waitcnt lgkmcnt(0)
	s_barrier
	s_setprio 1
	s_waitcnt lgkmcnt(0)
	v_mfma_f32_16x16x32_bf16 v[64:67], v[112:115], v[198:201], v[64:67]
	v_mfma_f32_16x16x32_bf16 v[60:63], v[136:139], v[198:201], v[60:63]
	v_mfma_f32_16x16x32_bf16 v[48:51], v[112:115], v[206:209], v[48:51]
	v_mfma_f32_16x16x32_bf16 v[44:47], v[136:139], v[206:209], v[44:47]
	v_mfma_f32_16x16x32_bf16 v[28:31], v[112:115], v[214:217], v[28:31]
	v_mfma_f32_16x16x32_bf16 v[24:27], v[136:139], v[214:217], v[24:27]
	v_mfma_f32_16x16x32_bf16 v[12:15], v[112:115], v[222:225], v[12:15]
	v_mfma_f32_16x16x32_bf16 v[8:11], v[136:139], v[222:225], v[8:11]
	v_mfma_f32_16x16x32_bf16 v[64:67], v[124:127], v[202:205], v[64:67]
	v_mfma_f32_16x16x32_bf16 v[60:63], v[140:143], v[202:205], v[60:63]
	v_mfma_f32_16x16x32_bf16 v[48:51], v[124:127], v[210:213], v[48:51]
	v_mfma_f32_16x16x32_bf16 v[44:47], v[140:143], v[210:213], v[44:47]
	v_mfma_f32_16x16x32_bf16 v[28:31], v[124:127], v[218:221], v[28:31]
	v_mfma_f32_16x16x32_bf16 v[24:27], v[140:143], v[218:221], v[24:27]
	v_mfma_f32_16x16x32_bf16 v[12:15], v[124:127], v[246:249], v[12:15]
	v_mfma_f32_16x16x32_bf16 v[8:11], v[140:143], v[246:249], v[8:11]
	v_mfma_f32_16x16x32_bf16 v[56:59], v[144:147], v[198:201], v[56:59]
	v_mfma_f32_16x16x32_bf16 v[52:55], v[174:177], v[198:201], v[52:55]
	v_mfma_f32_16x16x32_bf16 v[38:41], v[144:147], v[206:209], v[40:43]
	v_mfma_f32_16x16x32_bf16 v[34:37], v[174:177], v[206:209], v[34:37]
	v_mfma_f32_16x16x32_bf16 v[20:23], v[144:147], v[214:217], v[20:23]
	v_mfma_f32_16x16x32_bf16 v[16:19], v[174:177], v[214:217], v[16:19]
	v_mfma_f32_16x16x32_bf16 v[4:7], v[144:147], v[222:225], v[4:7]
	v_mfma_f32_16x16x32_bf16 v[0:3], v[174:177], v[222:225], v[0:3]
	v_mfma_f32_16x16x32_bf16 v[56:59], v[152:155], v[202:205], v[56:59]
	v_mfma_f32_16x16x32_bf16 v[52:55], v[178:181], v[202:205], v[52:55]
	v_mfma_f32_16x16x32_bf16 v[40:43], v[152:155], v[210:213], v[38:41]
	v_mfma_f32_16x16x32_bf16 v[36:39], v[178:181], v[210:213], v[34:37]
	v_mfma_f32_16x16x32_bf16 v[20:23], v[152:155], v[218:221], v[20:23]
	v_mfma_f32_16x16x32_bf16 v[16:19], v[178:181], v[218:221], v[16:19]
	v_mfma_f32_16x16x32_bf16 v[4:7], v[152:155], v[246:249], v[4:7]
	v_mfma_f32_16x16x32_bf16 v[0:3], v[178:181], v[246:249], v[0:3]
	s_setprio 0
	s_barrier
	s_and_b32 s26, s47, 6
	s_cmp_lg_u32 s26, 6
	s_cbranch_scc1 .LBB0_844
; #define PG8_LAS __attribute__((address_space(3)))
; template <class Epi, class Sched, bool ALIGN_EPI = false, bool SP2 = false, bool KHOOK = false>
; __device__ __forceinline__ void gemm_phase(PG8_LAS unsigned char* lds, const Gemm g, const Sched& S, const Epi& E, const int tid_in) {
;     ...
;             if constexpr (KHOOK) { if ((t & 7) == 6) {
;                 const PG8_LAS float* RT = (const PG8_LAS float*)(lds + 8 * 16384) + (t >> 3) * 256 + wr * 64 + fr; float f[2][4];
; #pragma unroll
;                 for (int a = 0; a < 2; ++a)
; #pragma unroll
;                     for (int m = 0; m < 4; ++m) f[a][m] = RT[a * HALF + m * 16];
; #pragma unroll
;                 for (int a = 0; a < 2; ++a)
; #pragma unroll
;                     for (int b = 0; b < 2; ++b)
; #pragma unroll
;                         for (int m = 0; m < 4; ++m)
; #pragma unroll
;                             for (int n = 0; n < 2; ++n) acc[a][b][m][n] *= f[a][m]; } }
	s_and_b32 s26, s46, 0x700
	v_lshl_add_u32 v32, s26, 2, v188
	ds_read2_b32 v[112:113], v32 offset1:16
	ds_read2_b32 v[114:115], v32 offset0:32 offset1:48
	ds_read2_b32 v[124:125], v32 offset0:128 offset1:144
	ds_read2_b32 v[34:35], v32 offset0:160 offset1:176
	s_waitcnt lgkmcnt(0)
	v_mov_b32_e32 v32, v113
	v_pk_mul_f32 v[158:159], v[158:159], v[112:113] op_sel_hi:[1,0]
	v_pk_mul_f32 v[156:157], v[156:157], v[112:113] op_sel_hi:[1,0]
	v_pk_mul_f32 v[150:151], v[150:151], v[112:113] op_sel_hi:[1,0]
	v_pk_mul_f32 v[148:149], v[148:149], v[112:113] op_sel_hi:[1,0]
	v_pk_mul_f32 v[122:123], v[122:123], v[32:33] op_sel_hi:[1,0]
	v_pk_mul_f32 v[120:121], v[120:121], v[32:33] op_sel_hi:[1,0]
	v_pk_mul_f32 v[118:119], v[118:119], v[32:33] op_sel_hi:[1,0]
	v_pk_mul_f32 v[116:117], v[116:117], v[32:33] op_sel_hi:[1,0]
	v_mov_b32_e32 v126, v115
	v_pk_mul_f32 v[134:135], v[134:135], v[112:113] op_sel_hi:[1,0]
	v_pk_mul_f32 v[132:133], v[132:133], v[112:113] op_sel_hi:[1,0]
	v_pk_mul_f32 v[130:131], v[130:131], v[112:113] op_sel_hi:[1,0]
	v_pk_mul_f32 v[128:129], v[128:129], v[112:113] op_sel_hi:[1,0]
	v_pk_mul_f32 v[110:111], v[110:111], v[32:33] op_sel_hi:[1,0]
	v_pk_mul_f32 v[108:109], v[108:109], v[32:33] op_sel_hi:[1,0]
	v_pk_mul_f32 v[106:107], v[106:107], v[32:33] op_sel_hi:[1,0]
	v_pk_mul_f32 v[104:105], v[104:105], v[32:33] op_sel_hi:[1,0]
	v_mov_b32_e32 v32, v125
	v_mov_b32_e32 v112, v35
	v_pk_mul_f32 v[98:99], v[98:99], v[114:115] op_sel_hi:[1,0]
	v_pk_mul_f32 v[96:97], v[96:97], v[114:115] op_sel_hi:[1,0]
	v_pk_mul_f32 v[94:95], v[94:95], v[114:115] op_sel_hi:[1,0]
	v_pk_mul_f32 v[92:93], v[92:93], v[114:115] op_sel_hi:[1,0]
	v_pk_mul_f32 v[82:83], v[82:83], v[126:127] op_sel_hi:[1,0]
	v_pk_mul_f32 v[80:81], v[80:81], v[126:127] op_sel_hi:[1,0]
	v_pk_mul_f32 v[78:79], v[78:79], v[126:127] op_sel_hi:[1,0]
	v_pk_mul_f32 v[76:77], v[76:77], v[126:127] op_sel_hi:[1,0]
	v_pk_mul_f32 v[90:91], v[90:91], v[114:115] op_sel_hi:[1,0]
	v_pk_mul_f32 v[88:89], v[88:89], v[114:115] op_sel_hi:[1,0]
	v_pk_mul_f32 v[86:87], v[86:87], v[114:115] op_sel_hi:[1,0]
	v_pk_mul_f32 v[84:85], v[84:85], v[114:115] op_sel_hi:[1,0]
	v_pk_mul_f32 v[74:75], v[74:75], v[126:127] op_sel_hi:[1,0]
	v_pk_mul_f32 v[72:73], v[72:73], v[126:127] op_sel_hi:[1,0]
	v_pk_mul_f32 v[70:71], v[70:71], v[126:127] op_sel_hi:[1,0]
	v_pk_mul_f32 v[68:69], v[68:69], v[126:127] op_sel_hi:[1,0]
	v_pk_mul_f32 v[66:67], v[66:67], v[124:125] op_sel_hi:[1,0]
	v_pk_mul_f32 v[64:65], v[64:65], v[124:125] op_sel_hi:[1,0]
	v_pk_mul_f32 v[62:63], v[62:63], v[124:125] op_sel_hi:[1,0]
	v_pk_mul_f32 v[60:61], v[60:61], v[124:125] op_sel_hi:[1,0]
	v_pk_mul_f32 v[50:51], v[50:51], v[32:33] op_sel_hi:[1,0]
	v_pk_mul_f32 v[48:49], v[48:49], v[32:33] op_sel_hi:[1,0]
	v_pk_mul_f32 v[46:47], v[46:47], v[32:33] op_sel_hi:[1,0]
	v_pk_mul_f32 v[44:45], v[44:45], v[32:33] op_sel_hi:[1,0]
	v_pk_mul_f32 v[30:31], v[30:31], v[34:35] op_sel_hi:[1,0]
	v_pk_mul_f32 v[28:29], v[28:29], v[34:35] op_sel_hi:[1,0]
	v_pk_mul_f32 v[26:27], v[26:27], v[34:35] op_sel_hi:[1,0]
	v_pk_mul_f32 v[24:25], v[24:25], v[34:35] op_sel_hi:[1,0]
	v_pk_mul_f32 v[14:15], v[14:15], v[112:113] op_sel_hi:[1,0]
	v_pk_mul_f32 v[12:13], v[12:13], v[112:113] op_sel_hi:[1,0]
	v_pk_mul_f32 v[10:11], v[10:11], v[112:113] op_sel_hi:[1,0]
	v_pk_mul_f32 v[8:9], v[8:9], v[112:113] op_sel_hi:[1,0]
	v_pk_mul_f32 v[58:59], v[58:59], v[124:125] op_sel_hi:[1,0]
	v_pk_mul_f32 v[56:57], v[56:57], v[124:125] op_sel_hi:[1,0]
	v_pk_mul_f32 v[54:55], v[54:55], v[124:125] op_sel_hi:[1,0]
	v_pk_mul_f32 v[52:53], v[52:53], v[124:125] op_sel_hi:[1,0]
	v_pk_mul_f32 v[42:43], v[42:43], v[32:33] op_sel_hi:[1,0]
	v_pk_mul_f32 v[40:41], v[40:41], v[32:33] op_sel_hi:[1,0]
	v_pk_mul_f32 v[38:39], v[38:39], v[32:33] op_sel_hi:[1,0]
	v_pk_mul_f32 v[36:37], v[36:37], v[32:33] op_sel_hi:[1,0]
	v_pk_mul_f32 v[22:23], v[22:23], v[34:35] op_sel_hi:[1,0]
	v_pk_mul_f32 v[20:21], v[20:21], v[34:35] op_sel_hi:[1,0]
	v_pk_mul_f32 v[18:19], v[18:19], v[34:35] op_sel_hi:[1,0]
	v_pk_mul_f32 v[16:17], v[16:17], v[34:35] op_sel_hi:[1,0]
	v_pk_mul_f32 v[6:7], v[6:7], v[112:113] op_sel_hi:[1,0]
	v_pk_mul_f32 v[4:5], v[4:5], v[112:113] op_sel_hi:[1,0]
	v_pk_mul_f32 v[2:3], v[2:3], v[112:113] op_sel_hi:[1,0]
	v_pk_mul_f32 v[0:1], v[0:1], v[112:113] op_sel_hi:[1,0]
	s_branch .LBB0_844

; #define GPROBE_BEGIN(id) do { if (((PROBE_GEMM_SEL >> (id)) & 1) && blockIdx.x == 0 && tid_in < 64 && g.N == 20480) { volatile PG8_LAS unsigned long long* PW_ = (volatile PG8_LAS unsigned long long*)(lds + 163840 - 512 + 64); PW_[0] = __builtin_amdgcn_s_memrealtime(); } } while (0)
; #define GPROBE_END(id) do { if (((PROBE_GEMM_SEL >> (id)) & 1) && blockIdx.x == 0 && tid_in < 64 && g.N == 20480) { volatile PG8_LAS unsigned long long* PW_ = (volatile PG8_LAS unsigned long long*)(lds + 163840 - 512 + 64); PW_[1] += __builtin_amdgcn_s_memrealtime() - PW_[0]; } } while (0)
; #define PG8_STAGE(bufoff, gbase, voff) do { _Pragma("unroll") for (int _i = 0; _i < 2; ++_i) \
;         __builtin_amdgcn_global_load_lds((const unsigned*)((const char*)(gbase) + (voff)[_i]), (PG8_LAS unsigned*)(lds + (bufoff) + ldsw + _i * 8192), 16, 0, 0); } while (0)
; #define PG8_BAR __builtin_amdgcn_s_barrier()
; template <class Epi, class Sched, bool ALIGN_EPI = false, bool SP2 = false, bool KHOOK = false>
; __device__ __forceinline__ void gemm_phase(PG8_LAS unsigned char* lds, const Gemm g, const Sched& S, const Epi& E, const int tid_in) {
;     ...
;         const char* nA = has_next ? (const char*)g.A + (size_t)nxt.pm * tstep + (size_t)nxt.pn * ksl : cA; const char* nB = has_next ? (const char*)g.Bt + (size_t)nxt.pn * bts + (size_t)nxt.pn * ksl + (gdv ? (size_t)(nxt.pm / gdv) * gst : 0) : cB;
;         GPROBE_END(2); GPROBE_BEGIN(1);
;         for (int t = 0; t < nt; t += 2) {
;             const bool last = (t == nt - 2);
;             const char* a1 = cA + (size_t)(t + 1) * kstep;
;             const char* a2 = last ? nA : cA + (size_t)(t + 2) * kstep; const char* b2 = last ? nB : cB + (size_t)(t + 2) * kstep;
;             const char* a3 = a2 + kstep; const char* b3 = b2 + kstep;
;             if (last && has_next) S.a_ready(nxt);
;             if constexpr (SP2) {
;             PG8_LDB(B0, 0, 0); PG8_LDB(B1, 0, 1); PG8_SCHED; PG8_LDA(At, 0, 0); PG8_STAGE(PG8_SA(1, 1), a1 + hstep, voffA);
;             PG8_WAIT_V(8); PG8_WAIT_L(0); PG8_BAR; PG8_MMA(0, 0, At, B0); PG8_MMA(0, 1, At, B1); PG8_BAR; PG8_SCHED;
;             PG8_LDA(At, 0, 1); PG8_STAGE(PG8_SB(0, 0), b2, voffB); PG8_STAGE(PG8_SB(0, 1), b2 + hstep, voffB); PG8_STAGE(PG8_SA(0, 0), a2, voffA);
;             PG8_WAIT_V(8); PG8_WAIT_L(0); PG8_BAR; PG8_MMA(1, 0, At, B0); PG8_MMA(1, 1, At, B1); PG8_BAR; PG8_SCHED;
.LBB0_866:
	s_ashr_i32 s9, s8, 31
	s_lshl_b64 s[12:13], s[8:9], 20
	s_add_u32 s12, s55, s12
	v_readlane_b32 s7, v253, 61
	s_addc_u32 s13, s7, s13
	s_and_b64 s[14:15], s[10:11], exec
	s_cselect_b32 s9, s13, s17
	s_cselect_b32 s39, s12, s16
	s_ashr_i32 s7, s6, 31
	s_lshl_b64 s[14:15], s[6:7], 20
	s_add_u32 s14, s2, s14
	s_addc_u32 s15, s18, s15
	s_and_b64 s[26:27], s[10:11], exec
	s_cselect_b32 s7, s15, s23
	s_cselect_b32 s40, s14, s22
	s_add_u32 s16, s16, 0x80080
	s_addc_u32 s17, s17, 0
	s_add_u32 s41, s22, 0x100
	s_addc_u32 s42, s23, 0
	s_mov_b32 s44, -2
	s_add_u32 s22, s16, 0xfff80080
	s_addc_u32 s23, s17, -1
	s_add_i32 s45, 0, 0x10000
	s_cmp_eq_u32 s44, 28
	s_cselect_b32 s27, s9, s23
	s_cselect_b32 s26, s39, s22
	s_cselect_b32 s23, s7, s42
	s_cselect_b32 s22, s40, s41
	s_add_i32 s48, 0, 0x14000
	v_add_u32_e32 v130, s45, v247
	v_add_u32_e32 v154, s48, v247
	ds_read_b128 v[106:109], v130
	ds_read_b128 v[110:113], v130 offset:1024
	ds_read_b128 v[122:125], v130 offset:2048
	ds_read_b128 v[130:133], v130 offset:3072
	ds_read_b128 v[134:137], v154
	ds_read_b128 v[138:141], v154 offset:1024
	ds_read_b128 v[150:153], v154 offset:2048
	ds_read_b128 v[154:157], v154 offset:3072
	v_lshl_add_u64 v[198:199], s[16:17], 0, v[208:209]
	s_add_i32 m0, s20, 0xc000
	ds_read_b128 v[158:161], v249
	ds_read_b128 v[162:165], v249 offset:1024
	ds_read_b128 v[170:173], v249 offset:2048
	ds_read_b128 v[174:177], v249 offset:3072
	ds_read_b128 v[178:181], v249 offset:4096
	ds_read_b128 v[182:185], v249 offset:5120
	ds_read_b128 v[186:189], v249 offset:6144
	ds_read_b128 v[190:193], v249 offset:7168
	global_load_lds_dwordx4 v[198:199], off
	v_lshl_add_u64 v[198:199], s[16:17], 0, v[210:211]
	s_add_i32 m0, s20, 0xe000
	s_nop 0
	global_load_lds_dwordx4 v[198:199], off
	s_waitcnt vmcnt(8)
	s_waitcnt lgkmcnt(0)
	s_barrier
	s_setprio 1
	s_waitcnt lgkmcnt(0)
	v_mfma_f32_16x16x32_bf16 v[166:169], v[106:109], v[158:161], 0
	v_mfma_f32_16x16x32_bf16 v[146:149], v[122:125], v[158:161], 0
	v_mfma_f32_16x16x32_bf16 v[118:121], v[106:109], v[170:173], 0
	v_mfma_f32_16x16x32_bf16 v[114:117], v[122:125], v[170:173], 0
	v_mfma_f32_16x16x32_bf16 v[94:97], v[106:109], v[178:181], 0
	v_mfma_f32_16x16x32_bf16 v[90:93], v[122:125], v[178:181], 0
	v_mfma_f32_16x16x32_bf16 v[78:81], v[106:109], v[186:189], 0
	v_mfma_f32_16x16x32_bf16 v[74:77], v[122:125], v[186:189], 0
	v_mfma_f32_16x16x32_bf16 v[166:169], v[110:113], v[162:165], v[166:169]
	v_mfma_f32_16x16x32_bf16 v[146:149], v[130:133], v[162:165], v[146:149]
	v_mfma_f32_16x16x32_bf16 v[118:121], v[110:113], v[174:177], v[118:121]
	v_mfma_f32_16x16x32_bf16 v[114:117], v[130:133], v[174:177], v[114:117]
	v_mfma_f32_16x16x32_bf16 v[94:97], v[110:113], v[182:185], v[94:97]
	v_mfma_f32_16x16x32_bf16 v[90:93], v[130:133], v[182:185], v[90:93]
	v_mfma_f32_16x16x32_bf16 v[78:81], v[110:113], v[190:193], v[78:81]
	v_mfma_f32_16x16x32_bf16 v[74:77], v[130:133], v[190:193], v[74:77]
	v_mfma_f32_16x16x32_bf16 v[142:145], v[134:137], v[158:161], 0
	v_mfma_f32_16x16x32_bf16 v[126:129], v[150:153], v[158:161], 0
	v_mfma_f32_16x16x32_bf16 v[102:105], v[134:137], v[170:173], 0
	v_mfma_f32_16x16x32_bf16 v[98:101], v[150:153], v[170:173], 0
	v_mfma_f32_16x16x32_bf16 v[86:89], v[134:137], v[178:181], 0
	v_mfma_f32_16x16x32_bf16 v[82:85], v[150:153], v[178:181], 0
	v_mfma_f32_16x16x32_bf16 v[70:73], v[134:137], v[186:189], 0
	v_mfma_f32_16x16x32_bf16 v[66:69], v[150:153], v[186:189], 0
	v_mfma_f32_16x16x32_bf16 v[142:145], v[138:141], v[162:165], v[142:145]
	v_mfma_f32_16x16x32_bf16 v[126:129], v[154:157], v[162:165], v[126:129]
	v_mfma_f32_16x16x32_bf16 v[102:105], v[138:141], v[174:177], v[102:105]
	v_mfma_f32_16x16x32_bf16 v[98:101], v[154:157], v[174:177], v[98:101]
	v_mfma_f32_16x16x32_bf16 v[86:89], v[138:141], v[182:185], v[86:89]
	v_mfma_f32_16x16x32_bf16 v[82:85], v[154:157], v[182:185], v[82:85]
	v_mfma_f32_16x16x32_bf16 v[70:73], v[138:141], v[190:193], v[70:73]
	v_mfma_f32_16x16x32_bf16 v[66:69], v[154:157], v[190:193], v[66:69]
	s_setprio 0
	s_barrier
	s_add_i32 s45, s45, s19
	v_lshl_add_u64 v[198:199], s[22:23], 0, v[32:33]
	s_mov_b32 m0, s45
	ds_read_b128 v[158:161], v249 offset:16384
	ds_read_b128 v[162:165], v249 offset:17408
	ds_read_b128 v[170:173], v249 offset:18432
	ds_read_b128 v[174:177], v249 offset:19456
	ds_read_b128 v[178:181], v249 offset:20480
	ds_read_b128 v[182:185], v249 offset:21504
	ds_read_b128 v[186:189], v249 offset:22528
	ds_read_b128 v[190:193], v249 offset:23552
	global_load_lds_dwordx4 v[198:199], off
	s_add_i32 m0, s45, 0x2000
	s_add_u32 s46, s22, 0x80000
	v_lshl_add_u64 v[200:201], s[22:23], 0, v[202:203]
	s_addc_u32 s47, s23, 0
	s_add_i32 s45, s48, s19
	global_load_lds_dwordx4 v[200:201], off
	v_lshl_add_u64 v[212:213], s[46:47], 0, v[32:33]
	s_mov_b32 m0, s45
	v_lshl_add_u64 v[214:215], s[26:27], 0, v[204:205]
	global_load_lds_dwordx4 v[212:213], off
	v_lshl_add_u64 v[212:213], s[46:47], 0, v[202:203]
	s_add_i32 m0, s45, 0x2000
	s_nop 0
	global_load_lds_dwordx4 v[212:213], off
	v_lshl_add_u64 v[212:213], s[26:27], 0, v[206:207]
	s_mov_b32 m0, s20
	s_nop 0
	global_load_lds_dwordx4 v[212:213], off
	s_mov_b32 m0, s30
	s_nop 0
	global_load_lds_dwordx4 v[214:215], off
	s_waitcnt vmcnt(8)
	s_waitcnt lgkmcnt(0)
	s_barrier
; #define PG8_STAGE(bufoff, gbase, voff) do { _Pragma("unroll") for (int _i = 0; _i < 2; ++_i) \
;         __builtin_amdgcn_global_load_lds((const unsigned*)((const char*)(gbase) + (voff)[_i]), (PG8_LAS unsigned*)(lds + (bufoff) + ldsw + _i * 8192), 16, 0, 0); } while (0)
; #define PG8_LDA(dst, b, h) do { _Pragma("unroll") for (int m = 0; m < 4; ++m) _Pragma("unroll") for (int k = 0; k < 2; ++k) dst[m][k] = *(const PG8_LAS bf16x8*)(lds + PG8_SA(b, h) + aoff + m * 2048 + k * 1024); } while (0)
; #define PG8_LDB(dst, b, h) do { _Pragma("unroll") for (int n = 0; n < 2; ++n) _Pragma("unroll") for (int k = 0; k < 2; ++k) dst[n][k] = *(const PG8_LAS bf16x8*)(lds + PG8_SB(b, h) + boff + n * 2048 + k * 1024); } while (0)
; #define PG8_MMA(ai, bj, At, Bt) do { __builtin_amdgcn_s_setprio(1); _Pragma("unroll") for (int m = 0; m < 4; ++m) _Pragma("unroll") for (int n = 0; n < 2; ++n) _Pragma("unroll") for (int k = 0; k < 2; ++k) \
;         acc[ai][bj][m][n] = __builtin_amdgcn_mfma_f32_16x16x32_bf16(Bt[n][k], At[m][k], acc[ai][bj][m][n], 0, 0, 0); __builtin_amdgcn_s_setprio(0); } while (0)
; #define PG8_WAIT_V(n) asm volatile("s_waitcnt vmcnt(" #n ")" ::: "memory")
; #define PG8_WAIT_L(n) asm volatile("s_waitcnt lgkmcnt(" #n ")" ::: "memory")
; #define PG8_BAR __builtin_amdgcn_s_barrier()
; #define PG8_SCHED __builtin_amdgcn_sched_barrier(0)
; template <class Epi, class Sched, bool ALIGN_EPI = false, bool SP2 = false, bool KHOOK = false>
; __device__ __forceinline__ void gemm_phase(PG8_LAS unsigned char* lds, const Gemm g, const Sched& S, const Epi& E, const int tid_in) {
;     ...
;             PG8_WAIT_V(8); PG8_WAIT_L(0); PG8_BAR; PG8_MMA(1, 0, At, B0); PG8_MMA(1, 1, At, B1); PG8_BAR; PG8_SCHED;
;             PG8_LDB(B0, 1, 0); PG8_LDB(B1, 1, 1); PG8_SCHED; PG8_LDA(At, 1, 0); PG8_STAGE(PG8_SA(0, 1), a2 + hstep, voffA);
;             PG8_WAIT_V(8); PG8_WAIT_L(0); PG8_BAR; PG8_MMA(0, 0, At, B0); PG8_MMA(0, 1, At, B1); PG8_BAR; PG8_SCHED;
	s_setprio 1
	s_waitcnt lgkmcnt(0)
	v_mfma_f32_16x16x32_bf16 v[62:65], v[106:109], v[158:161], 0
	v_mfma_f32_16x16x32_bf16 v[58:61], v[122:125], v[158:161], 0
	v_mfma_f32_16x16x32_bf16 v[46:49], v[106:109], v[170:173], 0
	v_mfma_f32_16x16x32_bf16 v[42:45], v[122:125], v[170:173], 0
	v_mfma_f32_16x16x32_bf16 v[28:31], v[106:109], v[178:181], 0
	v_mfma_f32_16x16x32_bf16 v[24:27], v[122:125], v[178:181], 0
	v_mfma_f32_16x16x32_bf16 v[12:15], v[106:109], v[186:189], 0
	v_mfma_f32_16x16x32_bf16 v[8:11], v[122:125], v[186:189], 0
	v_mfma_f32_16x16x32_bf16 v[62:65], v[110:113], v[162:165], v[62:65]
	v_mfma_f32_16x16x32_bf16 v[58:61], v[130:133], v[162:165], v[58:61]
	v_mfma_f32_16x16x32_bf16 v[46:49], v[110:113], v[174:177], v[46:49]
	v_mfma_f32_16x16x32_bf16 v[42:45], v[130:133], v[174:177], v[42:45]
	v_mfma_f32_16x16x32_bf16 v[28:31], v[110:113], v[182:185], v[28:31]
	v_mfma_f32_16x16x32_bf16 v[24:27], v[130:133], v[182:185], v[24:27]
	v_mfma_f32_16x16x32_bf16 v[12:15], v[110:113], v[190:193], v[12:15]
	v_mfma_f32_16x16x32_bf16 v[8:11], v[130:133], v[190:193], v[8:11]
	v_mfma_f32_16x16x32_bf16 v[54:57], v[134:137], v[158:161], 0
	v_mfma_f32_16x16x32_bf16 v[50:53], v[150:153], v[158:161], 0
	v_mfma_f32_16x16x32_bf16 v[38:41], v[134:137], v[170:173], 0
	v_mfma_f32_16x16x32_bf16 v[34:37], v[150:153], v[170:173], 0
	v_mfma_f32_16x16x32_bf16 v[20:23], v[134:137], v[178:181], 0
	v_mfma_f32_16x16x32_bf16 v[16:19], v[150:153], v[178:181], 0
	v_mfma_f32_16x16x32_bf16 v[4:7], v[134:137], v[186:189], 0
	v_mfma_f32_16x16x32_bf16 v[0:3], v[150:153], v[186:189], 0
	v_mfma_f32_16x16x32_bf16 v[54:57], v[138:141], v[162:165], v[54:57]
	v_mfma_f32_16x16x32_bf16 v[50:53], v[154:157], v[162:165], v[50:53]
	v_mfma_f32_16x16x32_bf16 v[38:41], v[138:141], v[174:177], v[38:41]
	v_mfma_f32_16x16x32_bf16 v[34:37], v[154:157], v[174:177], v[34:37]
	v_mfma_f32_16x16x32_bf16 v[20:23], v[138:141], v[182:185], v[20:23]
	v_mfma_f32_16x16x32_bf16 v[16:19], v[154:157], v[182:185], v[16:19]
	v_mfma_f32_16x16x32_bf16 v[4:7], v[138:141], v[190:193], v[4:7]
	v_mfma_f32_16x16x32_bf16 v[0:3], v[154:157], v[190:193], v[0:3]
	s_setprio 0
	s_barrier
	s_add_i32 s45, 0, 0x18000
	s_add_i32 s46, 0, 0x1c000
	v_add_u32_e32 v130, s45, v247
	v_add_u32_e32 v154, s46, v247
	ds_read_b128 v[106:109], v130
	ds_read_b128 v[110:113], v130 offset:1024
	ds_read_b128 v[122:125], v130 offset:2048
	ds_read_b128 v[130:133], v130 offset:3072
	ds_read_b128 v[134:137], v154
	ds_read_b128 v[138:141], v154 offset:1024
	ds_read_b128 v[150:153], v154 offset:2048
	ds_read_b128 v[154:157], v154 offset:3072
	s_add_u32 s26, s26, 0x80000
	s_addc_u32 s27, s27, 0
	s_mov_b32 m0, s31
	v_lshl_add_u64 v[216:217], s[26:27], 0, v[206:207]
	ds_read_b128 v[158:161], v249 offset:32768
	ds_read_b128 v[162:165], v249 offset:33792
	ds_read_b128 v[170:173], v249 offset:34816
	ds_read_b128 v[174:177], v249 offset:35840
	ds_read_b128 v[178:181], v249 offset:36864
	ds_read_b128 v[182:185], v249 offset:37888
	ds_read_b128 v[186:189], v249 offset:38912
	ds_read_b128 v[190:193], v249 offset:39936
	global_load_lds_dwordx4 v[216:217], off
	v_lshl_add_u64 v[216:217], s[26:27], 0, v[204:205]
	s_mov_b32 m0, s33
	s_nop 0
	global_load_lds_dwordx4 v[216:217], off
	s_waitcnt vmcnt(8)
	s_waitcnt lgkmcnt(0)
	s_barrier
	s_setprio 1
	s_waitcnt lgkmcnt(0)
	v_mfma_f32_16x16x32_bf16 v[166:169], v[106:109], v[158:161], v[166:169]
	v_mfma_f32_16x16x32_bf16 v[146:149], v[122:125], v[158:161], v[146:149]
	v_mfma_f32_16x16x32_bf16 v[118:121], v[106:109], v[170:173], v[118:121]
	v_mfma_f32_16x16x32_bf16 v[114:117], v[122:125], v[170:173], v[114:117]
	v_mfma_f32_16x16x32_bf16 v[94:97], v[106:109], v[178:181], v[94:97]
	v_mfma_f32_16x16x32_bf16 v[90:93], v[122:125], v[178:181], v[90:93]
	v_mfma_f32_16x16x32_bf16 v[78:81], v[106:109], v[186:189], v[78:81]
	v_mfma_f32_16x16x32_bf16 v[74:77], v[122:125], v[186:189], v[74:77]
	v_mfma_f32_16x16x32_bf16 v[166:169], v[110:113], v[162:165], v[166:169]
	v_mfma_f32_16x16x32_bf16 v[146:149], v[130:133], v[162:165], v[146:149]
	v_mfma_f32_16x16x32_bf16 v[118:121], v[110:113], v[174:177], v[118:121]
	v_mfma_f32_16x16x32_bf16 v[114:117], v[130:133], v[174:177], v[114:117]
	v_mfma_f32_16x16x32_bf16 v[94:97], v[110:113], v[182:185], v[94:97]
	v_mfma_f32_16x16x32_bf16 v[90:93], v[130:133], v[182:185], v[90:93]
	v_mfma_f32_16x16x32_bf16 v[78:81], v[110:113], v[190:193], v[78:81]
	v_mfma_f32_16x16x32_bf16 v[74:77], v[130:133], v[190:193], v[74:77]
	v_mfma_f32_16x16x32_bf16 v[142:145], v[134:137], v[158:161], v[142:145]
	v_mfma_f32_16x16x32_bf16 v[126:129], v[150:153], v[158:161], v[126:129]
	v_mfma_f32_16x16x32_bf16 v[102:105], v[134:137], v[170:173], v[102:105]
	v_mfma_f32_16x16x32_bf16 v[98:101], v[150:153], v[170:173], v[98:101]
	v_mfma_f32_16x16x32_bf16 v[86:89], v[134:137], v[178:181], v[86:89]
	v_mfma_f32_16x16x32_bf16 v[82:85], v[150:153], v[178:181], v[82:85]
	v_mfma_f32_16x16x32_bf16 v[70:73], v[134:137], v[186:189], v[70:73]
	v_mfma_f32_16x16x32_bf16 v[66:69], v[150:153], v[186:189], v[66:69]
	v_mfma_f32_16x16x32_bf16 v[142:145], v[138:141], v[162:165], v[142:145]
	v_mfma_f32_16x16x32_bf16 v[126:129], v[154:157], v[162:165], v[126:129]
	v_mfma_f32_16x16x32_bf16 v[102:105], v[138:141], v[174:177], v[102:105]
	v_mfma_f32_16x16x32_bf16 v[98:101], v[154:157], v[174:177], v[98:101]
	v_mfma_f32_16x16x32_bf16 v[86:89], v[138:141], v[182:185], v[86:89]
	v_mfma_f32_16x16x32_bf16 v[82:85], v[154:157], v[182:185], v[82:85]
	v_mfma_f32_16x16x32_bf16 v[70:73], v[138:141], v[190:193], v[70:73]
	v_mfma_f32_16x16x32_bf16 v[66:69], v[154:157], v[190:193], v[66:69]
	s_setprio 0
	s_barrier
; #define PG8_STAGE(bufoff, gbase, voff) do { _Pragma("unroll") for (int _i = 0; _i < 2; ++_i) \
;         __builtin_amdgcn_global_load_lds((const unsigned*)((const char*)(gbase) + (voff)[_i]), (PG8_LAS unsigned*)(lds + (bufoff) + ldsw + _i * 8192), 16, 0, 0); } while (0)
; #define PG8_LDA(dst, b, h) do { _Pragma("unroll") for (int m = 0; m < 4; ++m) _Pragma("unroll") for (int k = 0; k < 2; ++k) dst[m][k] = *(const PG8_LAS bf16x8*)(lds + PG8_SA(b, h) + aoff + m * 2048 + k * 1024); } while (0)
; #define PG8_LDB(dst, b, h) do { _Pragma("unroll") for (int n = 0; n < 2; ++n) _Pragma("unroll") for (int k = 0; k < 2; ++k) dst[n][k] = *(const PG8_LAS bf16x8*)(lds + PG8_SB(b, h) + boff + n * 2048 + k * 1024); } while (0)
; #define PG8_MMA(ai, bj, At, Bt) do { __builtin_amdgcn_s_setprio(1); _Pragma("unroll") for (int m = 0; m < 4; ++m) _Pragma("unroll") for (int n = 0; n < 2; ++n) _Pragma("unroll") for (int k = 0; k < 2; ++k) \
;         acc[ai][bj][m][n] = __builtin_amdgcn_mfma_f32_16x16x32_bf16(Bt[n][k], At[m][k], acc[ai][bj][m][n], 0, 0, 0); __builtin_amdgcn_s_setprio(0); } while (0)
; #define PG8_WAIT_V(n) asm volatile("s_waitcnt vmcnt(" #n ")" ::: "memory")
; #define PG8_WAIT_L(n) asm volatile("s_waitcnt lgkmcnt(" #n ")" ::: "memory")
; #define PG8_BAR __builtin_amdgcn_s_barrier()
; #define PG8_SCHED __builtin_amdgcn_sched_barrier(0)
; template <class Epi, class Sched, bool ALIGN_EPI = false, bool SP2 = false, bool KHOOK = false>
; __device__ __forceinline__ void gemm_phase(PG8_LAS unsigned char* lds, const Gemm g, const Sched& S, const Epi& E, const int tid_in) {
;     ...
;             const bool last = (t == nt - 2);
;             const char* a1 = cA + (size_t)(t + 1) * kstep;
;             const char* a2 = last ? nA : cA + (size_t)(t + 2) * kstep; const char* b2 = last ? nB : cB + (size_t)(t + 2) * kstep;
;             const char* a3 = a2 + kstep; const char* b3 = b2 + kstep;
;             if (last && has_next) S.a_ready(nxt);
;             if constexpr (SP2) {
;             PG8_LDB(B0, 0, 0); PG8_LDB(B1, 0, 1); PG8_SCHED; PG8_LDA(At, 0, 0); PG8_STAGE(PG8_SA(1, 1), a1 + hstep, voffA);
;     ...
;             PG8_LDA(At, 1, 1); PG8_STAGE(PG8_SB(1, 0), b3, voffB); PG8_STAGE(PG8_SB(1, 1), b3 + hstep, voffB); PG8_STAGE(PG8_SA(1, 0), a3, voffA);
;             PG8_WAIT_V(8); PG8_WAIT_L(0); PG8_BAR; PG8_MMA(1, 0, At, B0); PG8_MMA(1, 1, At, B1); PG8_BAR; PG8_SCHED;
	s_add_i32 s26, s45, s19
	v_lshl_add_u64 v[198:199], v[198:199], 0, s[90:91]
	s_mov_b32 m0, s26
	ds_read_b128 v[158:161], v249 offset:49152
	ds_read_b128 v[162:165], v249 offset:50176
	ds_read_b128 v[170:173], v249 offset:51200
	ds_read_b128 v[174:177], v249 offset:52224
	ds_read_b128 v[178:181], v249 offset:53248
	ds_read_b128 v[182:185], v249 offset:54272
	ds_read_b128 v[186:189], v249 offset:55296
	ds_read_b128 v[190:193], v249 offset:56320
	global_load_lds_dwordx4 v[198:199], off
	s_add_i32 m0, s26, 0x2000
	s_add_u32 s22, s22, 0x80080
	v_lshl_add_u64 v[198:199], v[200:201], 0, s[90:91]
	s_addc_u32 s23, s23, 0
	s_add_i32 s26, s46, s19
	global_load_lds_dwordx4 v[198:199], off
	v_lshl_add_u64 v[198:199], s[22:23], 0, v[32:33]
	s_mov_b32 m0, s26
	s_nop 0
	global_load_lds_dwordx4 v[198:199], off
	v_lshl_add_u64 v[198:199], s[22:23], 0, v[202:203]
	s_add_i32 m0, s26, 0x2000
	s_nop 0
	global_load_lds_dwordx4 v[198:199], off
	v_lshl_add_u64 v[198:199], v[212:213], 0, s[90:91]
	s_mov_b32 m0, s36
	s_nop 0
	global_load_lds_dwordx4 v[198:199], off
	v_lshl_add_u64 v[198:199], v[214:215], 0, s[90:91]
	s_mov_b32 m0, s37
	s_nop 0
	global_load_lds_dwordx4 v[198:199], off
	s_waitcnt vmcnt(8)
	s_waitcnt lgkmcnt(0)
	s_barrier
	s_setprio 1
	s_waitcnt lgkmcnt(0)
	v_mfma_f32_16x16x32_bf16 v[62:65], v[106:109], v[158:161], v[62:65]
	v_mfma_f32_16x16x32_bf16 v[58:61], v[122:125], v[158:161], v[58:61]
	v_mfma_f32_16x16x32_bf16 v[46:49], v[106:109], v[170:173], v[46:49]
	v_mfma_f32_16x16x32_bf16 v[42:45], v[122:125], v[170:173], v[42:45]
	v_mfma_f32_16x16x32_bf16 v[28:31], v[106:109], v[178:181], v[28:31]
	v_mfma_f32_16x16x32_bf16 v[24:27], v[122:125], v[178:181], v[24:27]
	v_mfma_f32_16x16x32_bf16 v[12:15], v[106:109], v[186:189], v[12:15]
	v_mfma_f32_16x16x32_bf16 v[8:11], v[122:125], v[186:189], v[8:11]
	v_mfma_f32_16x16x32_bf16 v[62:65], v[110:113], v[162:165], v[62:65]
	v_mfma_f32_16x16x32_bf16 v[58:61], v[130:133], v[162:165], v[58:61]
	v_mfma_f32_16x16x32_bf16 v[46:49], v[110:113], v[174:177], v[46:49]
	v_mfma_f32_16x16x32_bf16 v[42:45], v[130:133], v[174:177], v[42:45]
	v_mfma_f32_16x16x32_bf16 v[28:31], v[110:113], v[182:185], v[28:31]
	v_mfma_f32_16x16x32_bf16 v[24:27], v[130:133], v[182:185], v[24:27]
	v_mfma_f32_16x16x32_bf16 v[12:15], v[110:113], v[190:193], v[12:15]
	v_mfma_f32_16x16x32_bf16 v[8:11], v[130:133], v[190:193], v[8:11]
	v_mfma_f32_16x16x32_bf16 v[54:57], v[134:137], v[158:161], v[54:57]
	v_mfma_f32_16x16x32_bf16 v[50:53], v[150:153], v[158:161], v[50:53]
	v_mfma_f32_16x16x32_bf16 v[38:41], v[134:137], v[170:173], v[38:41]
	v_mfma_f32_16x16x32_bf16 v[34:37], v[150:153], v[170:173], v[34:37]
	v_mfma_f32_16x16x32_bf16 v[20:23], v[134:137], v[178:181], v[20:23]
	v_mfma_f32_16x16x32_bf16 v[16:19], v[150:153], v[178:181], v[16:19]
	v_mfma_f32_16x16x32_bf16 v[4:7], v[134:137], v[186:189], v[4:7]
	v_mfma_f32_16x16x32_bf16 v[0:3], v[150:153], v[186:189], v[0:3]
	v_mfma_f32_16x16x32_bf16 v[54:57], v[138:141], v[162:165], v[54:57]
	v_mfma_f32_16x16x32_bf16 v[50:53], v[154:157], v[162:165], v[50:53]
	v_mfma_f32_16x16x32_bf16 v[38:41], v[138:141], v[174:177], v[38:41]
	v_mfma_f32_16x16x32_bf16 v[34:37], v[154:157], v[174:177], v[34:37]
	v_mfma_f32_16x16x32_bf16 v[20:23], v[138:141], v[182:185], v[20:23]
	v_mfma_f32_16x16x32_bf16 v[16:19], v[154:157], v[182:185], v[16:19]
	v_mfma_f32_16x16x32_bf16 v[4:7], v[138:141], v[190:193], v[4:7]
	v_mfma_f32_16x16x32_bf16 v[0:3], v[154:157], v[190:193], v[0:3]
	s_setprio 0
	s_barrier
	s_add_i32 s44, s44, 2
	s_add_u32 s16, s16, 0x100
	s_addc_u32 s17, s17, 0
	s_add_u32 s41, s41, 0x100
	s_addc_u32 s42, s42, 0
	s_cmp_gt_u32 s44, 29
.LBB0_867:
	s_add_u32 s22, s16, 0xfff80080
	s_addc_u32 s23, s17, -1
	s_add_i32 s45, 0, 0x10000
	s_cmp_eq_u32 s44, 28
	s_cselect_b32 s27, s9, s23
	s_cselect_b32 s26, s39, s22
	s_cselect_b32 s23, s7, s42
	s_cselect_b32 s22, s40, s41
	s_add_i32 s48, 0, 0x14000
	v_add_u32_e32 v130, s45, v247
	v_add_u32_e32 v154, s48, v247
	ds_read_b128 v[106:109], v130
	ds_read_b128 v[110:113], v130 offset:1024
	ds_read_b128 v[122:125], v130 offset:2048
	ds_read_b128 v[130:133], v130 offset:3072
	ds_read_b128 v[134:137], v154
	ds_read_b128 v[138:141], v154 offset:1024
	ds_read_b128 v[150:153], v154 offset:2048
	ds_read_b128 v[154:157], v154 offset:3072
	v_lshl_add_u64 v[198:199], s[16:17], 0, v[208:209]
	s_add_i32 m0, s20, 0xc000
	ds_read_b128 v[158:161], v249
	ds_read_b128 v[162:165], v249 offset:1024
	ds_read_b128 v[170:173], v249 offset:2048
	ds_read_b128 v[174:177], v249 offset:3072
	ds_read_b128 v[178:181], v249 offset:4096
	ds_read_b128 v[182:185], v249 offset:5120
	ds_read_b128 v[186:189], v249 offset:6144
	ds_read_b128 v[190:193], v249 offset:7168
	global_load_lds_dwordx4 v[198:199], off
	v_lshl_add_u64 v[198:199], s[16:17], 0, v[210:211]
	s_add_i32 m0, s20, 0xe000
	s_nop 0
	global_load_lds_dwordx4 v[198:199], off
	s_waitcnt vmcnt(8)
	s_waitcnt lgkmcnt(0)
	s_barrier
; #define PG8_STAGE(bufoff, gbase, voff) do { _Pragma("unroll") for (int _i = 0; _i < 2; ++_i) \
;         __builtin_amdgcn_global_load_lds((const unsigned*)((const char*)(gbase) + (voff)[_i]), (PG8_LAS unsigned*)(lds + (bufoff) + ldsw + _i * 8192), 16, 0, 0); } while (0)
; #define PG8_LDA(dst, b, h) do { _Pragma("unroll") for (int m = 0; m < 4; ++m) _Pragma("unroll") for (int k = 0; k < 2; ++k) dst[m][k] = *(const PG8_LAS bf16x8*)(lds + PG8_SA(b, h) + aoff + m * 2048 + k * 1024); } while (0)
; #define PG8_LDB(dst, b, h) do { _Pragma("unroll") for (int n = 0; n < 2; ++n) _Pragma("unroll") for (int k = 0; k < 2; ++k) dst[n][k] = *(const PG8_LAS bf16x8*)(lds + PG8_SB(b, h) + boff + n * 2048 + k * 1024); } while (0)
; #define PG8_MMA(ai, bj, At, Bt) do { __builtin_amdgcn_s_setprio(1); _Pragma("unroll") for (int m = 0; m < 4; ++m) _Pragma("unroll") for (int n = 0; n < 2; ++n) _Pragma("unroll") for (int k = 0; k < 2; ++k) \
;         acc[ai][bj][m][n] = __builtin_amdgcn_mfma_f32_16x16x32_bf16(Bt[n][k], At[m][k], acc[ai][bj][m][n], 0, 0, 0); __builtin_amdgcn_s_setprio(0); } while (0)
; #define PG8_WAIT_V(n) asm volatile("s_waitcnt vmcnt(" #n ")" ::: "memory")
; #define PG8_WAIT_L(n) asm volatile("s_waitcnt lgkmcnt(" #n ")" ::: "memory")
; #define PG8_BAR __builtin_amdgcn_s_barrier()
; #define PG8_SCHED __builtin_amdgcn_sched_barrier(0)
; template <class Epi, class Sched, bool ALIGN_EPI = false, bool SP2 = false, bool KHOOK = false>
; __device__ __forceinline__ void gemm_phase(PG8_LAS unsigned char* lds, const Gemm g, const Sched& S, const Epi& E, const int tid_in) {
;     ...
;             PG8_WAIT_V(8); PG8_WAIT_L(0); PG8_BAR; PG8_MMA(0, 0, At, B0); PG8_MMA(0, 1, At, B1); PG8_BAR; PG8_SCHED;
;             PG8_LDA(At, 0, 1); PG8_STAGE(PG8_SB(0, 0), b2, voffB); PG8_STAGE(PG8_SB(0, 1), b2 + hstep, voffB); PG8_STAGE(PG8_SA(0, 0), a2, voffA);
;             PG8_WAIT_V(8); PG8_WAIT_L(0); PG8_BAR; PG8_MMA(1, 0, At, B0); PG8_MMA(1, 1, At, B1); PG8_BAR; PG8_SCHED;
;             PG8_LDB(B0, 1, 0); PG8_LDB(B1, 1, 1); PG8_SCHED; PG8_LDA(At, 1, 0); PG8_STAGE(PG8_SA(0, 1), a2 + hstep, voffA);
;             PG8_WAIT_V(8); PG8_WAIT_L(0); PG8_BAR; PG8_MMA(0, 0, At, B0); PG8_MMA(0, 1, At, B1); PG8_BAR; PG8_SCHED;
	s_setprio 1
	s_waitcnt lgkmcnt(0)
	v_mfma_f32_16x16x32_bf16 v[166:169], v[106:109], v[158:161], v[166:169]
	v_mfma_f32_16x16x32_bf16 v[146:149], v[122:125], v[158:161], v[146:149]
	v_mfma_f32_16x16x32_bf16 v[118:121], v[106:109], v[170:173], v[118:121]
	v_mfma_f32_16x16x32_bf16 v[114:117], v[122:125], v[170:173], v[114:117]
	v_mfma_f32_16x16x32_bf16 v[94:97], v[106:109], v[178:181], v[94:97]
	v_mfma_f32_16x16x32_bf16 v[90:93], v[122:125], v[178:181], v[90:93]
	v_mfma_f32_16x16x32_bf16 v[78:81], v[106:109], v[186:189], v[78:81]
	v_mfma_f32_16x16x32_bf16 v[74:77], v[122:125], v[186:189], v[74:77]
	v_mfma_f32_16x16x32_bf16 v[166:169], v[110:113], v[162:165], v[166:169]
	v_mfma_f32_16x16x32_bf16 v[146:149], v[130:133], v[162:165], v[146:149]
	v_mfma_f32_16x16x32_bf16 v[118:121], v[110:113], v[174:177], v[118:121]
	v_mfma_f32_16x16x32_bf16 v[114:117], v[130:133], v[174:177], v[114:117]
	v_mfma_f32_16x16x32_bf16 v[94:97], v[110:113], v[182:185], v[94:97]
	v_mfma_f32_16x16x32_bf16 v[90:93], v[130:133], v[182:185], v[90:93]
	v_mfma_f32_16x16x32_bf16 v[78:81], v[110:113], v[190:193], v[78:81]
	v_mfma_f32_16x16x32_bf16 v[74:77], v[130:133], v[190:193], v[74:77]
	v_mfma_f32_16x16x32_bf16 v[142:145], v[134:137], v[158:161], v[142:145]
	v_mfma_f32_16x16x32_bf16 v[126:129], v[150:153], v[158:161], v[126:129]
	v_mfma_f32_16x16x32_bf16 v[102:105], v[134:137], v[170:173], v[102:105]
	v_mfma_f32_16x16x32_bf16 v[98:101], v[150:153], v[170:173], v[98:101]
	v_mfma_f32_16x16x32_bf16 v[86:89], v[134:137], v[178:181], v[86:89]
	v_mfma_f32_16x16x32_bf16 v[82:85], v[150:153], v[178:181], v[82:85]
	v_mfma_f32_16x16x32_bf16 v[70:73], v[134:137], v[186:189], v[70:73]
	v_mfma_f32_16x16x32_bf16 v[66:69], v[150:153], v[186:189], v[66:69]
	v_mfma_f32_16x16x32_bf16 v[142:145], v[138:141], v[162:165], v[142:145]
	v_mfma_f32_16x16x32_bf16 v[126:129], v[154:157], v[162:165], v[126:129]
	v_mfma_f32_16x16x32_bf16 v[102:105], v[138:141], v[174:177], v[102:105]
	v_mfma_f32_16x16x32_bf16 v[98:101], v[154:157], v[174:177], v[98:101]
	v_mfma_f32_16x16x32_bf16 v[86:89], v[138:141], v[182:185], v[86:89]
	v_mfma_f32_16x16x32_bf16 v[82:85], v[154:157], v[182:185], v[82:85]
	v_mfma_f32_16x16x32_bf16 v[70:73], v[138:141], v[190:193], v[70:73]
	v_mfma_f32_16x16x32_bf16 v[66:69], v[154:157], v[190:193], v[66:69]
	s_setprio 0
	s_barrier
	s_add_i32 s45, s45, s19
	v_lshl_add_u64 v[198:199], s[22:23], 0, v[32:33]
	s_mov_b32 m0, s45
	ds_read_b128 v[158:161], v249 offset:16384
	ds_read_b128 v[162:165], v249 offset:17408
	ds_read_b128 v[170:173], v249 offset:18432
	ds_read_b128 v[174:177], v249 offset:19456
	ds_read_b128 v[178:181], v249 offset:20480
	ds_read_b128 v[182:185], v249 offset:21504
	ds_read_b128 v[186:189], v249 offset:22528
	ds_read_b128 v[190:193], v249 offset:23552
	global_load_lds_dwordx4 v[198:199], off
	s_add_i32 m0, s45, 0x2000
	s_add_u32 s46, s22, 0x80000
	v_lshl_add_u64 v[200:201], s[22:23], 0, v[202:203]
	s_addc_u32 s47, s23, 0
	s_add_i32 s45, s48, s19
	global_load_lds_dwordx4 v[200:201], off
	v_lshl_add_u64 v[212:213], s[46:47], 0, v[32:33]
	s_mov_b32 m0, s45
	v_lshl_add_u64 v[214:215], s[26:27], 0, v[204:205]
	global_load_lds_dwordx4 v[212:213], off
	v_lshl_add_u64 v[212:213], s[46:47], 0, v[202:203]
	s_add_i32 m0, s45, 0x2000
	s_nop 0
	global_load_lds_dwordx4 v[212:213], off
	v_lshl_add_u64 v[212:213], s[26:27], 0, v[206:207]
	s_mov_b32 m0, s20
	s_nop 0
	global_load_lds_dwordx4 v[212:213], off
	s_mov_b32 m0, s30
	s_nop 0
	global_load_lds_dwordx4 v[214:215], off
	s_waitcnt vmcnt(8)
	s_waitcnt lgkmcnt(0)
	s_barrier
	s_setprio 1
	s_waitcnt lgkmcnt(0)
	v_mfma_f32_16x16x32_bf16 v[62:65], v[106:109], v[158:161], v[62:65]
	v_mfma_f32_16x16x32_bf16 v[58:61], v[122:125], v[158:161], v[58:61]
	v_mfma_f32_16x16x32_bf16 v[46:49], v[106:109], v[170:173], v[46:49]
	v_mfma_f32_16x16x32_bf16 v[42:45], v[122:125], v[170:173], v[42:45]
	v_mfma_f32_16x16x32_bf16 v[28:31], v[106:109], v[178:181], v[28:31]
	v_mfma_f32_16x16x32_bf16 v[24:27], v[122:125], v[178:181], v[24:27]
	v_mfma_f32_16x16x32_bf16 v[12:15], v[106:109], v[186:189], v[12:15]
	v_mfma_f32_16x16x32_bf16 v[8:11], v[122:125], v[186:189], v[8:11]
	v_mfma_f32_16x16x32_bf16 v[62:65], v[110:113], v[162:165], v[62:65]
	v_mfma_f32_16x16x32_bf16 v[58:61], v[130:133], v[162:165], v[58:61]
	v_mfma_f32_16x16x32_bf16 v[46:49], v[110:113], v[174:177], v[46:49]
	v_mfma_f32_16x16x32_bf16 v[42:45], v[130:133], v[174:177], v[42:45]
	v_mfma_f32_16x16x32_bf16 v[28:31], v[110:113], v[182:185], v[28:31]
	v_mfma_f32_16x16x32_bf16 v[24:27], v[130:133], v[182:185], v[24:27]
	v_mfma_f32_16x16x32_bf16 v[12:15], v[110:113], v[190:193], v[12:15]
	v_mfma_f32_16x16x32_bf16 v[8:11], v[130:133], v[190:193], v[8:11]
	v_mfma_f32_16x16x32_bf16 v[54:57], v[134:137], v[158:161], v[54:57]
	v_mfma_f32_16x16x32_bf16 v[50:53], v[150:153], v[158:161], v[50:53]
	v_mfma_f32_16x16x32_bf16 v[38:41], v[134:137], v[170:173], v[38:41]
	v_mfma_f32_16x16x32_bf16 v[34:37], v[150:153], v[170:173], v[34:37]
	v_mfma_f32_16x16x32_bf16 v[20:23], v[134:137], v[178:181], v[20:23]
	v_mfma_f32_16x16x32_bf16 v[16:19], v[150:153], v[178:181], v[16:19]
	v_mfma_f32_16x16x32_bf16 v[4:7], v[134:137], v[186:189], v[4:7]
	v_mfma_f32_16x16x32_bf16 v[0:3], v[150:153], v[186:189], v[0:3]
	v_mfma_f32_16x16x32_bf16 v[54:57], v[138:141], v[162:165], v[54:57]
	v_mfma_f32_16x16x32_bf16 v[50:53], v[154:157], v[162:165], v[50:53]
	v_mfma_f32_16x16x32_bf16 v[38:41], v[138:141], v[174:177], v[38:41]
	v_mfma_f32_16x16x32_bf16 v[34:37], v[154:157], v[174:177], v[34:37]
	v_mfma_f32_16x16x32_bf16 v[20:23], v[138:141], v[182:185], v[20:23]
	v_mfma_f32_16x16x32_bf16 v[16:19], v[154:157], v[182:185], v[16:19]
	v_mfma_f32_16x16x32_bf16 v[4:7], v[138:141], v[190:193], v[4:7]
	v_mfma_f32_16x16x32_bf16 v[0:3], v[154:157], v[190:193], v[0:3]
	s_setprio 0
	s_barrier
; #define PG8_STAGE(bufoff, gbase, voff) do { _Pragma("unroll") for (int _i = 0; _i < 2; ++_i) \
;         __builtin_amdgcn_global_load_lds((const unsigned*)((const char*)(gbase) + (voff)[_i]), (PG8_LAS unsigned*)(lds + (bufoff) + ldsw + _i * 8192), 16, 0, 0); } while (0)
; #define PG8_LDA(dst, b, h) do { _Pragma("unroll") for (int m = 0; m < 4; ++m) _Pragma("unroll") for (int k = 0; k < 2; ++k) dst[m][k] = *(const PG8_LAS bf16x8*)(lds + PG8_SA(b, h) + aoff + m * 2048 + k * 1024); } while (0)
; #define PG8_LDB(dst, b, h) do { _Pragma("unroll") for (int n = 0; n < 2; ++n) _Pragma("unroll") for (int k = 0; k < 2; ++k) dst[n][k] = *(const PG8_LAS bf16x8*)(lds + PG8_SB(b, h) + boff + n * 2048 + k * 1024); } while (0)
; #define PG8_MMA(ai, bj, At, Bt) do { __builtin_amdgcn_s_setprio(1); _Pragma("unroll") for (int m = 0; m < 4; ++m) _Pragma("unroll") for (int n = 0; n < 2; ++n) _Pragma("unroll") for (int k = 0; k < 2; ++k) \
;         acc[ai][bj][m][n] = __builtin_amdgcn_mfma_f32_16x16x32_bf16(Bt[n][k], At[m][k], acc[ai][bj][m][n], 0, 0, 0); __builtin_amdgcn_s_setprio(0); } while (0)
; #define PG8_WAIT_V(n) asm volatile("s_waitcnt vmcnt(" #n ")" ::: "memory")
; #define PG8_WAIT_L(n) asm volatile("s_waitcnt lgkmcnt(" #n ")" ::: "memory")
; #define PG8_BAR __builtin_amdgcn_s_barrier()
; #define PG8_SCHED __builtin_amdgcn_sched_barrier(0)
; template <class Epi, class Sched, bool ALIGN_EPI = false, bool SP2 = false, bool KHOOK = false>
; __device__ __forceinline__ void gemm_phase(PG8_LAS unsigned char* lds, const Gemm g, const Sched& S, const Epi& E, const int tid_in) {
;     ...
;             PG8_LDB(B0, 1, 0); PG8_LDB(B1, 1, 1); PG8_SCHED; PG8_LDA(At, 1, 0); PG8_STAGE(PG8_SA(0, 1), a2 + hstep, voffA);
;             PG8_WAIT_V(8); PG8_WAIT_L(0); PG8_BAR; PG8_MMA(0, 0, At, B0); PG8_MMA(0, 1, At, B1); PG8_BAR; PG8_SCHED;
	s_add_i32 s45, 0, 0x18000
	s_add_i32 s46, 0, 0x1c000
	v_add_u32_e32 v130, s45, v247
	v_add_u32_e32 v154, s46, v247
	ds_read_b128 v[106:109], v130
	ds_read_b128 v[110:113], v130 offset:1024
	ds_read_b128 v[122:125], v130 offset:2048
	ds_read_b128 v[130:133], v130 offset:3072
	ds_read_b128 v[134:137], v154
	ds_read_b128 v[138:141], v154 offset:1024
	ds_read_b128 v[150:153], v154 offset:2048
	ds_read_b128 v[154:157], v154 offset:3072
	s_add_u32 s26, s26, 0x80000
	s_addc_u32 s27, s27, 0
	s_mov_b32 m0, s31
	v_lshl_add_u64 v[216:217], s[26:27], 0, v[206:207]
	ds_read_b128 v[158:161], v249 offset:32768
	ds_read_b128 v[162:165], v249 offset:33792
	ds_read_b128 v[170:173], v249 offset:34816
	ds_read_b128 v[174:177], v249 offset:35840
	ds_read_b128 v[178:181], v249 offset:36864
	ds_read_b128 v[182:185], v249 offset:37888
	ds_read_b128 v[186:189], v249 offset:38912
	ds_read_b128 v[190:193], v249 offset:39936
	global_load_lds_dwordx4 v[216:217], off
	v_lshl_add_u64 v[216:217], s[26:27], 0, v[204:205]
	s_mov_b32 m0, s33
	s_nop 0
	global_load_lds_dwordx4 v[216:217], off
	s_waitcnt vmcnt(8)
	s_waitcnt lgkmcnt(0)
	s_barrier
	s_setprio 1
	s_waitcnt lgkmcnt(0)
	v_mfma_f32_16x16x32_bf16 v[166:169], v[106:109], v[158:161], v[166:169]
	v_mfma_f32_16x16x32_bf16 v[146:149], v[122:125], v[158:161], v[146:149]
	v_mfma_f32_16x16x32_bf16 v[118:121], v[106:109], v[170:173], v[118:121]
	v_mfma_f32_16x16x32_bf16 v[114:117], v[122:125], v[170:173], v[114:117]
	v_mfma_f32_16x16x32_bf16 v[94:97], v[106:109], v[178:181], v[94:97]
	v_mfma_f32_16x16x32_bf16 v[90:93], v[122:125], v[178:181], v[90:93]
	v_mfma_f32_16x16x32_bf16 v[78:81], v[106:109], v[186:189], v[78:81]
	v_mfma_f32_16x16x32_bf16 v[74:77], v[122:125], v[186:189], v[74:77]
	v_mfma_f32_16x16x32_bf16 v[166:169], v[110:113], v[162:165], v[166:169]
	v_mfma_f32_16x16x32_bf16 v[146:149], v[130:133], v[162:165], v[146:149]
	v_mfma_f32_16x16x32_bf16 v[118:121], v[110:113], v[174:177], v[118:121]
	v_mfma_f32_16x16x32_bf16 v[114:117], v[130:133], v[174:177], v[114:117]
	v_mfma_f32_16x16x32_bf16 v[94:97], v[110:113], v[182:185], v[94:97]
	v_mfma_f32_16x16x32_bf16 v[90:93], v[130:133], v[182:185], v[90:93]
	v_mfma_f32_16x16x32_bf16 v[78:81], v[110:113], v[190:193], v[78:81]
	v_mfma_f32_16x16x32_bf16 v[74:77], v[130:133], v[190:193], v[74:77]
	v_mfma_f32_16x16x32_bf16 v[142:145], v[134:137], v[158:161], v[142:145]
	v_mfma_f32_16x16x32_bf16 v[126:129], v[150:153], v[158:161], v[126:129]
	v_mfma_f32_16x16x32_bf16 v[102:105], v[134:137], v[170:173], v[102:105]
	v_mfma_f32_16x16x32_bf16 v[98:101], v[150:153], v[170:173], v[98:101]
	v_mfma_f32_16x16x32_bf16 v[86:89], v[134:137], v[178:181], v[86:89]
	v_mfma_f32_16x16x32_bf16 v[82:85], v[150:153], v[178:181], v[82:85]
	v_mfma_f32_16x16x32_bf16 v[70:73], v[134:137], v[186:189], v[70:73]
	v_mfma_f32_16x16x32_bf16 v[66:69], v[150:153], v[186:189], v[66:69]
	v_mfma_f32_16x16x32_bf16 v[142:145], v[138:141], v[162:165], v[142:145]
	v_mfma_f32_16x16x32_bf16 v[126:129], v[154:157], v[162:165], v[126:129]
	v_mfma_f32_16x16x32_bf16 v[102:105], v[138:141], v[174:177], v[102:105]
	v_mfma_f32_16x16x32_bf16 v[98:101], v[154:157], v[174:177], v[98:101]
	v_mfma_f32_16x16x32_bf16 v[86:89], v[138:141], v[182:185], v[86:89]
	v_mfma_f32_16x16x32_bf16 v[82:85], v[154:157], v[182:185], v[82:85]
	v_mfma_f32_16x16x32_bf16 v[70:73], v[138:141], v[190:193], v[70:73]
	v_mfma_f32_16x16x32_bf16 v[66:69], v[154:157], v[190:193], v[66:69]
	s_setprio 0
	s_barrier
; #define PG8_STAGE(bufoff, gbase, voff) do { _Pragma("unroll") for (int _i = 0; _i < 2; ++_i) \
;         __builtin_amdgcn_global_load_lds((const unsigned*)((const char*)(gbase) + (voff)[_i]), (PG8_LAS unsigned*)(lds + (bufoff) + ldsw + _i * 8192), 16, 0, 0); } while (0)
; #define PG8_LDA(dst, b, h) do { _Pragma("unroll") for (int m = 0; m < 4; ++m) _Pragma("unroll") for (int k = 0; k < 2; ++k) dst[m][k] = *(const PG8_LAS bf16x8*)(lds + PG8_SA(b, h) + aoff + m * 2048 + k * 1024); } while (0)
; #define PG8_MMA(ai, bj, At, Bt) do { __builtin_amdgcn_s_setprio(1); _Pragma("unroll") for (int m = 0; m < 4; ++m) _Pragma("unroll") for (int n = 0; n < 2; ++n) _Pragma("unroll") for (int k = 0; k < 2; ++k) \
;         acc[ai][bj][m][n] = __builtin_amdgcn_mfma_f32_16x16x32_bf16(Bt[n][k], At[m][k], acc[ai][bj][m][n], 0, 0, 0); __builtin_amdgcn_s_setprio(0); } while (0)
; #define PG8_WAIT_V(n) asm volatile("s_waitcnt vmcnt(" #n ")" ::: "memory")
; #define PG8_WAIT_L(n) asm volatile("s_waitcnt lgkmcnt(" #n ")" ::: "memory")
; #define PG8_BAR __builtin_amdgcn_s_barrier()
; #define PG8_SCHED __builtin_amdgcn_sched_barrier(0)
; template <class Epi, class Sched, bool ALIGN_EPI = false, bool SP2 = false, bool KHOOK = false>
; __device__ __forceinline__ void gemm_phase(PG8_LAS unsigned char* lds, const Gemm g, const Sched& S, const Epi& E, const int tid_in) {
;     ...
;             PG8_LDA(At, 1, 1); PG8_STAGE(PG8_SB(1, 0), b3, voffB); PG8_STAGE(PG8_SB(1, 1), b3 + hstep, voffB); PG8_STAGE(PG8_SA(1, 0), a3, voffA);
;             PG8_WAIT_V(8); PG8_WAIT_L(0); PG8_BAR; PG8_MMA(1, 0, At, B0); PG8_MMA(1, 1, At, B1); PG8_BAR; PG8_SCHED;
;     ...
;         if constexpr (ALIGN_EPI) { if (wr == 0) PG8_BAR; }
	s_add_i32 s26, s45, s19
	v_lshl_add_u64 v[198:199], v[198:199], 0, s[90:91]
	s_mov_b32 m0, s26
	ds_read_b128 v[158:161], v249 offset:49152
	ds_read_b128 v[162:165], v249 offset:50176
	ds_read_b128 v[170:173], v249 offset:51200
	ds_read_b128 v[174:177], v249 offset:52224
	ds_read_b128 v[178:181], v249 offset:53248
	ds_read_b128 v[182:185], v249 offset:54272
	ds_read_b128 v[186:189], v249 offset:55296
	ds_read_b128 v[190:193], v249 offset:56320
	global_load_lds_dwordx4 v[198:199], off
	s_add_i32 m0, s26, 0x2000
	s_add_u32 s22, s22, 0x80080
	v_lshl_add_u64 v[198:199], v[200:201], 0, s[90:91]
	s_addc_u32 s23, s23, 0
	s_add_i32 s26, s46, s19
	global_load_lds_dwordx4 v[198:199], off
	v_lshl_add_u64 v[198:199], s[22:23], 0, v[32:33]
	s_mov_b32 m0, s26
	s_nop 0
	global_load_lds_dwordx4 v[198:199], off
	v_lshl_add_u64 v[198:199], s[22:23], 0, v[202:203]
	s_add_i32 m0, s26, 0x2000
	s_nop 0
	global_load_lds_dwordx4 v[198:199], off
	v_lshl_add_u64 v[198:199], v[212:213], 0, s[90:91]
	s_mov_b32 m0, s36
	s_nop 0
	global_load_lds_dwordx4 v[198:199], off
	v_lshl_add_u64 v[198:199], v[214:215], 0, s[90:91]
	s_mov_b32 m0, s37
	s_nop 0
	global_load_lds_dwordx4 v[198:199], off
	s_waitcnt vmcnt(8)
	s_waitcnt lgkmcnt(0)
	s_barrier
	s_setprio 1
	s_waitcnt lgkmcnt(0)
	v_mfma_f32_16x16x32_bf16 v[62:65], v[106:109], v[158:161], v[62:65]
	v_mfma_f32_16x16x32_bf16 v[58:61], v[122:125], v[158:161], v[58:61]
	v_mfma_f32_16x16x32_bf16 v[46:49], v[106:109], v[170:173], v[46:49]
	v_mfma_f32_16x16x32_bf16 v[42:45], v[122:125], v[170:173], v[42:45]
	v_mfma_f32_16x16x32_bf16 v[28:31], v[106:109], v[178:181], v[28:31]
	v_mfma_f32_16x16x32_bf16 v[24:27], v[122:125], v[178:181], v[24:27]
	v_mfma_f32_16x16x32_bf16 v[12:15], v[106:109], v[186:189], v[12:15]
	v_mfma_f32_16x16x32_bf16 v[8:11], v[122:125], v[186:189], v[8:11]
	v_mfma_f32_16x16x32_bf16 v[62:65], v[110:113], v[162:165], v[62:65]
	v_mfma_f32_16x16x32_bf16 v[58:61], v[130:133], v[162:165], v[58:61]
	v_mfma_f32_16x16x32_bf16 v[46:49], v[110:113], v[174:177], v[46:49]
	v_mfma_f32_16x16x32_bf16 v[42:45], v[130:133], v[174:177], v[42:45]
	v_mfma_f32_16x16x32_bf16 v[28:31], v[110:113], v[182:185], v[28:31]
	v_mfma_f32_16x16x32_bf16 v[24:27], v[130:133], v[182:185], v[24:27]
	v_mfma_f32_16x16x32_bf16 v[12:15], v[110:113], v[190:193], v[12:15]
	v_mfma_f32_16x16x32_bf16 v[8:11], v[130:133], v[190:193], v[8:11]
	v_mfma_f32_16x16x32_bf16 v[54:57], v[134:137], v[158:161], v[54:57]
	v_mfma_f32_16x16x32_bf16 v[50:53], v[150:153], v[158:161], v[50:53]
	v_mfma_f32_16x16x32_bf16 v[38:41], v[134:137], v[170:173], v[38:41]
	v_mfma_f32_16x16x32_bf16 v[34:37], v[150:153], v[170:173], v[34:37]
	v_mfma_f32_16x16x32_bf16 v[20:23], v[134:137], v[178:181], v[20:23]
	v_mfma_f32_16x16x32_bf16 v[16:19], v[150:153], v[178:181], v[16:19]
	v_mfma_f32_16x16x32_bf16 v[4:7], v[134:137], v[186:189], v[4:7]
	v_mfma_f32_16x16x32_bf16 v[0:3], v[150:153], v[186:189], v[0:3]
	v_mfma_f32_16x16x32_bf16 v[54:57], v[138:141], v[162:165], v[54:57]
	v_mfma_f32_16x16x32_bf16 v[50:53], v[154:157], v[162:165], v[50:53]
	v_mfma_f32_16x16x32_bf16 v[38:41], v[138:141], v[174:177], v[38:41]
	v_mfma_f32_16x16x32_bf16 v[34:37], v[154:157], v[174:177], v[34:37]
	v_mfma_f32_16x16x32_bf16 v[20:23], v[138:141], v[182:185], v[20:23]
	v_mfma_f32_16x16x32_bf16 v[16:19], v[154:157], v[182:185], v[16:19]
	v_mfma_f32_16x16x32_bf16 v[4:7], v[138:141], v[190:193], v[4:7]
	v_mfma_f32_16x16x32_bf16 v[0:3], v[154:157], v[190:193], v[0:3]
	s_setprio 0
	s_barrier
	s_add_i32 s44, s44, 2
	s_add_u32 s16, s16, 0x100
	s_addc_u32 s17, s17, 0
	s_add_u32 s41, s41, 0x100
	s_addc_u32 s42, s42, 0
	s_cmp_gt_u32 s44, 29
	s_cbranch_scc0 .LBB0_867
	s_and_b64 vcc, exec, s[4:5]
	s_cbranch_vccz .LBB0_870
	s_barrier

; #define PG8_STAGE(bufoff, gbase, voff) do { _Pragma("unroll") for (int _i = 0; _i < 2; ++_i) \
;         __builtin_amdgcn_global_load_lds((const unsigned*)((const char*)(gbase) + (voff)[_i]), (PG8_LAS unsigned*)(lds + (bufoff) + ldsw + _i * 8192), 16, 0, 0); } while (0)
; #define PG8_LDA(dst, b, h) do { _Pragma("unroll") for (int m = 0; m < 4; ++m) _Pragma("unroll") for (int k = 0; k < 2; ++k) dst[m][k] = *(const PG8_LAS bf16x8*)(lds + PG8_SA(b, h) + aoff + m * 2048 + k * 1024); } while (0)
; #define PG8_LDB(dst, b, h) do { _Pragma("unroll") for (int n = 0; n < 2; ++n) _Pragma("unroll") for (int k = 0; k < 2; ++k) dst[n][k] = *(const PG8_LAS bf16x8*)(lds + PG8_SB(b, h) + boff + n * 2048 + k * 1024); } while (0)
; #define PG8_MMA(ai, bj, At, Bt) do { __builtin_amdgcn_s_setprio(1); _Pragma("unroll") for (int m = 0; m < 4; ++m) _Pragma("unroll") for (int n = 0; n < 2; ++n) _Pragma("unroll") for (int k = 0; k < 2; ++k) \
;         acc[ai][bj][m][n] = __builtin_amdgcn_mfma_f32_16x16x32_bf16(Bt[n][k], At[m][k], acc[ai][bj][m][n], 0, 0, 0); __builtin_amdgcn_s_setprio(0); } while (0)
; #define PG8_WAIT_V(n) asm volatile("s_waitcnt vmcnt(" #n ")" ::: "memory")
; #define PG8_WAIT_L(n) asm volatile("s_waitcnt lgkmcnt(" #n ")" ::: "memory")
; #define PG8_BAR __builtin_amdgcn_s_barrier()
; #define PG8_SCHED __builtin_amdgcn_sched_barrier(0)
; template <class Epi, class Sched, bool ALIGN_EPI = false, bool SP2 = false, bool KHOOK = false>
; __device__ __forceinline__ void gemm_phase(PG8_LAS unsigned char* lds, const Gemm g, const Sched& S, const Epi& E, const int tid_in) {
;     ...
;             const bool last = (t == nt - 2);
;             const char* a1 = cA + (size_t)(t + 1) * kstep;
;             const char* a2 = last ? nA : cA + (size_t)(t + 2) * kstep; const char* b2 = last ? nB : cB + (size_t)(t + 2) * kstep;
;             const char* a3 = a2 + kstep; const char* b3 = b2 + kstep;
;             if (last && has_next) S.a_ready(nxt);
;             if constexpr (SP2) {
;             PG8_LDB(B0, 0, 0); PG8_LDB(B1, 0, 1); PG8_SCHED; PG8_LDA(At, 0, 0); PG8_STAGE(PG8_SA(1, 1), a1 + hstep, voffA);
;             PG8_WAIT_V(8); PG8_WAIT_L(0); PG8_BAR; PG8_MMA(0, 0, At, B0); PG8_MMA(0, 1, At, B1); PG8_BAR; PG8_SCHED;
;             PG8_LDA(At, 0, 1); PG8_STAGE(PG8_SB(0, 0), b2, voffB); PG8_STAGE(PG8_SB(0, 1), b2 + hstep, voffB); PG8_STAGE(PG8_SA(0, 0), a2, voffA);
.LBB0_948:
	s_add_u32 s48, s4, s22
	s_addc_u32 s49, s5, s23
	s_add_u32 s48, s48, 0x100
	s_addc_u32 s49, s49, 0
	s_add_u32 s57, s18, s22
	s_addc_u32 s58, s19, s23
	s_add_i32 s59, 0, 0x10000
	s_cmpk_eq_i32 s22, 0xf00
	s_cselect_b32 s53, s13, s49
	s_cselect_b32 s52, s25, s48
	s_cselect_b32 s49, s11, s58
	s_cselect_b32 s48, s51, s57
	s_add_i32 s57, 0, 0x14000
	v_add_u32_e32 v158, s59, v144
	v_add_u32_e32 v170, s57, v144
	ds_read_b128 v[146:149], v158
	ds_read_b128 v[150:153], v158 offset:1024
	ds_read_b128 v[154:157], v158 offset:2048
	ds_read_b128 v[158:161], v158 offset:3072
	ds_read_b128 v[162:165], v170
	ds_read_b128 v[166:169], v170 offset:1024
	ds_read_b128 v[176:179], v170 offset:2048
	ds_read_b128 v[180:183], v170 offset:3072
	v_lshl_add_u64 v[170:171], v[140:141], 0, s[22:23]
	s_add_i32 m0, s40, 0xc000
	ds_read_b128 v[184:187], v145
	ds_read_b128 v[188:191], v145 offset:1024
	ds_read_b128 v[198:201], v145 offset:2048
	ds_read_b128 v[202:205], v145 offset:3072
	ds_read_b128 v[206:209], v145 offset:4096
	ds_read_b128 v[210:213], v145 offset:5120
	ds_read_b128 v[214:217], v145 offset:6144
	ds_read_b128 v[218:221], v145 offset:7168
	global_load_lds_dwordx4 v[170:171], off
	v_lshl_add_u64 v[170:171], v[142:143], 0, s[22:23]
	s_add_i32 m0, s40, 0xe000
	s_nop 0
	global_load_lds_dwordx4 v[170:171], off
	s_waitcnt vmcnt(8)
	s_waitcnt lgkmcnt(0)
	s_barrier
	s_setprio 1
	s_waitcnt lgkmcnt(0)
	v_mfma_f32_16x16x32_bf16 v[118:121], v[146:149], v[184:187], v[118:121]
	v_mfma_f32_16x16x32_bf16 v[114:117], v[154:157], v[184:187], v[114:117]
	v_mfma_f32_16x16x32_bf16 v[134:137], v[146:149], v[198:201], v[134:137]
	v_mfma_f32_16x16x32_bf16 v[130:133], v[154:157], v[198:201], v[130:133]
	v_mfma_f32_16x16x32_bf16 v[94:97], v[146:149], v[206:209], v[94:97]
	v_mfma_f32_16x16x32_bf16 v[90:93], v[154:157], v[206:209], v[90:93]
	v_mfma_f32_16x16x32_bf16 v[78:81], v[146:149], v[214:217], v[78:81]
	v_mfma_f32_16x16x32_bf16 v[74:77], v[154:157], v[214:217], v[74:77]
	v_mfma_f32_16x16x32_bf16 v[118:121], v[150:153], v[188:191], v[118:121]
	v_mfma_f32_16x16x32_bf16 v[114:117], v[158:161], v[188:191], v[114:117]
	v_mfma_f32_16x16x32_bf16 v[134:137], v[150:153], v[202:205], v[134:137]
	v_mfma_f32_16x16x32_bf16 v[130:133], v[158:161], v[202:205], v[130:133]
	v_mfma_f32_16x16x32_bf16 v[94:97], v[150:153], v[210:213], v[94:97]
	v_mfma_f32_16x16x32_bf16 v[90:93], v[158:161], v[210:213], v[90:93]
	v_mfma_f32_16x16x32_bf16 v[78:81], v[150:153], v[218:221], v[78:81]
	v_mfma_f32_16x16x32_bf16 v[74:77], v[158:161], v[218:221], v[74:77]
	v_mfma_f32_16x16x32_bf16 v[106:109], v[162:165], v[184:187], v[106:109]
	v_mfma_f32_16x16x32_bf16 v[102:105], v[176:179], v[184:187], v[102:105]
	v_mfma_f32_16x16x32_bf16 v[110:113], v[162:165], v[198:201], v[110:113]
	v_mfma_f32_16x16x32_bf16 v[98:101], v[176:179], v[198:201], v[98:101]
	v_mfma_f32_16x16x32_bf16 v[86:89], v[162:165], v[206:209], v[86:89]
	v_mfma_f32_16x16x32_bf16 v[82:85], v[176:179], v[206:209], v[82:85]
	v_mfma_f32_16x16x32_bf16 v[70:73], v[162:165], v[214:217], v[70:73]
	v_mfma_f32_16x16x32_bf16 v[66:69], v[176:179], v[214:217], v[66:69]
	v_mfma_f32_16x16x32_bf16 v[106:109], v[166:169], v[188:191], v[106:109]
	v_mfma_f32_16x16x32_bf16 v[102:105], v[180:183], v[188:191], v[102:105]
	v_mfma_f32_16x16x32_bf16 v[110:113], v[166:169], v[202:205], v[110:113]
	v_mfma_f32_16x16x32_bf16 v[98:101], v[180:183], v[202:205], v[98:101]
	v_mfma_f32_16x16x32_bf16 v[86:89], v[166:169], v[210:213], v[86:89]
	v_mfma_f32_16x16x32_bf16 v[82:85], v[180:183], v[210:213], v[82:85]
	v_mfma_f32_16x16x32_bf16 v[70:73], v[166:169], v[218:221], v[70:73]
	v_mfma_f32_16x16x32_bf16 v[66:69], v[180:183], v[218:221], v[66:69]
	s_setprio 0
	s_barrier
	s_add_i32 s58, s59, s39
	v_lshl_add_u64 v[170:171], s[48:49], 0, v[32:33]
	s_mov_b32 m0, s58
	ds_read_b128 v[184:187], v145 offset:16384
	ds_read_b128 v[188:191], v145 offset:17408
	ds_read_b128 v[198:201], v145 offset:18432
	ds_read_b128 v[202:205], v145 offset:19456
	ds_read_b128 v[206:209], v145 offset:20480
	ds_read_b128 v[210:213], v145 offset:21504
	ds_read_b128 v[214:217], v145 offset:22528
	ds_read_b128 v[218:221], v145 offset:23552
	global_load_lds_dwordx4 v[170:171], off
	s_add_i32 m0, s58, 0x2000
	s_add_u32 s58, s48, 0x80000
	v_lshl_add_u64 v[192:193], s[48:49], 0, v[122:123]
	s_addc_u32 s59, s49, 0
	s_add_i32 s57, s57, s39
	global_load_lds_dwordx4 v[192:193], off
	v_lshl_add_u64 v[222:223], s[58:59], 0, v[32:33]
	s_mov_b32 m0, s57
	v_lshl_add_u64 v[224:225], s[52:53], 0, v[124:125]
	global_load_lds_dwordx4 v[222:223], off
	v_lshl_add_u64 v[222:223], s[58:59], 0, v[122:123]
	s_add_i32 m0, s57, 0x2000
	s_nop 0
	global_load_lds_dwordx4 v[222:223], off
	v_lshl_add_u64 v[222:223], s[52:53], 0, v[126:127]
	s_mov_b32 m0, s40
	s_nop 0
	global_load_lds_dwordx4 v[222:223], off
	s_mov_b32 m0, s41
	s_nop 0
	global_load_lds_dwordx4 v[224:225], off
	s_waitcnt vmcnt(8)
	s_waitcnt lgkmcnt(0)
	s_barrier
; #define PG8_STAGE(bufoff, gbase, voff) do { _Pragma("unroll") for (int _i = 0; _i < 2; ++_i) \
;         __builtin_amdgcn_global_load_lds((const unsigned*)((const char*)(gbase) + (voff)[_i]), (PG8_LAS unsigned*)(lds + (bufoff) + ldsw + _i * 8192), 16, 0, 0); } while (0)
; #define PG8_LDA(dst, b, h) do { _Pragma("unroll") for (int m = 0; m < 4; ++m) _Pragma("unroll") for (int k = 0; k < 2; ++k) dst[m][k] = *(const PG8_LAS bf16x8*)(lds + PG8_SA(b, h) + aoff + m * 2048 + k * 1024); } while (0)
; #define PG8_LDB(dst, b, h) do { _Pragma("unroll") for (int n = 0; n < 2; ++n) _Pragma("unroll") for (int k = 0; k < 2; ++k) dst[n][k] = *(const PG8_LAS bf16x8*)(lds + PG8_SB(b, h) + boff + n * 2048 + k * 1024); } while (0)
; #define PG8_MMA(ai, bj, At, Bt) do { __builtin_amdgcn_s_setprio(1); _Pragma("unroll") for (int m = 0; m < 4; ++m) _Pragma("unroll") for (int n = 0; n < 2; ++n) _Pragma("unroll") for (int k = 0; k < 2; ++k) \
;         acc[ai][bj][m][n] = __builtin_amdgcn_mfma_f32_16x16x32_bf16(Bt[n][k], At[m][k], acc[ai][bj][m][n], 0, 0, 0); __builtin_amdgcn_s_setprio(0); } while (0)
; #define PG8_WAIT_V(n) asm volatile("s_waitcnt vmcnt(" #n ")" ::: "memory")
; #define PG8_WAIT_L(n) asm volatile("s_waitcnt lgkmcnt(" #n ")" ::: "memory")
; #define PG8_BAR __builtin_amdgcn_s_barrier()
; #define PG8_SCHED __builtin_amdgcn_sched_barrier(0)
; template <class Epi, class Sched, bool ALIGN_EPI = false, bool SP2 = false, bool KHOOK = false>
; __device__ __forceinline__ void gemm_phase(PG8_LAS unsigned char* lds, const Gemm g, const Sched& S, const Epi& E, const int tid_in) {
;     ...
;             PG8_WAIT_V(8); PG8_WAIT_L(0); PG8_BAR; PG8_MMA(1, 0, At, B0); PG8_MMA(1, 1, At, B1); PG8_BAR; PG8_SCHED;
;             PG8_LDB(B0, 1, 0); PG8_LDB(B1, 1, 1); PG8_SCHED; PG8_LDA(At, 1, 0); PG8_STAGE(PG8_SA(0, 1), a2 + hstep, voffA);
;             PG8_WAIT_V(8); PG8_WAIT_L(0); PG8_BAR; PG8_MMA(0, 0, At, B0); PG8_MMA(0, 1, At, B1); PG8_BAR; PG8_SCHED;
	s_setprio 1
	s_waitcnt lgkmcnt(0)
	v_mfma_f32_16x16x32_bf16 v[62:65], v[146:149], v[184:187], v[62:65]
	v_mfma_f32_16x16x32_bf16 v[58:61], v[154:157], v[184:187], v[58:61]
	v_mfma_f32_16x16x32_bf16 v[46:49], v[146:149], v[198:201], v[46:49]
	v_mfma_f32_16x16x32_bf16 v[42:45], v[154:157], v[198:201], v[42:45]
	v_mfma_f32_16x16x32_bf16 v[28:31], v[146:149], v[206:209], v[28:31]
	v_mfma_f32_16x16x32_bf16 v[24:27], v[154:157], v[206:209], v[24:27]
	v_mfma_f32_16x16x32_bf16 v[12:15], v[146:149], v[214:217], v[12:15]
	v_mfma_f32_16x16x32_bf16 v[8:11], v[154:157], v[214:217], v[8:11]
	v_mfma_f32_16x16x32_bf16 v[62:65], v[150:153], v[188:191], v[62:65]
	v_mfma_f32_16x16x32_bf16 v[58:61], v[158:161], v[188:191], v[58:61]
	v_mfma_f32_16x16x32_bf16 v[46:49], v[150:153], v[202:205], v[46:49]
	v_mfma_f32_16x16x32_bf16 v[42:45], v[158:161], v[202:205], v[42:45]
	v_mfma_f32_16x16x32_bf16 v[28:31], v[150:153], v[210:213], v[28:31]
	v_mfma_f32_16x16x32_bf16 v[24:27], v[158:161], v[210:213], v[24:27]
	v_mfma_f32_16x16x32_bf16 v[12:15], v[150:153], v[218:221], v[12:15]
	v_mfma_f32_16x16x32_bf16 v[8:11], v[158:161], v[218:221], v[8:11]
	v_mfma_f32_16x16x32_bf16 v[54:57], v[162:165], v[184:187], v[54:57]
	v_mfma_f32_16x16x32_bf16 v[50:53], v[176:179], v[184:187], v[50:53]
	v_mfma_f32_16x16x32_bf16 v[38:41], v[162:165], v[198:201], v[38:41]
	v_mfma_f32_16x16x32_bf16 v[34:37], v[176:179], v[198:201], v[34:37]
	v_mfma_f32_16x16x32_bf16 v[20:23], v[162:165], v[206:209], v[20:23]
	v_mfma_f32_16x16x32_bf16 v[16:19], v[176:179], v[206:209], v[16:19]
	v_mfma_f32_16x16x32_bf16 v[4:7], v[162:165], v[214:217], v[4:7]
	v_mfma_f32_16x16x32_bf16 v[0:3], v[176:179], v[214:217], v[0:3]
	v_mfma_f32_16x16x32_bf16 v[54:57], v[166:169], v[188:191], v[54:57]
	v_mfma_f32_16x16x32_bf16 v[50:53], v[180:183], v[188:191], v[50:53]
	v_mfma_f32_16x16x32_bf16 v[38:41], v[166:169], v[202:205], v[38:41]
	v_mfma_f32_16x16x32_bf16 v[34:37], v[180:183], v[202:205], v[34:37]
	v_mfma_f32_16x16x32_bf16 v[20:23], v[166:169], v[210:213], v[20:23]
	v_mfma_f32_16x16x32_bf16 v[16:19], v[180:183], v[210:213], v[16:19]
	v_mfma_f32_16x16x32_bf16 v[4:7], v[166:169], v[218:221], v[4:7]
	v_mfma_f32_16x16x32_bf16 v[0:3], v[180:183], v[218:221], v[0:3]
	s_setprio 0
	s_barrier
	s_add_i32 s57, 0, 0x18000
	s_add_i32 s58, 0, 0x1c000
	v_add_u32_e32 v158, s57, v144
	v_add_u32_e32 v175, s58, v144
	ds_read_b128 v[146:149], v158
	ds_read_b128 v[150:153], v158 offset:1024
	ds_read_b128 v[154:157], v158 offset:2048
	ds_read_b128 v[158:161], v158 offset:3072
	ds_read_b128 v[162:165], v175
	ds_read_b128 v[166:169], v175 offset:1024
	ds_read_b128 v[176:179], v175 offset:2048
	ds_read_b128 v[180:183], v175 offset:3072
	s_add_u32 s52, s52, 0x80000
	s_addc_u32 s53, s53, 0
	s_mov_b32 m0, s42
	v_lshl_add_u64 v[226:227], s[52:53], 0, v[126:127]
	ds_read_b128 v[184:187], v145 offset:32768
	ds_read_b128 v[188:191], v145 offset:33792
	ds_read_b128 v[198:201], v145 offset:34816
	ds_read_b128 v[202:205], v145 offset:35840
	ds_read_b128 v[206:209], v145 offset:36864
	ds_read_b128 v[210:213], v145 offset:37888
	ds_read_b128 v[214:217], v145 offset:38912
	ds_read_b128 v[218:221], v145 offset:39936
	global_load_lds_dwordx4 v[226:227], off
	v_lshl_add_u64 v[226:227], s[52:53], 0, v[124:125]
	s_mov_b32 m0, s44
	s_nop 0
	global_load_lds_dwordx4 v[226:227], off
	s_waitcnt vmcnt(8)
	s_waitcnt lgkmcnt(0)
	s_barrier
	s_setprio 1
	s_waitcnt lgkmcnt(0)
	v_mfma_f32_16x16x32_bf16 v[118:121], v[146:149], v[184:187], v[118:121]
	v_mfma_f32_16x16x32_bf16 v[114:117], v[154:157], v[184:187], v[114:117]
	v_mfma_f32_16x16x32_bf16 v[134:137], v[146:149], v[198:201], v[134:137]
	v_mfma_f32_16x16x32_bf16 v[130:133], v[154:157], v[198:201], v[130:133]
	v_mfma_f32_16x16x32_bf16 v[94:97], v[146:149], v[206:209], v[94:97]
	v_mfma_f32_16x16x32_bf16 v[90:93], v[154:157], v[206:209], v[90:93]
	v_mfma_f32_16x16x32_bf16 v[78:81], v[146:149], v[214:217], v[78:81]
	v_mfma_f32_16x16x32_bf16 v[74:77], v[154:157], v[214:217], v[74:77]
	v_mfma_f32_16x16x32_bf16 v[118:121], v[150:153], v[188:191], v[118:121]
	v_mfma_f32_16x16x32_bf16 v[114:117], v[158:161], v[188:191], v[114:117]
	v_mfma_f32_16x16x32_bf16 v[134:137], v[150:153], v[202:205], v[134:137]
	v_mfma_f32_16x16x32_bf16 v[130:133], v[158:161], v[202:205], v[130:133]
	v_mfma_f32_16x16x32_bf16 v[94:97], v[150:153], v[210:213], v[94:97]
	v_mfma_f32_16x16x32_bf16 v[90:93], v[158:161], v[210:213], v[90:93]
	v_mfma_f32_16x16x32_bf16 v[78:81], v[150:153], v[218:221], v[78:81]
	v_mfma_f32_16x16x32_bf16 v[74:77], v[158:161], v[218:221], v[74:77]
	v_mfma_f32_16x16x32_bf16 v[106:109], v[162:165], v[184:187], v[106:109]
	v_mfma_f32_16x16x32_bf16 v[102:105], v[176:179], v[184:187], v[102:105]
	v_mfma_f32_16x16x32_bf16 v[110:113], v[162:165], v[198:201], v[110:113]
	v_mfma_f32_16x16x32_bf16 v[98:101], v[176:179], v[198:201], v[98:101]
	v_mfma_f32_16x16x32_bf16 v[86:89], v[162:165], v[206:209], v[86:89]
	v_mfma_f32_16x16x32_bf16 v[82:85], v[176:179], v[206:209], v[82:85]
	v_mfma_f32_16x16x32_bf16 v[70:73], v[162:165], v[214:217], v[70:73]
	v_mfma_f32_16x16x32_bf16 v[66:69], v[176:179], v[214:217], v[66:69]
	v_mfma_f32_16x16x32_bf16 v[106:109], v[166:169], v[188:191], v[106:109]
	v_mfma_f32_16x16x32_bf16 v[102:105], v[180:183], v[188:191], v[102:105]
	v_mfma_f32_16x16x32_bf16 v[110:113], v[166:169], v[202:205], v[110:113]
	v_mfma_f32_16x16x32_bf16 v[98:101], v[180:183], v[202:205], v[98:101]
	v_mfma_f32_16x16x32_bf16 v[86:89], v[166:169], v[210:213], v[86:89]
	v_mfma_f32_16x16x32_bf16 v[82:85], v[180:183], v[210:213], v[82:85]
	v_mfma_f32_16x16x32_bf16 v[70:73], v[166:169], v[218:221], v[70:73]
	v_mfma_f32_16x16x32_bf16 v[66:69], v[180:183], v[218:221], v[66:69]
	s_setprio 0
	s_barrier
; #define PG8_STAGE(bufoff, gbase, voff) do { _Pragma("unroll") for (int _i = 0; _i < 2; ++_i) \
;         __builtin_amdgcn_global_load_lds((const unsigned*)((const char*)(gbase) + (voff)[_i]), (PG8_LAS unsigned*)(lds + (bufoff) + ldsw + _i * 8192), 16, 0, 0); } while (0)
; #define PG8_LDA(dst, b, h) do { _Pragma("unroll") for (int m = 0; m < 4; ++m) _Pragma("unroll") for (int k = 0; k < 2; ++k) dst[m][k] = *(const PG8_LAS bf16x8*)(lds + PG8_SA(b, h) + aoff + m * 2048 + k * 1024); } while (0)
; #define PG8_MMA(ai, bj, At, Bt) do { __builtin_amdgcn_s_setprio(1); _Pragma("unroll") for (int m = 0; m < 4; ++m) _Pragma("unroll") for (int n = 0; n < 2; ++n) _Pragma("unroll") for (int k = 0; k < 2; ++k) \
;         acc[ai][bj][m][n] = __builtin_amdgcn_mfma_f32_16x16x32_bf16(Bt[n][k], At[m][k], acc[ai][bj][m][n], 0, 0, 0); __builtin_amdgcn_s_setprio(0); } while (0)
; #define PG8_WAIT_V(n) asm volatile("s_waitcnt vmcnt(" #n ")" ::: "memory")
; #define PG8_WAIT_L(n) asm volatile("s_waitcnt lgkmcnt(" #n ")" ::: "memory")
; #define PG8_BAR __builtin_amdgcn_s_barrier()
; #define PG8_SCHED __builtin_amdgcn_sched_barrier(0)
; template <class Epi, class Sched, bool ALIGN_EPI = false, bool SP2 = false, bool KHOOK = false>
; __device__ __forceinline__ void gemm_phase(PG8_LAS unsigned char* lds, const Gemm g, const Sched& S, const Epi& E, const int tid_in) {
;     ...
;             PG8_LDA(At, 1, 1); PG8_STAGE(PG8_SB(1, 0), b3, voffB); PG8_STAGE(PG8_SB(1, 1), b3 + hstep, voffB); PG8_STAGE(PG8_SA(1, 0), a3, voffA);
;             PG8_WAIT_V(8); PG8_WAIT_L(0); PG8_BAR; PG8_MMA(1, 0, At, B0); PG8_MMA(1, 1, At, B1); PG8_BAR; PG8_SCHED;
;     ...
;         if (!has_next) break;
; #pragma unroll
;         for (int a = 0; a < 2; ++a)
; #pragma unroll
;             for (int b = 0; b < 2; ++b)
; #pragma unroll
;                 for (int m = 0; m < 4; ++m)
; #pragma unroll
;                     for (int n = 0; n < 2; ++n) acc[a][b][m][n] = (f32x4){0.f, 0.f, 0.f, 0.f};
	s_add_i32 s52, s57, s39
	v_lshl_add_u64 v[170:171], v[170:171], 0, s[90:91]
	s_mov_b32 m0, s52
	ds_read_b128 v[184:187], v145 offset:49152
	ds_read_b128 v[188:191], v145 offset:50176
	ds_read_b128 v[198:201], v145 offset:51200
	ds_read_b128 v[202:205], v145 offset:52224
	ds_read_b128 v[206:209], v145 offset:53248
	ds_read_b128 v[210:213], v145 offset:54272
	ds_read_b128 v[214:217], v145 offset:55296
	ds_read_b128 v[218:221], v145 offset:56320
	global_load_lds_dwordx4 v[170:171], off
	s_add_i32 m0, s52, 0x2000
	s_add_u32 s48, s48, 0x80080
	v_lshl_add_u64 v[170:171], v[192:193], 0, s[90:91]
	s_addc_u32 s49, s49, 0
	s_add_i32 s52, s58, s39
	global_load_lds_dwordx4 v[170:171], off
	v_lshl_add_u64 v[170:171], s[48:49], 0, v[32:33]
	s_mov_b32 m0, s52
	s_nop 0
	global_load_lds_dwordx4 v[170:171], off
	v_lshl_add_u64 v[170:171], s[48:49], 0, v[122:123]
	s_add_i32 m0, s52, 0x2000
	s_nop 0
	global_load_lds_dwordx4 v[170:171], off
	v_lshl_add_u64 v[170:171], v[222:223], 0, s[90:91]
	s_mov_b32 m0, s46
	s_nop 0
	global_load_lds_dwordx4 v[170:171], off
	v_lshl_add_u64 v[170:171], v[224:225], 0, s[90:91]
	s_mov_b32 m0, s47
	s_nop 0
	global_load_lds_dwordx4 v[170:171], off
	s_waitcnt vmcnt(8)
	s_waitcnt lgkmcnt(0)
	s_barrier
	s_setprio 1
	s_waitcnt lgkmcnt(0)
	v_mfma_f32_16x16x32_bf16 v[62:65], v[146:149], v[184:187], v[62:65]
	v_mfma_f32_16x16x32_bf16 v[58:61], v[154:157], v[184:187], v[58:61]
	v_mfma_f32_16x16x32_bf16 v[46:49], v[146:149], v[198:201], v[46:49]
	v_mfma_f32_16x16x32_bf16 v[42:45], v[154:157], v[198:201], v[42:45]
	v_mfma_f32_16x16x32_bf16 v[28:31], v[146:149], v[206:209], v[28:31]
	v_mfma_f32_16x16x32_bf16 v[24:27], v[154:157], v[206:209], v[24:27]
	v_mfma_f32_16x16x32_bf16 v[12:15], v[146:149], v[214:217], v[12:15]
	v_mfma_f32_16x16x32_bf16 v[8:11], v[154:157], v[214:217], v[8:11]
	v_mfma_f32_16x16x32_bf16 v[62:65], v[150:153], v[188:191], v[62:65]
	v_mfma_f32_16x16x32_bf16 v[58:61], v[158:161], v[188:191], v[58:61]
	v_mfma_f32_16x16x32_bf16 v[46:49], v[150:153], v[202:205], v[46:49]
	v_mfma_f32_16x16x32_bf16 v[42:45], v[158:161], v[202:205], v[42:45]
	v_mfma_f32_16x16x32_bf16 v[28:31], v[150:153], v[210:213], v[28:31]
	v_mfma_f32_16x16x32_bf16 v[24:27], v[158:161], v[210:213], v[24:27]
	v_mfma_f32_16x16x32_bf16 v[12:15], v[150:153], v[218:221], v[12:15]
	v_mfma_f32_16x16x32_bf16 v[8:11], v[158:161], v[218:221], v[8:11]
	v_mfma_f32_16x16x32_bf16 v[54:57], v[162:165], v[184:187], v[54:57]
	v_mfma_f32_16x16x32_bf16 v[50:53], v[176:179], v[184:187], v[50:53]
	v_mfma_f32_16x16x32_bf16 v[38:41], v[162:165], v[198:201], v[38:41]
	v_mfma_f32_16x16x32_bf16 v[34:37], v[176:179], v[198:201], v[34:37]
	v_mfma_f32_16x16x32_bf16 v[20:23], v[162:165], v[206:209], v[20:23]
	v_mfma_f32_16x16x32_bf16 v[16:19], v[176:179], v[206:209], v[16:19]
	v_mfma_f32_16x16x32_bf16 v[4:7], v[162:165], v[214:217], v[4:7]
	v_mfma_f32_16x16x32_bf16 v[0:3], v[176:179], v[214:217], v[0:3]
	v_mfma_f32_16x16x32_bf16 v[54:57], v[166:169], v[188:191], v[54:57]
	v_mfma_f32_16x16x32_bf16 v[50:53], v[180:183], v[188:191], v[50:53]
	v_mfma_f32_16x16x32_bf16 v[38:41], v[166:169], v[202:205], v[38:41]
	v_mfma_f32_16x16x32_bf16 v[34:37], v[180:183], v[202:205], v[34:37]
	v_mfma_f32_16x16x32_bf16 v[20:23], v[166:169], v[210:213], v[20:23]
	v_mfma_f32_16x16x32_bf16 v[16:19], v[180:183], v[210:213], v[16:19]
	v_mfma_f32_16x16x32_bf16 v[4:7], v[166:169], v[218:221], v[4:7]
	v_mfma_f32_16x16x32_bf16 v[0:3], v[180:183], v[218:221], v[0:3]
	s_setprio 0
	s_barrier
	s_add_i32 s56, s56, 2
	s_add_u32 s22, s22, 0x100
	s_addc_u32 s23, s23, 0
	s_cmp_gt_u32 s56, 29
	s_cbranch_scc0 .LBB0_948
	s_add_u32 s18, s18, 0xffffff00
	s_addc_u32 s19, s19, -1
	s_andn2_b64 vcc, exec, s[26:27]
	s_cbranch_vccnz .LBB0_951
	v_mov_b32_e32 v0, 0
	s_mov_b32 s33, s12
	s_mov_b32 s0, s10
	s_mov_b64 s[4:5], s[30:31]
	s_mov_b32 s50, s24
	v_mov_b32_e32 v1, v0
	v_mov_b32_e32 v2, v0
	v_mov_b32_e32 v3, v0
	v_mov_b32_e32 v4, v0
	v_mov_b32_e32 v5, v0
	v_mov_b32_e32 v6, v0
	v_mov_b32_e32 v7, v0
	v_mov_b32_e32 v16, v0
	v_mov_b32_e32 v17, v0
	v_mov_b32_e32 v18, v0
	v_mov_b32_e32 v19, v0
	v_mov_b32_e32 v20, v0
	v_mov_b32_e32 v21, v0
	v_mov_b32_e32 v22, v0
	v_mov_b32_e32 v23, v0
	v_mov_b32_e32 v34, v0
	v_mov_b32_e32 v35, v0
	v_mov_b32_e32 v36, v0
	v_mov_b32_e32 v37, v0
	v_mov_b32_e32 v38, v0
	v_mov_b32_e32 v39, v0
	v_mov_b32_e32 v40, v0
	v_mov_b32_e32 v41, v0
	v_mov_b32_e32 v50, v0
	v_mov_b32_e32 v51, v0
	v_mov_b32_e32 v52, v0
	v_mov_b32_e32 v53, v0
	v_mov_b32_e32 v54, v0
	v_mov_b32_e32 v55, v0
	v_mov_b32_e32 v56, v0
	v_mov_b32_e32 v57, v0
	v_mov_b32_e32 v8, v0
	v_mov_b32_e32 v9, v0
	v_mov_b32_e32 v10, v0
	v_mov_b32_e32 v11, v0
	v_mov_b32_e32 v12, v0
	v_mov_b32_e32 v13, v0
	v_mov_b32_e32 v14, v0
	v_mov_b32_e32 v15, v0
	v_mov_b32_e32 v24, v0
	v_mov_b32_e32 v25, v0
	v_mov_b32_e32 v26, v0
	v_mov_b32_e32 v27, v0
	v_mov_b32_e32 v28, v0
	v_mov_b32_e32 v29, v0
	v_mov_b32_e32 v30, v0
	v_mov_b32_e32 v31, v0
	v_mov_b32_e32 v42, v0
	v_mov_b32_e32 v43, v0
	v_mov_b32_e32 v44, v0
	v_mov_b32_e32 v45, v0
	v_mov_b32_e32 v46, v0
	v_mov_b32_e32 v47, v0
	v_mov_b32_e32 v48, v0
	v_mov_b32_e32 v49, v0
	v_mov_b32_e32 v58, v0
	v_mov_b32_e32 v59, v0
	v_mov_b32_e32 v60, v0
	v_mov_b32_e32 v61, v0
	v_mov_b32_e32 v62, v0
	v_mov_b32_e32 v63, v0
	v_mov_b32_e32 v64, v0
	v_mov_b32_e32 v65, v0
	v_mov_b32_e32 v66, v0
	v_mov_b32_e32 v67, v0
	v_mov_b32_e32 v68, v0
	v_mov_b32_e32 v69, v0
	v_mov_b32_e32 v70, v0
	v_mov_b32_e32 v71, v0
	v_mov_b32_e32 v72, v0
	v_mov_b32_e32 v73, v0
	v_mov_b32_e32 v82, v0
	v_mov_b32_e32 v83, v0
	v_mov_b32_e32 v84, v0
	v_mov_b32_e32 v85, v0
	v_mov_b32_e32 v86, v0
	v_mov_b32_e32 v87, v0
	v_mov_b32_e32 v88, v0
	v_mov_b32_e32 v89, v0
	v_mov_b32_e32 v98, v0
	v_mov_b32_e32 v99, v0
	v_mov_b32_e32 v100, v0
	v_mov_b32_e32 v101, v0
	v_mov_b32_e32 v110, v0
	v_mov_b32_e32 v111, v0
	v_mov_b32_e32 v112, v0
	v_mov_b32_e32 v113, v0
	v_mov_b32_e32 v102, v0
	v_mov_b32_e32 v103, v0
	v_mov_b32_e32 v104, v0
	v_mov_b32_e32 v105, v0
	v_mov_b32_e32 v106, v0
	v_mov_b32_e32 v107, v0
	v_mov_b32_e32 v108, v0
	v_mov_b32_e32 v109, v0
	v_mov_b32_e32 v74, v0
	v_mov_b32_e32 v75, v0
	v_mov_b32_e32 v76, v0
	v_mov_b32_e32 v77, v0
	v_mov_b32_e32 v78, v0
	v_mov_b32_e32 v79, v0
	v_mov_b32_e32 v80, v0
	v_mov_b32_e32 v81, v0
	v_mov_b32_e32 v90, v0
	v_mov_b32_e32 v91, v0
	v_mov_b32_e32 v92, v0
	v_mov_b32_e32 v93, v0
	v_mov_b32_e32 v94, v0
	v_mov_b32_e32 v95, v0
	v_mov_b32_e32 v96, v0
	v_mov_b32_e32 v97, v0
	v_mov_b32_e32 v130, v0
	v_mov_b32_e32 v131, v0
	v_mov_b32_e32 v132, v0
	v_mov_b32_e32 v133, v0
	v_mov_b32_e32 v134, v0
	v_mov_b32_e32 v135, v0
	v_mov_b32_e32 v136, v0
	v_mov_b32_e32 v137, v0
	v_mov_b32_e32 v114, v0
	v_mov_b32_e32 v115, v0
	v_mov_b32_e32 v116, v0
	v_mov_b32_e32 v117, v0
	v_mov_b32_e32 v118, v0
	v_mov_b32_e32 v119, v0
	v_mov_b32_e32 v120, v0
	v_mov_b32_e32 v121, v0
	s_andn2_b64 vcc, exec, s[14:15]
	s_cbranch_vccnz .LBB0_952
	s_branch .LBB0_953

; #define GPROBE_BEGIN(id) do { if (((PROBE_GEMM_SEL >> (id)) & 1) && blockIdx.x == 0 && tid_in < 64 && g.N == 20480) { volatile PG8_LAS unsigned long long* PW_ = (volatile PG8_LAS unsigned long long*)(lds + 163840 - 512 + 64); PW_[0] = __builtin_amdgcn_s_memrealtime(); } } while (0)
; #define GPROBE_END(id) do { if (((PROBE_GEMM_SEL >> (id)) & 1) && blockIdx.x == 0 && tid_in < 64 && g.N == 20480) { volatile PG8_LAS unsigned long long* PW_ = (volatile PG8_LAS unsigned long long*)(lds + 163840 - 512 + 64); PW_[1] += __builtin_amdgcn_s_memrealtime() - PW_[0]; } } while (0)
; #define PG8_STAGE(bufoff, gbase, voff) do { _Pragma("unroll") for (int _i = 0; _i < 2; ++_i) \
;         __builtin_amdgcn_global_load_lds((const unsigned*)((const char*)(gbase) + (voff)[_i]), (PG8_LAS unsigned*)(lds + (bufoff) + ldsw + _i * 8192), 16, 0, 0); } while (0)
; #define PG8_WAIT_V(n) asm volatile("s_waitcnt vmcnt(" #n ")" ::: "memory")
; #define PG8_WAIT_L(n) asm volatile("s_waitcnt lgkmcnt(" #n ")" ::: "memory")
; template <class Epi, class Sched, bool ALIGN_EPI = false, bool SP2 = false, bool KHOOK = false>
; __device__ __forceinline__ void gemm_phase(PG8_LAS unsigned char* lds, const Gemm g, const Sched& S, const Epi& E, const int tid_in) {
;     ...
;         const char* nA = has_next ? (const char*)g.A + (size_t)nxt.pm * tstep + (size_t)nxt.pn * ksl : cA; const char* nB = has_next ? (const char*)g.Bt + (size_t)nxt.pn * bts + (size_t)nxt.pn * ksl + (gdv ? (size_t)(nxt.pm / gdv) * gst : 0) : cB;
;         GPROBE_END(2); GPROBE_BEGIN(1);
;         for (int t = 0; t < nt; t += 2) {
;             const bool last = (t == nt - 2);
;             const char* a1 = cA + (size_t)(t + 1) * kstep;
;             const char* a2 = last ? nA : cA + (size_t)(t + 2) * kstep; const char* b2 = last ? nB : cB + (size_t)(t + 2) * kstep;
;             const char* a3 = a2 + kstep; const char* b3 = b2 + kstep;
;             if (last && has_next) S.a_ready(nxt);
;             if constexpr (SP2) {
;             PG8_LDB(B0, 0, 0); PG8_LDB(B1, 0, 1); PG8_SCHED; PG8_LDA(At, 0, 0); PG8_STAGE(PG8_SA(1, 1), a1 + hstep, voffA);
;             PG8_WAIT_V(8); PG8_WAIT_L(0); PG8_BAR; PG8_MMA(0, 0, At, B0); PG8_MMA(0, 1, At, B1); PG8_BAR; PG8_SCHED;
;             PG8_LDA(At, 0, 1); PG8_STAGE(PG8_SB(0, 0), b2, voffB); PG8_STAGE(PG8_SB(0, 1), b2 + hstep, voffB); PG8_STAGE(PG8_SA(0, 0), a2, voffA);
.LBB0_1062:
	s_ashr_i32 s13, s12, 31
	s_lshl_b64 s[16:17], s[12:13], 20
	v_readlane_b32 s22, v254, 34
	v_readlane_b32 s23, v254, 35
	s_add_u32 s16, s22, s16
	s_addc_u32 s17, s23, s17
	s_and_b64 s[22:23], s[14:15], exec
	s_cselect_b32 s13, s17, s27
	s_cselect_b32 s24, s16, s26
	s_ashr_i32 s11, s10, 31
	s_lshl_b64 s[22:23], s[10:11], 20
	s_add_u32 s22, s2, s22
	s_addc_u32 s23, s20, s23
	s_and_b64 s[44:45], s[14:15], exec
	s_cselect_b32 s11, s23, s31
	s_cselect_b32 s25, s22, s30
	s_add_u32 s26, s26, 0x80080
	s_addc_u32 s27, s27, 0
	s_add_u32 s44, s30, 0x100
	s_addc_u32 s45, s31, 0
	s_mov_b32 s46, -2
	s_add_u32 s30, s26, 0xfff80080
	s_addc_u32 s31, s27, -1
	s_add_i32 s47, 0, 0x10000
	s_cmp_eq_u32 s46, 28
	s_cselect_b32 s49, s13, s31
	s_cselect_b32 s48, s24, s30
	s_cselect_b32 s31, s11, s45
	s_cselect_b32 s30, s25, s44
	s_add_i32 s52, 0, 0x14000
	v_add_u32_e32 v152, s47, v137
	v_add_u32_e32 v168, s52, v137
	ds_read_b128 v[140:143], v152
	ds_read_b128 v[144:147], v152 offset:1024
	ds_read_b128 v[148:151], v152 offset:2048
	ds_read_b128 v[152:155], v152 offset:3072
	ds_read_b128 v[156:159], v168
	ds_read_b128 v[160:163], v168 offset:1024
	ds_read_b128 v[164:167], v168 offset:2048
	ds_read_b128 v[168:171], v168 offset:3072
	v_lshl_add_u64 v[192:193], s[26:27], 0, v[132:133]
	s_add_i32 m0, s36, 0xc000
	ds_read_b128 v[172:175], v139
	ds_read_b128 v[176:179], v139 offset:1024
	ds_read_b128 v[180:183], v139 offset:2048
	ds_read_b128 v[184:187], v139 offset:3072
	ds_read_b128 v[188:191], v139 offset:4096
	ds_read_b128 v[198:201], v139 offset:5120
	ds_read_b128 v[202:205], v139 offset:6144
	ds_read_b128 v[206:209], v139 offset:7168
	global_load_lds_dwordx4 v[192:193], off
	v_lshl_add_u64 v[192:193], s[26:27], 0, v[134:135]
	s_add_i32 m0, s36, 0xe000
	s_nop 0
	global_load_lds_dwordx4 v[192:193], off
	s_waitcnt vmcnt(10)
	s_waitcnt lgkmcnt(0)
	s_barrier
	s_setprio 1
	s_waitcnt lgkmcnt(0)
	v_mfma_f32_16x16x32_bf16 v[126:129], v[140:143], v[172:175], 0
	v_mfma_f32_16x16x32_bf16 v[122:125], v[148:151], v[172:175], 0
	v_mfma_f32_16x16x32_bf16 v[110:113], v[140:143], v[180:183], 0
	v_mfma_f32_16x16x32_bf16 v[106:109], v[148:151], v[180:183], 0
	v_mfma_f32_16x16x32_bf16 v[94:97], v[140:143], v[188:191], 0
	v_mfma_f32_16x16x32_bf16 v[90:93], v[148:151], v[188:191], 0
	v_mfma_f32_16x16x32_bf16 v[78:81], v[140:143], v[202:205], 0
	v_mfma_f32_16x16x32_bf16 v[74:77], v[148:151], v[202:205], 0
	v_mfma_f32_16x16x32_bf16 v[126:129], v[144:147], v[176:179], v[126:129]
	v_mfma_f32_16x16x32_bf16 v[122:125], v[152:155], v[176:179], v[122:125]
	v_mfma_f32_16x16x32_bf16 v[110:113], v[144:147], v[184:187], v[110:113]
	v_mfma_f32_16x16x32_bf16 v[106:109], v[152:155], v[184:187], v[106:109]
	v_mfma_f32_16x16x32_bf16 v[94:97], v[144:147], v[198:201], v[94:97]
	v_mfma_f32_16x16x32_bf16 v[90:93], v[152:155], v[198:201], v[90:93]
	v_mfma_f32_16x16x32_bf16 v[78:81], v[144:147], v[206:209], v[78:81]
	v_mfma_f32_16x16x32_bf16 v[74:77], v[152:155], v[206:209], v[74:77]
	v_mfma_f32_16x16x32_bf16 v[118:121], v[156:159], v[172:175], 0
	v_mfma_f32_16x16x32_bf16 v[114:117], v[164:167], v[172:175], 0
	v_mfma_f32_16x16x32_bf16 v[102:105], v[156:159], v[180:183], 0
	v_mfma_f32_16x16x32_bf16 v[98:101], v[164:167], v[180:183], 0
	v_mfma_f32_16x16x32_bf16 v[86:89], v[156:159], v[188:191], 0
	v_mfma_f32_16x16x32_bf16 v[82:85], v[164:167], v[188:191], 0
	v_mfma_f32_16x16x32_bf16 v[70:73], v[156:159], v[202:205], 0
	v_mfma_f32_16x16x32_bf16 v[66:69], v[164:167], v[202:205], 0
	v_mfma_f32_16x16x32_bf16 v[118:121], v[160:163], v[176:179], v[118:121]
	v_mfma_f32_16x16x32_bf16 v[114:117], v[168:171], v[176:179], v[114:117]
	v_mfma_f32_16x16x32_bf16 v[102:105], v[160:163], v[184:187], v[102:105]
	v_mfma_f32_16x16x32_bf16 v[98:101], v[168:171], v[184:187], v[98:101]
	v_mfma_f32_16x16x32_bf16 v[86:89], v[160:163], v[198:201], v[86:89]
	v_mfma_f32_16x16x32_bf16 v[82:85], v[168:171], v[198:201], v[82:85]
	v_mfma_f32_16x16x32_bf16 v[70:73], v[160:163], v[206:209], v[70:73]
	v_mfma_f32_16x16x32_bf16 v[66:69], v[168:171], v[206:209], v[66:69]
	s_setprio 0
	s_barrier
	s_add_i32 s47, s47, s33
	v_lshl_add_u64 v[192:193], s[30:31], 0, v[32:33]
	s_mov_b32 m0, s47
	ds_read_b128 v[172:175], v139 offset:16384
	ds_read_b128 v[176:179], v139 offset:17408
	ds_read_b128 v[180:183], v139 offset:18432
	ds_read_b128 v[184:187], v139 offset:19456
	ds_read_b128 v[188:191], v139 offset:20480
	ds_read_b128 v[198:201], v139 offset:21504
	ds_read_b128 v[202:205], v139 offset:22528
	ds_read_b128 v[206:209], v139 offset:23552
	global_load_lds_dwordx4 v[192:193], off
	s_add_i32 m0, s47, 0x2000
	s_add_u32 s50, s30, 0x80000
	v_lshl_add_u64 v[210:211], s[30:31], 0, v[130:131]
	s_addc_u32 s51, s31, 0
	s_add_i32 s47, s52, s33
	global_load_lds_dwordx4 v[210:211], off
	v_lshl_add_u64 v[212:213], s[50:51], 0, v[32:33]
	s_mov_b32 m0, s47
	v_lshl_add_u64 v[214:215], s[48:49], 0, v[130:131]
	global_load_lds_dwordx4 v[212:213], off
	v_lshl_add_u64 v[212:213], s[50:51], 0, v[130:131]
	s_add_i32 m0, s47, 0x2000
	s_nop 0
	global_load_lds_dwordx4 v[212:213], off
	v_lshl_add_u64 v[212:213], s[48:49], 0, v[32:33]
	s_mov_b32 m0, s36
	s_nop 0
	global_load_lds_dwordx4 v[212:213], off
	s_mov_b32 m0, s37
	s_nop 0
	global_load_lds_dwordx4 v[214:215], off
	s_waitcnt vmcnt(16)
	s_waitcnt lgkmcnt(0)
	s_barrier
; #define PG8_STAGE(bufoff, gbase, voff) do { _Pragma("unroll") for (int _i = 0; _i < 2; ++_i) \
;         __builtin_amdgcn_global_load_lds((const unsigned*)((const char*)(gbase) + (voff)[_i]), (PG8_LAS unsigned*)(lds + (bufoff) + ldsw + _i * 8192), 16, 0, 0); } while (0)
; #define PG8_LDA(dst, b, h) do { _Pragma("unroll") for (int m = 0; m < 4; ++m) _Pragma("unroll") for (int k = 0; k < 2; ++k) dst[m][k] = *(const PG8_LAS bf16x8*)(lds + PG8_SA(b, h) + aoff + m * 2048 + k * 1024); } while (0)
; #define PG8_LDB(dst, b, h) do { _Pragma("unroll") for (int n = 0; n < 2; ++n) _Pragma("unroll") for (int k = 0; k < 2; ++k) dst[n][k] = *(const PG8_LAS bf16x8*)(lds + PG8_SB(b, h) + boff + n * 2048 + k * 1024); } while (0)
; #define PG8_MMA(ai, bj, At, Bt) do { __builtin_amdgcn_s_setprio(1); _Pragma("unroll") for (int m = 0; m < 4; ++m) _Pragma("unroll") for (int n = 0; n < 2; ++n) _Pragma("unroll") for (int k = 0; k < 2; ++k) \
;         acc[ai][bj][m][n] = __builtin_amdgcn_mfma_f32_16x16x32_bf16(Bt[n][k], At[m][k], acc[ai][bj][m][n], 0, 0, 0); __builtin_amdgcn_s_setprio(0); } while (0)
; #define PG8_WAIT_V(n) asm volatile("s_waitcnt vmcnt(" #n ")" ::: "memory")
; #define PG8_WAIT_L(n) asm volatile("s_waitcnt lgkmcnt(" #n ")" ::: "memory")
; #define PG8_BAR __builtin_amdgcn_s_barrier()
; #define PG8_SCHED __builtin_amdgcn_sched_barrier(0)
; template <class Epi, class Sched, bool ALIGN_EPI = false, bool SP2 = false, bool KHOOK = false>
; __device__ __forceinline__ void gemm_phase(PG8_LAS unsigned char* lds, const Gemm g, const Sched& S, const Epi& E, const int tid_in) {
;     ...
;             PG8_WAIT_V(8); PG8_WAIT_L(0); PG8_BAR; PG8_MMA(1, 0, At, B0); PG8_MMA(1, 1, At, B1); PG8_BAR; PG8_SCHED;
;             PG8_LDB(B0, 1, 0); PG8_LDB(B1, 1, 1); PG8_SCHED; PG8_LDA(At, 1, 0); PG8_STAGE(PG8_SA(0, 1), a2 + hstep, voffA);
;             PG8_WAIT_V(8); PG8_WAIT_L(0); PG8_BAR; PG8_MMA(0, 0, At, B0); PG8_MMA(0, 1, At, B1); PG8_BAR; PG8_SCHED;
	s_setprio 1
	s_waitcnt lgkmcnt(0)
	v_mfma_f32_16x16x32_bf16 v[62:65], v[140:143], v[172:175], 0
	v_mfma_f32_16x16x32_bf16 v[58:61], v[148:151], v[172:175], 0
	v_mfma_f32_16x16x32_bf16 v[46:49], v[140:143], v[180:183], 0
	v_mfma_f32_16x16x32_bf16 v[42:45], v[148:151], v[180:183], 0
	v_mfma_f32_16x16x32_bf16 v[28:31], v[140:143], v[188:191], 0
	v_mfma_f32_16x16x32_bf16 v[24:27], v[148:151], v[188:191], 0
	v_mfma_f32_16x16x32_bf16 v[12:15], v[140:143], v[202:205], 0
	v_mfma_f32_16x16x32_bf16 v[8:11], v[148:151], v[202:205], 0
	v_mfma_f32_16x16x32_bf16 v[62:65], v[144:147], v[176:179], v[62:65]
	v_mfma_f32_16x16x32_bf16 v[58:61], v[152:155], v[176:179], v[58:61]
	v_mfma_f32_16x16x32_bf16 v[46:49], v[144:147], v[184:187], v[46:49]
	v_mfma_f32_16x16x32_bf16 v[42:45], v[152:155], v[184:187], v[42:45]
	v_mfma_f32_16x16x32_bf16 v[28:31], v[144:147], v[198:201], v[28:31]
	v_mfma_f32_16x16x32_bf16 v[24:27], v[152:155], v[198:201], v[24:27]
	v_mfma_f32_16x16x32_bf16 v[12:15], v[144:147], v[206:209], v[12:15]
	v_mfma_f32_16x16x32_bf16 v[8:11], v[152:155], v[206:209], v[8:11]
	v_mfma_f32_16x16x32_bf16 v[54:57], v[156:159], v[172:175], 0
	v_mfma_f32_16x16x32_bf16 v[50:53], v[164:167], v[172:175], 0
	v_mfma_f32_16x16x32_bf16 v[38:41], v[156:159], v[180:183], 0
	v_mfma_f32_16x16x32_bf16 v[34:37], v[164:167], v[180:183], 0
	v_mfma_f32_16x16x32_bf16 v[20:23], v[156:159], v[188:191], 0
	v_mfma_f32_16x16x32_bf16 v[16:19], v[164:167], v[188:191], 0
	v_mfma_f32_16x16x32_bf16 v[4:7], v[156:159], v[202:205], 0
	v_mfma_f32_16x16x32_bf16 v[0:3], v[164:167], v[202:205], 0
	v_mfma_f32_16x16x32_bf16 v[54:57], v[160:163], v[176:179], v[54:57]
	v_mfma_f32_16x16x32_bf16 v[50:53], v[168:171], v[176:179], v[50:53]
	v_mfma_f32_16x16x32_bf16 v[38:41], v[160:163], v[184:187], v[38:41]
	v_mfma_f32_16x16x32_bf16 v[34:37], v[168:171], v[184:187], v[34:37]
	v_mfma_f32_16x16x32_bf16 v[20:23], v[160:163], v[198:201], v[20:23]
	v_mfma_f32_16x16x32_bf16 v[16:19], v[168:171], v[198:201], v[16:19]
	v_mfma_f32_16x16x32_bf16 v[4:7], v[160:163], v[206:209], v[4:7]
	v_mfma_f32_16x16x32_bf16 v[0:3], v[168:171], v[206:209], v[0:3]
	s_setprio 0
	s_barrier
	s_add_i32 s47, 0, 0x18000
	s_add_i32 s50, 0, 0x1c000
	v_add_u32_e32 v152, s47, v137
	v_add_u32_e32 v168, s50, v137
	ds_read_b128 v[140:143], v152
	ds_read_b128 v[144:147], v152 offset:1024
	ds_read_b128 v[148:151], v152 offset:2048
	ds_read_b128 v[152:155], v152 offset:3072
	ds_read_b128 v[156:159], v168
	ds_read_b128 v[160:163], v168 offset:1024
	ds_read_b128 v[164:167], v168 offset:2048
	ds_read_b128 v[168:171], v168 offset:3072
	s_add_u32 s48, s48, 0x80000
	s_addc_u32 s49, s49, 0
	s_mov_b32 m0, s38
	v_lshl_add_u64 v[216:217], s[48:49], 0, v[32:33]
	ds_read_b128 v[172:175], v139 offset:32768
	ds_read_b128 v[176:179], v139 offset:33792
	ds_read_b128 v[180:183], v139 offset:34816
	ds_read_b128 v[184:187], v139 offset:35840
	ds_read_b128 v[188:191], v139 offset:36864
	ds_read_b128 v[198:201], v139 offset:37888
	ds_read_b128 v[202:205], v139 offset:38912
	ds_read_b128 v[206:209], v139 offset:39936
	global_load_lds_dwordx4 v[216:217], off
	v_lshl_add_u64 v[216:217], s[48:49], 0, v[130:131]
	s_mov_b32 m0, s39
	s_nop 0
	global_load_lds_dwordx4 v[216:217], off
	s_waitcnt vmcnt(8)
	s_waitcnt lgkmcnt(0)
	s_barrier
	s_setprio 1
	s_waitcnt lgkmcnt(0)
	v_mfma_f32_16x16x32_bf16 v[126:129], v[140:143], v[172:175], v[126:129]
	v_mfma_f32_16x16x32_bf16 v[122:125], v[148:151], v[172:175], v[122:125]
	v_mfma_f32_16x16x32_bf16 v[110:113], v[140:143], v[180:183], v[110:113]
	v_mfma_f32_16x16x32_bf16 v[106:109], v[148:151], v[180:183], v[106:109]
	v_mfma_f32_16x16x32_bf16 v[94:97], v[140:143], v[188:191], v[94:97]
	v_mfma_f32_16x16x32_bf16 v[90:93], v[148:151], v[188:191], v[90:93]
	v_mfma_f32_16x16x32_bf16 v[78:81], v[140:143], v[202:205], v[78:81]
	v_mfma_f32_16x16x32_bf16 v[74:77], v[148:151], v[202:205], v[74:77]
	v_mfma_f32_16x16x32_bf16 v[126:129], v[144:147], v[176:179], v[126:129]
	v_mfma_f32_16x16x32_bf16 v[122:125], v[152:155], v[176:179], v[122:125]
	v_mfma_f32_16x16x32_bf16 v[110:113], v[144:147], v[184:187], v[110:113]
	v_mfma_f32_16x16x32_bf16 v[106:109], v[152:155], v[184:187], v[106:109]
	v_mfma_f32_16x16x32_bf16 v[94:97], v[144:147], v[198:201], v[94:97]
	v_mfma_f32_16x16x32_bf16 v[90:93], v[152:155], v[198:201], v[90:93]
	v_mfma_f32_16x16x32_bf16 v[78:81], v[144:147], v[206:209], v[78:81]
	v_mfma_f32_16x16x32_bf16 v[74:77], v[152:155], v[206:209], v[74:77]
	v_mfma_f32_16x16x32_bf16 v[118:121], v[156:159], v[172:175], v[118:121]
	v_mfma_f32_16x16x32_bf16 v[114:117], v[164:167], v[172:175], v[114:117]
	v_mfma_f32_16x16x32_bf16 v[102:105], v[156:159], v[180:183], v[102:105]
	v_mfma_f32_16x16x32_bf16 v[98:101], v[164:167], v[180:183], v[98:101]
	v_mfma_f32_16x16x32_bf16 v[86:89], v[156:159], v[188:191], v[86:89]
	v_mfma_f32_16x16x32_bf16 v[82:85], v[164:167], v[188:191], v[82:85]
	v_mfma_f32_16x16x32_bf16 v[70:73], v[156:159], v[202:205], v[70:73]
	v_mfma_f32_16x16x32_bf16 v[66:69], v[164:167], v[202:205], v[66:69]
	v_mfma_f32_16x16x32_bf16 v[118:121], v[160:163], v[176:179], v[118:121]
	v_mfma_f32_16x16x32_bf16 v[114:117], v[168:171], v[176:179], v[114:117]
	v_mfma_f32_16x16x32_bf16 v[102:105], v[160:163], v[184:187], v[102:105]
	v_mfma_f32_16x16x32_bf16 v[98:101], v[168:171], v[184:187], v[98:101]
	v_mfma_f32_16x16x32_bf16 v[86:89], v[160:163], v[198:201], v[86:89]
	v_mfma_f32_16x16x32_bf16 v[82:85], v[168:171], v[198:201], v[82:85]
	v_mfma_f32_16x16x32_bf16 v[70:73], v[160:163], v[206:209], v[70:73]
	v_mfma_f32_16x16x32_bf16 v[66:69], v[168:171], v[206:209], v[66:69]
	s_setprio 0
	s_barrier
; #define PG8_STAGE(bufoff, gbase, voff) do { _Pragma("unroll") for (int _i = 0; _i < 2; ++_i) \
;         __builtin_amdgcn_global_load_lds((const unsigned*)((const char*)(gbase) + (voff)[_i]), (PG8_LAS unsigned*)(lds + (bufoff) + ldsw + _i * 8192), 16, 0, 0); } while (0)
; #define PG8_LDA(dst, b, h) do { _Pragma("unroll") for (int m = 0; m < 4; ++m) _Pragma("unroll") for (int k = 0; k < 2; ++k) dst[m][k] = *(const PG8_LAS bf16x8*)(lds + PG8_SA(b, h) + aoff + m * 2048 + k * 1024); } while (0)
; #define PG8_LDB(dst, b, h) do { _Pragma("unroll") for (int n = 0; n < 2; ++n) _Pragma("unroll") for (int k = 0; k < 2; ++k) dst[n][k] = *(const PG8_LAS bf16x8*)(lds + PG8_SB(b, h) + boff + n * 2048 + k * 1024); } while (0)
; #define PG8_MMA(ai, bj, At, Bt) do { __builtin_amdgcn_s_setprio(1); _Pragma("unroll") for (int m = 0; m < 4; ++m) _Pragma("unroll") for (int n = 0; n < 2; ++n) _Pragma("unroll") for (int k = 0; k < 2; ++k) \
;         acc[ai][bj][m][n] = __builtin_amdgcn_mfma_f32_16x16x32_bf16(Bt[n][k], At[m][k], acc[ai][bj][m][n], 0, 0, 0); __builtin_amdgcn_s_setprio(0); } while (0)
; #define PG8_WAIT_V(n) asm volatile("s_waitcnt vmcnt(" #n ")" ::: "memory")
; #define PG8_WAIT_L(n) asm volatile("s_waitcnt lgkmcnt(" #n ")" ::: "memory")
; #define PG8_BAR __builtin_amdgcn_s_barrier()
; #define PG8_SCHED __builtin_amdgcn_sched_barrier(0)
; template <class Epi, class Sched, bool ALIGN_EPI = false, bool SP2 = false, bool KHOOK = false>
; __device__ __forceinline__ void gemm_phase(PG8_LAS unsigned char* lds, const Gemm g, const Sched& S, const Epi& E, const int tid_in) {
;     ...
;             const bool last = (t == nt - 2);
;             const char* a1 = cA + (size_t)(t + 1) * kstep;
;             const char* a2 = last ? nA : cA + (size_t)(t + 2) * kstep; const char* b2 = last ? nB : cB + (size_t)(t + 2) * kstep;
;             const char* a3 = a2 + kstep; const char* b3 = b2 + kstep;
;             if (last && has_next) S.a_ready(nxt);
;             if constexpr (SP2) {
;             PG8_LDB(B0, 0, 0); PG8_LDB(B1, 0, 1); PG8_SCHED; PG8_LDA(At, 0, 0); PG8_STAGE(PG8_SA(1, 1), a1 + hstep, voffA);
;     ...
;             PG8_LDA(At, 1, 1); PG8_STAGE(PG8_SB(1, 0), b3, voffB); PG8_STAGE(PG8_SB(1, 1), b3 + hstep, voffB); PG8_STAGE(PG8_SA(1, 0), a3, voffA);
;             PG8_WAIT_V(8); PG8_WAIT_L(0); PG8_BAR; PG8_MMA(1, 0, At, B0); PG8_MMA(1, 1, At, B1); PG8_BAR; PG8_SCHED;
	s_add_i32 s47, s47, s33
	v_lshl_add_u64 v[192:193], v[192:193], 0, s[90:91]
	s_mov_b32 m0, s47
	ds_read_b128 v[172:175], v139 offset:49152
	ds_read_b128 v[176:179], v139 offset:50176
	ds_read_b128 v[180:183], v139 offset:51200
	ds_read_b128 v[184:187], v139 offset:52224
	ds_read_b128 v[188:191], v139 offset:53248
	ds_read_b128 v[198:201], v139 offset:54272
	ds_read_b128 v[202:205], v139 offset:55296
	ds_read_b128 v[206:209], v139 offset:56320
	global_load_lds_dwordx4 v[192:193], off
	s_add_i32 m0, s47, 0x2000
	s_add_u32 s30, s30, 0x80080
	v_lshl_add_u64 v[192:193], v[210:211], 0, s[90:91]
	s_addc_u32 s31, s31, 0
	s_add_i32 s47, s50, s33
	global_load_lds_dwordx4 v[192:193], off
	v_lshl_add_u64 v[192:193], s[30:31], 0, v[32:33]
	s_mov_b32 m0, s47
	s_nop 0
	global_load_lds_dwordx4 v[192:193], off
	v_lshl_add_u64 v[192:193], s[30:31], 0, v[130:131]
	s_add_i32 m0, s47, 0x2000
	s_nop 0
	global_load_lds_dwordx4 v[192:193], off
	v_lshl_add_u64 v[192:193], v[212:213], 0, s[90:91]
	s_mov_b32 m0, s40
	s_nop 0
	global_load_lds_dwordx4 v[192:193], off
	v_lshl_add_u64 v[192:193], v[214:215], 0, s[90:91]
	s_mov_b32 m0, s41
	s_nop 0
	global_load_lds_dwordx4 v[192:193], off
	s_waitcnt vmcnt(8)
	s_waitcnt lgkmcnt(0)
	s_barrier
	s_setprio 1
	s_waitcnt lgkmcnt(0)
	v_mfma_f32_16x16x32_bf16 v[62:65], v[140:143], v[172:175], v[62:65]
	v_mfma_f32_16x16x32_bf16 v[58:61], v[148:151], v[172:175], v[58:61]
	v_mfma_f32_16x16x32_bf16 v[46:49], v[140:143], v[180:183], v[46:49]
	v_mfma_f32_16x16x32_bf16 v[42:45], v[148:151], v[180:183], v[42:45]
	v_mfma_f32_16x16x32_bf16 v[28:31], v[140:143], v[188:191], v[28:31]
	v_mfma_f32_16x16x32_bf16 v[24:27], v[148:151], v[188:191], v[24:27]
	v_mfma_f32_16x16x32_bf16 v[12:15], v[140:143], v[202:205], v[12:15]
	v_mfma_f32_16x16x32_bf16 v[8:11], v[148:151], v[202:205], v[8:11]
	v_mfma_f32_16x16x32_bf16 v[62:65], v[144:147], v[176:179], v[62:65]
	v_mfma_f32_16x16x32_bf16 v[58:61], v[152:155], v[176:179], v[58:61]
	v_mfma_f32_16x16x32_bf16 v[46:49], v[144:147], v[184:187], v[46:49]
	v_mfma_f32_16x16x32_bf16 v[42:45], v[152:155], v[184:187], v[42:45]
	v_mfma_f32_16x16x32_bf16 v[28:31], v[144:147], v[198:201], v[28:31]
	v_mfma_f32_16x16x32_bf16 v[24:27], v[152:155], v[198:201], v[24:27]
	v_mfma_f32_16x16x32_bf16 v[12:15], v[144:147], v[206:209], v[12:15]
	v_mfma_f32_16x16x32_bf16 v[8:11], v[152:155], v[206:209], v[8:11]
	v_mfma_f32_16x16x32_bf16 v[54:57], v[156:159], v[172:175], v[54:57]
	v_mfma_f32_16x16x32_bf16 v[50:53], v[164:167], v[172:175], v[50:53]
	v_mfma_f32_16x16x32_bf16 v[38:41], v[156:159], v[180:183], v[38:41]
	v_mfma_f32_16x16x32_bf16 v[34:37], v[164:167], v[180:183], v[34:37]
	v_mfma_f32_16x16x32_bf16 v[20:23], v[156:159], v[188:191], v[20:23]
	v_mfma_f32_16x16x32_bf16 v[16:19], v[164:167], v[188:191], v[16:19]
	v_mfma_f32_16x16x32_bf16 v[4:7], v[156:159], v[202:205], v[4:7]
	v_mfma_f32_16x16x32_bf16 v[0:3], v[164:167], v[202:205], v[0:3]
	v_mfma_f32_16x16x32_bf16 v[54:57], v[160:163], v[176:179], v[54:57]
	v_mfma_f32_16x16x32_bf16 v[50:53], v[168:171], v[176:179], v[50:53]
	v_mfma_f32_16x16x32_bf16 v[38:41], v[160:163], v[184:187], v[38:41]
	v_mfma_f32_16x16x32_bf16 v[34:37], v[168:171], v[184:187], v[34:37]
	v_mfma_f32_16x16x32_bf16 v[20:23], v[160:163], v[198:201], v[20:23]
	v_mfma_f32_16x16x32_bf16 v[16:19], v[168:171], v[198:201], v[16:19]
	v_mfma_f32_16x16x32_bf16 v[4:7], v[160:163], v[206:209], v[4:7]
	v_mfma_f32_16x16x32_bf16 v[0:3], v[168:171], v[206:209], v[0:3]
	s_setprio 0
	s_barrier
	s_add_i32 s46, s46, 2
	s_add_u32 s26, s26, 0x100
	s_addc_u32 s27, s27, 0
	s_add_u32 s44, s44, 0x100
	s_addc_u32 s45, s45, 0
	s_cmp_gt_u32 s46, 29
.LBB0_1063:
	s_add_u32 s30, s26, 0xfff80080
	s_addc_u32 s31, s27, -1
	s_add_i32 s47, 0, 0x10000
	s_cmp_eq_u32 s46, 28
	s_cselect_b32 s49, s13, s31
	s_cselect_b32 s48, s24, s30
	s_cselect_b32 s31, s11, s45
	s_cselect_b32 s30, s25, s44
	s_add_i32 s52, 0, 0x14000
	v_add_u32_e32 v152, s47, v137
	v_add_u32_e32 v168, s52, v137
	ds_read_b128 v[140:143], v152
	ds_read_b128 v[144:147], v152 offset:1024
	ds_read_b128 v[148:151], v152 offset:2048
	ds_read_b128 v[152:155], v152 offset:3072
	ds_read_b128 v[156:159], v168
	ds_read_b128 v[160:163], v168 offset:1024
	ds_read_b128 v[164:167], v168 offset:2048
	ds_read_b128 v[168:171], v168 offset:3072
	v_lshl_add_u64 v[192:193], s[26:27], 0, v[132:133]
	s_add_i32 m0, s36, 0xc000
	ds_read_b128 v[172:175], v139
	ds_read_b128 v[176:179], v139 offset:1024
	ds_read_b128 v[180:183], v139 offset:2048
	ds_read_b128 v[184:187], v139 offset:3072
	ds_read_b128 v[188:191], v139 offset:4096
	ds_read_b128 v[198:201], v139 offset:5120
	ds_read_b128 v[202:205], v139 offset:6144
	ds_read_b128 v[206:209], v139 offset:7168
	global_load_lds_dwordx4 v[192:193], off
	v_lshl_add_u64 v[192:193], s[26:27], 0, v[134:135]
	s_add_i32 m0, s36, 0xe000
	s_nop 0
	global_load_lds_dwordx4 v[192:193], off
	s_waitcnt vmcnt(8)
	s_waitcnt lgkmcnt(0)
	s_barrier
; #define PG8_STAGE(bufoff, gbase, voff) do { _Pragma("unroll") for (int _i = 0; _i < 2; ++_i) \
;         __builtin_amdgcn_global_load_lds((const unsigned*)((const char*)(gbase) + (voff)[_i]), (PG8_LAS unsigned*)(lds + (bufoff) + ldsw + _i * 8192), 16, 0, 0); } while (0)
; #define PG8_LDA(dst, b, h) do { _Pragma("unroll") for (int m = 0; m < 4; ++m) _Pragma("unroll") for (int k = 0; k < 2; ++k) dst[m][k] = *(const PG8_LAS bf16x8*)(lds + PG8_SA(b, h) + aoff + m * 2048 + k * 1024); } while (0)
; #define PG8_LDB(dst, b, h) do { _Pragma("unroll") for (int n = 0; n < 2; ++n) _Pragma("unroll") for (int k = 0; k < 2; ++k) dst[n][k] = *(const PG8_LAS bf16x8*)(lds + PG8_SB(b, h) + boff + n * 2048 + k * 1024); } while (0)
; #define PG8_MMA(ai, bj, At, Bt) do { __builtin_amdgcn_s_setprio(1); _Pragma("unroll") for (int m = 0; m < 4; ++m) _Pragma("unroll") for (int n = 0; n < 2; ++n) _Pragma("unroll") for (int k = 0; k < 2; ++k) \
;         acc[ai][bj][m][n] = __builtin_amdgcn_mfma_f32_16x16x32_bf16(Bt[n][k], At[m][k], acc[ai][bj][m][n], 0, 0, 0); __builtin_amdgcn_s_setprio(0); } while (0)
; #define PG8_WAIT_V(n) asm volatile("s_waitcnt vmcnt(" #n ")" ::: "memory")
; #define PG8_WAIT_L(n) asm volatile("s_waitcnt lgkmcnt(" #n ")" ::: "memory")
; #define PG8_BAR __builtin_amdgcn_s_barrier()
; #define PG8_SCHED __builtin_amdgcn_sched_barrier(0)
; template <class Epi, class Sched, bool ALIGN_EPI = false, bool SP2 = false, bool KHOOK = false>
; __device__ __forceinline__ void gemm_phase(PG8_LAS unsigned char* lds, const Gemm g, const Sched& S, const Epi& E, const int tid_in) {
;     ...
;             PG8_WAIT_V(8); PG8_WAIT_L(0); PG8_BAR; PG8_MMA(0, 0, At, B0); PG8_MMA(0, 1, At, B1); PG8_BAR; PG8_SCHED;
;             PG8_LDA(At, 0, 1); PG8_STAGE(PG8_SB(0, 0), b2, voffB); PG8_STAGE(PG8_SB(0, 1), b2 + hstep, voffB); PG8_STAGE(PG8_SA(0, 0), a2, voffA);
;             PG8_WAIT_V(8); PG8_WAIT_L(0); PG8_BAR; PG8_MMA(1, 0, At, B0); PG8_MMA(1, 1, At, B1); PG8_BAR; PG8_SCHED;
;             PG8_LDB(B0, 1, 0); PG8_LDB(B1, 1, 1); PG8_SCHED; PG8_LDA(At, 1, 0); PG8_STAGE(PG8_SA(0, 1), a2 + hstep, voffA);
;             PG8_WAIT_V(8); PG8_WAIT_L(0); PG8_BAR; PG8_MMA(0, 0, At, B0); PG8_MMA(0, 1, At, B1); PG8_BAR; PG8_SCHED;
	s_setprio 1
	s_waitcnt lgkmcnt(0)
	v_mfma_f32_16x16x32_bf16 v[126:129], v[140:143], v[172:175], v[126:129]
	v_mfma_f32_16x16x32_bf16 v[122:125], v[148:151], v[172:175], v[122:125]
	v_mfma_f32_16x16x32_bf16 v[110:113], v[140:143], v[180:183], v[110:113]
	v_mfma_f32_16x16x32_bf16 v[106:109], v[148:151], v[180:183], v[106:109]
	v_mfma_f32_16x16x32_bf16 v[94:97], v[140:143], v[188:191], v[94:97]
	v_mfma_f32_16x16x32_bf16 v[90:93], v[148:151], v[188:191], v[90:93]
	v_mfma_f32_16x16x32_bf16 v[78:81], v[140:143], v[202:205], v[78:81]
	v_mfma_f32_16x16x32_bf16 v[74:77], v[148:151], v[202:205], v[74:77]
	v_mfma_f32_16x16x32_bf16 v[126:129], v[144:147], v[176:179], v[126:129]
	v_mfma_f32_16x16x32_bf16 v[122:125], v[152:155], v[176:179], v[122:125]
	v_mfma_f32_16x16x32_bf16 v[110:113], v[144:147], v[184:187], v[110:113]
	v_mfma_f32_16x16x32_bf16 v[106:109], v[152:155], v[184:187], v[106:109]
	v_mfma_f32_16x16x32_bf16 v[94:97], v[144:147], v[198:201], v[94:97]
	v_mfma_f32_16x16x32_bf16 v[90:93], v[152:155], v[198:201], v[90:93]
	v_mfma_f32_16x16x32_bf16 v[78:81], v[144:147], v[206:209], v[78:81]
	v_mfma_f32_16x16x32_bf16 v[74:77], v[152:155], v[206:209], v[74:77]
	v_mfma_f32_16x16x32_bf16 v[118:121], v[156:159], v[172:175], v[118:121]
	v_mfma_f32_16x16x32_bf16 v[114:117], v[164:167], v[172:175], v[114:117]
	v_mfma_f32_16x16x32_bf16 v[102:105], v[156:159], v[180:183], v[102:105]
	v_mfma_f32_16x16x32_bf16 v[98:101], v[164:167], v[180:183], v[98:101]
	v_mfma_f32_16x16x32_bf16 v[86:89], v[156:159], v[188:191], v[86:89]
	v_mfma_f32_16x16x32_bf16 v[82:85], v[164:167], v[188:191], v[82:85]
	v_mfma_f32_16x16x32_bf16 v[70:73], v[156:159], v[202:205], v[70:73]
	v_mfma_f32_16x16x32_bf16 v[66:69], v[164:167], v[202:205], v[66:69]
	v_mfma_f32_16x16x32_bf16 v[118:121], v[160:163], v[176:179], v[118:121]
	v_mfma_f32_16x16x32_bf16 v[114:117], v[168:171], v[176:179], v[114:117]
	v_mfma_f32_16x16x32_bf16 v[102:105], v[160:163], v[184:187], v[102:105]
	v_mfma_f32_16x16x32_bf16 v[98:101], v[168:171], v[184:187], v[98:101]
	v_mfma_f32_16x16x32_bf16 v[86:89], v[160:163], v[198:201], v[86:89]
	v_mfma_f32_16x16x32_bf16 v[82:85], v[168:171], v[198:201], v[82:85]
	v_mfma_f32_16x16x32_bf16 v[70:73], v[160:163], v[206:209], v[70:73]
	v_mfma_f32_16x16x32_bf16 v[66:69], v[168:171], v[206:209], v[66:69]
	s_setprio 0
	s_barrier
	s_add_i32 s47, s47, s33
	v_lshl_add_u64 v[192:193], s[30:31], 0, v[32:33]
	s_mov_b32 m0, s47
	ds_read_b128 v[172:175], v139 offset:16384
	ds_read_b128 v[176:179], v139 offset:17408
	ds_read_b128 v[180:183], v139 offset:18432
	ds_read_b128 v[184:187], v139 offset:19456
	ds_read_b128 v[188:191], v139 offset:20480
	ds_read_b128 v[198:201], v139 offset:21504
	ds_read_b128 v[202:205], v139 offset:22528
	ds_read_b128 v[206:209], v139 offset:23552
	global_load_lds_dwordx4 v[192:193], off
	s_add_i32 m0, s47, 0x2000
	s_add_u32 s50, s30, 0x80000
	v_lshl_add_u64 v[210:211], s[30:31], 0, v[130:131]
	s_addc_u32 s51, s31, 0
	s_add_i32 s47, s52, s33
	global_load_lds_dwordx4 v[210:211], off
	v_lshl_add_u64 v[212:213], s[50:51], 0, v[32:33]
	s_mov_b32 m0, s47
	v_lshl_add_u64 v[214:215], s[48:49], 0, v[130:131]
	global_load_lds_dwordx4 v[212:213], off
	v_lshl_add_u64 v[212:213], s[50:51], 0, v[130:131]
	s_add_i32 m0, s47, 0x2000
	s_nop 0
	global_load_lds_dwordx4 v[212:213], off
	v_lshl_add_u64 v[212:213], s[48:49], 0, v[32:33]
	s_mov_b32 m0, s36
	s_nop 0
	global_load_lds_dwordx4 v[212:213], off
	s_mov_b32 m0, s37
	s_nop 0
	global_load_lds_dwordx4 v[214:215], off
	s_waitcnt vmcnt(8)
	s_waitcnt lgkmcnt(0)
	s_barrier
	s_setprio 1
	s_waitcnt lgkmcnt(0)
	v_mfma_f32_16x16x32_bf16 v[62:65], v[140:143], v[172:175], v[62:65]
	v_mfma_f32_16x16x32_bf16 v[58:61], v[148:151], v[172:175], v[58:61]
	v_mfma_f32_16x16x32_bf16 v[46:49], v[140:143], v[180:183], v[46:49]
	v_mfma_f32_16x16x32_bf16 v[42:45], v[148:151], v[180:183], v[42:45]
	v_mfma_f32_16x16x32_bf16 v[28:31], v[140:143], v[188:191], v[28:31]
	v_mfma_f32_16x16x32_bf16 v[24:27], v[148:151], v[188:191], v[24:27]
	v_mfma_f32_16x16x32_bf16 v[12:15], v[140:143], v[202:205], v[12:15]
	v_mfma_f32_16x16x32_bf16 v[8:11], v[148:151], v[202:205], v[8:11]
	v_mfma_f32_16x16x32_bf16 v[62:65], v[144:147], v[176:179], v[62:65]
	v_mfma_f32_16x16x32_bf16 v[58:61], v[152:155], v[176:179], v[58:61]
	v_mfma_f32_16x16x32_bf16 v[46:49], v[144:147], v[184:187], v[46:49]
	v_mfma_f32_16x16x32_bf16 v[42:45], v[152:155], v[184:187], v[42:45]
	v_mfma_f32_16x16x32_bf16 v[28:31], v[144:147], v[198:201], v[28:31]
	v_mfma_f32_16x16x32_bf16 v[24:27], v[152:155], v[198:201], v[24:27]
	v_mfma_f32_16x16x32_bf16 v[12:15], v[144:147], v[206:209], v[12:15]
	v_mfma_f32_16x16x32_bf16 v[8:11], v[152:155], v[206:209], v[8:11]
	v_mfma_f32_16x16x32_bf16 v[54:57], v[156:159], v[172:175], v[54:57]
	v_mfma_f32_16x16x32_bf16 v[50:53], v[164:167], v[172:175], v[50:53]
	v_mfma_f32_16x16x32_bf16 v[38:41], v[156:159], v[180:183], v[38:41]
	v_mfma_f32_16x16x32_bf16 v[34:37], v[164:167], v[180:183], v[34:37]
	v_mfma_f32_16x16x32_bf16 v[20:23], v[156:159], v[188:191], v[20:23]
	v_mfma_f32_16x16x32_bf16 v[16:19], v[164:167], v[188:191], v[16:19]
	v_mfma_f32_16x16x32_bf16 v[4:7], v[156:159], v[202:205], v[4:7]
	v_mfma_f32_16x16x32_bf16 v[0:3], v[164:167], v[202:205], v[0:3]
	v_mfma_f32_16x16x32_bf16 v[54:57], v[160:163], v[176:179], v[54:57]
	v_mfma_f32_16x16x32_bf16 v[50:53], v[168:171], v[176:179], v[50:53]
	v_mfma_f32_16x16x32_bf16 v[38:41], v[160:163], v[184:187], v[38:41]
	v_mfma_f32_16x16x32_bf16 v[34:37], v[168:171], v[184:187], v[34:37]
	v_mfma_f32_16x16x32_bf16 v[20:23], v[160:163], v[198:201], v[20:23]
	v_mfma_f32_16x16x32_bf16 v[16:19], v[168:171], v[198:201], v[16:19]
	v_mfma_f32_16x16x32_bf16 v[4:7], v[160:163], v[206:209], v[4:7]
	v_mfma_f32_16x16x32_bf16 v[0:3], v[168:171], v[206:209], v[0:3]
	s_setprio 0
	s_barrier
; #define PG8_STAGE(bufoff, gbase, voff) do { _Pragma("unroll") for (int _i = 0; _i < 2; ++_i) \
;         __builtin_amdgcn_global_load_lds((const unsigned*)((const char*)(gbase) + (voff)[_i]), (PG8_LAS unsigned*)(lds + (bufoff) + ldsw + _i * 8192), 16, 0, 0); } while (0)
; #define PG8_LDA(dst, b, h) do { _Pragma("unroll") for (int m = 0; m < 4; ++m) _Pragma("unroll") for (int k = 0; k < 2; ++k) dst[m][k] = *(const PG8_LAS bf16x8*)(lds + PG8_SA(b, h) + aoff + m * 2048 + k * 1024); } while (0)
; #define PG8_LDB(dst, b, h) do { _Pragma("unroll") for (int n = 0; n < 2; ++n) _Pragma("unroll") for (int k = 0; k < 2; ++k) dst[n][k] = *(const PG8_LAS bf16x8*)(lds + PG8_SB(b, h) + boff + n * 2048 + k * 1024); } while (0)
; #define PG8_MMA(ai, bj, At, Bt) do { __builtin_amdgcn_s_setprio(1); _Pragma("unroll") for (int m = 0; m < 4; ++m) _Pragma("unroll") for (int n = 0; n < 2; ++n) _Pragma("unroll") for (int k = 0; k < 2; ++k) \
;         acc[ai][bj][m][n] = __builtin_amdgcn_mfma_f32_16x16x32_bf16(Bt[n][k], At[m][k], acc[ai][bj][m][n], 0, 0, 0); __builtin_amdgcn_s_setprio(0); } while (0)
; #define PG8_WAIT_V(n) asm volatile("s_waitcnt vmcnt(" #n ")" ::: "memory")
; #define PG8_WAIT_L(n) asm volatile("s_waitcnt lgkmcnt(" #n ")" ::: "memory")
; #define PG8_BAR __builtin_amdgcn_s_barrier()
; #define PG8_SCHED __builtin_amdgcn_sched_barrier(0)
; template <class Epi, class Sched, bool ALIGN_EPI = false, bool SP2 = false, bool KHOOK = false>
; __device__ __forceinline__ void gemm_phase(PG8_LAS unsigned char* lds, const Gemm g, const Sched& S, const Epi& E, const int tid_in) {
;     ...
;             PG8_LDB(B0, 1, 0); PG8_LDB(B1, 1, 1); PG8_SCHED; PG8_LDA(At, 1, 0); PG8_STAGE(PG8_SA(0, 1), a2 + hstep, voffA);
;             PG8_WAIT_V(8); PG8_WAIT_L(0); PG8_BAR; PG8_MMA(0, 0, At, B0); PG8_MMA(0, 1, At, B1); PG8_BAR; PG8_SCHED;
	s_add_i32 s47, 0, 0x18000
	s_add_i32 s50, 0, 0x1c000
	v_add_u32_e32 v152, s47, v137
	v_add_u32_e32 v168, s50, v137
	ds_read_b128 v[140:143], v152
	ds_read_b128 v[144:147], v152 offset:1024
	ds_read_b128 v[148:151], v152 offset:2048
	ds_read_b128 v[152:155], v152 offset:3072
	ds_read_b128 v[156:159], v168
	ds_read_b128 v[160:163], v168 offset:1024
	ds_read_b128 v[164:167], v168 offset:2048
	ds_read_b128 v[168:171], v168 offset:3072
	s_add_u32 s48, s48, 0x80000
	s_addc_u32 s49, s49, 0
	s_mov_b32 m0, s38
	v_lshl_add_u64 v[216:217], s[48:49], 0, v[32:33]
	ds_read_b128 v[172:175], v139 offset:32768
	ds_read_b128 v[176:179], v139 offset:33792
	ds_read_b128 v[180:183], v139 offset:34816
	ds_read_b128 v[184:187], v139 offset:35840
	ds_read_b128 v[188:191], v139 offset:36864
	ds_read_b128 v[198:201], v139 offset:37888
	ds_read_b128 v[202:205], v139 offset:38912
	ds_read_b128 v[206:209], v139 offset:39936
	global_load_lds_dwordx4 v[216:217], off
	v_lshl_add_u64 v[216:217], s[48:49], 0, v[130:131]
	s_mov_b32 m0, s39
	s_nop 0
	global_load_lds_dwordx4 v[216:217], off
	s_waitcnt vmcnt(8)
	s_waitcnt lgkmcnt(0)
	s_barrier
	s_setprio 1
	s_waitcnt lgkmcnt(0)
	v_mfma_f32_16x16x32_bf16 v[126:129], v[140:143], v[172:175], v[126:129]
	v_mfma_f32_16x16x32_bf16 v[122:125], v[148:151], v[172:175], v[122:125]
	v_mfma_f32_16x16x32_bf16 v[110:113], v[140:143], v[180:183], v[110:113]
	v_mfma_f32_16x16x32_bf16 v[106:109], v[148:151], v[180:183], v[106:109]
	v_mfma_f32_16x16x32_bf16 v[94:97], v[140:143], v[188:191], v[94:97]
	v_mfma_f32_16x16x32_bf16 v[90:93], v[148:151], v[188:191], v[90:93]
	v_mfma_f32_16x16x32_bf16 v[78:81], v[140:143], v[202:205], v[78:81]
	v_mfma_f32_16x16x32_bf16 v[74:77], v[148:151], v[202:205], v[74:77]
	v_mfma_f32_16x16x32_bf16 v[126:129], v[144:147], v[176:179], v[126:129]
	v_mfma_f32_16x16x32_bf16 v[122:125], v[152:155], v[176:179], v[122:125]
	v_mfma_f32_16x16x32_bf16 v[110:113], v[144:147], v[184:187], v[110:113]
	v_mfma_f32_16x16x32_bf16 v[106:109], v[152:155], v[184:187], v[106:109]
	v_mfma_f32_16x16x32_bf16 v[94:97], v[144:147], v[198:201], v[94:97]
	v_mfma_f32_16x16x32_bf16 v[90:93], v[152:155], v[198:201], v[90:93]
	v_mfma_f32_16x16x32_bf16 v[78:81], v[144:147], v[206:209], v[78:81]
	v_mfma_f32_16x16x32_bf16 v[74:77], v[152:155], v[206:209], v[74:77]
	v_mfma_f32_16x16x32_bf16 v[118:121], v[156:159], v[172:175], v[118:121]
	v_mfma_f32_16x16x32_bf16 v[114:117], v[164:167], v[172:175], v[114:117]
	v_mfma_f32_16x16x32_bf16 v[102:105], v[156:159], v[180:183], v[102:105]
	v_mfma_f32_16x16x32_bf16 v[98:101], v[164:167], v[180:183], v[98:101]
	v_mfma_f32_16x16x32_bf16 v[86:89], v[156:159], v[188:191], v[86:89]
	v_mfma_f32_16x16x32_bf16 v[82:85], v[164:167], v[188:191], v[82:85]
	v_mfma_f32_16x16x32_bf16 v[70:73], v[156:159], v[202:205], v[70:73]
	v_mfma_f32_16x16x32_bf16 v[66:69], v[164:167], v[202:205], v[66:69]
	v_mfma_f32_16x16x32_bf16 v[118:121], v[160:163], v[176:179], v[118:121]
	v_mfma_f32_16x16x32_bf16 v[114:117], v[168:171], v[176:179], v[114:117]
	v_mfma_f32_16x16x32_bf16 v[102:105], v[160:163], v[184:187], v[102:105]
	v_mfma_f32_16x16x32_bf16 v[98:101], v[168:171], v[184:187], v[98:101]
	v_mfma_f32_16x16x32_bf16 v[86:89], v[160:163], v[198:201], v[86:89]
	v_mfma_f32_16x16x32_bf16 v[82:85], v[168:171], v[198:201], v[82:85]
	v_mfma_f32_16x16x32_bf16 v[70:73], v[160:163], v[206:209], v[70:73]
	v_mfma_f32_16x16x32_bf16 v[66:69], v[168:171], v[206:209], v[66:69]
	s_setprio 0
	s_barrier
; #define PG8_STAGE(bufoff, gbase, voff) do { _Pragma("unroll") for (int _i = 0; _i < 2; ++_i) \
;         __builtin_amdgcn_global_load_lds((const unsigned*)((const char*)(gbase) + (voff)[_i]), (PG8_LAS unsigned*)(lds + (bufoff) + ldsw + _i * 8192), 16, 0, 0); } while (0)
; #define PG8_LDA(dst, b, h) do { _Pragma("unroll") for (int m = 0; m < 4; ++m) _Pragma("unroll") for (int k = 0; k < 2; ++k) dst[m][k] = *(const PG8_LAS bf16x8*)(lds + PG8_SA(b, h) + aoff + m * 2048 + k * 1024); } while (0)
; #define PG8_MMA(ai, bj, At, Bt) do { __builtin_amdgcn_s_setprio(1); _Pragma("unroll") for (int m = 0; m < 4; ++m) _Pragma("unroll") for (int n = 0; n < 2; ++n) _Pragma("unroll") for (int k = 0; k < 2; ++k) \
;         acc[ai][bj][m][n] = __builtin_amdgcn_mfma_f32_16x16x32_bf16(Bt[n][k], At[m][k], acc[ai][bj][m][n], 0, 0, 0); __builtin_amdgcn_s_setprio(0); } while (0)
; #define PG8_WAIT_V(n) asm volatile("s_waitcnt vmcnt(" #n ")" ::: "memory")
; #define PG8_WAIT_L(n) asm volatile("s_waitcnt lgkmcnt(" #n ")" ::: "memory")
; #define PG8_BAR __builtin_amdgcn_s_barrier()
; #define PG8_SCHED __builtin_amdgcn_sched_barrier(0)
; template <class Epi, class Sched, bool ALIGN_EPI = false, bool SP2 = false, bool KHOOK = false>
; __device__ __forceinline__ void gemm_phase(PG8_LAS unsigned char* lds, const Gemm g, const Sched& S, const Epi& E, const int tid_in) {
;     ...
;             PG8_LDA(At, 1, 1); PG8_STAGE(PG8_SB(1, 0), b3, voffB); PG8_STAGE(PG8_SB(1, 1), b3 + hstep, voffB); PG8_STAGE(PG8_SA(1, 0), a3, voffA);
;             PG8_WAIT_V(8); PG8_WAIT_L(0); PG8_BAR; PG8_MMA(1, 0, At, B0); PG8_MMA(1, 1, At, B1); PG8_BAR; PG8_SCHED;
;     ...
;         if constexpr (ALIGN_EPI) { if (wr == 0) PG8_BAR; }
	s_add_i32 s47, s47, s33
	v_lshl_add_u64 v[192:193], v[192:193], 0, s[90:91]
	s_mov_b32 m0, s47
	ds_read_b128 v[172:175], v139 offset:49152
	ds_read_b128 v[176:179], v139 offset:50176
	ds_read_b128 v[180:183], v139 offset:51200
	ds_read_b128 v[184:187], v139 offset:52224
	ds_read_b128 v[188:191], v139 offset:53248
	ds_read_b128 v[198:201], v139 offset:54272
	ds_read_b128 v[202:205], v139 offset:55296
	ds_read_b128 v[206:209], v139 offset:56320
	global_load_lds_dwordx4 v[192:193], off
	s_add_i32 m0, s47, 0x2000
	s_add_u32 s30, s30, 0x80080
	v_lshl_add_u64 v[192:193], v[210:211], 0, s[90:91]
	s_addc_u32 s31, s31, 0
	s_add_i32 s47, s50, s33
	global_load_lds_dwordx4 v[192:193], off
	v_lshl_add_u64 v[192:193], s[30:31], 0, v[32:33]
	s_mov_b32 m0, s47
	s_nop 0
	global_load_lds_dwordx4 v[192:193], off
	v_lshl_add_u64 v[192:193], s[30:31], 0, v[130:131]
	s_add_i32 m0, s47, 0x2000
	s_nop 0
	global_load_lds_dwordx4 v[192:193], off
	v_lshl_add_u64 v[192:193], v[212:213], 0, s[90:91]
	s_mov_b32 m0, s40
	s_nop 0
	global_load_lds_dwordx4 v[192:193], off
	v_lshl_add_u64 v[192:193], v[214:215], 0, s[90:91]
	s_mov_b32 m0, s41
	s_nop 0
	global_load_lds_dwordx4 v[192:193], off
	s_waitcnt vmcnt(8)
	s_waitcnt lgkmcnt(0)
	s_barrier
	s_setprio 1
	s_waitcnt lgkmcnt(0)
	v_mfma_f32_16x16x32_bf16 v[62:65], v[140:143], v[172:175], v[62:65]
	v_mfma_f32_16x16x32_bf16 v[58:61], v[148:151], v[172:175], v[58:61]
	v_mfma_f32_16x16x32_bf16 v[46:49], v[140:143], v[180:183], v[46:49]
	v_mfma_f32_16x16x32_bf16 v[42:45], v[148:151], v[180:183], v[42:45]
	v_mfma_f32_16x16x32_bf16 v[28:31], v[140:143], v[188:191], v[28:31]
	v_mfma_f32_16x16x32_bf16 v[24:27], v[148:151], v[188:191], v[24:27]
	v_mfma_f32_16x16x32_bf16 v[12:15], v[140:143], v[202:205], v[12:15]
	v_mfma_f32_16x16x32_bf16 v[8:11], v[148:151], v[202:205], v[8:11]
	v_mfma_f32_16x16x32_bf16 v[62:65], v[144:147], v[176:179], v[62:65]
	v_mfma_f32_16x16x32_bf16 v[58:61], v[152:155], v[176:179], v[58:61]
	v_mfma_f32_16x16x32_bf16 v[46:49], v[144:147], v[184:187], v[46:49]
	v_mfma_f32_16x16x32_bf16 v[42:45], v[152:155], v[184:187], v[42:45]
	v_mfma_f32_16x16x32_bf16 v[28:31], v[144:147], v[198:201], v[28:31]
	v_mfma_f32_16x16x32_bf16 v[24:27], v[152:155], v[198:201], v[24:27]
	v_mfma_f32_16x16x32_bf16 v[12:15], v[144:147], v[206:209], v[12:15]
	v_mfma_f32_16x16x32_bf16 v[8:11], v[152:155], v[206:209], v[8:11]
	v_mfma_f32_16x16x32_bf16 v[54:57], v[156:159], v[172:175], v[54:57]
	v_mfma_f32_16x16x32_bf16 v[50:53], v[164:167], v[172:175], v[50:53]
	v_mfma_f32_16x16x32_bf16 v[38:41], v[156:159], v[180:183], v[38:41]
	v_mfma_f32_16x16x32_bf16 v[34:37], v[164:167], v[180:183], v[34:37]
	v_mfma_f32_16x16x32_bf16 v[20:23], v[156:159], v[188:191], v[20:23]
	v_mfma_f32_16x16x32_bf16 v[16:19], v[164:167], v[188:191], v[16:19]
	v_mfma_f32_16x16x32_bf16 v[4:7], v[156:159], v[202:205], v[4:7]
	v_mfma_f32_16x16x32_bf16 v[0:3], v[164:167], v[202:205], v[0:3]
	v_mfma_f32_16x16x32_bf16 v[54:57], v[160:163], v[176:179], v[54:57]
	v_mfma_f32_16x16x32_bf16 v[50:53], v[168:171], v[176:179], v[50:53]
	v_mfma_f32_16x16x32_bf16 v[38:41], v[160:163], v[184:187], v[38:41]
	v_mfma_f32_16x16x32_bf16 v[34:37], v[168:171], v[184:187], v[34:37]
	v_mfma_f32_16x16x32_bf16 v[20:23], v[160:163], v[198:201], v[20:23]
	v_mfma_f32_16x16x32_bf16 v[16:19], v[168:171], v[198:201], v[16:19]
	v_mfma_f32_16x16x32_bf16 v[4:7], v[160:163], v[206:209], v[4:7]
	v_mfma_f32_16x16x32_bf16 v[0:3], v[168:171], v[206:209], v[0:3]
	s_setprio 0
	s_barrier
	s_add_i32 s46, s46, 2
	s_add_u32 s26, s26, 0x100
	s_addc_u32 s27, s27, 0
	s_add_u32 s44, s44, 0x100
	s_addc_u32 s45, s45, 0
	s_cmp_gt_u32 s46, 29
	s_cbranch_scc0 .LBB0_1063
	s_and_b64 vcc, exec, s[4:5]
	s_cbranch_vccz .LBB0_1066
	s_barrier

; #define PG8_STAGE(bufoff, gbase, voff) do { _Pragma("unroll") for (int _i = 0; _i < 2; ++_i) \
;         __builtin_amdgcn_global_load_lds((const unsigned*)((const char*)(gbase) + (voff)[_i]), (PG8_LAS unsigned*)(lds + (bufoff) + ldsw + _i * 8192), 16, 0, 0); } while (0)
; #define PG8_LDA(dst, b, h) do { _Pragma("unroll") for (int m = 0; m < 4; ++m) _Pragma("unroll") for (int k = 0; k < 2; ++k) dst[m][k] = *(const PG8_LAS bf16x8*)(lds + PG8_SA(b, h) + aoff + m * 2048 + k * 1024); } while (0)
; #define PG8_LDB(dst, b, h) do { _Pragma("unroll") for (int n = 0; n < 2; ++n) _Pragma("unroll") for (int k = 0; k < 2; ++k) dst[n][k] = *(const PG8_LAS bf16x8*)(lds + PG8_SB(b, h) + boff + n * 2048 + k * 1024); } while (0)
; #define PG8_MMA(ai, bj, At, Bt) do { __builtin_amdgcn_s_setprio(1); _Pragma("unroll") for (int m = 0; m < 4; ++m) _Pragma("unroll") for (int n = 0; n < 2; ++n) _Pragma("unroll") for (int k = 0; k < 2; ++k) \
;         acc[ai][bj][m][n] = __builtin_amdgcn_mfma_f32_16x16x32_bf16(Bt[n][k], At[m][k], acc[ai][bj][m][n], 0, 0, 0); __builtin_amdgcn_s_setprio(0); } while (0)
; #define PG8_WAIT_V(n) asm volatile("s_waitcnt vmcnt(" #n ")" ::: "memory")
; #define PG8_WAIT_L(n) asm volatile("s_waitcnt lgkmcnt(" #n ")" ::: "memory")
; template <class Epi, class Sched, bool ALIGN_EPI = false, bool SP2 = false, bool KHOOK = false>
; __device__ __forceinline__ void gemm_phase(PG8_LAS unsigned char* lds, const Gemm g, const Sched& S, const Epi& E, const int tid_in) {
;     ...
;             const bool last = (t == nt - 2);
;             const char* a1 = cA + (size_t)(t + 1) * kstep;
;             const char* a2 = last ? nA : cA + (size_t)(t + 2) * kstep; const char* b2 = last ? nB : cB + (size_t)(t + 2) * kstep;
;             const char* a3 = a2 + kstep; const char* b3 = b2 + kstep;
;             if (last && has_next) S.a_ready(nxt);
;             if constexpr (SP2) {
;             PG8_LDB(B0, 0, 0); PG8_LDB(B1, 0, 1); PG8_SCHED; PG8_LDA(At, 0, 0); PG8_STAGE(PG8_SA(1, 1), a1 + hstep, voffA);
;             PG8_WAIT_V(8); PG8_WAIT_L(0); PG8_BAR; PG8_MMA(0, 0, At, B0); PG8_MMA(0, 1, At, B1); PG8_BAR; PG8_SCHED;
;             PG8_LDA(At, 0, 1); PG8_STAGE(PG8_SB(0, 0), b2, voffB); PG8_STAGE(PG8_SB(0, 1), b2 + hstep, voffB); PG8_STAGE(PG8_SA(0, 0), a2, voffA);
;             PG8_WAIT_V(8); PG8_WAIT_L(0); PG8_BAR; PG8_MMA(1, 0, At, B0); PG8_MMA(1, 1, At, B1); PG8_BAR; PG8_SCHED;
.LBB0_1086:
	v_cndmask_b32_e64 v172, 0, 1, s[56:57]
	s_add_u32 s56, s14, s46
	s_addc_u32 s57, s15, 0
	s_add_u32 s47, s56, 0x100
	s_addc_u32 s58, s57, 0
	s_and_b64 s[50:51], s[52:53], exec
	s_cselect_b32 s59, s18, s58
	s_cselect_b32 s58, s19, s47
	s_add_u32 s46, s12, s46
	s_addc_u32 s47, s13, 0
	s_add_u32 s50, s46, 0x100
	s_addc_u32 s51, s47, 0
	s_add_i32 s75, 0, 0x10000
	s_and_b64 s[46:47], s[52:53], exec
	s_cselect_b32 s65, s17, s51
	s_cselect_b32 s64, s23, s50
	s_add_i32 s53, 0, 0x14000
	s_add_u32 s70, s56, 0x10080
	s_addc_u32 s71, s57, 0
	s_add_i32 s74, s75, s37
	s_add_i32 m0, s38, 0xc000
	s_add_i32 s81, s38, 0xe000
	s_add_i32 s60, s74, 0x2000
	s_add_u32 s68, s64, 0x10000
	v_add_u32_e32 v152, s75, v137
	v_add_u32_e32 v168, s53, v137
	s_addc_u32 s69, s65, 0
	s_add_i32 s66, s53, s37
	ds_read_b128 v[140:143], v152
	ds_read_b128 v[144:147], v152 offset:1024
	ds_read_b128 v[148:151], v152 offset:2048
	ds_read_b128 v[152:155], v152 offset:3072
	ds_read_b128 v[156:159], v168
	ds_read_b128 v[160:163], v168 offset:1024
	ds_read_b128 v[164:167], v168 offset:2048
	ds_read_b128 v[168:171], v168 offset:3072
	s_add_i32 s61, s66, 0x2000
	s_add_i32 s51, 0, 0x18000
	s_add_i32 s50, 0, 0x1c000
	s_add_u32 s56, s58, 0x10000
	s_addc_u32 s57, s59, 0
	s_add_i32 s47, s51, s37
	s_add_i32 s46, s47, 0x2000
	s_add_u32 s52, s64, 0x10080
	s_addc_u32 s53, s65, 0
	s_add_i32 s79, s50, s37
	s_add_i32 s75, s79, 0x2000
	v_cmp_ne_u32_e32 vcc, 1, v172
	v_lshl_add_u64 v[192:193], s[70:71], 0, v[134:135]
	ds_read_b128 v[172:175], v139
	ds_read_b128 v[176:179], v139 offset:1024
	ds_read_b128 v[180:183], v139 offset:2048
	ds_read_b128 v[184:187], v139 offset:3072
	ds_read_b128 v[188:191], v139 offset:4096
	ds_read_b128 v[198:201], v139 offset:5120
	ds_read_b128 v[202:205], v139 offset:6144
	ds_read_b128 v[206:209], v139 offset:7168
	global_load_lds_dwordx4 v[192:193], off
	v_lshl_add_u64 v[192:193], s[70:71], 0, v[132:133]
	s_mov_b32 m0, s81
	s_nop 0
	global_load_lds_dwordx4 v[192:193], off
	s_waitcnt vmcnt(8)
	s_waitcnt lgkmcnt(0)
	s_barrier
	s_setprio 1
	s_waitcnt lgkmcnt(0)
	v_mfma_f32_16x16x32_bf16 v[126:129], v[140:143], v[172:175], v[126:129]
	v_mfma_f32_16x16x32_bf16 v[122:125], v[148:151], v[172:175], v[122:125]
	v_mfma_f32_16x16x32_bf16 v[118:121], v[140:143], v[180:183], v[118:121]
	v_mfma_f32_16x16x32_bf16 v[114:117], v[148:151], v[180:183], v[114:117]
	v_mfma_f32_16x16x32_bf16 v[102:105], v[140:143], v[188:191], v[102:105]
	v_mfma_f32_16x16x32_bf16 v[98:101], v[148:151], v[188:191], v[98:101]
	v_mfma_f32_16x16x32_bf16 v[86:89], v[140:143], v[202:205], v[86:89]
	v_mfma_f32_16x16x32_bf16 v[82:85], v[148:151], v[202:205], v[82:85]
	v_mfma_f32_16x16x32_bf16 v[126:129], v[144:147], v[176:179], v[126:129]
	v_mfma_f32_16x16x32_bf16 v[122:125], v[152:155], v[176:179], v[122:125]
	v_mfma_f32_16x16x32_bf16 v[118:121], v[144:147], v[184:187], v[118:121]
	v_mfma_f32_16x16x32_bf16 v[114:117], v[152:155], v[184:187], v[114:117]
	v_mfma_f32_16x16x32_bf16 v[102:105], v[144:147], v[198:201], v[102:105]
	v_mfma_f32_16x16x32_bf16 v[98:101], v[152:155], v[198:201], v[98:101]
	v_mfma_f32_16x16x32_bf16 v[86:89], v[144:147], v[206:209], v[86:89]
	v_mfma_f32_16x16x32_bf16 v[82:85], v[152:155], v[206:209], v[82:85]
	v_mfma_f32_16x16x32_bf16 v[110:113], v[156:159], v[172:175], v[110:113]
	v_mfma_f32_16x16x32_bf16 v[106:109], v[164:167], v[172:175], v[106:109]
	v_mfma_f32_16x16x32_bf16 v[94:97], v[156:159], v[180:183], v[94:97]
	v_mfma_f32_16x16x32_bf16 v[90:93], v[164:167], v[180:183], v[90:93]
	v_mfma_f32_16x16x32_bf16 v[78:81], v[156:159], v[188:191], v[78:81]
	v_mfma_f32_16x16x32_bf16 v[74:77], v[164:167], v[188:191], v[74:77]
	v_mfma_f32_16x16x32_bf16 v[70:73], v[156:159], v[202:205], v[70:73]
	v_mfma_f32_16x16x32_bf16 v[66:69], v[164:167], v[202:205], v[66:69]
	v_mfma_f32_16x16x32_bf16 v[110:113], v[160:163], v[176:179], v[110:113]
	v_mfma_f32_16x16x32_bf16 v[106:109], v[168:171], v[176:179], v[106:109]
	v_mfma_f32_16x16x32_bf16 v[94:97], v[160:163], v[184:187], v[94:97]
	v_mfma_f32_16x16x32_bf16 v[90:93], v[168:171], v[184:187], v[90:93]
	v_mfma_f32_16x16x32_bf16 v[78:81], v[160:163], v[198:201], v[78:81]
	v_mfma_f32_16x16x32_bf16 v[74:77], v[168:171], v[198:201], v[74:77]
	v_mfma_f32_16x16x32_bf16 v[70:73], v[160:163], v[206:209], v[70:73]
	v_mfma_f32_16x16x32_bf16 v[66:69], v[168:171], v[206:209], v[66:69]
	s_setprio 0
	s_barrier
	s_mov_b32 m0, s74
	v_lshl_add_u64 v[192:193], s[64:65], 0, v[32:33]
	ds_read_b128 v[172:175], v139 offset:16384
	ds_read_b128 v[176:179], v139 offset:17408
	ds_read_b128 v[180:183], v139 offset:18432
	ds_read_b128 v[184:187], v139 offset:19456
	ds_read_b128 v[188:191], v139 offset:20480
	ds_read_b128 v[198:201], v139 offset:21504
	ds_read_b128 v[202:205], v139 offset:22528
	ds_read_b128 v[206:209], v139 offset:23552
	global_load_lds_dwordx4 v[192:193], off
	v_lshl_add_u64 v[210:211], s[64:65], 0, v[130:131]
	s_mov_b32 m0, s60
	v_lshl_add_u64 v[212:213], s[68:69], 0, v[32:33]
	global_load_lds_dwordx4 v[210:211], off
	s_mov_b32 m0, s66
	v_lshl_add_u64 v[214:215], s[58:59], 0, v[132:133]
	global_load_lds_dwordx4 v[212:213], off
	v_lshl_add_u64 v[212:213], s[68:69], 0, v[130:131]
	s_mov_b32 m0, s61
	s_nop 0
	global_load_lds_dwordx4 v[212:213], off
	v_lshl_add_u64 v[212:213], s[58:59], 0, v[134:135]
	s_mov_b32 m0, s38
	s_nop 0
	global_load_lds_dwordx4 v[212:213], off
	s_mov_b32 m0, s39
	s_nop 0
	global_load_lds_dwordx4 v[214:215], off
	s_waitcnt vmcnt(8)
	s_waitcnt lgkmcnt(0)
	s_barrier
; #define PG8_STAGE(bufoff, gbase, voff) do { _Pragma("unroll") for (int _i = 0; _i < 2; ++_i) \
;         __builtin_amdgcn_global_load_lds((const unsigned*)((const char*)(gbase) + (voff)[_i]), (PG8_LAS unsigned*)(lds + (bufoff) + ldsw + _i * 8192), 16, 0, 0); } while (0)
; #define PG8_LDA(dst, b, h) do { _Pragma("unroll") for (int m = 0; m < 4; ++m) _Pragma("unroll") for (int k = 0; k < 2; ++k) dst[m][k] = *(const PG8_LAS bf16x8*)(lds + PG8_SA(b, h) + aoff + m * 2048 + k * 1024); } while (0)
; #define PG8_LDB(dst, b, h) do { _Pragma("unroll") for (int n = 0; n < 2; ++n) _Pragma("unroll") for (int k = 0; k < 2; ++k) dst[n][k] = *(const PG8_LAS bf16x8*)(lds + PG8_SB(b, h) + boff + n * 2048 + k * 1024); } while (0)
; #define PG8_MMA(ai, bj, At, Bt) do { __builtin_amdgcn_s_setprio(1); _Pragma("unroll") for (int m = 0; m < 4; ++m) _Pragma("unroll") for (int n = 0; n < 2; ++n) _Pragma("unroll") for (int k = 0; k < 2; ++k) \
;         acc[ai][bj][m][n] = __builtin_amdgcn_mfma_f32_16x16x32_bf16(Bt[n][k], At[m][k], acc[ai][bj][m][n], 0, 0, 0); __builtin_amdgcn_s_setprio(0); } while (0)
; #define PG8_WAIT_V(n) asm volatile("s_waitcnt vmcnt(" #n ")" ::: "memory")
; #define PG8_WAIT_L(n) asm volatile("s_waitcnt lgkmcnt(" #n ")" ::: "memory")
; #define PG8_BAR __builtin_amdgcn_s_barrier()
; #define PG8_SCHED __builtin_amdgcn_sched_barrier(0)
; template <class Epi, class Sched, bool ALIGN_EPI = false, bool SP2 = false, bool KHOOK = false>
; __device__ __forceinline__ void gemm_phase(PG8_LAS unsigned char* lds, const Gemm g, const Sched& S, const Epi& E, const int tid_in) {
;     ...
;             PG8_WAIT_V(8); PG8_WAIT_L(0); PG8_BAR; PG8_MMA(1, 0, At, B0); PG8_MMA(1, 1, At, B1); PG8_BAR; PG8_SCHED;
;             PG8_LDB(B0, 1, 0); PG8_LDB(B1, 1, 1); PG8_SCHED; PG8_LDA(At, 1, 0); PG8_STAGE(PG8_SA(0, 1), a2 + hstep, voffA);
;             PG8_WAIT_V(8); PG8_WAIT_L(0); PG8_BAR; PG8_MMA(0, 0, At, B0); PG8_MMA(0, 1, At, B1); PG8_BAR; PG8_SCHED;
	s_setprio 1
	s_waitcnt lgkmcnt(0)
	v_mfma_f32_16x16x32_bf16 v[62:65], v[140:143], v[172:175], v[62:65]
	v_mfma_f32_16x16x32_bf16 v[58:61], v[148:151], v[172:175], v[58:61]
	v_mfma_f32_16x16x32_bf16 v[54:57], v[140:143], v[180:183], v[54:57]
	v_mfma_f32_16x16x32_bf16 v[50:53], v[148:151], v[180:183], v[50:53]
	v_mfma_f32_16x16x32_bf16 v[38:41], v[140:143], v[188:191], v[38:41]
	v_mfma_f32_16x16x32_bf16 v[34:37], v[148:151], v[188:191], v[34:37]
	v_mfma_f32_16x16x32_bf16 v[20:23], v[140:143], v[202:205], v[20:23]
	v_mfma_f32_16x16x32_bf16 v[16:19], v[148:151], v[202:205], v[16:19]
	v_mfma_f32_16x16x32_bf16 v[62:65], v[144:147], v[176:179], v[62:65]
	v_mfma_f32_16x16x32_bf16 v[58:61], v[152:155], v[176:179], v[58:61]
	v_mfma_f32_16x16x32_bf16 v[54:57], v[144:147], v[184:187], v[54:57]
	v_mfma_f32_16x16x32_bf16 v[50:53], v[152:155], v[184:187], v[50:53]
	v_mfma_f32_16x16x32_bf16 v[38:41], v[144:147], v[198:201], v[38:41]
	v_mfma_f32_16x16x32_bf16 v[34:37], v[152:155], v[198:201], v[34:37]
	v_mfma_f32_16x16x32_bf16 v[20:23], v[144:147], v[206:209], v[20:23]
	v_mfma_f32_16x16x32_bf16 v[16:19], v[152:155], v[206:209], v[16:19]
	v_mfma_f32_16x16x32_bf16 v[46:49], v[156:159], v[172:175], v[46:49]
	v_mfma_f32_16x16x32_bf16 v[42:45], v[164:167], v[172:175], v[42:45]
	v_mfma_f32_16x16x32_bf16 v[28:31], v[156:159], v[180:183], v[28:31]
	v_mfma_f32_16x16x32_bf16 v[24:27], v[164:167], v[180:183], v[24:27]
	v_mfma_f32_16x16x32_bf16 v[12:15], v[156:159], v[188:191], v[12:15]
	v_mfma_f32_16x16x32_bf16 v[8:11], v[164:167], v[188:191], v[8:11]
	v_mfma_f32_16x16x32_bf16 v[4:7], v[156:159], v[202:205], v[4:7]
	v_mfma_f32_16x16x32_bf16 v[0:3], v[164:167], v[202:205], v[0:3]
	v_mfma_f32_16x16x32_bf16 v[46:49], v[160:163], v[176:179], v[46:49]
	v_mfma_f32_16x16x32_bf16 v[42:45], v[168:171], v[176:179], v[42:45]
	v_mfma_f32_16x16x32_bf16 v[28:31], v[160:163], v[184:187], v[28:31]
	v_mfma_f32_16x16x32_bf16 v[24:27], v[168:171], v[184:187], v[24:27]
	v_mfma_f32_16x16x32_bf16 v[12:15], v[160:163], v[198:201], v[12:15]
	v_mfma_f32_16x16x32_bf16 v[8:11], v[168:171], v[198:201], v[8:11]
	v_mfma_f32_16x16x32_bf16 v[4:7], v[160:163], v[206:209], v[4:7]
	v_mfma_f32_16x16x32_bf16 v[0:3], v[168:171], v[206:209], v[0:3]
	s_setprio 0
	s_barrier
	v_add_u32_e32 v152, s51, v137
	v_add_u32_e32 v168, s50, v137
	ds_read_b128 v[140:143], v152
	ds_read_b128 v[144:147], v152 offset:1024
	ds_read_b128 v[148:151], v152 offset:2048
	ds_read_b128 v[152:155], v152 offset:3072
	ds_read_b128 v[156:159], v168
	ds_read_b128 v[160:163], v168 offset:1024
	ds_read_b128 v[164:167], v168 offset:2048
	ds_read_b128 v[168:171], v168 offset:3072
	s_mov_b32 m0, s40
	v_lshl_add_u64 v[216:217], s[56:57], 0, v[134:135]
	ds_read_b128 v[172:175], v139 offset:32768
	ds_read_b128 v[176:179], v139 offset:33792
	ds_read_b128 v[180:183], v139 offset:34816
	ds_read_b128 v[184:187], v139 offset:35840
	ds_read_b128 v[188:191], v139 offset:36864
	ds_read_b128 v[198:201], v139 offset:37888
	ds_read_b128 v[202:205], v139 offset:38912
	ds_read_b128 v[206:209], v139 offset:39936
	global_load_lds_dwordx4 v[216:217], off
	v_lshl_add_u64 v[216:217], s[56:57], 0, v[132:133]
	s_mov_b32 m0, s41
	s_nop 0
	global_load_lds_dwordx4 v[216:217], off
	s_waitcnt vmcnt(8)
	s_waitcnt lgkmcnt(0)
	s_barrier
	s_setprio 1
	s_waitcnt lgkmcnt(0)
	v_mfma_f32_16x16x32_bf16 v[126:129], v[140:143], v[172:175], v[126:129]
	v_mfma_f32_16x16x32_bf16 v[122:125], v[148:151], v[172:175], v[122:125]
	v_mfma_f32_16x16x32_bf16 v[118:121], v[140:143], v[180:183], v[118:121]
	v_mfma_f32_16x16x32_bf16 v[114:117], v[148:151], v[180:183], v[114:117]
	v_mfma_f32_16x16x32_bf16 v[102:105], v[140:143], v[188:191], v[102:105]
	v_mfma_f32_16x16x32_bf16 v[98:101], v[148:151], v[188:191], v[98:101]
	v_mfma_f32_16x16x32_bf16 v[86:89], v[140:143], v[202:205], v[86:89]
	v_mfma_f32_16x16x32_bf16 v[82:85], v[148:151], v[202:205], v[82:85]
	v_mfma_f32_16x16x32_bf16 v[126:129], v[144:147], v[176:179], v[126:129]
	v_mfma_f32_16x16x32_bf16 v[122:125], v[152:155], v[176:179], v[122:125]
	v_mfma_f32_16x16x32_bf16 v[118:121], v[144:147], v[184:187], v[118:121]
	v_mfma_f32_16x16x32_bf16 v[114:117], v[152:155], v[184:187], v[114:117]
	v_mfma_f32_16x16x32_bf16 v[102:105], v[144:147], v[198:201], v[102:105]
	v_mfma_f32_16x16x32_bf16 v[98:101], v[152:155], v[198:201], v[98:101]
	v_mfma_f32_16x16x32_bf16 v[86:89], v[144:147], v[206:209], v[86:89]
	v_mfma_f32_16x16x32_bf16 v[82:85], v[152:155], v[206:209], v[82:85]
	v_mfma_f32_16x16x32_bf16 v[110:113], v[156:159], v[172:175], v[110:113]
	v_mfma_f32_16x16x32_bf16 v[106:109], v[164:167], v[172:175], v[106:109]
	v_mfma_f32_16x16x32_bf16 v[94:97], v[156:159], v[180:183], v[94:97]
	v_mfma_f32_16x16x32_bf16 v[90:93], v[164:167], v[180:183], v[90:93]
	v_mfma_f32_16x16x32_bf16 v[78:81], v[156:159], v[188:191], v[78:81]
	v_mfma_f32_16x16x32_bf16 v[74:77], v[164:167], v[188:191], v[74:77]
	v_mfma_f32_16x16x32_bf16 v[70:73], v[156:159], v[202:205], v[70:73]
	v_mfma_f32_16x16x32_bf16 v[66:69], v[164:167], v[202:205], v[66:69]
	v_mfma_f32_16x16x32_bf16 v[110:113], v[160:163], v[176:179], v[110:113]
	v_mfma_f32_16x16x32_bf16 v[106:109], v[168:171], v[176:179], v[106:109]
	v_mfma_f32_16x16x32_bf16 v[94:97], v[160:163], v[184:187], v[94:97]
	v_mfma_f32_16x16x32_bf16 v[90:93], v[168:171], v[184:187], v[90:93]
	v_mfma_f32_16x16x32_bf16 v[78:81], v[160:163], v[198:201], v[78:81]
	v_mfma_f32_16x16x32_bf16 v[74:77], v[168:171], v[198:201], v[74:77]
	v_mfma_f32_16x16x32_bf16 v[70:73], v[160:163], v[206:209], v[70:73]
	v_mfma_f32_16x16x32_bf16 v[66:69], v[168:171], v[206:209], v[66:69]
	s_setprio 0
	s_barrier
; #define PG8_STAGE(bufoff, gbase, voff) do { _Pragma("unroll") for (int _i = 0; _i < 2; ++_i) \
;         __builtin_amdgcn_global_load_lds((const unsigned*)((const char*)(gbase) + (voff)[_i]), (PG8_LAS unsigned*)(lds + (bufoff) + ldsw + _i * 8192), 16, 0, 0); } while (0)
; #define PG8_LDA(dst, b, h) do { _Pragma("unroll") for (int m = 0; m < 4; ++m) _Pragma("unroll") for (int k = 0; k < 2; ++k) dst[m][k] = *(const PG8_LAS bf16x8*)(lds + PG8_SA(b, h) + aoff + m * 2048 + k * 1024); } while (0)
; #define PG8_MMA(ai, bj, At, Bt) do { __builtin_amdgcn_s_setprio(1); _Pragma("unroll") for (int m = 0; m < 4; ++m) _Pragma("unroll") for (int n = 0; n < 2; ++n) _Pragma("unroll") for (int k = 0; k < 2; ++k) \
;         acc[ai][bj][m][n] = __builtin_amdgcn_mfma_f32_16x16x32_bf16(Bt[n][k], At[m][k], acc[ai][bj][m][n], 0, 0, 0); __builtin_amdgcn_s_setprio(0); } while (0)
; #define PG8_WAIT_V(n) asm volatile("s_waitcnt vmcnt(" #n ")" ::: "memory")
; #define PG8_WAIT_L(n) asm volatile("s_waitcnt lgkmcnt(" #n ")" ::: "memory")
; #define PG8_BAR __builtin_amdgcn_s_barrier()
; #define PG8_SCHED __builtin_amdgcn_sched_barrier(0)
; template <class Epi, class Sched, bool ALIGN_EPI = false, bool SP2 = false, bool KHOOK = false>
; __device__ __forceinline__ void gemm_phase(PG8_LAS unsigned char* lds, const Gemm g, const Sched& S, const Epi& E, const int tid_in) {
;     ...
;             PG8_LDA(At, 1, 1); PG8_STAGE(PG8_SB(1, 0), b3, voffB); PG8_STAGE(PG8_SB(1, 1), b3 + hstep, voffB); PG8_STAGE(PG8_SA(1, 0), a3, voffA);
;             PG8_WAIT_V(8); PG8_WAIT_L(0); PG8_BAR; PG8_MMA(1, 0, At, B0); PG8_MMA(1, 1, At, B1); PG8_BAR; PG8_SCHED;
	s_mov_b32 m0, s47
	v_lshl_add_u64 v[192:193], v[192:193], 0, s[90:91]
	ds_read_b128 v[172:175], v139 offset:49152
	ds_read_b128 v[176:179], v139 offset:50176
	ds_read_b128 v[180:183], v139 offset:51200
	ds_read_b128 v[184:187], v139 offset:52224
	ds_read_b128 v[188:191], v139 offset:53248
	ds_read_b128 v[198:201], v139 offset:54272
	ds_read_b128 v[202:205], v139 offset:55296
	ds_read_b128 v[206:209], v139 offset:56320
	global_load_lds_dwordx4 v[192:193], off
	v_lshl_add_u64 v[192:193], v[210:211], 0, s[90:91]
	s_mov_b32 m0, s46
	s_nop 0
	global_load_lds_dwordx4 v[192:193], off
	v_lshl_add_u64 v[192:193], s[52:53], 0, v[32:33]
	s_mov_b32 m0, s79
	s_nop 0
	global_load_lds_dwordx4 v[192:193], off
	v_lshl_add_u64 v[192:193], s[52:53], 0, v[130:131]
	s_mov_b32 m0, s75
	s_nop 0
	global_load_lds_dwordx4 v[192:193], off
	v_lshl_add_u64 v[192:193], v[212:213], 0, s[90:91]
	s_mov_b32 m0, s24
	s_nop 0
	global_load_lds_dwordx4 v[192:193], off
	v_lshl_add_u64 v[192:193], v[214:215], 0, s[90:91]
	s_mov_b32 m0, s25
	s_nop 0
	global_load_lds_dwordx4 v[192:193], off
	s_waitcnt vmcnt(8)
	s_waitcnt lgkmcnt(0)
	s_barrier
	s_setprio 1
	s_waitcnt lgkmcnt(0)
	v_mfma_f32_16x16x32_bf16 v[62:65], v[140:143], v[172:175], v[62:65]
	v_mfma_f32_16x16x32_bf16 v[58:61], v[148:151], v[172:175], v[58:61]
	v_mfma_f32_16x16x32_bf16 v[54:57], v[140:143], v[180:183], v[54:57]
	v_mfma_f32_16x16x32_bf16 v[50:53], v[148:151], v[180:183], v[50:53]
	v_mfma_f32_16x16x32_bf16 v[38:41], v[140:143], v[188:191], v[38:41]
	v_mfma_f32_16x16x32_bf16 v[34:37], v[148:151], v[188:191], v[34:37]
	v_mfma_f32_16x16x32_bf16 v[20:23], v[140:143], v[202:205], v[20:23]
	v_mfma_f32_16x16x32_bf16 v[16:19], v[148:151], v[202:205], v[16:19]
	v_mfma_f32_16x16x32_bf16 v[62:65], v[144:147], v[176:179], v[62:65]
	v_mfma_f32_16x16x32_bf16 v[58:61], v[152:155], v[176:179], v[58:61]
	v_mfma_f32_16x16x32_bf16 v[54:57], v[144:147], v[184:187], v[54:57]
	v_mfma_f32_16x16x32_bf16 v[50:53], v[152:155], v[184:187], v[50:53]
	v_mfma_f32_16x16x32_bf16 v[38:41], v[144:147], v[198:201], v[38:41]
	v_mfma_f32_16x16x32_bf16 v[34:37], v[152:155], v[198:201], v[34:37]
	v_mfma_f32_16x16x32_bf16 v[20:23], v[144:147], v[206:209], v[20:23]
	v_mfma_f32_16x16x32_bf16 v[16:19], v[152:155], v[206:209], v[16:19]
	v_mfma_f32_16x16x32_bf16 v[46:49], v[156:159], v[172:175], v[46:49]
	v_mfma_f32_16x16x32_bf16 v[42:45], v[164:167], v[172:175], v[42:45]
	v_mfma_f32_16x16x32_bf16 v[28:31], v[156:159], v[180:183], v[28:31]
	v_mfma_f32_16x16x32_bf16 v[24:27], v[164:167], v[180:183], v[24:27]
	v_mfma_f32_16x16x32_bf16 v[12:15], v[156:159], v[188:191], v[12:15]
	v_mfma_f32_16x16x32_bf16 v[8:11], v[164:167], v[188:191], v[8:11]
	v_mfma_f32_16x16x32_bf16 v[4:7], v[156:159], v[202:205], v[4:7]
	v_mfma_f32_16x16x32_bf16 v[0:3], v[164:167], v[202:205], v[0:3]
	v_mfma_f32_16x16x32_bf16 v[46:49], v[160:163], v[176:179], v[46:49]
	v_mfma_f32_16x16x32_bf16 v[42:45], v[168:171], v[176:179], v[42:45]
	v_mfma_f32_16x16x32_bf16 v[28:31], v[160:163], v[184:187], v[28:31]
	v_mfma_f32_16x16x32_bf16 v[24:27], v[168:171], v[184:187], v[24:27]
	v_mfma_f32_16x16x32_bf16 v[12:15], v[160:163], v[198:201], v[12:15]
	v_mfma_f32_16x16x32_bf16 v[8:11], v[168:171], v[198:201], v[8:11]
	v_mfma_f32_16x16x32_bf16 v[4:7], v[160:163], v[206:209], v[4:7]
	v_mfma_f32_16x16x32_bf16 v[0:3], v[168:171], v[206:209], v[0:3]
	s_setprio 0
	s_barrier
	s_movk_i32 s46, 0x100
	s_mov_b64 s[56:57], 0
	s_mov_b64 s[52:53], -1
	s_cbranch_vccz .LBB0_1086
	s_and_b64 vcc, exec, s[10:11]
	s_cbranch_vccz .LBB0_1089
	s_barrier

; #define PG8_STAGE(bufoff, gbase, voff) do { _Pragma("unroll") for (int _i = 0; _i < 2; ++_i) \
;         __builtin_amdgcn_global_load_lds((const unsigned*)((const char*)(gbase) + (voff)[_i]), (PG8_LAS unsigned*)(lds + (bufoff) + ldsw + _i * 8192), 16, 0, 0); } while (0)
; #define PG8_LDA(dst, b, h) do { _Pragma("unroll") for (int m = 0; m < 4; ++m) _Pragma("unroll") for (int k = 0; k < 2; ++k) dst[m][k] = *(const PG8_LAS bf16x8*)(lds + PG8_SA(b, h) + aoff + m * 2048 + k * 1024); } while (0)
; #define PG8_LDB(dst, b, h) do { _Pragma("unroll") for (int n = 0; n < 2; ++n) _Pragma("unroll") for (int k = 0; k < 2; ++k) dst[n][k] = *(const PG8_LAS bf16x8*)(lds + PG8_SB(b, h) + boff + n * 2048 + k * 1024); } while (0)
; #define PG8_MMA(ai, bj, At, Bt) do { __builtin_amdgcn_s_setprio(1); _Pragma("unroll") for (int m = 0; m < 4; ++m) _Pragma("unroll") for (int n = 0; n < 2; ++n) _Pragma("unroll") for (int k = 0; k < 2; ++k) \
;         acc[ai][bj][m][n] = __builtin_amdgcn_mfma_f32_16x16x32_bf16(Bt[n][k], At[m][k], acc[ai][bj][m][n], 0, 0, 0); __builtin_amdgcn_s_setprio(0); } while (0)
; #define PG8_WAIT_V(n) asm volatile("s_waitcnt vmcnt(" #n ")" ::: "memory")
; #define PG8_WAIT_L(n) asm volatile("s_waitcnt lgkmcnt(" #n ")" ::: "memory")
; #define PG8_BAR __builtin_amdgcn_s_barrier()
; #define PG8_SCHED __builtin_amdgcn_sched_barrier(0)
; template <class Epi, class Sched, bool ALIGN_EPI = false, bool SP2 = false, bool KHOOK = false>
; __device__ __forceinline__ void gemm_phase(PG8_LAS unsigned char* lds, const Gemm g, const Sched& S, const Epi& E, const int tid_in) {
;     ...
;             const bool last = (t == nt - 2);
;             const char* a1 = cA + (size_t)(t + 1) * kstep;
;             const char* a2 = last ? nA : cA + (size_t)(t + 2) * kstep; const char* b2 = last ? nB : cB + (size_t)(t + 2) * kstep;
;             const char* a3 = a2 + kstep; const char* b3 = b2 + kstep;
;             if (last && has_next) S.a_ready(nxt);
;             if constexpr (SP2) {
;             PG8_LDB(B0, 0, 0); PG8_LDB(B1, 0, 1); PG8_SCHED; PG8_LDA(At, 0, 0); PG8_STAGE(PG8_SA(1, 1), a1 + hstep, voffA);
;             PG8_WAIT_V(8); PG8_WAIT_L(0); PG8_BAR; PG8_MMA(0, 0, At, B0); PG8_MMA(0, 1, At, B1); PG8_BAR; PG8_SCHED;
;             PG8_LDA(At, 0, 1); PG8_STAGE(PG8_SB(0, 0), b2, voffB); PG8_STAGE(PG8_SB(0, 1), b2 + hstep, voffB); PG8_STAGE(PG8_SA(0, 0), a2, voffA);
.LBB0_1170:
	s_add_u32 s26, s10, s22
	s_addc_u32 s27, s11, s23
	s_add_u32 s26, s26, 0x100
	s_addc_u32 s27, s27, 0
	s_add_u32 s51, s18, s22
	s_addc_u32 s52, s19, s23
	s_add_i32 s53, 0, 0x10000
	s_cmpk_eq_i32 s22, 0x2b00
	s_cselect_b32 s31, s17, s27
	s_cselect_b32 s30, s16, s26
	s_cselect_b32 s27, s15, s52
	s_cselect_b32 s26, s14, s51
	s_add_i32 s51, 0, 0x14000
	v_add_u32_e32 v158, s53, v144
	v_add_u32_e32 v170, s51, v144
	ds_read_b128 v[146:149], v158
	ds_read_b128 v[150:153], v158 offset:1024
	ds_read_b128 v[154:157], v158 offset:2048
	ds_read_b128 v[158:161], v158 offset:3072
	ds_read_b128 v[162:165], v170
	ds_read_b128 v[166:169], v170 offset:1024
	ds_read_b128 v[176:179], v170 offset:2048
	ds_read_b128 v[180:183], v170 offset:3072
	v_lshl_add_u64 v[170:171], v[140:141], 0, s[22:23]
	s_add_i32 m0, s40, 0xc000
	ds_read_b128 v[184:187], v145
	ds_read_b128 v[188:191], v145 offset:1024
	ds_read_b128 v[198:201], v145 offset:2048
	ds_read_b128 v[202:205], v145 offset:3072
	ds_read_b128 v[206:209], v145 offset:4096
	ds_read_b128 v[210:213], v145 offset:5120
	ds_read_b128 v[214:217], v145 offset:6144
	ds_read_b128 v[218:221], v145 offset:7168
	global_load_lds_dwordx4 v[170:171], off
	v_lshl_add_u64 v[170:171], v[142:143], 0, s[22:23]
	s_add_i32 m0, s40, 0xe000
	s_nop 0
	global_load_lds_dwordx4 v[170:171], off
	s_waitcnt vmcnt(8)
	s_waitcnt lgkmcnt(0)
	s_barrier
	s_setprio 1
	s_waitcnt lgkmcnt(0)
	v_mfma_f32_16x16x32_bf16 v[118:121], v[146:149], v[184:187], v[118:121]
	v_mfma_f32_16x16x32_bf16 v[114:117], v[154:157], v[184:187], v[114:117]
	v_mfma_f32_16x16x32_bf16 v[134:137], v[146:149], v[198:201], v[134:137]
	v_mfma_f32_16x16x32_bf16 v[130:133], v[154:157], v[198:201], v[130:133]
	v_mfma_f32_16x16x32_bf16 v[94:97], v[146:149], v[206:209], v[94:97]
	v_mfma_f32_16x16x32_bf16 v[90:93], v[154:157], v[206:209], v[90:93]
	v_mfma_f32_16x16x32_bf16 v[78:81], v[146:149], v[214:217], v[78:81]
	v_mfma_f32_16x16x32_bf16 v[74:77], v[154:157], v[214:217], v[74:77]
	v_mfma_f32_16x16x32_bf16 v[118:121], v[150:153], v[188:191], v[118:121]
	v_mfma_f32_16x16x32_bf16 v[114:117], v[158:161], v[188:191], v[114:117]
	v_mfma_f32_16x16x32_bf16 v[134:137], v[150:153], v[202:205], v[134:137]
	v_mfma_f32_16x16x32_bf16 v[130:133], v[158:161], v[202:205], v[130:133]
	v_mfma_f32_16x16x32_bf16 v[94:97], v[150:153], v[210:213], v[94:97]
	v_mfma_f32_16x16x32_bf16 v[90:93], v[158:161], v[210:213], v[90:93]
	v_mfma_f32_16x16x32_bf16 v[78:81], v[150:153], v[218:221], v[78:81]
	v_mfma_f32_16x16x32_bf16 v[74:77], v[158:161], v[218:221], v[74:77]
	v_mfma_f32_16x16x32_bf16 v[102:105], v[162:165], v[184:187], v[102:105]
	v_mfma_f32_16x16x32_bf16 v[98:101], v[176:179], v[184:187], v[98:101]
	v_mfma_f32_16x16x32_bf16 v[110:113], v[162:165], v[198:201], v[110:113]
	v_mfma_f32_16x16x32_bf16 v[106:109], v[176:179], v[198:201], v[106:109]
	v_mfma_f32_16x16x32_bf16 v[86:89], v[162:165], v[206:209], v[86:89]
	v_mfma_f32_16x16x32_bf16 v[82:85], v[176:179], v[206:209], v[82:85]
	v_mfma_f32_16x16x32_bf16 v[70:73], v[162:165], v[214:217], v[70:73]
	v_mfma_f32_16x16x32_bf16 v[66:69], v[176:179], v[214:217], v[66:69]
	v_mfma_f32_16x16x32_bf16 v[102:105], v[166:169], v[188:191], v[102:105]
	v_mfma_f32_16x16x32_bf16 v[98:101], v[180:183], v[188:191], v[98:101]
	v_mfma_f32_16x16x32_bf16 v[110:113], v[166:169], v[202:205], v[110:113]
	v_mfma_f32_16x16x32_bf16 v[106:109], v[180:183], v[202:205], v[106:109]
	v_mfma_f32_16x16x32_bf16 v[86:89], v[166:169], v[210:213], v[86:89]
	v_mfma_f32_16x16x32_bf16 v[82:85], v[180:183], v[210:213], v[82:85]
	v_mfma_f32_16x16x32_bf16 v[70:73], v[166:169], v[218:221], v[70:73]
	v_mfma_f32_16x16x32_bf16 v[66:69], v[180:183], v[218:221], v[66:69]
	s_setprio 0
	s_barrier
	s_add_i32 s52, s53, s39
	v_lshl_add_u64 v[170:171], s[26:27], 0, v[32:33]
	s_mov_b32 m0, s52
	ds_read_b128 v[184:187], v145 offset:16384
	ds_read_b128 v[188:191], v145 offset:17408
	ds_read_b128 v[198:201], v145 offset:18432
	ds_read_b128 v[202:205], v145 offset:19456
	ds_read_b128 v[206:209], v145 offset:20480
	ds_read_b128 v[210:213], v145 offset:21504
	ds_read_b128 v[214:217], v145 offset:22528
	ds_read_b128 v[218:221], v145 offset:23552
	global_load_lds_dwordx4 v[170:171], off
	s_add_i32 m0, s52, 0x2000
	s_add_u32 s52, s26, 0x160000
	v_lshl_add_u64 v[192:193], s[26:27], 0, v[122:123]
	s_addc_u32 s53, s27, 0
	s_add_i32 s51, s51, s39
	global_load_lds_dwordx4 v[192:193], off
	v_lshl_add_u64 v[222:223], s[52:53], 0, v[32:33]
	s_mov_b32 m0, s51
	v_lshl_add_u64 v[224:225], s[30:31], 0, v[124:125]
	global_load_lds_dwordx4 v[222:223], off
	v_lshl_add_u64 v[222:223], s[52:53], 0, v[122:123]
	s_add_i32 m0, s51, 0x2000
	s_nop 0
	global_load_lds_dwordx4 v[222:223], off
	v_lshl_add_u64 v[222:223], s[30:31], 0, v[126:127]
	s_mov_b32 m0, s40
	s_nop 0
	global_load_lds_dwordx4 v[222:223], off
	s_mov_b32 m0, s41
	s_nop 0
	global_load_lds_dwordx4 v[224:225], off
	s_waitcnt vmcnt(8)
	s_waitcnt lgkmcnt(0)
	s_barrier
; #define PG8_STAGE(bufoff, gbase, voff) do { _Pragma("unroll") for (int _i = 0; _i < 2; ++_i) \
;         __builtin_amdgcn_global_load_lds((const unsigned*)((const char*)(gbase) + (voff)[_i]), (PG8_LAS unsigned*)(lds + (bufoff) + ldsw + _i * 8192), 16, 0, 0); } while (0)
; #define PG8_LDA(dst, b, h) do { _Pragma("unroll") for (int m = 0; m < 4; ++m) _Pragma("unroll") for (int k = 0; k < 2; ++k) dst[m][k] = *(const PG8_LAS bf16x8*)(lds + PG8_SA(b, h) + aoff + m * 2048 + k * 1024); } while (0)
; #define PG8_LDB(dst, b, h) do { _Pragma("unroll") for (int n = 0; n < 2; ++n) _Pragma("unroll") for (int k = 0; k < 2; ++k) dst[n][k] = *(const PG8_LAS bf16x8*)(lds + PG8_SB(b, h) + boff + n * 2048 + k * 1024); } while (0)
; #define PG8_MMA(ai, bj, At, Bt) do { __builtin_amdgcn_s_setprio(1); _Pragma("unroll") for (int m = 0; m < 4; ++m) _Pragma("unroll") for (int n = 0; n < 2; ++n) _Pragma("unroll") for (int k = 0; k < 2; ++k) \
;         acc[ai][bj][m][n] = __builtin_amdgcn_mfma_f32_16x16x32_bf16(Bt[n][k], At[m][k], acc[ai][bj][m][n], 0, 0, 0); __builtin_amdgcn_s_setprio(0); } while (0)
; #define PG8_WAIT_V(n) asm volatile("s_waitcnt vmcnt(" #n ")" ::: "memory")
; #define PG8_WAIT_L(n) asm volatile("s_waitcnt lgkmcnt(" #n ")" ::: "memory")
; #define PG8_BAR __builtin_amdgcn_s_barrier()
; #define PG8_SCHED __builtin_amdgcn_sched_barrier(0)
; template <class Epi, class Sched, bool ALIGN_EPI = false, bool SP2 = false, bool KHOOK = false>
; __device__ __forceinline__ void gemm_phase(PG8_LAS unsigned char* lds, const Gemm g, const Sched& S, const Epi& E, const int tid_in) {
;     ...
;             PG8_WAIT_V(8); PG8_WAIT_L(0); PG8_BAR; PG8_MMA(1, 0, At, B0); PG8_MMA(1, 1, At, B1); PG8_BAR; PG8_SCHED;
;             PG8_LDB(B0, 1, 0); PG8_LDB(B1, 1, 1); PG8_SCHED; PG8_LDA(At, 1, 0); PG8_STAGE(PG8_SA(0, 1), a2 + hstep, voffA);
;             PG8_WAIT_V(8); PG8_WAIT_L(0); PG8_BAR; PG8_MMA(0, 0, At, B0); PG8_MMA(0, 1, At, B1); PG8_BAR; PG8_SCHED;
	s_setprio 1
	s_waitcnt lgkmcnt(0)
	v_mfma_f32_16x16x32_bf16 v[62:65], v[146:149], v[184:187], v[62:65]
	v_mfma_f32_16x16x32_bf16 v[58:61], v[154:157], v[184:187], v[58:61]
	v_mfma_f32_16x16x32_bf16 v[46:49], v[146:149], v[198:201], v[46:49]
	v_mfma_f32_16x16x32_bf16 v[42:45], v[154:157], v[198:201], v[42:45]
	v_mfma_f32_16x16x32_bf16 v[28:31], v[146:149], v[206:209], v[28:31]
	v_mfma_f32_16x16x32_bf16 v[24:27], v[154:157], v[206:209], v[24:27]
	v_mfma_f32_16x16x32_bf16 v[12:15], v[146:149], v[214:217], v[12:15]
	v_mfma_f32_16x16x32_bf16 v[8:11], v[154:157], v[214:217], v[8:11]
	v_mfma_f32_16x16x32_bf16 v[62:65], v[150:153], v[188:191], v[62:65]
	v_mfma_f32_16x16x32_bf16 v[58:61], v[158:161], v[188:191], v[58:61]
	v_mfma_f32_16x16x32_bf16 v[46:49], v[150:153], v[202:205], v[46:49]
	v_mfma_f32_16x16x32_bf16 v[42:45], v[158:161], v[202:205], v[42:45]
	v_mfma_f32_16x16x32_bf16 v[28:31], v[150:153], v[210:213], v[28:31]
	v_mfma_f32_16x16x32_bf16 v[24:27], v[158:161], v[210:213], v[24:27]
	v_mfma_f32_16x16x32_bf16 v[12:15], v[150:153], v[218:221], v[12:15]
	v_mfma_f32_16x16x32_bf16 v[8:11], v[158:161], v[218:221], v[8:11]
	v_mfma_f32_16x16x32_bf16 v[54:57], v[162:165], v[184:187], v[54:57]
	v_mfma_f32_16x16x32_bf16 v[50:53], v[176:179], v[184:187], v[50:53]
	v_mfma_f32_16x16x32_bf16 v[38:41], v[162:165], v[198:201], v[38:41]
	v_mfma_f32_16x16x32_bf16 v[34:37], v[176:179], v[198:201], v[34:37]
	v_mfma_f32_16x16x32_bf16 v[20:23], v[162:165], v[206:209], v[20:23]
	v_mfma_f32_16x16x32_bf16 v[16:19], v[176:179], v[206:209], v[16:19]
	v_mfma_f32_16x16x32_bf16 v[4:7], v[162:165], v[214:217], v[4:7]
	v_mfma_f32_16x16x32_bf16 v[0:3], v[176:179], v[214:217], v[0:3]
	v_mfma_f32_16x16x32_bf16 v[54:57], v[166:169], v[188:191], v[54:57]
	v_mfma_f32_16x16x32_bf16 v[50:53], v[180:183], v[188:191], v[50:53]
	v_mfma_f32_16x16x32_bf16 v[38:41], v[166:169], v[202:205], v[38:41]
	v_mfma_f32_16x16x32_bf16 v[34:37], v[180:183], v[202:205], v[34:37]
	v_mfma_f32_16x16x32_bf16 v[20:23], v[166:169], v[210:213], v[20:23]
	v_mfma_f32_16x16x32_bf16 v[16:19], v[180:183], v[210:213], v[16:19]
	v_mfma_f32_16x16x32_bf16 v[4:7], v[166:169], v[218:221], v[4:7]
	v_mfma_f32_16x16x32_bf16 v[0:3], v[180:183], v[218:221], v[0:3]
	s_setprio 0
	s_barrier
	s_add_i32 s51, 0, 0x18000
	s_add_i32 s52, 0, 0x1c000
	v_add_u32_e32 v158, s51, v144
	v_add_u32_e32 v175, s52, v144
	ds_read_b128 v[146:149], v158
	ds_read_b128 v[150:153], v158 offset:1024
	ds_read_b128 v[154:157], v158 offset:2048
	ds_read_b128 v[158:161], v158 offset:3072
	ds_read_b128 v[162:165], v175
	ds_read_b128 v[166:169], v175 offset:1024
	ds_read_b128 v[176:179], v175 offset:2048
	ds_read_b128 v[180:183], v175 offset:3072
	s_add_u32 s30, s30, 0x160000
	s_addc_u32 s31, s31, 0
	s_mov_b32 m0, s42
	v_lshl_add_u64 v[226:227], s[30:31], 0, v[126:127]
	ds_read_b128 v[184:187], v145 offset:32768
	ds_read_b128 v[188:191], v145 offset:33792
	ds_read_b128 v[198:201], v145 offset:34816
	ds_read_b128 v[202:205], v145 offset:35840
	ds_read_b128 v[206:209], v145 offset:36864
	ds_read_b128 v[210:213], v145 offset:37888
	ds_read_b128 v[214:217], v145 offset:38912
	ds_read_b128 v[218:221], v145 offset:39936
	global_load_lds_dwordx4 v[226:227], off
	v_lshl_add_u64 v[226:227], s[30:31], 0, v[124:125]
	s_mov_b32 m0, s44
	s_nop 0
	global_load_lds_dwordx4 v[226:227], off
	s_waitcnt vmcnt(8)
	s_waitcnt lgkmcnt(0)
	s_barrier
	s_setprio 1
	s_waitcnt lgkmcnt(0)
	v_mfma_f32_16x16x32_bf16 v[118:121], v[146:149], v[184:187], v[118:121]
	v_mfma_f32_16x16x32_bf16 v[114:117], v[154:157], v[184:187], v[114:117]
	v_mfma_f32_16x16x32_bf16 v[134:137], v[146:149], v[198:201], v[134:137]
	v_mfma_f32_16x16x32_bf16 v[130:133], v[154:157], v[198:201], v[130:133]
	v_mfma_f32_16x16x32_bf16 v[94:97], v[146:149], v[206:209], v[94:97]
	v_mfma_f32_16x16x32_bf16 v[90:93], v[154:157], v[206:209], v[90:93]
	v_mfma_f32_16x16x32_bf16 v[78:81], v[146:149], v[214:217], v[78:81]
	v_mfma_f32_16x16x32_bf16 v[74:77], v[154:157], v[214:217], v[74:77]
	v_mfma_f32_16x16x32_bf16 v[118:121], v[150:153], v[188:191], v[118:121]
	v_mfma_f32_16x16x32_bf16 v[114:117], v[158:161], v[188:191], v[114:117]
	v_mfma_f32_16x16x32_bf16 v[134:137], v[150:153], v[202:205], v[134:137]
	v_mfma_f32_16x16x32_bf16 v[130:133], v[158:161], v[202:205], v[130:133]
	v_mfma_f32_16x16x32_bf16 v[94:97], v[150:153], v[210:213], v[94:97]
	v_mfma_f32_16x16x32_bf16 v[90:93], v[158:161], v[210:213], v[90:93]
	v_mfma_f32_16x16x32_bf16 v[78:81], v[150:153], v[218:221], v[78:81]
	v_mfma_f32_16x16x32_bf16 v[74:77], v[158:161], v[218:221], v[74:77]
	v_mfma_f32_16x16x32_bf16 v[102:105], v[162:165], v[184:187], v[102:105]
	v_mfma_f32_16x16x32_bf16 v[98:101], v[176:179], v[184:187], v[98:101]
	v_mfma_f32_16x16x32_bf16 v[110:113], v[162:165], v[198:201], v[110:113]
	v_mfma_f32_16x16x32_bf16 v[106:109], v[176:179], v[198:201], v[106:109]
	v_mfma_f32_16x16x32_bf16 v[86:89], v[162:165], v[206:209], v[86:89]
	v_mfma_f32_16x16x32_bf16 v[82:85], v[176:179], v[206:209], v[82:85]
	v_mfma_f32_16x16x32_bf16 v[70:73], v[162:165], v[214:217], v[70:73]
	v_mfma_f32_16x16x32_bf16 v[66:69], v[176:179], v[214:217], v[66:69]
	v_mfma_f32_16x16x32_bf16 v[102:105], v[166:169], v[188:191], v[102:105]
	v_mfma_f32_16x16x32_bf16 v[98:101], v[180:183], v[188:191], v[98:101]
	v_mfma_f32_16x16x32_bf16 v[110:113], v[166:169], v[202:205], v[110:113]
	v_mfma_f32_16x16x32_bf16 v[106:109], v[180:183], v[202:205], v[106:109]
	v_mfma_f32_16x16x32_bf16 v[86:89], v[166:169], v[210:213], v[86:89]
	v_mfma_f32_16x16x32_bf16 v[82:85], v[180:183], v[210:213], v[82:85]
	v_mfma_f32_16x16x32_bf16 v[70:73], v[166:169], v[218:221], v[70:73]
	v_mfma_f32_16x16x32_bf16 v[66:69], v[180:183], v[218:221], v[66:69]
	s_setprio 0
	s_barrier
; #define PG8_STAGE(bufoff, gbase, voff) do { _Pragma("unroll") for (int _i = 0; _i < 2; ++_i) \
;         __builtin_amdgcn_global_load_lds((const unsigned*)((const char*)(gbase) + (voff)[_i]), (PG8_LAS unsigned*)(lds + (bufoff) + ldsw + _i * 8192), 16, 0, 0); } while (0)
; #define PG8_LDA(dst, b, h) do { _Pragma("unroll") for (int m = 0; m < 4; ++m) _Pragma("unroll") for (int k = 0; k < 2; ++k) dst[m][k] = *(const PG8_LAS bf16x8*)(lds + PG8_SA(b, h) + aoff + m * 2048 + k * 1024); } while (0)
; #define PG8_MMA(ai, bj, At, Bt) do { __builtin_amdgcn_s_setprio(1); _Pragma("unroll") for (int m = 0; m < 4; ++m) _Pragma("unroll") for (int n = 0; n < 2; ++n) _Pragma("unroll") for (int k = 0; k < 2; ++k) \
;         acc[ai][bj][m][n] = __builtin_amdgcn_mfma_f32_16x16x32_bf16(Bt[n][k], At[m][k], acc[ai][bj][m][n], 0, 0, 0); __builtin_amdgcn_s_setprio(0); } while (0)
; #define PG8_WAIT_V(n) asm volatile("s_waitcnt vmcnt(" #n ")" ::: "memory")
; #define PG8_WAIT_L(n) asm volatile("s_waitcnt lgkmcnt(" #n ")" ::: "memory")
; #define PG8_BAR __builtin_amdgcn_s_barrier()
; #define PG8_SCHED __builtin_amdgcn_sched_barrier(0)
; template <class Epi, class Sched, bool ALIGN_EPI = false, bool SP2 = false, bool KHOOK = false>
; __device__ __forceinline__ void gemm_phase(PG8_LAS unsigned char* lds, const Gemm g, const Sched& S, const Epi& E, const int tid_in) {
;     ...
;             PG8_LDA(At, 1, 1); PG8_STAGE(PG8_SB(1, 0), b3, voffB); PG8_STAGE(PG8_SB(1, 1), b3 + hstep, voffB); PG8_STAGE(PG8_SA(1, 0), a3, voffA);
;             PG8_WAIT_V(8); PG8_WAIT_L(0); PG8_BAR; PG8_MMA(1, 0, At, B0); PG8_MMA(1, 1, At, B1); PG8_BAR; PG8_SCHED;
;     ...
;         if (!has_next) break;
; #pragma unroll
;         for (int a = 0; a < 2; ++a)
; #pragma unroll
;             for (int b = 0; b < 2; ++b)
; #pragma unroll
;                 for (int m = 0; m < 4; ++m)
; #pragma unroll
;                     for (int n = 0; n < 2; ++n) acc[a][b][m][n] = (f32x4){0.f, 0.f, 0.f, 0.f};
;         cur = nxt; cA = nA; cB = nB; ++ui; load_rr(cur);
	s_add_i32 s30, s51, s39
	v_lshl_add_u64 v[170:171], v[170:171], 0, s[90:91]
	s_mov_b32 m0, s30
	ds_read_b128 v[184:187], v145 offset:49152
	ds_read_b128 v[188:191], v145 offset:50176
	ds_read_b128 v[198:201], v145 offset:51200
	ds_read_b128 v[202:205], v145 offset:52224
	ds_read_b128 v[206:209], v145 offset:53248
	ds_read_b128 v[210:213], v145 offset:54272
	ds_read_b128 v[214:217], v145 offset:55296
	ds_read_b128 v[218:221], v145 offset:56320
	global_load_lds_dwordx4 v[170:171], off
	s_add_i32 m0, s30, 0x2000
	s_add_u32 s26, s26, 0x160080
	v_lshl_add_u64 v[170:171], v[192:193], 0, s[90:91]
	s_addc_u32 s27, s27, 0
	s_add_i32 s30, s52, s39
	global_load_lds_dwordx4 v[170:171], off
	v_lshl_add_u64 v[170:171], s[26:27], 0, v[32:33]
	s_mov_b32 m0, s30
	s_nop 0
	global_load_lds_dwordx4 v[170:171], off
	v_lshl_add_u64 v[170:171], s[26:27], 0, v[122:123]
	s_add_i32 m0, s30, 0x2000
	s_nop 0
	global_load_lds_dwordx4 v[170:171], off
	v_lshl_add_u64 v[170:171], v[222:223], 0, s[90:91]
	s_mov_b32 m0, s46
	s_nop 0
	global_load_lds_dwordx4 v[170:171], off
	v_lshl_add_u64 v[170:171], v[224:225], 0, s[90:91]
	s_mov_b32 m0, s47
	s_nop 0
	global_load_lds_dwordx4 v[170:171], off
	s_waitcnt vmcnt(8)
	s_waitcnt lgkmcnt(0)
	s_barrier
	s_setprio 1
	s_waitcnt lgkmcnt(0)
	v_mfma_f32_16x16x32_bf16 v[62:65], v[146:149], v[184:187], v[62:65]
	v_mfma_f32_16x16x32_bf16 v[58:61], v[154:157], v[184:187], v[58:61]
	v_mfma_f32_16x16x32_bf16 v[46:49], v[146:149], v[198:201], v[46:49]
	v_mfma_f32_16x16x32_bf16 v[42:45], v[154:157], v[198:201], v[42:45]
	v_mfma_f32_16x16x32_bf16 v[28:31], v[146:149], v[206:209], v[28:31]
	v_mfma_f32_16x16x32_bf16 v[24:27], v[154:157], v[206:209], v[24:27]
	v_mfma_f32_16x16x32_bf16 v[12:15], v[146:149], v[214:217], v[12:15]
	v_mfma_f32_16x16x32_bf16 v[8:11], v[154:157], v[214:217], v[8:11]
	v_mfma_f32_16x16x32_bf16 v[62:65], v[150:153], v[188:191], v[62:65]
	v_mfma_f32_16x16x32_bf16 v[58:61], v[158:161], v[188:191], v[58:61]
	v_mfma_f32_16x16x32_bf16 v[46:49], v[150:153], v[202:205], v[46:49]
	v_mfma_f32_16x16x32_bf16 v[42:45], v[158:161], v[202:205], v[42:45]
	v_mfma_f32_16x16x32_bf16 v[28:31], v[150:153], v[210:213], v[28:31]
	v_mfma_f32_16x16x32_bf16 v[24:27], v[158:161], v[210:213], v[24:27]
	v_mfma_f32_16x16x32_bf16 v[12:15], v[150:153], v[218:221], v[12:15]
	v_mfma_f32_16x16x32_bf16 v[8:11], v[158:161], v[218:221], v[8:11]
	v_mfma_f32_16x16x32_bf16 v[54:57], v[162:165], v[184:187], v[54:57]
	v_mfma_f32_16x16x32_bf16 v[50:53], v[176:179], v[184:187], v[50:53]
	v_mfma_f32_16x16x32_bf16 v[38:41], v[162:165], v[198:201], v[38:41]
	v_mfma_f32_16x16x32_bf16 v[34:37], v[176:179], v[198:201], v[34:37]
	v_mfma_f32_16x16x32_bf16 v[20:23], v[162:165], v[206:209], v[20:23]
	v_mfma_f32_16x16x32_bf16 v[16:19], v[176:179], v[206:209], v[16:19]
	v_mfma_f32_16x16x32_bf16 v[4:7], v[162:165], v[214:217], v[4:7]
	v_mfma_f32_16x16x32_bf16 v[0:3], v[176:179], v[214:217], v[0:3]
	v_mfma_f32_16x16x32_bf16 v[54:57], v[166:169], v[188:191], v[54:57]
	v_mfma_f32_16x16x32_bf16 v[50:53], v[180:183], v[188:191], v[50:53]
	v_mfma_f32_16x16x32_bf16 v[38:41], v[166:169], v[202:205], v[38:41]
	v_mfma_f32_16x16x32_bf16 v[34:37], v[180:183], v[202:205], v[34:37]
	v_mfma_f32_16x16x32_bf16 v[20:23], v[166:169], v[210:213], v[20:23]
	v_mfma_f32_16x16x32_bf16 v[16:19], v[180:183], v[210:213], v[16:19]
	v_mfma_f32_16x16x32_bf16 v[4:7], v[166:169], v[218:221], v[4:7]
	v_mfma_f32_16x16x32_bf16 v[0:3], v[180:183], v[218:221], v[0:3]
	s_setprio 0
	s_barrier
	s_add_i32 s25, s25, 2
	s_add_u32 s22, s22, 0x100
	s_addc_u32 s23, s23, 0
	s_cmpk_gt_u32 s25, 0x55
	s_cbranch_scc0 .LBB0_1170
	s_add_u32 s18, s18, 0xffffff00
	s_addc_u32 s19, s19, -1
	s_and_b64 vcc, exec, s[4:5]
	s_cbranch_vccnz .LBB0_1173
	v_mov_b32_e32 v0, 0
	s_mov_b32 s33, s50
	s_mov_b32 s0, s49
	s_mov_b64 s[10:11], s[16:17]
	s_mov_b32 s48, s24
	v_mov_b32_e32 v1, v0
	v_mov_b32_e32 v2, v0
	v_mov_b32_e32 v3, v0
	v_mov_b32_e32 v4, v0
	v_mov_b32_e32 v5, v0
	v_mov_b32_e32 v6, v0
	v_mov_b32_e32 v7, v0
	v_mov_b32_e32 v16, v0
	v_mov_b32_e32 v17, v0
	v_mov_b32_e32 v18, v0
	v_mov_b32_e32 v19, v0
	v_mov_b32_e32 v20, v0
	v_mov_b32_e32 v21, v0
	v_mov_b32_e32 v22, v0
	v_mov_b32_e32 v23, v0
	v_mov_b32_e32 v34, v0
	v_mov_b32_e32 v35, v0
	v_mov_b32_e32 v36, v0
	v_mov_b32_e32 v37, v0
	v_mov_b32_e32 v38, v0
	v_mov_b32_e32 v39, v0
	v_mov_b32_e32 v40, v0
	v_mov_b32_e32 v41, v0
	v_mov_b32_e32 v50, v0
	v_mov_b32_e32 v51, v0
	v_mov_b32_e32 v52, v0
	v_mov_b32_e32 v53, v0
	v_mov_b32_e32 v54, v0
	v_mov_b32_e32 v55, v0
	v_mov_b32_e32 v56, v0
	v_mov_b32_e32 v57, v0
	v_mov_b32_e32 v8, v0
	v_mov_b32_e32 v9, v0
	v_mov_b32_e32 v10, v0
	v_mov_b32_e32 v11, v0
	v_mov_b32_e32 v12, v0
	v_mov_b32_e32 v13, v0
	v_mov_b32_e32 v14, v0
	v_mov_b32_e32 v15, v0
	v_mov_b32_e32 v24, v0
	v_mov_b32_e32 v25, v0
	v_mov_b32_e32 v26, v0
	v_mov_b32_e32 v27, v0
	v_mov_b32_e32 v28, v0
	v_mov_b32_e32 v29, v0
	v_mov_b32_e32 v30, v0
	v_mov_b32_e32 v31, v0
	v_mov_b32_e32 v42, v0
	v_mov_b32_e32 v43, v0
	v_mov_b32_e32 v44, v0
	v_mov_b32_e32 v45, v0
	v_mov_b32_e32 v46, v0
	v_mov_b32_e32 v47, v0
	v_mov_b32_e32 v48, v0
	v_mov_b32_e32 v49, v0
	v_mov_b32_e32 v58, v0
	v_mov_b32_e32 v59, v0
	v_mov_b32_e32 v60, v0
	v_mov_b32_e32 v61, v0
	v_mov_b32_e32 v62, v0
	v_mov_b32_e32 v63, v0
	v_mov_b32_e32 v64, v0
	v_mov_b32_e32 v65, v0
	v_mov_b32_e32 v66, v0
	v_mov_b32_e32 v67, v0
	v_mov_b32_e32 v68, v0
	v_mov_b32_e32 v69, v0
	v_mov_b32_e32 v70, v0
	v_mov_b32_e32 v71, v0
	v_mov_b32_e32 v72, v0
	v_mov_b32_e32 v73, v0
	v_mov_b32_e32 v82, v0
	v_mov_b32_e32 v83, v0
	v_mov_b32_e32 v84, v0
	v_mov_b32_e32 v85, v0
	v_mov_b32_e32 v86, v0
	v_mov_b32_e32 v87, v0
	v_mov_b32_e32 v88, v0
	v_mov_b32_e32 v89, v0
	v_mov_b32_e32 v106, v0
	v_mov_b32_e32 v107, v0
	v_mov_b32_e32 v108, v0
	v_mov_b32_e32 v109, v0
	v_mov_b32_e32 v110, v0
	v_mov_b32_e32 v111, v0
	v_mov_b32_e32 v112, v0
	v_mov_b32_e32 v113, v0
	v_mov_b32_e32 v98, v0
	v_mov_b32_e32 v99, v0
	v_mov_b32_e32 v100, v0
	v_mov_b32_e32 v101, v0
	v_mov_b32_e32 v102, v0
	v_mov_b32_e32 v103, v0
	v_mov_b32_e32 v104, v0
	v_mov_b32_e32 v105, v0
	v_mov_b32_e32 v74, v0
	v_mov_b32_e32 v75, v0
	v_mov_b32_e32 v76, v0
	v_mov_b32_e32 v77, v0
	v_mov_b32_e32 v78, v0
	v_mov_b32_e32 v79, v0
	v_mov_b32_e32 v80, v0
	v_mov_b32_e32 v81, v0
	v_mov_b32_e32 v90, v0
	v_mov_b32_e32 v91, v0
	v_mov_b32_e32 v92, v0
	v_mov_b32_e32 v93, v0
	v_mov_b32_e32 v94, v0
	v_mov_b32_e32 v95, v0
	v_mov_b32_e32 v96, v0
	v_mov_b32_e32 v97, v0
	v_mov_b32_e32 v130, v0
	v_mov_b32_e32 v131, v0
	v_mov_b32_e32 v132, v0
	v_mov_b32_e32 v133, v0
	v_mov_b32_e32 v134, v0
	v_mov_b32_e32 v135, v0
	v_mov_b32_e32 v136, v0
	v_mov_b32_e32 v137, v0
	v_mov_b32_e32 v114, v0
	v_mov_b32_e32 v115, v0
	v_mov_b32_e32 v116, v0
	v_mov_b32_e32 v117, v0
	v_mov_b32_e32 v118, v0
	v_mov_b32_e32 v119, v0
	v_mov_b32_e32 v120, v0
	v_mov_b32_e32 v121, v0
	s_andn2_b64 vcc, exec, s[12:13]
	s_cbranch_vccnz .LBB0_1174
	s_branch .LBB0_1175

; #define PG8_STAGE(bufoff, gbase, voff) do { _Pragma("unroll") for (int _i = 0; _i < 2; ++_i) \
;         __builtin_amdgcn_global_load_lds((const unsigned*)((const char*)(gbase) + (voff)[_i]), (PG8_LAS unsigned*)(lds + (bufoff) + ldsw + _i * 8192), 16, 0, 0); } while (0)
; #define PG8_LDA(dst, b, h) do { _Pragma("unroll") for (int m = 0; m < 4; ++m) _Pragma("unroll") for (int k = 0; k < 2; ++k) dst[m][k] = *(const PG8_LAS bf16x8*)(lds + PG8_SA(b, h) + aoff + m * 2048 + k * 1024); } while (0)
; #define PG8_LDB(dst, b, h) do { _Pragma("unroll") for (int n = 0; n < 2; ++n) _Pragma("unroll") for (int k = 0; k < 2; ++k) dst[n][k] = *(const PG8_LAS bf16x8*)(lds + PG8_SB(b, h) + boff + n * 2048 + k * 1024); } while (0)
; #define PG8_MMA(ai, bj, At, Bt) do { __builtin_amdgcn_s_setprio(1); _Pragma("unroll") for (int m = 0; m < 4; ++m) _Pragma("unroll") for (int n = 0; n < 2; ++n) _Pragma("unroll") for (int k = 0; k < 2; ++k) \
;         acc[ai][bj][m][n] = __builtin_amdgcn_mfma_f32_16x16x32_bf16(Bt[n][k], At[m][k], acc[ai][bj][m][n], 0, 0, 0); __builtin_amdgcn_s_setprio(0); } while (0)
; #define PG8_WAIT_V(n) asm volatile("s_waitcnt vmcnt(" #n ")" ::: "memory")
; #define PG8_WAIT_L(n) asm volatile("s_waitcnt lgkmcnt(" #n ")" ::: "memory")
; #define PG8_BAR __builtin_amdgcn_s_barrier()
; template <class Epi, class Sched, bool ALIGN_EPI = false, bool SP2 = false, bool KHOOK = false>
; __device__ __forceinline__ void gemm_phase(PG8_LAS unsigned char* lds, const Gemm g, const Sched& S, const Epi& E, const int tid_in) {
;     ...
;         for (int t = 0; t < nt; t += 2) {
;             const bool last = (t == nt - 2);
;             const char* a1 = cA + (size_t)(t + 1) * kstep;
;             const char* a2 = last ? nA : cA + (size_t)(t + 2) * kstep; const char* b2 = last ? nB : cB + (size_t)(t + 2) * kstep;
;             const char* a3 = a2 + kstep; const char* b3 = b2 + kstep;
;             if (last && has_next) S.a_ready(nxt);
;             if constexpr (SP2) {
;             PG8_LDB(B0, 0, 0); PG8_LDB(B1, 0, 1); PG8_SCHED; PG8_LDA(At, 0, 0); PG8_STAGE(PG8_SA(1, 1), a1 + hstep, voffA);
;             PG8_WAIT_V(8); PG8_WAIT_L(0); PG8_BAR; PG8_MMA(0, 0, At, B0); PG8_MMA(0, 1, At, B1); PG8_BAR; PG8_SCHED;
;             PG8_LDA(At, 0, 1); PG8_STAGE(PG8_SB(0, 0), b2, voffB); PG8_STAGE(PG8_SB(0, 1), b2 + hstep, voffB); PG8_STAGE(PG8_SA(0, 0), a2, voffA);
.LBB0_1287:
	s_add_u32 s30, s4, s16
	s_addc_u32 s31, s5, s17
	s_add_u32 s30, s30, 0x100
	s_addc_u32 s31, s31, 0
	s_add_u32 s53, s25, s16
	s_addc_u32 s56, s47, s17
	s_add_i32 s57, 0, 0x10000
	s_cmpk_eq_i32 s16, 0xf00
	s_cselect_b32 s49, s11, s31
	s_cselect_b32 s48, s50, s30
	s_cselect_b32 s31, s9, s56
	s_cselect_b32 s30, s51, s53
	s_add_i32 s53, 0, 0x14000
	v_add_u32_e32 v158, s57, v144
	v_add_u32_e32 v174, s53, v144
	ds_read_b128 v[146:149], v158
	ds_read_b128 v[150:153], v158 offset:1024
	ds_read_b128 v[154:157], v158 offset:2048
	ds_read_b128 v[158:161], v158 offset:3072
	ds_read_b128 v[162:165], v174
	ds_read_b128 v[166:169], v174 offset:1024
	ds_read_b128 v[170:173], v174 offset:2048
	ds_read_b128 v[174:177], v174 offset:3072
	v_lshl_add_u64 v[218:219], v[140:141], 0, s[16:17]
	s_add_i32 m0, s38, 0xc000
	ds_read_b128 v[178:181], v145
	ds_read_b128 v[182:185], v145 offset:1024
	ds_read_b128 v[186:189], v145 offset:2048
	ds_read_b128 v[190:193], v145 offset:3072
	ds_read_b128 v[198:201], v145 offset:4096
	ds_read_b128 v[202:205], v145 offset:5120
	ds_read_b128 v[206:209], v145 offset:6144
	ds_read_b128 v[210:213], v145 offset:7168
	global_load_lds_dwordx4 v[218:219], off
	v_lshl_add_u64 v[218:219], v[142:143], 0, s[16:17]
	s_add_i32 m0, s38, 0xe000
	s_nop 0
	global_load_lds_dwordx4 v[218:219], off
	s_waitcnt vmcnt(8)
	s_waitcnt lgkmcnt(0)
	s_barrier
	s_setprio 1
	s_waitcnt lgkmcnt(0)
	v_mfma_f32_16x16x32_bf16 v[54:57], v[146:149], v[178:181], v[54:57]
	v_mfma_f32_16x16x32_bf16 v[62:65], v[154:157], v[178:181], v[62:65]
	v_mfma_f32_16x16x32_bf16 v[82:85], v[146:149], v[186:189], v[82:85]
	v_mfma_f32_16x16x32_bf16 v[86:89], v[154:157], v[186:189], v[86:89]
	v_mfma_f32_16x16x32_bf16 v[106:109], v[146:149], v[198:201], v[106:109]
	v_mfma_f32_16x16x32_bf16 v[110:113], v[154:157], v[198:201], v[110:113]
	v_mfma_f32_16x16x32_bf16 v[126:129], v[146:149], v[206:209], v[126:129]
	v_mfma_f32_16x16x32_bf16 v[122:125], v[154:157], v[206:209], v[122:125]
	v_mfma_f32_16x16x32_bf16 v[54:57], v[150:153], v[182:185], v[54:57]
	v_mfma_f32_16x16x32_bf16 v[62:65], v[158:161], v[182:185], v[62:65]
	v_mfma_f32_16x16x32_bf16 v[82:85], v[150:153], v[190:193], v[82:85]
	v_mfma_f32_16x16x32_bf16 v[86:89], v[158:161], v[190:193], v[86:89]
	v_mfma_f32_16x16x32_bf16 v[106:109], v[150:153], v[202:205], v[106:109]
	v_mfma_f32_16x16x32_bf16 v[110:113], v[158:161], v[202:205], v[110:113]
	v_mfma_f32_16x16x32_bf16 v[126:129], v[150:153], v[210:213], v[126:129]
	v_mfma_f32_16x16x32_bf16 v[122:125], v[158:161], v[210:213], v[122:125]
	v_mfma_f32_16x16x32_bf16 v[70:73], v[162:165], v[178:181], v[70:73]
	v_mfma_f32_16x16x32_bf16 v[78:81], v[170:173], v[178:181], v[78:81]
	v_mfma_f32_16x16x32_bf16 v[90:93], v[162:165], v[186:189], v[90:93]
	v_mfma_f32_16x16x32_bf16 v[98:101], v[170:173], v[186:189], v[98:101]
	v_mfma_f32_16x16x32_bf16 v[114:117], v[162:165], v[198:201], v[114:117]
	v_mfma_f32_16x16x32_bf16 v[118:121], v[170:173], v[198:201], v[118:121]
	v_mfma_f32_16x16x32_bf16 v[102:105], v[162:165], v[206:209], v[102:105]
	v_mfma_f32_16x16x32_bf16 v[94:97], v[170:173], v[206:209], v[94:97]
	v_mfma_f32_16x16x32_bf16 v[70:73], v[166:169], v[182:185], v[70:73]
	v_mfma_f32_16x16x32_bf16 v[78:81], v[174:177], v[182:185], v[78:81]
	v_mfma_f32_16x16x32_bf16 v[90:93], v[166:169], v[190:193], v[90:93]
	v_mfma_f32_16x16x32_bf16 v[98:101], v[174:177], v[190:193], v[98:101]
	v_mfma_f32_16x16x32_bf16 v[114:117], v[166:169], v[202:205], v[114:117]
	v_mfma_f32_16x16x32_bf16 v[118:121], v[174:177], v[202:205], v[118:121]
	v_mfma_f32_16x16x32_bf16 v[102:105], v[166:169], v[210:213], v[102:105]
	v_mfma_f32_16x16x32_bf16 v[94:97], v[174:177], v[210:213], v[94:97]
	s_setprio 0
	s_barrier
	s_add_i32 s56, s57, s37
	v_lshl_add_u64 v[218:219], s[30:31], 0, v[32:33]
	s_mov_b32 m0, s56
	ds_read_b128 v[178:181], v145 offset:16384
	ds_read_b128 v[182:185], v145 offset:17408
	ds_read_b128 v[186:189], v145 offset:18432
	ds_read_b128 v[190:193], v145 offset:19456
	ds_read_b128 v[198:201], v145 offset:20480
	ds_read_b128 v[202:205], v145 offset:21504
	ds_read_b128 v[206:209], v145 offset:22528
	ds_read_b128 v[210:213], v145 offset:23552
	global_load_lds_dwordx4 v[218:219], off
	s_add_i32 m0, s56, 0x2000
	s_add_u32 s56, s30, 0x80000
	v_lshl_add_u64 v[220:221], s[30:31], 0, v[130:131]
	s_addc_u32 s57, s31, 0
	s_add_i32 s53, s53, s37
	global_load_lds_dwordx4 v[220:221], off
	v_lshl_add_u64 v[222:223], s[56:57], 0, v[32:33]
	s_mov_b32 m0, s53
	v_lshl_add_u64 v[224:225], s[48:49], 0, v[132:133]
	global_load_lds_dwordx4 v[222:223], off
	v_lshl_add_u64 v[222:223], s[56:57], 0, v[130:131]
	s_add_i32 m0, s53, 0x2000
	s_nop 0
	global_load_lds_dwordx4 v[222:223], off
	v_lshl_add_u64 v[222:223], s[48:49], 0, v[134:135]
	s_mov_b32 m0, s38
	s_nop 0
	global_load_lds_dwordx4 v[222:223], off
	s_mov_b32 m0, s39
	s_nop 0
	global_load_lds_dwordx4 v[224:225], off
	s_waitcnt vmcnt(8)
	s_waitcnt lgkmcnt(0)
	s_barrier
; #define PG8_STAGE(bufoff, gbase, voff) do { _Pragma("unroll") for (int _i = 0; _i < 2; ++_i) \
;         __builtin_amdgcn_global_load_lds((const unsigned*)((const char*)(gbase) + (voff)[_i]), (PG8_LAS unsigned*)(lds + (bufoff) + ldsw + _i * 8192), 16, 0, 0); } while (0)
; #define PG8_LDA(dst, b, h) do { _Pragma("unroll") for (int m = 0; m < 4; ++m) _Pragma("unroll") for (int k = 0; k < 2; ++k) dst[m][k] = *(const PG8_LAS bf16x8*)(lds + PG8_SA(b, h) + aoff + m * 2048 + k * 1024); } while (0)
; #define PG8_LDB(dst, b, h) do { _Pragma("unroll") for (int n = 0; n < 2; ++n) _Pragma("unroll") for (int k = 0; k < 2; ++k) dst[n][k] = *(const PG8_LAS bf16x8*)(lds + PG8_SB(b, h) + boff + n * 2048 + k * 1024); } while (0)
; #define PG8_MMA(ai, bj, At, Bt) do { __builtin_amdgcn_s_setprio(1); _Pragma("unroll") for (int m = 0; m < 4; ++m) _Pragma("unroll") for (int n = 0; n < 2; ++n) _Pragma("unroll") for (int k = 0; k < 2; ++k) \
;         acc[ai][bj][m][n] = __builtin_amdgcn_mfma_f32_16x16x32_bf16(Bt[n][k], At[m][k], acc[ai][bj][m][n], 0, 0, 0); __builtin_amdgcn_s_setprio(0); } while (0)
; #define PG8_WAIT_V(n) asm volatile("s_waitcnt vmcnt(" #n ")" ::: "memory")
; #define PG8_WAIT_L(n) asm volatile("s_waitcnt lgkmcnt(" #n ")" ::: "memory")
; #define PG8_BAR __builtin_amdgcn_s_barrier()
; #define PG8_SCHED __builtin_amdgcn_sched_barrier(0)
; template <class Epi, class Sched, bool ALIGN_EPI = false, bool SP2 = false, bool KHOOK = false>
; __device__ __forceinline__ void gemm_phase(PG8_LAS unsigned char* lds, const Gemm g, const Sched& S, const Epi& E, const int tid_in) {
;     ...
;             PG8_WAIT_V(8); PG8_WAIT_L(0); PG8_BAR; PG8_MMA(1, 0, At, B0); PG8_MMA(1, 1, At, B1); PG8_BAR; PG8_SCHED;
;             PG8_LDB(B0, 1, 0); PG8_LDB(B1, 1, 1); PG8_SCHED; PG8_LDA(At, 1, 0); PG8_STAGE(PG8_SA(0, 1), a2 + hstep, voffA);
;             PG8_WAIT_V(8); PG8_WAIT_L(0); PG8_BAR; PG8_MMA(0, 0, At, B0); PG8_MMA(0, 1, At, B1); PG8_BAR; PG8_SCHED;
	s_setprio 1
	s_waitcnt lgkmcnt(0)
	v_mfma_f32_16x16x32_bf16 v[74:77], v[146:149], v[178:181], v[74:77]
	v_mfma_f32_16x16x32_bf16 v[66:69], v[154:157], v[178:181], v[66:69]
	v_mfma_f32_16x16x32_bf16 v[46:49], v[146:149], v[186:189], v[46:49]
	v_mfma_f32_16x16x32_bf16 v[42:45], v[154:157], v[186:189], v[42:45]
	v_mfma_f32_16x16x32_bf16 v[28:31], v[146:149], v[198:201], v[28:31]
	v_mfma_f32_16x16x32_bf16 v[24:27], v[154:157], v[198:201], v[24:27]
	v_mfma_f32_16x16x32_bf16 v[12:15], v[146:149], v[206:209], v[12:15]
	v_mfma_f32_16x16x32_bf16 v[8:11], v[154:157], v[206:209], v[8:11]
	v_mfma_f32_16x16x32_bf16 v[74:77], v[150:153], v[182:185], v[74:77]
	v_mfma_f32_16x16x32_bf16 v[66:69], v[158:161], v[182:185], v[66:69]
	v_mfma_f32_16x16x32_bf16 v[46:49], v[150:153], v[190:193], v[46:49]
	v_mfma_f32_16x16x32_bf16 v[42:45], v[158:161], v[190:193], v[42:45]
	v_mfma_f32_16x16x32_bf16 v[28:31], v[150:153], v[202:205], v[28:31]
	v_mfma_f32_16x16x32_bf16 v[24:27], v[158:161], v[202:205], v[24:27]
	v_mfma_f32_16x16x32_bf16 v[12:15], v[150:153], v[210:213], v[12:15]
	v_mfma_f32_16x16x32_bf16 v[8:11], v[158:161], v[210:213], v[8:11]
	v_mfma_f32_16x16x32_bf16 v[58:61], v[162:165], v[178:181], v[58:61]
	v_mfma_f32_16x16x32_bf16 v[50:53], v[170:173], v[178:181], v[50:53]
	v_mfma_f32_16x16x32_bf16 v[38:41], v[162:165], v[186:189], v[38:41]
	v_mfma_f32_16x16x32_bf16 v[34:37], v[170:173], v[186:189], v[34:37]
	v_mfma_f32_16x16x32_bf16 v[20:23], v[162:165], v[198:201], v[20:23]
	v_mfma_f32_16x16x32_bf16 v[16:19], v[170:173], v[198:201], v[16:19]
	v_mfma_f32_16x16x32_bf16 v[4:7], v[162:165], v[206:209], v[4:7]
	v_mfma_f32_16x16x32_bf16 v[0:3], v[170:173], v[206:209], v[0:3]
	v_mfma_f32_16x16x32_bf16 v[58:61], v[166:169], v[182:185], v[58:61]
	v_mfma_f32_16x16x32_bf16 v[50:53], v[174:177], v[182:185], v[50:53]
	v_mfma_f32_16x16x32_bf16 v[38:41], v[166:169], v[190:193], v[38:41]
	v_mfma_f32_16x16x32_bf16 v[34:37], v[174:177], v[190:193], v[34:37]
	v_mfma_f32_16x16x32_bf16 v[20:23], v[166:169], v[202:205], v[20:23]
	v_mfma_f32_16x16x32_bf16 v[16:19], v[174:177], v[202:205], v[16:19]
	v_mfma_f32_16x16x32_bf16 v[4:7], v[166:169], v[210:213], v[4:7]
	v_mfma_f32_16x16x32_bf16 v[0:3], v[174:177], v[210:213], v[0:3]
	s_setprio 0
	s_barrier
	s_add_i32 s53, 0, 0x18000
	s_add_i32 s56, 0, 0x1c000
	v_add_u32_e32 v158, s53, v144
	v_add_u32_e32 v174, s56, v144
	ds_read_b128 v[146:149], v158
	ds_read_b128 v[150:153], v158 offset:1024
	ds_read_b128 v[154:157], v158 offset:2048
	ds_read_b128 v[158:161], v158 offset:3072
	ds_read_b128 v[162:165], v174
	ds_read_b128 v[166:169], v174 offset:1024
	ds_read_b128 v[170:173], v174 offset:2048
	ds_read_b128 v[174:177], v174 offset:3072
	s_add_u32 s48, s48, 0x80000
	s_addc_u32 s49, s49, 0
	s_mov_b32 m0, s40
	v_lshl_add_u64 v[226:227], s[48:49], 0, v[134:135]
	ds_read_b128 v[178:181], v145 offset:32768
	ds_read_b128 v[182:185], v145 offset:33792
	ds_read_b128 v[186:189], v145 offset:34816
	ds_read_b128 v[190:193], v145 offset:35840
	ds_read_b128 v[198:201], v145 offset:36864
	ds_read_b128 v[202:205], v145 offset:37888
	ds_read_b128 v[206:209], v145 offset:38912
	ds_read_b128 v[210:213], v145 offset:39936
	global_load_lds_dwordx4 v[226:227], off
	v_lshl_add_u64 v[226:227], s[48:49], 0, v[132:133]
	s_mov_b32 m0, s42
	s_nop 0
	global_load_lds_dwordx4 v[226:227], off
	s_waitcnt vmcnt(8)
	s_waitcnt lgkmcnt(0)
	s_barrier
	s_setprio 1
	s_waitcnt lgkmcnt(0)
	v_mfma_f32_16x16x32_bf16 v[54:57], v[146:149], v[178:181], v[54:57]
	v_mfma_f32_16x16x32_bf16 v[62:65], v[154:157], v[178:181], v[62:65]
	v_mfma_f32_16x16x32_bf16 v[82:85], v[146:149], v[186:189], v[82:85]
	v_mfma_f32_16x16x32_bf16 v[86:89], v[154:157], v[186:189], v[86:89]
	v_mfma_f32_16x16x32_bf16 v[106:109], v[146:149], v[198:201], v[106:109]
	v_mfma_f32_16x16x32_bf16 v[110:113], v[154:157], v[198:201], v[110:113]
	v_mfma_f32_16x16x32_bf16 v[126:129], v[146:149], v[206:209], v[126:129]
	v_mfma_f32_16x16x32_bf16 v[122:125], v[154:157], v[206:209], v[122:125]
	v_mfma_f32_16x16x32_bf16 v[54:57], v[150:153], v[182:185], v[54:57]
	v_mfma_f32_16x16x32_bf16 v[62:65], v[158:161], v[182:185], v[62:65]
	v_mfma_f32_16x16x32_bf16 v[82:85], v[150:153], v[190:193], v[82:85]
	v_mfma_f32_16x16x32_bf16 v[86:89], v[158:161], v[190:193], v[86:89]
	v_mfma_f32_16x16x32_bf16 v[106:109], v[150:153], v[202:205], v[106:109]
	v_mfma_f32_16x16x32_bf16 v[110:113], v[158:161], v[202:205], v[110:113]
	v_mfma_f32_16x16x32_bf16 v[126:129], v[150:153], v[210:213], v[126:129]
	v_mfma_f32_16x16x32_bf16 v[122:125], v[158:161], v[210:213], v[122:125]
	v_mfma_f32_16x16x32_bf16 v[70:73], v[162:165], v[178:181], v[70:73]
	v_mfma_f32_16x16x32_bf16 v[78:81], v[170:173], v[178:181], v[78:81]
	v_mfma_f32_16x16x32_bf16 v[90:93], v[162:165], v[186:189], v[90:93]
	v_mfma_f32_16x16x32_bf16 v[98:101], v[170:173], v[186:189], v[98:101]
	v_mfma_f32_16x16x32_bf16 v[114:117], v[162:165], v[198:201], v[114:117]
	v_mfma_f32_16x16x32_bf16 v[118:121], v[170:173], v[198:201], v[118:121]
	v_mfma_f32_16x16x32_bf16 v[102:105], v[162:165], v[206:209], v[102:105]
	v_mfma_f32_16x16x32_bf16 v[94:97], v[170:173], v[206:209], v[94:97]
	v_mfma_f32_16x16x32_bf16 v[70:73], v[166:169], v[182:185], v[70:73]
	v_mfma_f32_16x16x32_bf16 v[78:81], v[174:177], v[182:185], v[78:81]
	v_mfma_f32_16x16x32_bf16 v[90:93], v[166:169], v[190:193], v[90:93]
	v_mfma_f32_16x16x32_bf16 v[98:101], v[174:177], v[190:193], v[98:101]
	v_mfma_f32_16x16x32_bf16 v[114:117], v[166:169], v[202:205], v[114:117]
	v_mfma_f32_16x16x32_bf16 v[118:121], v[174:177], v[202:205], v[118:121]
	v_mfma_f32_16x16x32_bf16 v[102:105], v[166:169], v[210:213], v[102:105]
	v_mfma_f32_16x16x32_bf16 v[94:97], v[174:177], v[210:213], v[94:97]
	s_setprio 0
	s_barrier
; #define PG8_STAGE(bufoff, gbase, voff) do { _Pragma("unroll") for (int _i = 0; _i < 2; ++_i) \
;         __builtin_amdgcn_global_load_lds((const unsigned*)((const char*)(gbase) + (voff)[_i]), (PG8_LAS unsigned*)(lds + (bufoff) + ldsw + _i * 8192), 16, 0, 0); } while (0)
; #define PG8_LDA(dst, b, h) do { _Pragma("unroll") for (int m = 0; m < 4; ++m) _Pragma("unroll") for (int k = 0; k < 2; ++k) dst[m][k] = *(const PG8_LAS bf16x8*)(lds + PG8_SA(b, h) + aoff + m * 2048 + k * 1024); } while (0)
; #define PG8_MMA(ai, bj, At, Bt) do { __builtin_amdgcn_s_setprio(1); _Pragma("unroll") for (int m = 0; m < 4; ++m) _Pragma("unroll") for (int n = 0; n < 2; ++n) _Pragma("unroll") for (int k = 0; k < 2; ++k) \
;         acc[ai][bj][m][n] = __builtin_amdgcn_mfma_f32_16x16x32_bf16(Bt[n][k], At[m][k], acc[ai][bj][m][n], 0, 0, 0); __builtin_amdgcn_s_setprio(0); } while (0)
; #define PG8_WAIT_V(n) asm volatile("s_waitcnt vmcnt(" #n ")" ::: "memory")
; #define PG8_WAIT_L(n) asm volatile("s_waitcnt lgkmcnt(" #n ")" ::: "memory")
; #define PG8_BAR __builtin_amdgcn_s_barrier()
; #define PG8_SCHED __builtin_amdgcn_sched_barrier(0)
; template <class Epi, class Sched, bool ALIGN_EPI = false, bool SP2 = false, bool KHOOK = false>
; __device__ __forceinline__ void gemm_phase(PG8_LAS unsigned char* lds, const Gemm g, const Sched& S, const Epi& E, const int tid_in) {
;     ...
;             PG8_LDA(At, 1, 1); PG8_STAGE(PG8_SB(1, 0), b3, voffB); PG8_STAGE(PG8_SB(1, 1), b3 + hstep, voffB); PG8_STAGE(PG8_SA(1, 0), a3, voffA);
;             PG8_WAIT_V(8); PG8_WAIT_L(0); PG8_BAR; PG8_MMA(1, 0, At, B0); PG8_MMA(1, 1, At, B1); PG8_BAR; PG8_SCHED;
;     ...
;         if (!has_next) break;
; #pragma unroll
;         for (int a = 0; a < 2; ++a)
; #pragma unroll
;             for (int b = 0; b < 2; ++b)
; #pragma unroll
;                 for (int m = 0; m < 4; ++m)
; #pragma unroll
;                     for (int n = 0; n < 2; ++n) acc[a][b][m][n] = (f32x4){0.f, 0.f, 0.f, 0.f};
;         cur = nxt; cA = nA; cB = nB; ++ui; load_rr(cur);
	s_add_i32 s48, s53, s37
	v_lshl_add_u64 v[218:219], v[218:219], 0, s[90:91]
	s_mov_b32 m0, s48
	ds_read_b128 v[178:181], v145 offset:49152
	ds_read_b128 v[182:185], v145 offset:50176
	ds_read_b128 v[186:189], v145 offset:51200
	ds_read_b128 v[190:193], v145 offset:52224
	ds_read_b128 v[198:201], v145 offset:53248
	ds_read_b128 v[202:205], v145 offset:54272
	ds_read_b128 v[206:209], v145 offset:55296
	ds_read_b128 v[210:213], v145 offset:56320
	global_load_lds_dwordx4 v[218:219], off
	s_add_i32 m0, s48, 0x2000
	s_add_u32 s30, s30, 0x80080
	v_lshl_add_u64 v[218:219], v[220:221], 0, s[90:91]
	s_addc_u32 s31, s31, 0
	s_add_i32 s48, s56, s37
	global_load_lds_dwordx4 v[218:219], off
	v_lshl_add_u64 v[218:219], s[30:31], 0, v[32:33]
	s_mov_b32 m0, s48
	s_nop 0
	global_load_lds_dwordx4 v[218:219], off
	v_lshl_add_u64 v[218:219], s[30:31], 0, v[130:131]
	s_add_i32 m0, s48, 0x2000
	s_nop 0
	global_load_lds_dwordx4 v[218:219], off
	v_lshl_add_u64 v[218:219], v[222:223], 0, s[90:91]
	s_mov_b32 m0, s44
	s_nop 0
	global_load_lds_dwordx4 v[218:219], off
	v_lshl_add_u64 v[218:219], v[224:225], 0, s[90:91]
	s_mov_b32 m0, s45
	s_nop 0
	global_load_lds_dwordx4 v[218:219], off
	s_waitcnt vmcnt(8)
	s_waitcnt lgkmcnt(0)
	s_barrier
	s_setprio 1
	s_waitcnt lgkmcnt(0)
	v_mfma_f32_16x16x32_bf16 v[74:77], v[146:149], v[178:181], v[74:77]
	v_mfma_f32_16x16x32_bf16 v[66:69], v[154:157], v[178:181], v[66:69]
	v_mfma_f32_16x16x32_bf16 v[46:49], v[146:149], v[186:189], v[46:49]
	v_mfma_f32_16x16x32_bf16 v[42:45], v[154:157], v[186:189], v[42:45]
	v_mfma_f32_16x16x32_bf16 v[28:31], v[146:149], v[198:201], v[28:31]
	v_mfma_f32_16x16x32_bf16 v[24:27], v[154:157], v[198:201], v[24:27]
	v_mfma_f32_16x16x32_bf16 v[12:15], v[146:149], v[206:209], v[12:15]
	v_mfma_f32_16x16x32_bf16 v[8:11], v[154:157], v[206:209], v[8:11]
	v_mfma_f32_16x16x32_bf16 v[74:77], v[150:153], v[182:185], v[74:77]
	v_mfma_f32_16x16x32_bf16 v[66:69], v[158:161], v[182:185], v[66:69]
	v_mfma_f32_16x16x32_bf16 v[46:49], v[150:153], v[190:193], v[46:49]
	v_mfma_f32_16x16x32_bf16 v[42:45], v[158:161], v[190:193], v[42:45]
	v_mfma_f32_16x16x32_bf16 v[28:31], v[150:153], v[202:205], v[28:31]
	v_mfma_f32_16x16x32_bf16 v[24:27], v[158:161], v[202:205], v[24:27]
	v_mfma_f32_16x16x32_bf16 v[12:15], v[150:153], v[210:213], v[12:15]
	v_mfma_f32_16x16x32_bf16 v[8:11], v[158:161], v[210:213], v[8:11]
	v_mfma_f32_16x16x32_bf16 v[58:61], v[162:165], v[178:181], v[58:61]
	v_mfma_f32_16x16x32_bf16 v[50:53], v[170:173], v[178:181], v[50:53]
	v_mfma_f32_16x16x32_bf16 v[38:41], v[162:165], v[186:189], v[38:41]
	v_mfma_f32_16x16x32_bf16 v[34:37], v[170:173], v[186:189], v[34:37]
	v_mfma_f32_16x16x32_bf16 v[20:23], v[162:165], v[198:201], v[20:23]
	v_mfma_f32_16x16x32_bf16 v[16:19], v[170:173], v[198:201], v[16:19]
	v_mfma_f32_16x16x32_bf16 v[4:7], v[162:165], v[206:209], v[4:7]
	v_mfma_f32_16x16x32_bf16 v[0:3], v[170:173], v[206:209], v[0:3]
	v_mfma_f32_16x16x32_bf16 v[58:61], v[166:169], v[182:185], v[58:61]
	v_mfma_f32_16x16x32_bf16 v[50:53], v[174:177], v[182:185], v[50:53]
	v_mfma_f32_16x16x32_bf16 v[38:41], v[166:169], v[190:193], v[38:41]
	v_mfma_f32_16x16x32_bf16 v[34:37], v[174:177], v[190:193], v[34:37]
	v_mfma_f32_16x16x32_bf16 v[20:23], v[166:169], v[202:205], v[20:23]
	v_mfma_f32_16x16x32_bf16 v[16:19], v[174:177], v[202:205], v[16:19]
	v_mfma_f32_16x16x32_bf16 v[4:7], v[166:169], v[210:213], v[4:7]
	v_mfma_f32_16x16x32_bf16 v[0:3], v[174:177], v[210:213], v[0:3]
	s_setprio 0
	s_barrier
	s_add_i32 s52, s52, 2
	s_add_u32 s16, s16, 0x100
	s_addc_u32 s17, s17, 0
	s_cmp_gt_u32 s52, 29
	s_cbranch_scc0 .LBB0_1287
	s_add_u32 s16, s25, 0xffffff00
	s_addc_u32 s17, s47, -1
	s_andn2_b64 vcc, exec, s[22:23]
	s_cbranch_vccnz .LBB0_1290
	v_mov_b32_e32 v0, 0
	s_mov_b32 s20, s10
	s_mov_b32 s0, s8
	s_mov_b64 s[4:5], s[26:27]
	s_mov_b32 s46, s24
	v_mov_b32_e32 v1, v0
	v_mov_b32_e32 v2, v0
	v_mov_b32_e32 v3, v0
	v_mov_b32_e32 v4, v0
	v_mov_b32_e32 v5, v0
	v_mov_b32_e32 v6, v0
	v_mov_b32_e32 v7, v0
	v_mov_b32_e32 v16, v0
	v_mov_b32_e32 v17, v0
	v_mov_b32_e32 v18, v0
	v_mov_b32_e32 v19, v0
	v_mov_b32_e32 v20, v0
	v_mov_b32_e32 v21, v0
	v_mov_b32_e32 v22, v0
	v_mov_b32_e32 v23, v0
	v_mov_b32_e32 v34, v0
	v_mov_b32_e32 v35, v0
	v_mov_b32_e32 v36, v0
	v_mov_b32_e32 v37, v0
	v_mov_b32_e32 v38, v0
	v_mov_b32_e32 v39, v0
	v_mov_b32_e32 v40, v0
	v_mov_b32_e32 v41, v0
	v_mov_b32_e32 v50, v0
	v_mov_b32_e32 v51, v0
	v_mov_b32_e32 v52, v0
	v_mov_b32_e32 v53, v0
	v_mov_b32_e32 v58, v0
	v_mov_b32_e32 v59, v0
	v_mov_b32_e32 v60, v0
	v_mov_b32_e32 v61, v0
	v_mov_b32_e32 v8, v0
	v_mov_b32_e32 v9, v0
	v_mov_b32_e32 v10, v0
	v_mov_b32_e32 v11, v0
	v_mov_b32_e32 v12, v0
	v_mov_b32_e32 v13, v0
	v_mov_b32_e32 v14, v0
	v_mov_b32_e32 v15, v0
	v_mov_b32_e32 v24, v0
	v_mov_b32_e32 v25, v0
	v_mov_b32_e32 v26, v0
	v_mov_b32_e32 v27, v0
	v_mov_b32_e32 v28, v0
	v_mov_b32_e32 v29, v0
	v_mov_b32_e32 v30, v0
	v_mov_b32_e32 v31, v0
	v_mov_b32_e32 v42, v0
	v_mov_b32_e32 v43, v0
	v_mov_b32_e32 v44, v0
	v_mov_b32_e32 v45, v0
	v_mov_b32_e32 v46, v0
	v_mov_b32_e32 v47, v0
	v_mov_b32_e32 v48, v0
	v_mov_b32_e32 v49, v0
	v_mov_b32_e32 v66, v0
	v_mov_b32_e32 v67, v0
	v_mov_b32_e32 v68, v0
	v_mov_b32_e32 v69, v0
	v_mov_b32_e32 v74, v0
	v_mov_b32_e32 v75, v0
	v_mov_b32_e32 v76, v0
	v_mov_b32_e32 v77, v0
	v_mov_b32_e32 v94, v0
	v_mov_b32_e32 v95, v0
	v_mov_b32_e32 v96, v0
	v_mov_b32_e32 v97, v0
	v_mov_b32_e32 v102, v0
	v_mov_b32_e32 v103, v0
	v_mov_b32_e32 v104, v0
	v_mov_b32_e32 v105, v0
	v_mov_b32_e32 v118, v0
	v_mov_b32_e32 v119, v0
	v_mov_b32_e32 v120, v0
	v_mov_b32_e32 v121, v0
	v_mov_b32_e32 v114, v0
	v_mov_b32_e32 v115, v0
	v_mov_b32_e32 v116, v0
	v_mov_b32_e32 v117, v0
	v_mov_b32_e32 v98, v0
	v_mov_b32_e32 v99, v0
	v_mov_b32_e32 v100, v0
	v_mov_b32_e32 v101, v0
	v_mov_b32_e32 v90, v0
	v_mov_b32_e32 v91, v0
	v_mov_b32_e32 v92, v0
	v_mov_b32_e32 v93, v0
	v_mov_b32_e32 v78, v0
	v_mov_b32_e32 v79, v0
	v_mov_b32_e32 v80, v0
	v_mov_b32_e32 v81, v0
	v_mov_b32_e32 v70, v0
	v_mov_b32_e32 v71, v0
	v_mov_b32_e32 v72, v0
	v_mov_b32_e32 v73, v0
	v_mov_b32_e32 v122, v0
	v_mov_b32_e32 v123, v0
	v_mov_b32_e32 v124, v0
	v_mov_b32_e32 v125, v0
	v_mov_b32_e32 v126, v0
	v_mov_b32_e32 v127, v0
	v_mov_b32_e32 v128, v0
	v_mov_b32_e32 v129, v0
	v_mov_b32_e32 v110, v0
	v_mov_b32_e32 v111, v0
	v_mov_b32_e32 v112, v0
	v_mov_b32_e32 v113, v0
	v_mov_b32_e32 v106, v0
	v_mov_b32_e32 v107, v0
	v_mov_b32_e32 v108, v0
	v_mov_b32_e32 v109, v0
	v_mov_b32_e32 v86, v0
	v_mov_b32_e32 v87, v0
	v_mov_b32_e32 v88, v0
	v_mov_b32_e32 v89, v0
	v_mov_b32_e32 v82, v0
	v_mov_b32_e32 v83, v0
	v_mov_b32_e32 v84, v0
	v_mov_b32_e32 v85, v0
	v_mov_b32_e32 v62, v0
	v_mov_b32_e32 v63, v0
	v_mov_b32_e32 v64, v0
	v_mov_b32_e32 v65, v0
	v_mov_b32_e32 v54, v0
	v_mov_b32_e32 v55, v0
	v_mov_b32_e32 v56, v0
	v_mov_b32_e32 v57, v0
	s_andn2_b64 vcc, exec, s[12:13]
	s_cbranch_vccnz .LBB0_1291
	s_branch .LBB0_1292
